# K-loop barrier handoff shortened: s_setprio 1 moved before the pre-MFMA barrier and s_setprio 0 after the post-MFMA barrier (timing-only)
# speedup vs baseline: 1.0088x; 1.0088x over previous
; #define PG8_STAGE(bufoff, gbase, voff) do { _Pragma("unroll") for (int _i = 0; _i < 2; ++_i) \
;         __builtin_amdgcn_global_load_lds((const unsigned*)((const char*)(gbase) + (voff)[_i]), (PG8_LAS unsigned*)(lds + (bufoff) + ldsw + _i * 8192), 16, 0, 0); } while (0)
; #define PG8_SCHED __builtin_amdgcn_sched_barrier(0)
; __device__ __forceinline__ unsigned pk2(float lo, float hi) { return pg8::cvt_pk_bf16(lo, hi); }
; template <class Epi, class Sched, bool ALIGN_EPI = false, bool SP2 = false>
; __device__ __forceinline__ void gemm_phase(PG8_LAS unsigned char* lds, const Gemm g, const Sched& S, const Epi& E) {
;     ...
;         const bool has_next = S.next(ui + 1, nxt);
;         const char* nA = has_next ? (const char*)g.A + (size_t)nxt.pm * tstep : cA; const char* nB = has_next ? (const char*)g.Bt + (size_t)nxt.pn * tstep : cB;
;         for (int t = 0; t < nt; t += 2) {
;             const bool last = (t == nt - 2);
;             const char* a1 = cA + (size_t)(t + 1) * kstep;
;             const char* a2 = last ? nA : cA + (size_t)(t + 2) * kstep; const char* b2 = last ? nB : cB + (size_t)(t + 2) * kstep;
;             const char* a3 = a2 + kstep; const char* b3 = b2 + kstep;
;             if (last && has_next) S.a_ready(nxt);
;             if constexpr (SP2) {
;             PG8_LDB(B0, 0, 0); PG8_LDB(B1, 0, 1); PG8_SCHED; PG8_LDA(At, 0, 0); PG8_STAGE(PG8_SA(1, 1), a1 + hstep, voffA);
;     __device__ __forceinline__ void operator()(const f32x4 (&acc)[2][2][4][2], const pg8::Unit& u, int wr, int wc, int fr, int fq) const {
;         const int row0 = u.pm * 256 + wr * 64 + fr, col = u.pn * 128 + wc * 32 + 8 * fq;
; #pragma unroll
;         for (int ai = 0; ai < 2; ++ai)
; #pragma unroll
;             for (int m = 0; m < 4; ++m) {
;                 const int row = row0 + ai * 128 + m * 16;
;                 const float rs = sumsq ? rsqrtf(sumsq[row] * (1.f / 1024.f) + EPS) : 1.f;
;                 float o[8];
; #pragma unroll
;                 for (int n = 0; n < 2; ++n)
; #pragma unroll
;                     for (int e = 0; e < 4; ++e) { const float g = acc[ai][0][m][n][e] * rs, up = acc[ai][1][m][n][e] * rs; o[4 * n + e] = silu_f(g) * up; }
;                 u32x4 w; w.x = pk2(o[0], o[1]); w.y = pk2(o[2], o[3]); w.z = pk2(o[4], o[5]); w.w = pk2(o[6], o[7]);
;                 *(u32x4*)(H + (size_t)row * DFF + col) = w;
.LBB0_191:
	s_ashr_i32 s15, s14, 31
	s_lshl_b64 s[16:17], s[14:15], 19
	v_readlane_b32 s18, v235, 31
	v_readlane_b32 s19, v235, 32
	s_add_u32 s16, s18, s16
	s_addc_u32 s17, s19, s17
	s_and_b64 s[18:19], s[0:1], exec
	s_cselect_b32 s15, s17, s23
	s_cselect_b32 s50, s16, s22
	s_ashr_i32 s9, s8, 31
	s_lshl_b64 s[18:19], s[8:9], 19
	s_add_u32 s18, s33, s18
	s_addc_u32 s19, s34, s19
	s_and_b64 s[30:31], s[0:1], exec
	s_cselect_b32 s9, s19, s25
	s_cselect_b32 s51, s18, s24
	s_add_u32 s22, s22, 0x40080
	s_addc_u32 s23, s23, 0
	s_add_u32 s52, s24, 0x100
	s_addc_u32 s53, s25, 0
	s_mov_b32 s54, -2
	s_cmp_eq_u32 s98, 0
	s_cbranch_scc1 .Lp1_plain
	ds_read_b128 v[150:153], v147
	ds_read_b128 v[154:157], v147 offset:1024
	ds_read_b128 v[158:161], v147 offset:2048
	ds_read_b128 v[162:165], v147 offset:3072
	ds_read_b128 v[166:169], v148
	ds_read_b128 v[170:173], v148 offset:1024
	ds_read_b128 v[174:177], v148 offset:2048
	ds_read_b128 v[178:181], v148 offset:3072
	s_add_u32 s24, s22, 0xfffc0080
	s_addc_u32 s25, s23, -1
	s_cmp_eq_u32 s54, 12
	s_cselect_b32 s31, s15, s25
	s_cselect_b32 s30, s50, s24
	s_cselect_b32 s25, s9, s53
	s_cselect_b32 s24, s51, s52
	v_lshl_add_u64 v[186:187], s[22:23], 0, v[136:137]
	s_add_i32 m0, s21, 0xc000
	ds_read_b128 v[182:185], v149
	ds_read_b128 v[192:195], v149 offset:1024
	ds_read_b128 v[196:199], v149 offset:2048
	ds_read_b128 v[200:203], v149 offset:3072
	ds_read_b128 v[204:207], v149 offset:4096
	ds_read_b128 v[208:211], v149 offset:5120
	ds_read_b128 v[212:215], v149 offset:6144
	ds_read_b128 v[216:219], v149 offset:7168
	global_load_lds_dwordx4 v[186:187], off
	v_lshl_add_u64 v[186:187], s[22:23], 0, v[138:139]
	s_add_i32 m0, s21, 0xe000
	s_nop 0
	global_load_lds_dwordx4 v[186:187], off
	s_nop 1
	v_add_f32_e32 v64, 1.0, v70
	v_rcp_f32_e32 v64, v64
	v_add_f32_e32 v65, 1.0, v71
	v_rcp_f32_e32 v65, v65
	v_add_u32_e32 v66, 0x80, v228
	v_mul_f32_e32 v60, v60, v64
	v_mul_f32_e32 v52, v60, v52
	v_mul_f32_e32 v60, v61, v65
	v_mul_f32_e32 v61, 0xbfb8aa3b, v62
	v_exp_f32_e32 v61, v61
	v_mul_f32_e32 v64, 0xbfb8aa3b, v63
	v_exp_f32_e32 v64, v64
	v_mul_f32_e32 v53, v60, v53
	v_add_f32_e32 v60, 1.0, v61
	v_rcp_f32_e32 v60, v60
	v_add_f32_e32 v61, 1.0, v64
	v_mul_f32_e32 v64, 0xbfb8aa3b, v56
	v_rcp_f32_e32 v61, v61
	v_exp_f32_e32 v64, v64
	v_mul_f32_e32 v60, v62, v60
	v_mul_f32_e32 v54, v60, v54
	v_mul_f32_e32 v60, v63, v61
	v_add_f32_e32 v61, 1.0, v64
	v_rcp_f32_e32 v61, v61
	v_mul_f32_e32 v62, 0xbfb8aa3b, v57
	v_exp_f32_e32 v62, v62
	v_mul_f32_e32 v55, v60, v55
	v_mul_f32_e32 v56, v56, v61
	v_mul_f32_e32 v56, v56, v48
	v_add_f32_e32 v48, 1.0, v62
	v_mul_f32_e32 v60, 0xbfb8aa3b, v58
	v_rcp_f32_e32 v48, v48
	v_exp_f32_e32 v60, v60
	v_mul_f32_e32 v61, 0xbfb8aa3b, v59
	v_exp_f32_e32 v61, v61
	v_mul_f32_e32 v48, v57, v48
	v_add_f32_e32 v57, 1.0, v60
	v_rcp_f32_e32 v57, v57
	v_add_f32_e32 v60, 1.0, v61
	v_rcp_f32_e32 v60, v60
	v_mul_f32_e32 v61, v48, v49
	v_mul_f32_e32 v48, v58, v57
	v_mul_f32_e32 v57, v48, v50
	v_mul_f32_e32 v48, v59, v60
	v_mul_f32_e32 v51, v48, v51
	v_cvt_pk_bf16_f32 v48, v52, v53
	v_cvt_pk_bf16_f32 v49, v54, v55
	v_mul_f32_e32 v54, 0xbfb8aa3b, v44
	v_exp_f32_e32 v54, v54
	v_mul_f32_e32 v55, 0xbfb8aa3b, v45
	v_exp_f32_e32 v55, v55
	v_mad_i64_i32 v[52:53], s[100:101], v66, s48, v[112:113]
	v_lshl_add_u64 v[52:53], v[52:53], 0, v[114:115]
	v_cvt_pk_bf16_f32 v50, v56, v61
	v_cvt_pk_bf16_f32 v51, v57, v51
	global_store_dwordx4 v[52:53], v[48:51], off
	s_nop 1
	v_add_f32_e32 v48, 1.0, v54
	v_rcp_f32_e32 v48, v48
	v_add_f32_e32 v49, 1.0, v55
	v_rcp_f32_e32 v49, v49
	v_add_u32_e32 v50, 0x90, v228
	v_mul_f32_e32 v44, v44, v48
	v_mul_f32_e32 v36, v44, v36
	v_mul_f32_e32 v44, v45, v49
	v_mul_f32_e32 v45, 0xbfb8aa3b, v46
	v_exp_f32_e32 v45, v45
	v_mul_f32_e32 v48, 0xbfb8aa3b, v47
	v_exp_f32_e32 v48, v48
	v_mul_f32_e32 v37, v44, v37
	v_add_f32_e32 v44, 1.0, v45
	v_rcp_f32_e32 v44, v44
	v_add_f32_e32 v45, 1.0, v48
	v_mul_f32_e32 v48, 0xbfb8aa3b, v40
	v_rcp_f32_e32 v45, v45
	v_exp_f32_e32 v48, v48
	v_mul_f32_e32 v44, v46, v44
	v_mul_f32_e32 v38, v44, v38
	v_mul_f32_e32 v44, v47, v45
	v_add_f32_e32 v45, 1.0, v48
	v_rcp_f32_e32 v45, v45
	v_mul_f32_e32 v46, 0xbfb8aa3b, v41
	v_exp_f32_e32 v46, v46
	v_mul_f32_e32 v39, v44, v39
	v_mul_f32_e32 v40, v40, v45
	v_mul_f32_e32 v40, v40, v32
	v_add_f32_e32 v32, 1.0, v46
	v_mul_f32_e32 v44, 0xbfb8aa3b, v42
	v_rcp_f32_e32 v32, v32
	v_exp_f32_e32 v44, v44
	v_mul_f32_e32 v45, 0xbfb8aa3b, v43
	v_exp_f32_e32 v45, v45
	v_mul_f32_e32 v32, v41, v32
	v_add_f32_e32 v41, 1.0, v44
	v_rcp_f32_e32 v41, v41
	v_add_f32_e32 v44, 1.0, v45
	v_rcp_f32_e32 v44, v44
	v_mul_f32_e32 v45, v32, v33
	v_mul_f32_e32 v32, v42, v41
	v_mul_f32_e32 v41, v32, v34
	v_mul_f32_e32 v32, v43, v44
	v_mul_f32_e32 v35, v32, v35
	v_cvt_pk_bf16_f32 v32, v36, v37
	v_cvt_pk_bf16_f32 v33, v38, v39
	v_mul_f32_e32 v38, 0xbfb8aa3b, v28
	v_exp_f32_e32 v38, v38
	v_mul_f32_e32 v39, 0xbfb8aa3b, v29
	v_exp_f32_e32 v39, v39
	v_mad_i64_i32 v[36:37], s[100:101], v50, s48, v[112:113]
	v_lshl_add_u64 v[36:37], v[36:37], 0, v[114:115]
	v_cvt_pk_bf16_f32 v34, v40, v45
	v_cvt_pk_bf16_f32 v35, v41, v35
	global_store_dwordx4 v[36:37], v[32:35], off
	s_nop 1
	v_add_f32_e32 v32, 1.0, v38
	v_rcp_f32_e32 v32, v32
	v_add_f32_e32 v33, 1.0, v39
	v_rcp_f32_e32 v33, v33
	v_add_u32_e32 v34, 0xa0, v228
	v_mul_f32_e32 v28, v28, v32
	v_mul_f32_e32 v20, v28, v20
	v_mul_f32_e32 v28, v29, v33
	v_mul_f32_e32 v29, 0xbfb8aa3b, v30
	v_exp_f32_e32 v29, v29
	v_mul_f32_e32 v32, 0xbfb8aa3b, v31
	v_exp_f32_e32 v32, v32
	v_mul_f32_e32 v21, v28, v21
	v_add_f32_e32 v28, 1.0, v29
	v_rcp_f32_e32 v28, v28
	v_add_f32_e32 v29, 1.0, v32
	v_mul_f32_e32 v32, 0xbfb8aa3b, v24
	v_rcp_f32_e32 v29, v29
; #define PG8_STAGE(bufoff, gbase, voff) do { _Pragma("unroll") for (int _i = 0; _i < 2; ++_i) \
;         __builtin_amdgcn_global_load_lds((const unsigned*)((const char*)(gbase) + (voff)[_i]), (PG8_LAS unsigned*)(lds + (bufoff) + ldsw + _i * 8192), 16, 0, 0); } while (0)
; #define PG8_LDA(dst, b, h) do { _Pragma("unroll") for (int m = 0; m < 4; ++m) _Pragma("unroll") for (int k = 0; k < 2; ++k) dst[m][k] = *(const PG8_LAS bf16x8*)(lds + PG8_SA(b, h) + aoff + m * 2048 + k * 1024); } while (0)
; #define PG8_LDB(dst, b, h) do { _Pragma("unroll") for (int n = 0; n < 2; ++n) _Pragma("unroll") for (int k = 0; k < 2; ++k) dst[n][k] = *(const PG8_LAS bf16x8*)(lds + PG8_SB(b, h) + boff + n * 2048 + k * 1024); } while (0)
; #define PG8_WAIT_V(n) asm volatile("s_waitcnt vmcnt(" #n ")" ::: "memory")
; #define PG8_WAIT_L(n) asm volatile("s_waitcnt lgkmcnt(" #n ")" ::: "memory")
; #define PG8_BAR __builtin_amdgcn_s_barrier()
; #define PG8_SCHED __builtin_amdgcn_sched_barrier(0)
; __device__ __forceinline__ float silu_f(float x) { return x * sigmoid_f(x); }
; template <class Epi, class Sched, bool ALIGN_EPI = false, bool SP2 = false>
; __device__ __forceinline__ void gemm_phase(PG8_LAS unsigned char* lds, const Gemm g, const Sched& S, const Epi& E) {
;     ...
;             PG8_LDB(B0, 0, 0); PG8_LDB(B1, 0, 1); PG8_SCHED; PG8_LDA(At, 0, 0); PG8_STAGE(PG8_SA(1, 1), a1 + hstep, voffA);
;             PG8_WAIT_V(8); PG8_WAIT_L(0); PG8_BAR; PG8_MMA(0, 0, At, B0); PG8_MMA(0, 1, At, B1); PG8_BAR; PG8_SCHED;
;             PG8_LDA(At, 0, 1); PG8_STAGE(PG8_SB(0, 0), b2, voffB); PG8_STAGE(PG8_SB(0, 1), b2 + hstep, voffB); PG8_STAGE(PG8_SA(0, 0), a2, voffA);
;     __device__ __forceinline__ void operator()(const f32x4 (&acc)[2][2][4][2], const pg8::Unit& u, int wr, int wc, int fr, int fq) const {
;     ...
;                 const int row = row0 + ai * 128 + m * 16;
;                 const float rs = sumsq ? rsqrtf(sumsq[row] * (1.f / 1024.f) + EPS) : 1.f;
;                 float o[8];
; #pragma unroll
;                 for (int n = 0; n < 2; ++n)
; #pragma unroll
;                     for (int e = 0; e < 4; ++e) { const float g = acc[ai][0][m][n][e] * rs, up = acc[ai][1][m][n][e] * rs; o[4 * n + e] = silu_f(g) * up; }
;                 u32x4 w; w.x = pk2(o[0], o[1]); w.y = pk2(o[2], o[3]); w.z = pk2(o[4], o[5]); w.w = pk2(o[6], o[7]);
;                 *(u32x4*)(H + (size_t)row * DFF + col) = w;
	v_exp_f32_e32 v32, v32
	v_mul_f32_e32 v28, v30, v28
	v_mul_f32_e32 v22, v28, v22
	v_mul_f32_e32 v28, v31, v29
	v_add_f32_e32 v29, 1.0, v32
	v_rcp_f32_e32 v29, v29
	v_mul_f32_e32 v30, 0xbfb8aa3b, v25
	v_exp_f32_e32 v30, v30
	v_mul_f32_e32 v23, v28, v23
	v_mul_f32_e32 v24, v24, v29
	v_mul_f32_e32 v24, v24, v16
	v_add_f32_e32 v16, 1.0, v30
	v_mul_f32_e32 v28, 0xbfb8aa3b, v26
	v_rcp_f32_e32 v16, v16
	v_exp_f32_e32 v28, v28
	v_mul_f32_e32 v29, 0xbfb8aa3b, v27
	v_exp_f32_e32 v29, v29
	v_mul_f32_e32 v16, v25, v16
	v_add_f32_e32 v25, 1.0, v28
	v_rcp_f32_e32 v25, v25
	v_add_f32_e32 v28, 1.0, v29
	v_rcp_f32_e32 v28, v28
	v_mul_f32_e32 v29, v16, v17
	v_mul_f32_e32 v16, v26, v25
	v_mul_f32_e32 v25, v16, v18
	v_mul_f32_e32 v16, v27, v28
	v_mul_f32_e32 v19, v16, v19
	v_cvt_pk_bf16_f32 v16, v20, v21
	v_cvt_pk_bf16_f32 v17, v22, v23
	v_mul_f32_e32 v22, 0xbfb8aa3b, v12
	v_exp_f32_e32 v22, v22
	v_mul_f32_e32 v23, 0xbfb8aa3b, v13
	v_exp_f32_e32 v23, v23
	v_mad_i64_i32 v[20:21], s[100:101], v34, s48, v[112:113]
	v_lshl_add_u64 v[20:21], v[20:21], 0, v[114:115]
	v_cvt_pk_bf16_f32 v18, v24, v29
	v_cvt_pk_bf16_f32 v19, v25, v19
	global_store_dwordx4 v[20:21], v[16:19], off
	s_nop 1
	v_add_f32_e32 v16, 1.0, v22
	v_rcp_f32_e32 v16, v16
	v_add_f32_e32 v17, 1.0, v23
	v_rcp_f32_e32 v17, v17
	v_add_u32_e32 v18, 0xb0, v228
	v_mul_f32_e32 v12, v12, v16
	v_mul_f32_e32 v4, v12, v4
	v_mul_f32_e32 v12, v13, v17
	v_mul_f32_e32 v13, 0xbfb8aa3b, v14
	v_exp_f32_e32 v13, v13
	v_mul_f32_e32 v16, 0xbfb8aa3b, v15
	v_exp_f32_e32 v16, v16
	v_mul_f32_e32 v5, v12, v5
	v_add_f32_e32 v12, 1.0, v13
	v_rcp_f32_e32 v12, v12
	v_add_f32_e32 v13, 1.0, v16
	v_mul_f32_e32 v16, 0xbfb8aa3b, v8
	v_rcp_f32_e32 v13, v13
	v_exp_f32_e32 v16, v16
	v_mul_f32_e32 v12, v14, v12
	v_mul_f32_e32 v6, v12, v6
	v_mul_f32_e32 v12, v15, v13
	v_add_f32_e32 v13, 1.0, v16
	v_rcp_f32_e32 v13, v13
	v_mul_f32_e32 v14, 0xbfb8aa3b, v9
	v_exp_f32_e32 v14, v14
	v_mul_f32_e32 v7, v12, v7
	v_mul_f32_e32 v8, v8, v13
	v_mul_f32_e32 v8, v8, v0
	v_add_f32_e32 v0, 1.0, v14
	v_mul_f32_e32 v12, 0xbfb8aa3b, v10
	v_rcp_f32_e32 v0, v0
	v_exp_f32_e32 v12, v12
	v_mul_f32_e32 v13, 0xbfb8aa3b, v11
	v_exp_f32_e32 v13, v13
	v_mul_f32_e32 v0, v9, v0
	v_add_f32_e32 v9, 1.0, v12
	v_rcp_f32_e32 v9, v9
	v_add_f32_e32 v12, 1.0, v13
	v_rcp_f32_e32 v12, v12
	v_mul_f32_e32 v13, v0, v1
	v_mul_f32_e32 v0, v10, v9
	v_mul_f32_e32 v9, v0, v2
	v_mul_f32_e32 v0, v11, v12
	v_mul_f32_e32 v3, v0, v3
	v_cvt_pk_bf16_f32 v0, v4, v5
	v_mad_i64_i32 v[4:5], s[100:101], v18, s48, v[112:113]
	v_lshl_add_u64 v[4:5], v[4:5], 0, v[114:115]
	v_cvt_pk_bf16_f32 v1, v6, v7
	v_cvt_pk_bf16_f32 v2, v8, v13
	v_cvt_pk_bf16_f32 v3, v9, v3
	global_store_dwordx4 v[4:5], v[0:3], off
	s_waitcnt vmcnt(16)
	s_waitcnt lgkmcnt(0)
	s_setprio 1
	s_barrier
	v_mfma_f32_16x16x32_bf16 v[124:127], v[150:153], v[182:185], 0
	v_mfma_f32_16x16x32_bf16 v[120:123], v[158:161], v[182:185], 0
	v_mfma_f32_16x16x32_bf16 v[108:111], v[150:153], v[196:199], 0
	v_mfma_f32_16x16x32_bf16 v[104:107], v[158:161], v[196:199], 0
	v_mfma_f32_16x16x32_bf16 v[92:95], v[150:153], v[204:207], 0
	v_mfma_f32_16x16x32_bf16 v[88:91], v[158:161], v[204:207], 0
	v_mfma_f32_16x16x32_bf16 v[76:79], v[150:153], v[212:215], 0
	v_mfma_f32_16x16x32_bf16 v[72:75], v[158:161], v[212:215], 0
	v_mfma_f32_16x16x32_bf16 v[124:127], v[154:157], v[192:195], v[124:127]
	v_mfma_f32_16x16x32_bf16 v[120:123], v[162:165], v[192:195], v[120:123]
	v_mfma_f32_16x16x32_bf16 v[108:111], v[154:157], v[200:203], v[108:111]
	v_mfma_f32_16x16x32_bf16 v[104:107], v[162:165], v[200:203], v[104:107]
	v_mfma_f32_16x16x32_bf16 v[92:95], v[154:157], v[208:211], v[92:95]
	v_mfma_f32_16x16x32_bf16 v[88:91], v[162:165], v[208:211], v[88:91]
	v_mfma_f32_16x16x32_bf16 v[76:79], v[154:157], v[216:219], v[76:79]
	v_mfma_f32_16x16x32_bf16 v[72:75], v[162:165], v[216:219], v[72:75]
	v_mfma_f32_16x16x32_bf16 v[116:119], v[166:169], v[182:185], 0
	v_mfma_f32_16x16x32_bf16 v[112:115], v[174:177], v[182:185], 0
	v_mfma_f32_16x16x32_bf16 v[100:103], v[166:169], v[196:199], 0
	v_mfma_f32_16x16x32_bf16 v[96:99], v[174:177], v[196:199], 0
	v_mfma_f32_16x16x32_bf16 v[84:87], v[166:169], v[204:207], 0
	v_mfma_f32_16x16x32_bf16 v[80:83], v[174:177], v[204:207], 0
	v_mfma_f32_16x16x32_bf16 v[68:71], v[166:169], v[212:215], 0
	v_mfma_f32_16x16x32_bf16 v[64:67], v[174:177], v[212:215], 0
	v_mfma_f32_16x16x32_bf16 v[116:119], v[170:173], v[192:195], v[116:119]
	v_mfma_f32_16x16x32_bf16 v[112:115], v[178:181], v[192:195], v[112:115]
	v_mfma_f32_16x16x32_bf16 v[100:103], v[170:173], v[200:203], v[100:103]
	v_mfma_f32_16x16x32_bf16 v[96:99], v[178:181], v[200:203], v[96:99]
	v_mfma_f32_16x16x32_bf16 v[84:87], v[170:173], v[208:211], v[84:87]
	v_mfma_f32_16x16x32_bf16 v[80:83], v[178:181], v[208:211], v[80:83]
	v_mfma_f32_16x16x32_bf16 v[68:71], v[170:173], v[216:219], v[68:71]
	v_mfma_f32_16x16x32_bf16 v[64:67], v[178:181], v[216:219], v[64:67]
	s_barrier
	s_setprio 0
	s_add_i32 s55, s46, s35
	v_lshl_add_u64 v[186:187], s[24:25], 0, v[132:133]
	s_mov_b32 m0, s55
	ds_read_b128 v[182:185], v149 offset:16384
	ds_read_b128 v[192:195], v149 offset:17408
	ds_read_b128 v[196:199], v149 offset:18432
	ds_read_b128 v[200:203], v149 offset:19456
	ds_read_b128 v[204:207], v149 offset:20480
	ds_read_b128 v[208:211], v149 offset:21504
	ds_read_b128 v[212:215], v149 offset:22528
	ds_read_b128 v[216:219], v149 offset:23552
	global_load_lds_dwordx4 v[186:187], off
	s_add_i32 m0, s55, 0x2000
	s_add_u32 s56, s24, 0x40000
	v_lshl_add_u64 v[220:221], s[24:25], 0, v[128:129]
	s_addc_u32 s57, s25, 0
	s_add_i32 s55, s47, s35
	global_load_lds_dwordx4 v[220:221], off
	v_lshl_add_u64 v[222:223], s[56:57], 0, v[132:133]
	s_mov_b32 m0, s55
	v_lshl_add_u64 v[224:225], s[30:31], 0, v[130:131]
	global_load_lds_dwordx4 v[222:223], off
	v_lshl_add_u64 v[222:223], s[56:57], 0, v[128:129]
	s_add_i32 m0, s55, 0x2000
	s_nop 0
	global_load_lds_dwordx4 v[222:223], off
	v_lshl_add_u64 v[222:223], s[30:31], 0, v[134:135]
	s_mov_b32 m0, s21
	s_nop 0
	global_load_lds_dwordx4 v[222:223], off
	s_mov_b32 m0, s38
	s_nop 0
	global_load_lds_dwordx4 v[224:225], off
	s_waitcnt vmcnt(16)
	s_waitcnt lgkmcnt(0)
	s_setprio 1
	s_barrier
; #define PG8_STAGE(bufoff, gbase, voff) do { _Pragma("unroll") for (int _i = 0; _i < 2; ++_i) \
;         __builtin_amdgcn_global_load_lds((const unsigned*)((const char*)(gbase) + (voff)[_i]), (PG8_LAS unsigned*)(lds + (bufoff) + ldsw + _i * 8192), 16, 0, 0); } while (0)
; #define PG8_LDA(dst, b, h) do { _Pragma("unroll") for (int m = 0; m < 4; ++m) _Pragma("unroll") for (int k = 0; k < 2; ++k) dst[m][k] = *(const PG8_LAS bf16x8*)(lds + PG8_SA(b, h) + aoff + m * 2048 + k * 1024); } while (0)
; #define PG8_LDB(dst, b, h) do { _Pragma("unroll") for (int n = 0; n < 2; ++n) _Pragma("unroll") for (int k = 0; k < 2; ++k) dst[n][k] = *(const PG8_LAS bf16x8*)(lds + PG8_SB(b, h) + boff + n * 2048 + k * 1024); } while (0)
; #define PG8_MMA(ai, bj, At, Bt) do { __builtin_amdgcn_s_setprio(1); _Pragma("unroll") for (int m = 0; m < 4; ++m) _Pragma("unroll") for (int n = 0; n < 2; ++n) _Pragma("unroll") for (int k = 0; k < 2; ++k) \
;         acc[ai][bj][m][n] = __builtin_amdgcn_mfma_f32_16x16x32_bf16(Bt[n][k], At[m][k], acc[ai][bj][m][n], 0, 0, 0); __builtin_amdgcn_s_setprio(0); } while (0)
; #define PG8_WAIT_V(n) asm volatile("s_waitcnt vmcnt(" #n ")" ::: "memory")
; #define PG8_WAIT_L(n) asm volatile("s_waitcnt lgkmcnt(" #n ")" ::: "memory")
; #define PG8_BAR __builtin_amdgcn_s_barrier()
; #define PG8_SCHED __builtin_amdgcn_sched_barrier(0)
; template <class Epi, class Sched, bool ALIGN_EPI = false, bool SP2 = false>
; __device__ __forceinline__ void gemm_phase(PG8_LAS unsigned char* lds, const Gemm g, const Sched& S, const Epi& E) {
;     ...
;             PG8_WAIT_V(8); PG8_WAIT_L(0); PG8_BAR; PG8_MMA(0, 0, At, B0); PG8_MMA(0, 1, At, B1); PG8_BAR; PG8_SCHED;
;             PG8_LDA(At, 0, 1); PG8_STAGE(PG8_SB(0, 0), b2, voffB); PG8_STAGE(PG8_SB(0, 1), b2 + hstep, voffB); PG8_STAGE(PG8_SA(0, 0), a2, voffA);
;             PG8_WAIT_V(8); PG8_WAIT_L(0); PG8_BAR; PG8_MMA(1, 0, At, B0); PG8_MMA(1, 1, At, B1); PG8_BAR; PG8_SCHED;
;             PG8_LDB(B0, 1, 0); PG8_LDB(B1, 1, 1); PG8_SCHED; PG8_LDA(At, 1, 0); PG8_STAGE(PG8_SA(0, 1), a2 + hstep, voffA);
;             PG8_WAIT_V(8); PG8_WAIT_L(0); PG8_BAR; PG8_MMA(0, 0, At, B0); PG8_MMA(0, 1, At, B1); PG8_BAR; PG8_SCHED;
	v_mfma_f32_16x16x32_bf16 v[60:63], v[150:153], v[182:185], 0
	v_mfma_f32_16x16x32_bf16 v[56:59], v[158:161], v[182:185], 0
	v_mfma_f32_16x16x32_bf16 v[44:47], v[150:153], v[196:199], 0
	v_mfma_f32_16x16x32_bf16 v[40:43], v[158:161], v[196:199], 0
	v_mfma_f32_16x16x32_bf16 v[28:31], v[150:153], v[204:207], 0
	v_mfma_f32_16x16x32_bf16 v[24:27], v[158:161], v[204:207], 0
	v_mfma_f32_16x16x32_bf16 v[12:15], v[150:153], v[212:215], 0
	v_mfma_f32_16x16x32_bf16 v[8:11], v[158:161], v[212:215], 0
	v_mfma_f32_16x16x32_bf16 v[60:63], v[154:157], v[192:195], v[60:63]
	v_mfma_f32_16x16x32_bf16 v[56:59], v[162:165], v[192:195], v[56:59]
	v_mfma_f32_16x16x32_bf16 v[44:47], v[154:157], v[200:203], v[44:47]
	v_mfma_f32_16x16x32_bf16 v[40:43], v[162:165], v[200:203], v[40:43]
	v_mfma_f32_16x16x32_bf16 v[28:31], v[154:157], v[208:211], v[28:31]
	v_mfma_f32_16x16x32_bf16 v[24:27], v[162:165], v[208:211], v[24:27]
	v_mfma_f32_16x16x32_bf16 v[12:15], v[154:157], v[216:219], v[12:15]
	v_mfma_f32_16x16x32_bf16 v[8:11], v[162:165], v[216:219], v[8:11]
	v_mfma_f32_16x16x32_bf16 v[52:55], v[166:169], v[182:185], 0
	v_mfma_f32_16x16x32_bf16 v[48:51], v[174:177], v[182:185], 0
	v_mfma_f32_16x16x32_bf16 v[36:39], v[166:169], v[196:199], 0
	v_mfma_f32_16x16x32_bf16 v[32:35], v[174:177], v[196:199], 0
	v_mfma_f32_16x16x32_bf16 v[20:23], v[166:169], v[204:207], 0
	v_mfma_f32_16x16x32_bf16 v[16:19], v[174:177], v[204:207], 0
	v_mfma_f32_16x16x32_bf16 v[4:7], v[166:169], v[212:215], 0
	v_mfma_f32_16x16x32_bf16 v[0:3], v[174:177], v[212:215], 0
	v_mfma_f32_16x16x32_bf16 v[52:55], v[170:173], v[192:195], v[52:55]
	v_mfma_f32_16x16x32_bf16 v[48:51], v[178:181], v[192:195], v[48:51]
	v_mfma_f32_16x16x32_bf16 v[36:39], v[170:173], v[200:203], v[36:39]
	v_mfma_f32_16x16x32_bf16 v[32:35], v[178:181], v[200:203], v[32:35]
	v_mfma_f32_16x16x32_bf16 v[20:23], v[170:173], v[208:211], v[20:23]
	v_mfma_f32_16x16x32_bf16 v[16:19], v[178:181], v[208:211], v[16:19]
	v_mfma_f32_16x16x32_bf16 v[4:7], v[170:173], v[216:219], v[4:7]
	v_mfma_f32_16x16x32_bf16 v[0:3], v[178:181], v[216:219], v[0:3]
	s_barrier
	s_setprio 0
	s_add_i32 s55, 0, 0x18000
	s_add_i32 s56, 0, 0x1c000
	v_add_u32_e32 v162, s55, v145
	v_add_u32_e32 v178, s56, v145
	ds_read_b128 v[150:153], v162
	ds_read_b128 v[154:157], v162 offset:1024
	ds_read_b128 v[158:161], v162 offset:2048
	ds_read_b128 v[162:165], v162 offset:3072
	ds_read_b128 v[166:169], v178
	ds_read_b128 v[170:173], v178 offset:1024
	ds_read_b128 v[174:177], v178 offset:2048
	ds_read_b128 v[178:181], v178 offset:3072
	s_add_u32 s30, s30, 0x40000
	s_addc_u32 s31, s31, 0
	s_mov_b32 m0, s39
	v_lshl_add_u64 v[226:227], s[30:31], 0, v[134:135]
	ds_read_b128 v[182:185], v149 offset:32768
	ds_read_b128 v[192:195], v149 offset:33792
	ds_read_b128 v[196:199], v149 offset:34816
	ds_read_b128 v[200:203], v149 offset:35840
	ds_read_b128 v[204:207], v149 offset:36864
	ds_read_b128 v[208:211], v149 offset:37888
	ds_read_b128 v[212:215], v149 offset:38912
	ds_read_b128 v[216:219], v149 offset:39936
	global_load_lds_dwordx4 v[226:227], off
	v_lshl_add_u64 v[226:227], s[30:31], 0, v[130:131]
	s_mov_b32 m0, s40
	s_nop 0
	global_load_lds_dwordx4 v[226:227], off
	s_waitcnt vmcnt(8)
	s_waitcnt lgkmcnt(0)
	s_setprio 1
	s_barrier
	v_mfma_f32_16x16x32_bf16 v[124:127], v[150:153], v[182:185], v[124:127]
	v_mfma_f32_16x16x32_bf16 v[120:123], v[158:161], v[182:185], v[120:123]
	v_mfma_f32_16x16x32_bf16 v[108:111], v[150:153], v[196:199], v[108:111]
	v_mfma_f32_16x16x32_bf16 v[104:107], v[158:161], v[196:199], v[104:107]
	v_mfma_f32_16x16x32_bf16 v[92:95], v[150:153], v[204:207], v[92:95]
	v_mfma_f32_16x16x32_bf16 v[88:91], v[158:161], v[204:207], v[88:91]
	v_mfma_f32_16x16x32_bf16 v[76:79], v[150:153], v[212:215], v[76:79]
	v_mfma_f32_16x16x32_bf16 v[72:75], v[158:161], v[212:215], v[72:75]
	v_mfma_f32_16x16x32_bf16 v[124:127], v[154:157], v[192:195], v[124:127]
	v_mfma_f32_16x16x32_bf16 v[120:123], v[162:165], v[192:195], v[120:123]
	v_mfma_f32_16x16x32_bf16 v[108:111], v[154:157], v[200:203], v[108:111]
	v_mfma_f32_16x16x32_bf16 v[104:107], v[162:165], v[200:203], v[104:107]
	v_mfma_f32_16x16x32_bf16 v[92:95], v[154:157], v[208:211], v[92:95]
	v_mfma_f32_16x16x32_bf16 v[88:91], v[162:165], v[208:211], v[88:91]
	v_mfma_f32_16x16x32_bf16 v[76:79], v[154:157], v[216:219], v[76:79]
	v_mfma_f32_16x16x32_bf16 v[72:75], v[162:165], v[216:219], v[72:75]
	v_mfma_f32_16x16x32_bf16 v[116:119], v[166:169], v[182:185], v[116:119]
	v_mfma_f32_16x16x32_bf16 v[112:115], v[174:177], v[182:185], v[112:115]
	v_mfma_f32_16x16x32_bf16 v[100:103], v[166:169], v[196:199], v[100:103]
	v_mfma_f32_16x16x32_bf16 v[96:99], v[174:177], v[196:199], v[96:99]
	v_mfma_f32_16x16x32_bf16 v[84:87], v[166:169], v[204:207], v[84:87]
	v_mfma_f32_16x16x32_bf16 v[80:83], v[174:177], v[204:207], v[80:83]
	v_mfma_f32_16x16x32_bf16 v[68:71], v[166:169], v[212:215], v[68:71]
	v_mfma_f32_16x16x32_bf16 v[64:67], v[174:177], v[212:215], v[64:67]
	v_mfma_f32_16x16x32_bf16 v[116:119], v[170:173], v[192:195], v[116:119]
	v_mfma_f32_16x16x32_bf16 v[112:115], v[178:181], v[192:195], v[112:115]
	v_mfma_f32_16x16x32_bf16 v[100:103], v[170:173], v[200:203], v[100:103]
	v_mfma_f32_16x16x32_bf16 v[96:99], v[178:181], v[200:203], v[96:99]
	v_mfma_f32_16x16x32_bf16 v[84:87], v[170:173], v[208:211], v[84:87]
	v_mfma_f32_16x16x32_bf16 v[80:83], v[178:181], v[208:211], v[80:83]
	v_mfma_f32_16x16x32_bf16 v[68:71], v[170:173], v[216:219], v[68:71]
	v_mfma_f32_16x16x32_bf16 v[64:67], v[178:181], v[216:219], v[64:67]
	s_barrier
; #define PG8_STAGE(bufoff, gbase, voff) do { _Pragma("unroll") for (int _i = 0; _i < 2; ++_i) \
;         __builtin_amdgcn_global_load_lds((const unsigned*)((const char*)(gbase) + (voff)[_i]), (PG8_LAS unsigned*)(lds + (bufoff) + ldsw + _i * 8192), 16, 0, 0); } while (0)
; #define PG8_LDA(dst, b, h) do { _Pragma("unroll") for (int m = 0; m < 4; ++m) _Pragma("unroll") for (int k = 0; k < 2; ++k) dst[m][k] = *(const PG8_LAS bf16x8*)(lds + PG8_SA(b, h) + aoff + m * 2048 + k * 1024); } while (0)
; #define PG8_LDB(dst, b, h) do { _Pragma("unroll") for (int n = 0; n < 2; ++n) _Pragma("unroll") for (int k = 0; k < 2; ++k) dst[n][k] = *(const PG8_LAS bf16x8*)(lds + PG8_SB(b, h) + boff + n * 2048 + k * 1024); } while (0)
; #define PG8_MMA(ai, bj, At, Bt) do { __builtin_amdgcn_s_setprio(1); _Pragma("unroll") for (int m = 0; m < 4; ++m) _Pragma("unroll") for (int n = 0; n < 2; ++n) _Pragma("unroll") for (int k = 0; k < 2; ++k) \
;         acc[ai][bj][m][n] = __builtin_amdgcn_mfma_f32_16x16x32_bf16(Bt[n][k], At[m][k], acc[ai][bj][m][n], 0, 0, 0); __builtin_amdgcn_s_setprio(0); } while (0)
; #define PG8_WAIT_V(n) asm volatile("s_waitcnt vmcnt(" #n ")" ::: "memory")
; #define PG8_WAIT_L(n) asm volatile("s_waitcnt lgkmcnt(" #n ")" ::: "memory")
; #define PG8_BAR __builtin_amdgcn_s_barrier()
; template <class Epi, class Sched, bool ALIGN_EPI = false, bool SP2 = false>
; __device__ __forceinline__ void gemm_phase(PG8_LAS unsigned char* lds, const Gemm g, const Sched& S, const Epi& E) {
;     ...
;             PG8_LDB(B0, 0, 0); PG8_LDB(B1, 0, 1); PG8_SCHED; PG8_LDA(At, 0, 0); PG8_STAGE(PG8_SA(1, 1), a1 + hstep, voffA);
;             PG8_WAIT_V(8); PG8_WAIT_L(0); PG8_BAR; PG8_MMA(0, 0, At, B0); PG8_MMA(0, 1, At, B1); PG8_BAR; PG8_SCHED;
;     ...
;             PG8_WAIT_V(8); PG8_WAIT_L(0); PG8_BAR; PG8_MMA(1, 0, At, B0); PG8_MMA(1, 1, At, B1); PG8_BAR; PG8_SCHED;
;             PG8_LDB(B0, 1, 0); PG8_LDB(B1, 1, 1); PG8_SCHED; PG8_LDA(At, 1, 0); PG8_STAGE(PG8_SA(0, 1), a2 + hstep, voffA);
;             PG8_WAIT_V(8); PG8_WAIT_L(0); PG8_BAR; PG8_MMA(0, 0, At, B0); PG8_MMA(0, 1, At, B1); PG8_BAR; PG8_SCHED;
;             PG8_LDA(At, 1, 1); PG8_STAGE(PG8_SB(1, 0), b3, voffB); PG8_STAGE(PG8_SB(1, 1), b3 + hstep, voffB); PG8_STAGE(PG8_SA(1, 0), a3, voffA);
;             PG8_WAIT_V(8); PG8_WAIT_L(0); PG8_BAR; PG8_MMA(1, 0, At, B0); PG8_MMA(1, 1, At, B1); PG8_BAR; PG8_SCHED;
	s_setprio 0
	s_add_i32 s30, s55, s35
	v_lshl_add_u64 v[186:187], v[186:187], 0, s[4:5]
	s_mov_b32 m0, s30
	ds_read_b128 v[182:185], v149 offset:49152
	ds_read_b128 v[192:195], v149 offset:50176
	ds_read_b128 v[196:199], v149 offset:51200
	ds_read_b128 v[200:203], v149 offset:52224
	ds_read_b128 v[204:207], v149 offset:53248
	ds_read_b128 v[208:211], v149 offset:54272
	ds_read_b128 v[212:215], v149 offset:55296
	ds_read_b128 v[216:219], v149 offset:56320
	global_load_lds_dwordx4 v[186:187], off
	s_add_i32 m0, s30, 0x2000
	s_add_u32 s24, s24, 0x40080
	v_lshl_add_u64 v[186:187], v[220:221], 0, s[4:5]
	s_addc_u32 s25, s25, 0
	s_add_i32 s30, s56, s35
	global_load_lds_dwordx4 v[186:187], off
	v_lshl_add_u64 v[186:187], s[24:25], 0, v[132:133]
	s_mov_b32 m0, s30
	s_nop 0
	global_load_lds_dwordx4 v[186:187], off
	v_lshl_add_u64 v[186:187], s[24:25], 0, v[128:129]
	s_add_i32 m0, s30, 0x2000
	s_nop 0
	global_load_lds_dwordx4 v[186:187], off
	v_lshl_add_u64 v[186:187], v[222:223], 0, s[4:5]
	s_mov_b32 m0, s42
	s_nop 0
	global_load_lds_dwordx4 v[186:187], off
	v_lshl_add_u64 v[186:187], v[224:225], 0, s[4:5]
	s_mov_b32 m0, s43
	s_nop 0
	global_load_lds_dwordx4 v[186:187], off
	s_waitcnt vmcnt(8)
	s_waitcnt lgkmcnt(0)
	s_setprio 1
	s_barrier
	v_mfma_f32_16x16x32_bf16 v[60:63], v[150:153], v[182:185], v[60:63]
	v_mfma_f32_16x16x32_bf16 v[56:59], v[158:161], v[182:185], v[56:59]
	v_mfma_f32_16x16x32_bf16 v[44:47], v[150:153], v[196:199], v[44:47]
	v_mfma_f32_16x16x32_bf16 v[40:43], v[158:161], v[196:199], v[40:43]
	v_mfma_f32_16x16x32_bf16 v[28:31], v[150:153], v[204:207], v[28:31]
	v_mfma_f32_16x16x32_bf16 v[24:27], v[158:161], v[204:207], v[24:27]
	v_mfma_f32_16x16x32_bf16 v[12:15], v[150:153], v[212:215], v[12:15]
	v_mfma_f32_16x16x32_bf16 v[8:11], v[158:161], v[212:215], v[8:11]
	v_mfma_f32_16x16x32_bf16 v[60:63], v[154:157], v[192:195], v[60:63]
	v_mfma_f32_16x16x32_bf16 v[56:59], v[162:165], v[192:195], v[56:59]
	v_mfma_f32_16x16x32_bf16 v[44:47], v[154:157], v[200:203], v[44:47]
	v_mfma_f32_16x16x32_bf16 v[40:43], v[162:165], v[200:203], v[40:43]
	v_mfma_f32_16x16x32_bf16 v[28:31], v[154:157], v[208:211], v[28:31]
	v_mfma_f32_16x16x32_bf16 v[24:27], v[162:165], v[208:211], v[24:27]
	v_mfma_f32_16x16x32_bf16 v[12:15], v[154:157], v[216:219], v[12:15]
	v_mfma_f32_16x16x32_bf16 v[8:11], v[162:165], v[216:219], v[8:11]
	v_mfma_f32_16x16x32_bf16 v[52:55], v[166:169], v[182:185], v[52:55]
	v_mfma_f32_16x16x32_bf16 v[48:51], v[174:177], v[182:185], v[48:51]
	v_mfma_f32_16x16x32_bf16 v[36:39], v[166:169], v[196:199], v[36:39]
	v_mfma_f32_16x16x32_bf16 v[32:35], v[174:177], v[196:199], v[32:35]
	v_mfma_f32_16x16x32_bf16 v[20:23], v[166:169], v[204:207], v[20:23]
	v_mfma_f32_16x16x32_bf16 v[16:19], v[174:177], v[204:207], v[16:19]
	v_mfma_f32_16x16x32_bf16 v[4:7], v[166:169], v[212:215], v[4:7]
	v_mfma_f32_16x16x32_bf16 v[0:3], v[174:177], v[212:215], v[0:3]
	v_mfma_f32_16x16x32_bf16 v[52:55], v[170:173], v[192:195], v[52:55]
	v_mfma_f32_16x16x32_bf16 v[48:51], v[178:181], v[192:195], v[48:51]
	v_mfma_f32_16x16x32_bf16 v[36:39], v[170:173], v[200:203], v[36:39]
	v_mfma_f32_16x16x32_bf16 v[32:35], v[178:181], v[200:203], v[32:35]
	v_mfma_f32_16x16x32_bf16 v[20:23], v[170:173], v[208:211], v[20:23]
	v_mfma_f32_16x16x32_bf16 v[16:19], v[178:181], v[208:211], v[16:19]
	v_mfma_f32_16x16x32_bf16 v[4:7], v[170:173], v[216:219], v[4:7]
	v_mfma_f32_16x16x32_bf16 v[0:3], v[178:181], v[216:219], v[0:3]
	s_barrier
	s_setprio 0
	s_add_i32 s54, s54, 2
	s_add_u32 s22, s22, 0x100
	s_addc_u32 s23, s23, 0
	s_add_u32 s52, s52, 0x100
	s_addc_u32 s53, s53, 0
	s_branch .LBB0_192
.Lp1_plain:
	ds_read_b128 v[150:153], v147
	ds_read_b128 v[154:157], v147 offset:1024
	ds_read_b128 v[158:161], v147 offset:2048
	ds_read_b128 v[162:165], v147 offset:3072
	ds_read_b128 v[166:169], v148
	ds_read_b128 v[170:173], v148 offset:1024
	ds_read_b128 v[174:177], v148 offset:2048
	ds_read_b128 v[178:181], v148 offset:3072
	s_add_u32 s24, s22, 0xfffc0080
	s_addc_u32 s25, s23, -1
	s_cmp_eq_u32 s54, 12
	s_cselect_b32 s31, s15, s25
	s_cselect_b32 s30, s50, s24
	s_cselect_b32 s25, s9, s53
	s_cselect_b32 s24, s51, s52
	v_lshl_add_u64 v[186:187], s[22:23], 0, v[136:137]
	s_add_i32 m0, s21, 0xc000
	ds_read_b128 v[182:185], v149
	ds_read_b128 v[192:195], v149 offset:1024
	ds_read_b128 v[196:199], v149 offset:2048
	ds_read_b128 v[200:203], v149 offset:3072
	ds_read_b128 v[204:207], v149 offset:4096
	ds_read_b128 v[208:211], v149 offset:5120
	ds_read_b128 v[212:215], v149 offset:6144
	ds_read_b128 v[216:219], v149 offset:7168
	global_load_lds_dwordx4 v[186:187], off
	v_lshl_add_u64 v[186:187], s[22:23], 0, v[138:139]
	s_add_i32 m0, s21, 0xe000
	s_nop 0
	global_load_lds_dwordx4 v[186:187], off
	s_waitcnt vmcnt(16)
	s_waitcnt lgkmcnt(0)
	s_setprio 1
	s_barrier
; #define PG8_STAGE(bufoff, gbase, voff) do { _Pragma("unroll") for (int _i = 0; _i < 2; ++_i) \
;         __builtin_amdgcn_global_load_lds((const unsigned*)((const char*)(gbase) + (voff)[_i]), (PG8_LAS unsigned*)(lds + (bufoff) + ldsw + _i * 8192), 16, 0, 0); } while (0)
; #define PG8_LDA(dst, b, h) do { _Pragma("unroll") for (int m = 0; m < 4; ++m) _Pragma("unroll") for (int k = 0; k < 2; ++k) dst[m][k] = *(const PG8_LAS bf16x8*)(lds + PG8_SA(b, h) + aoff + m * 2048 + k * 1024); } while (0)
; #define PG8_LDB(dst, b, h) do { _Pragma("unroll") for (int n = 0; n < 2; ++n) _Pragma("unroll") for (int k = 0; k < 2; ++k) dst[n][k] = *(const PG8_LAS bf16x8*)(lds + PG8_SB(b, h) + boff + n * 2048 + k * 1024); } while (0)
; #define PG8_MMA(ai, bj, At, Bt) do { __builtin_amdgcn_s_setprio(1); _Pragma("unroll") for (int m = 0; m < 4; ++m) _Pragma("unroll") for (int n = 0; n < 2; ++n) _Pragma("unroll") for (int k = 0; k < 2; ++k) \
;         acc[ai][bj][m][n] = __builtin_amdgcn_mfma_f32_16x16x32_bf16(Bt[n][k], At[m][k], acc[ai][bj][m][n], 0, 0, 0); __builtin_amdgcn_s_setprio(0); } while (0)
; #define PG8_WAIT_V(n) asm volatile("s_waitcnt vmcnt(" #n ")" ::: "memory")
; #define PG8_WAIT_L(n) asm volatile("s_waitcnt lgkmcnt(" #n ")" ::: "memory")
; #define PG8_BAR __builtin_amdgcn_s_barrier()
; #define PG8_SCHED __builtin_amdgcn_sched_barrier(0)
; template <class Epi, class Sched, bool ALIGN_EPI = false, bool SP2 = false>
; __device__ __forceinline__ void gemm_phase(PG8_LAS unsigned char* lds, const Gemm g, const Sched& S, const Epi& E) {
;     ...
;             PG8_LDB(B0, 0, 0); PG8_LDB(B1, 0, 1); PG8_SCHED; PG8_LDA(At, 0, 0); PG8_STAGE(PG8_SA(1, 1), a1 + hstep, voffA);
;             PG8_WAIT_V(8); PG8_WAIT_L(0); PG8_BAR; PG8_MMA(0, 0, At, B0); PG8_MMA(0, 1, At, B1); PG8_BAR; PG8_SCHED;
;             PG8_LDA(At, 0, 1); PG8_STAGE(PG8_SB(0, 0), b2, voffB); PG8_STAGE(PG8_SB(0, 1), b2 + hstep, voffB); PG8_STAGE(PG8_SA(0, 0), a2, voffA);
;             PG8_WAIT_V(8); PG8_WAIT_L(0); PG8_BAR; PG8_MMA(1, 0, At, B0); PG8_MMA(1, 1, At, B1); PG8_BAR; PG8_SCHED;
	v_mfma_f32_16x16x32_bf16 v[124:127], v[150:153], v[182:185], 0
	v_mfma_f32_16x16x32_bf16 v[120:123], v[158:161], v[182:185], 0
	v_mfma_f32_16x16x32_bf16 v[108:111], v[150:153], v[196:199], 0
	v_mfma_f32_16x16x32_bf16 v[104:107], v[158:161], v[196:199], 0
	v_mfma_f32_16x16x32_bf16 v[92:95], v[150:153], v[204:207], 0
	v_mfma_f32_16x16x32_bf16 v[88:91], v[158:161], v[204:207], 0
	v_mfma_f32_16x16x32_bf16 v[76:79], v[150:153], v[212:215], 0
	v_mfma_f32_16x16x32_bf16 v[72:75], v[158:161], v[212:215], 0
	v_mfma_f32_16x16x32_bf16 v[124:127], v[154:157], v[192:195], v[124:127]
	v_mfma_f32_16x16x32_bf16 v[120:123], v[162:165], v[192:195], v[120:123]
	v_mfma_f32_16x16x32_bf16 v[108:111], v[154:157], v[200:203], v[108:111]
	v_mfma_f32_16x16x32_bf16 v[104:107], v[162:165], v[200:203], v[104:107]
	v_mfma_f32_16x16x32_bf16 v[92:95], v[154:157], v[208:211], v[92:95]
	v_mfma_f32_16x16x32_bf16 v[88:91], v[162:165], v[208:211], v[88:91]
	v_mfma_f32_16x16x32_bf16 v[76:79], v[154:157], v[216:219], v[76:79]
	v_mfma_f32_16x16x32_bf16 v[72:75], v[162:165], v[216:219], v[72:75]
	v_mfma_f32_16x16x32_bf16 v[116:119], v[166:169], v[182:185], 0
	v_mfma_f32_16x16x32_bf16 v[112:115], v[174:177], v[182:185], 0
	v_mfma_f32_16x16x32_bf16 v[100:103], v[166:169], v[196:199], 0
	v_mfma_f32_16x16x32_bf16 v[96:99], v[174:177], v[196:199], 0
	v_mfma_f32_16x16x32_bf16 v[84:87], v[166:169], v[204:207], 0
	v_mfma_f32_16x16x32_bf16 v[80:83], v[174:177], v[204:207], 0
	v_mfma_f32_16x16x32_bf16 v[68:71], v[166:169], v[212:215], 0
	v_mfma_f32_16x16x32_bf16 v[64:67], v[174:177], v[212:215], 0
	v_mfma_f32_16x16x32_bf16 v[116:119], v[170:173], v[192:195], v[116:119]
	v_mfma_f32_16x16x32_bf16 v[112:115], v[178:181], v[192:195], v[112:115]
	v_mfma_f32_16x16x32_bf16 v[100:103], v[170:173], v[200:203], v[100:103]
	v_mfma_f32_16x16x32_bf16 v[96:99], v[178:181], v[200:203], v[96:99]
	v_mfma_f32_16x16x32_bf16 v[84:87], v[170:173], v[208:211], v[84:87]
	v_mfma_f32_16x16x32_bf16 v[80:83], v[178:181], v[208:211], v[80:83]
	v_mfma_f32_16x16x32_bf16 v[68:71], v[170:173], v[216:219], v[68:71]
	v_mfma_f32_16x16x32_bf16 v[64:67], v[178:181], v[216:219], v[64:67]
	s_barrier
	s_setprio 0
	s_add_i32 s55, s46, s35
	v_lshl_add_u64 v[186:187], s[24:25], 0, v[132:133]
	s_mov_b32 m0, s55
	ds_read_b128 v[182:185], v149 offset:16384
	ds_read_b128 v[192:195], v149 offset:17408
	ds_read_b128 v[196:199], v149 offset:18432
	ds_read_b128 v[200:203], v149 offset:19456
	ds_read_b128 v[204:207], v149 offset:20480
	ds_read_b128 v[208:211], v149 offset:21504
	ds_read_b128 v[212:215], v149 offset:22528
	ds_read_b128 v[216:219], v149 offset:23552
	global_load_lds_dwordx4 v[186:187], off
	s_add_i32 m0, s55, 0x2000
	s_add_u32 s56, s24, 0x40000
	v_lshl_add_u64 v[220:221], s[24:25], 0, v[128:129]
	s_addc_u32 s57, s25, 0
	s_add_i32 s55, s47, s35
	global_load_lds_dwordx4 v[220:221], off
	v_lshl_add_u64 v[222:223], s[56:57], 0, v[132:133]
	s_mov_b32 m0, s55
	v_lshl_add_u64 v[224:225], s[30:31], 0, v[130:131]
	global_load_lds_dwordx4 v[222:223], off
	v_lshl_add_u64 v[222:223], s[56:57], 0, v[128:129]
	s_add_i32 m0, s55, 0x2000
	s_nop 0
	global_load_lds_dwordx4 v[222:223], off
	v_lshl_add_u64 v[222:223], s[30:31], 0, v[134:135]
	s_mov_b32 m0, s21
	s_nop 0
	global_load_lds_dwordx4 v[222:223], off
	s_mov_b32 m0, s38
	s_nop 0
	global_load_lds_dwordx4 v[224:225], off
	s_waitcnt vmcnt(16)
	s_waitcnt lgkmcnt(0)
	s_setprio 1
	s_barrier
	v_mfma_f32_16x16x32_bf16 v[60:63], v[150:153], v[182:185], 0
	v_mfma_f32_16x16x32_bf16 v[56:59], v[158:161], v[182:185], 0
	v_mfma_f32_16x16x32_bf16 v[44:47], v[150:153], v[196:199], 0
	v_mfma_f32_16x16x32_bf16 v[40:43], v[158:161], v[196:199], 0
	v_mfma_f32_16x16x32_bf16 v[28:31], v[150:153], v[204:207], 0
	v_mfma_f32_16x16x32_bf16 v[24:27], v[158:161], v[204:207], 0
	v_mfma_f32_16x16x32_bf16 v[12:15], v[150:153], v[212:215], 0
	v_mfma_f32_16x16x32_bf16 v[8:11], v[158:161], v[212:215], 0
	v_mfma_f32_16x16x32_bf16 v[60:63], v[154:157], v[192:195], v[60:63]
	v_mfma_f32_16x16x32_bf16 v[56:59], v[162:165], v[192:195], v[56:59]
	v_mfma_f32_16x16x32_bf16 v[44:47], v[154:157], v[200:203], v[44:47]
	v_mfma_f32_16x16x32_bf16 v[40:43], v[162:165], v[200:203], v[40:43]
	v_mfma_f32_16x16x32_bf16 v[28:31], v[154:157], v[208:211], v[28:31]
	v_mfma_f32_16x16x32_bf16 v[24:27], v[162:165], v[208:211], v[24:27]
	v_mfma_f32_16x16x32_bf16 v[12:15], v[154:157], v[216:219], v[12:15]
	v_mfma_f32_16x16x32_bf16 v[8:11], v[162:165], v[216:219], v[8:11]
	v_mfma_f32_16x16x32_bf16 v[52:55], v[166:169], v[182:185], 0
	v_mfma_f32_16x16x32_bf16 v[48:51], v[174:177], v[182:185], 0
	v_mfma_f32_16x16x32_bf16 v[36:39], v[166:169], v[196:199], 0
	v_mfma_f32_16x16x32_bf16 v[32:35], v[174:177], v[196:199], 0
	v_mfma_f32_16x16x32_bf16 v[20:23], v[166:169], v[204:207], 0
	v_mfma_f32_16x16x32_bf16 v[16:19], v[174:177], v[204:207], 0
	v_mfma_f32_16x16x32_bf16 v[4:7], v[166:169], v[212:215], 0
	v_mfma_f32_16x16x32_bf16 v[0:3], v[174:177], v[212:215], 0
	v_mfma_f32_16x16x32_bf16 v[52:55], v[170:173], v[192:195], v[52:55]
	v_mfma_f32_16x16x32_bf16 v[48:51], v[178:181], v[192:195], v[48:51]
	v_mfma_f32_16x16x32_bf16 v[36:39], v[170:173], v[200:203], v[36:39]
	v_mfma_f32_16x16x32_bf16 v[32:35], v[178:181], v[200:203], v[32:35]
	v_mfma_f32_16x16x32_bf16 v[20:23], v[170:173], v[208:211], v[20:23]
	v_mfma_f32_16x16x32_bf16 v[16:19], v[178:181], v[208:211], v[16:19]
	v_mfma_f32_16x16x32_bf16 v[4:7], v[170:173], v[216:219], v[4:7]
	v_mfma_f32_16x16x32_bf16 v[0:3], v[178:181], v[216:219], v[0:3]
	s_barrier
; #define PG8_STAGE(bufoff, gbase, voff) do { _Pragma("unroll") for (int _i = 0; _i < 2; ++_i) \
;         __builtin_amdgcn_global_load_lds((const unsigned*)((const char*)(gbase) + (voff)[_i]), (PG8_LAS unsigned*)(lds + (bufoff) + ldsw + _i * 8192), 16, 0, 0); } while (0)
; #define PG8_LDA(dst, b, h) do { _Pragma("unroll") for (int m = 0; m < 4; ++m) _Pragma("unroll") for (int k = 0; k < 2; ++k) dst[m][k] = *(const PG8_LAS bf16x8*)(lds + PG8_SA(b, h) + aoff + m * 2048 + k * 1024); } while (0)
; #define PG8_LDB(dst, b, h) do { _Pragma("unroll") for (int n = 0; n < 2; ++n) _Pragma("unroll") for (int k = 0; k < 2; ++k) dst[n][k] = *(const PG8_LAS bf16x8*)(lds + PG8_SB(b, h) + boff + n * 2048 + k * 1024); } while (0)
; #define PG8_MMA(ai, bj, At, Bt) do { __builtin_amdgcn_s_setprio(1); _Pragma("unroll") for (int m = 0; m < 4; ++m) _Pragma("unroll") for (int n = 0; n < 2; ++n) _Pragma("unroll") for (int k = 0; k < 2; ++k) \
;         acc[ai][bj][m][n] = __builtin_amdgcn_mfma_f32_16x16x32_bf16(Bt[n][k], At[m][k], acc[ai][bj][m][n], 0, 0, 0); __builtin_amdgcn_s_setprio(0); } while (0)
; #define PG8_WAIT_V(n) asm volatile("s_waitcnt vmcnt(" #n ")" ::: "memory")
; #define PG8_WAIT_L(n) asm volatile("s_waitcnt lgkmcnt(" #n ")" ::: "memory")
; #define PG8_BAR __builtin_amdgcn_s_barrier()
; #define PG8_SCHED __builtin_amdgcn_sched_barrier(0)
; template <class Epi, class Sched, bool ALIGN_EPI = false, bool SP2 = false>
; __device__ __forceinline__ void gemm_phase(PG8_LAS unsigned char* lds, const Gemm g, const Sched& S, const Epi& E) {
;     ...
;             PG8_LDB(B0, 1, 0); PG8_LDB(B1, 1, 1); PG8_SCHED; PG8_LDA(At, 1, 0); PG8_STAGE(PG8_SA(0, 1), a2 + hstep, voffA);
;             PG8_WAIT_V(8); PG8_WAIT_L(0); PG8_BAR; PG8_MMA(0, 0, At, B0); PG8_MMA(0, 1, At, B1); PG8_BAR; PG8_SCHED;
;             PG8_LDA(At, 1, 1); PG8_STAGE(PG8_SB(1, 0), b3, voffB); PG8_STAGE(PG8_SB(1, 1), b3 + hstep, voffB); PG8_STAGE(PG8_SA(1, 0), a3, voffA);
;             PG8_WAIT_V(8); PG8_WAIT_L(0); PG8_BAR; PG8_MMA(1, 0, At, B0); PG8_MMA(1, 1, At, B1); PG8_BAR; PG8_SCHED;
	s_setprio 0
	s_add_i32 s55, 0, 0x18000
	s_add_i32 s56, 0, 0x1c000
	v_add_u32_e32 v162, s55, v145
	v_add_u32_e32 v178, s56, v145
	ds_read_b128 v[150:153], v162
	ds_read_b128 v[154:157], v162 offset:1024
	ds_read_b128 v[158:161], v162 offset:2048
	ds_read_b128 v[162:165], v162 offset:3072
	ds_read_b128 v[166:169], v178
	ds_read_b128 v[170:173], v178 offset:1024
	ds_read_b128 v[174:177], v178 offset:2048
	ds_read_b128 v[178:181], v178 offset:3072
	s_add_u32 s30, s30, 0x40000
	s_addc_u32 s31, s31, 0
	s_mov_b32 m0, s39
	v_lshl_add_u64 v[226:227], s[30:31], 0, v[134:135]
	ds_read_b128 v[182:185], v149 offset:32768
	ds_read_b128 v[192:195], v149 offset:33792
	ds_read_b128 v[196:199], v149 offset:34816
	ds_read_b128 v[200:203], v149 offset:35840
	ds_read_b128 v[204:207], v149 offset:36864
	ds_read_b128 v[208:211], v149 offset:37888
	ds_read_b128 v[212:215], v149 offset:38912
	ds_read_b128 v[216:219], v149 offset:39936
	global_load_lds_dwordx4 v[226:227], off
	v_lshl_add_u64 v[226:227], s[30:31], 0, v[130:131]
	s_mov_b32 m0, s40
	s_nop 0
	global_load_lds_dwordx4 v[226:227], off
	s_waitcnt vmcnt(8)
	s_waitcnt lgkmcnt(0)
	s_setprio 1
	s_barrier
	v_mfma_f32_16x16x32_bf16 v[124:127], v[150:153], v[182:185], v[124:127]
	v_mfma_f32_16x16x32_bf16 v[120:123], v[158:161], v[182:185], v[120:123]
	v_mfma_f32_16x16x32_bf16 v[108:111], v[150:153], v[196:199], v[108:111]
	v_mfma_f32_16x16x32_bf16 v[104:107], v[158:161], v[196:199], v[104:107]
	v_mfma_f32_16x16x32_bf16 v[92:95], v[150:153], v[204:207], v[92:95]
	v_mfma_f32_16x16x32_bf16 v[88:91], v[158:161], v[204:207], v[88:91]
	v_mfma_f32_16x16x32_bf16 v[76:79], v[150:153], v[212:215], v[76:79]
	v_mfma_f32_16x16x32_bf16 v[72:75], v[158:161], v[212:215], v[72:75]
	v_mfma_f32_16x16x32_bf16 v[124:127], v[154:157], v[192:195], v[124:127]
	v_mfma_f32_16x16x32_bf16 v[120:123], v[162:165], v[192:195], v[120:123]
	v_mfma_f32_16x16x32_bf16 v[108:111], v[154:157], v[200:203], v[108:111]
	v_mfma_f32_16x16x32_bf16 v[104:107], v[162:165], v[200:203], v[104:107]
	v_mfma_f32_16x16x32_bf16 v[92:95], v[154:157], v[208:211], v[92:95]
	v_mfma_f32_16x16x32_bf16 v[88:91], v[162:165], v[208:211], v[88:91]
	v_mfma_f32_16x16x32_bf16 v[76:79], v[154:157], v[216:219], v[76:79]
	v_mfma_f32_16x16x32_bf16 v[72:75], v[162:165], v[216:219], v[72:75]
	v_mfma_f32_16x16x32_bf16 v[116:119], v[166:169], v[182:185], v[116:119]
	v_mfma_f32_16x16x32_bf16 v[112:115], v[174:177], v[182:185], v[112:115]
	v_mfma_f32_16x16x32_bf16 v[100:103], v[166:169], v[196:199], v[100:103]
	v_mfma_f32_16x16x32_bf16 v[96:99], v[174:177], v[196:199], v[96:99]
	v_mfma_f32_16x16x32_bf16 v[84:87], v[166:169], v[204:207], v[84:87]
	v_mfma_f32_16x16x32_bf16 v[80:83], v[174:177], v[204:207], v[80:83]
	v_mfma_f32_16x16x32_bf16 v[68:71], v[166:169], v[212:215], v[68:71]
	v_mfma_f32_16x16x32_bf16 v[64:67], v[174:177], v[212:215], v[64:67]
	v_mfma_f32_16x16x32_bf16 v[116:119], v[170:173], v[192:195], v[116:119]
	v_mfma_f32_16x16x32_bf16 v[112:115], v[178:181], v[192:195], v[112:115]
	v_mfma_f32_16x16x32_bf16 v[100:103], v[170:173], v[200:203], v[100:103]
	v_mfma_f32_16x16x32_bf16 v[96:99], v[178:181], v[200:203], v[96:99]
	v_mfma_f32_16x16x32_bf16 v[84:87], v[170:173], v[208:211], v[84:87]
	v_mfma_f32_16x16x32_bf16 v[80:83], v[178:181], v[208:211], v[80:83]
	v_mfma_f32_16x16x32_bf16 v[68:71], v[170:173], v[216:219], v[68:71]
	v_mfma_f32_16x16x32_bf16 v[64:67], v[178:181], v[216:219], v[64:67]
	s_barrier
	s_setprio 0
	s_add_i32 s30, s55, s35
	v_lshl_add_u64 v[186:187], v[186:187], 0, s[4:5]
	s_mov_b32 m0, s30
	ds_read_b128 v[182:185], v149 offset:49152
	ds_read_b128 v[192:195], v149 offset:50176
	ds_read_b128 v[196:199], v149 offset:51200
	ds_read_b128 v[200:203], v149 offset:52224
	ds_read_b128 v[204:207], v149 offset:53248
	ds_read_b128 v[208:211], v149 offset:54272
	ds_read_b128 v[212:215], v149 offset:55296
	ds_read_b128 v[216:219], v149 offset:56320
	global_load_lds_dwordx4 v[186:187], off
	s_add_i32 m0, s30, 0x2000
	s_add_u32 s24, s24, 0x40080
	v_lshl_add_u64 v[186:187], v[220:221], 0, s[4:5]
	s_addc_u32 s25, s25, 0
	s_add_i32 s30, s56, s35
	global_load_lds_dwordx4 v[186:187], off
	v_lshl_add_u64 v[186:187], s[24:25], 0, v[132:133]
	s_mov_b32 m0, s30
	s_nop 0
	global_load_lds_dwordx4 v[186:187], off
	v_lshl_add_u64 v[186:187], s[24:25], 0, v[128:129]
	s_add_i32 m0, s30, 0x2000
	s_nop 0
	global_load_lds_dwordx4 v[186:187], off
	v_lshl_add_u64 v[186:187], v[222:223], 0, s[4:5]
	s_mov_b32 m0, s42
	s_nop 0
	global_load_lds_dwordx4 v[186:187], off
	v_lshl_add_u64 v[186:187], v[224:225], 0, s[4:5]
	s_mov_b32 m0, s43
	s_nop 0
	global_load_lds_dwordx4 v[186:187], off
	s_waitcnt vmcnt(8)
	s_waitcnt lgkmcnt(0)
	s_setprio 1
	s_barrier
	v_mfma_f32_16x16x32_bf16 v[60:63], v[150:153], v[182:185], v[60:63]
	v_mfma_f32_16x16x32_bf16 v[56:59], v[158:161], v[182:185], v[56:59]
	v_mfma_f32_16x16x32_bf16 v[44:47], v[150:153], v[196:199], v[44:47]
	v_mfma_f32_16x16x32_bf16 v[40:43], v[158:161], v[196:199], v[40:43]
	v_mfma_f32_16x16x32_bf16 v[28:31], v[150:153], v[204:207], v[28:31]
	v_mfma_f32_16x16x32_bf16 v[24:27], v[158:161], v[204:207], v[24:27]
	v_mfma_f32_16x16x32_bf16 v[12:15], v[150:153], v[212:215], v[12:15]
	v_mfma_f32_16x16x32_bf16 v[8:11], v[158:161], v[212:215], v[8:11]
	v_mfma_f32_16x16x32_bf16 v[60:63], v[154:157], v[192:195], v[60:63]
	v_mfma_f32_16x16x32_bf16 v[56:59], v[162:165], v[192:195], v[56:59]
	v_mfma_f32_16x16x32_bf16 v[44:47], v[154:157], v[200:203], v[44:47]
	v_mfma_f32_16x16x32_bf16 v[40:43], v[162:165], v[200:203], v[40:43]
	v_mfma_f32_16x16x32_bf16 v[28:31], v[154:157], v[208:211], v[28:31]
	v_mfma_f32_16x16x32_bf16 v[24:27], v[162:165], v[208:211], v[24:27]
	v_mfma_f32_16x16x32_bf16 v[12:15], v[154:157], v[216:219], v[12:15]
	v_mfma_f32_16x16x32_bf16 v[8:11], v[162:165], v[216:219], v[8:11]
	v_mfma_f32_16x16x32_bf16 v[52:55], v[166:169], v[182:185], v[52:55]
	v_mfma_f32_16x16x32_bf16 v[48:51], v[174:177], v[182:185], v[48:51]
	v_mfma_f32_16x16x32_bf16 v[36:39], v[166:169], v[196:199], v[36:39]
	v_mfma_f32_16x16x32_bf16 v[32:35], v[174:177], v[196:199], v[32:35]
	v_mfma_f32_16x16x32_bf16 v[20:23], v[166:169], v[204:207], v[20:23]
	v_mfma_f32_16x16x32_bf16 v[16:19], v[174:177], v[204:207], v[16:19]
	v_mfma_f32_16x16x32_bf16 v[4:7], v[166:169], v[212:215], v[4:7]
	v_mfma_f32_16x16x32_bf16 v[0:3], v[174:177], v[212:215], v[0:3]
	v_mfma_f32_16x16x32_bf16 v[52:55], v[170:173], v[192:195], v[52:55]
	v_mfma_f32_16x16x32_bf16 v[48:51], v[178:181], v[192:195], v[48:51]
	v_mfma_f32_16x16x32_bf16 v[36:39], v[170:173], v[200:203], v[36:39]
	v_mfma_f32_16x16x32_bf16 v[32:35], v[178:181], v[200:203], v[32:35]
	v_mfma_f32_16x16x32_bf16 v[20:23], v[170:173], v[208:211], v[20:23]
	v_mfma_f32_16x16x32_bf16 v[16:19], v[178:181], v[208:211], v[16:19]
	v_mfma_f32_16x16x32_bf16 v[4:7], v[170:173], v[216:219], v[4:7]
	v_mfma_f32_16x16x32_bf16 v[0:3], v[178:181], v[216:219], v[0:3]
	s_barrier
	s_setprio 0
	s_add_i32 s54, s54, 2
	s_add_u32 s22, s22, 0x100
	s_addc_u32 s23, s23, 0
	s_add_u32 s52, s52, 0x100
	s_addc_u32 s53, s53, 0
; #define PG8_STAGE(bufoff, gbase, voff) do { _Pragma("unroll") for (int _i = 0; _i < 2; ++_i) \
;         __builtin_amdgcn_global_load_lds((const unsigned*)((const char*)(gbase) + (voff)[_i]), (PG8_LAS unsigned*)(lds + (bufoff) + ldsw + _i * 8192), 16, 0, 0); } while (0)
; #define PG8_LDA(dst, b, h) do { _Pragma("unroll") for (int m = 0; m < 4; ++m) _Pragma("unroll") for (int k = 0; k < 2; ++k) dst[m][k] = *(const PG8_LAS bf16x8*)(lds + PG8_SA(b, h) + aoff + m * 2048 + k * 1024); } while (0)
; #define PG8_LDB(dst, b, h) do { _Pragma("unroll") for (int n = 0; n < 2; ++n) _Pragma("unroll") for (int k = 0; k < 2; ++k) dst[n][k] = *(const PG8_LAS bf16x8*)(lds + PG8_SB(b, h) + boff + n * 2048 + k * 1024); } while (0)
; #define PG8_MMA(ai, bj, At, Bt) do { __builtin_amdgcn_s_setprio(1); _Pragma("unroll") for (int m = 0; m < 4; ++m) _Pragma("unroll") for (int n = 0; n < 2; ++n) _Pragma("unroll") for (int k = 0; k < 2; ++k) \
;         acc[ai][bj][m][n] = __builtin_amdgcn_mfma_f32_16x16x32_bf16(Bt[n][k], At[m][k], acc[ai][bj][m][n], 0, 0, 0); __builtin_amdgcn_s_setprio(0); } while (0)
; #define PG8_WAIT_V(n) asm volatile("s_waitcnt vmcnt(" #n ")" ::: "memory")
; #define PG8_WAIT_L(n) asm volatile("s_waitcnt lgkmcnt(" #n ")" ::: "memory")
; #define PG8_BAR __builtin_amdgcn_s_barrier()
; #define PG8_SCHED __builtin_amdgcn_sched_barrier(0)
; template <class Epi, class Sched, bool ALIGN_EPI = false, bool SP2 = false>
; __device__ __forceinline__ void gemm_phase(PG8_LAS unsigned char* lds, const Gemm g, const Sched& S, const Epi& E) {
;     ...
;             PG8_LDB(B0, 0, 0); PG8_LDB(B1, 0, 1); PG8_SCHED; PG8_LDA(At, 0, 0); PG8_STAGE(PG8_SA(1, 1), a1 + hstep, voffA);
;             PG8_WAIT_V(8); PG8_WAIT_L(0); PG8_BAR; PG8_MMA(0, 0, At, B0); PG8_MMA(0, 1, At, B1); PG8_BAR; PG8_SCHED;
;             PG8_LDA(At, 0, 1); PG8_STAGE(PG8_SB(0, 0), b2, voffB); PG8_STAGE(PG8_SB(0, 1), b2 + hstep, voffB); PG8_STAGE(PG8_SA(0, 0), a2, voffA);
;             PG8_WAIT_V(8); PG8_WAIT_L(0); PG8_BAR; PG8_MMA(1, 0, At, B0); PG8_MMA(1, 1, At, B1); PG8_BAR; PG8_SCHED;
.LBB0_192:
	ds_read_b128 v[150:153], v147
	ds_read_b128 v[154:157], v147 offset:1024
	ds_read_b128 v[158:161], v147 offset:2048
	ds_read_b128 v[162:165], v147 offset:3072
	ds_read_b128 v[166:169], v148
	ds_read_b128 v[170:173], v148 offset:1024
	ds_read_b128 v[174:177], v148 offset:2048
	ds_read_b128 v[178:181], v148 offset:3072
	s_add_u32 s24, s22, 0xfffc0080
	s_addc_u32 s25, s23, -1
	s_cmp_eq_u32 s54, 12
	s_cselect_b32 s31, s15, s25
	s_cselect_b32 s30, s50, s24
	s_cselect_b32 s25, s9, s53
	s_cselect_b32 s24, s51, s52
	v_lshl_add_u64 v[186:187], s[22:23], 0, v[136:137]
	s_add_i32 m0, s21, 0xc000
	ds_read_b128 v[182:185], v149
	ds_read_b128 v[192:195], v149 offset:1024
	ds_read_b128 v[196:199], v149 offset:2048
	ds_read_b128 v[200:203], v149 offset:3072
	ds_read_b128 v[204:207], v149 offset:4096
	ds_read_b128 v[208:211], v149 offset:5120
	ds_read_b128 v[212:215], v149 offset:6144
	ds_read_b128 v[216:219], v149 offset:7168
	global_load_lds_dwordx4 v[186:187], off
	v_lshl_add_u64 v[186:187], s[22:23], 0, v[138:139]
	s_add_i32 m0, s21, 0xe000
	s_nop 0
	global_load_lds_dwordx4 v[186:187], off
	s_waitcnt vmcnt(8)
	s_waitcnt lgkmcnt(0)
	s_setprio 1
	s_barrier
	v_mfma_f32_16x16x32_bf16 v[124:127], v[150:153], v[182:185], v[124:127]
	v_mfma_f32_16x16x32_bf16 v[120:123], v[158:161], v[182:185], v[120:123]
	v_mfma_f32_16x16x32_bf16 v[108:111], v[150:153], v[196:199], v[108:111]
	v_mfma_f32_16x16x32_bf16 v[104:107], v[158:161], v[196:199], v[104:107]
	v_mfma_f32_16x16x32_bf16 v[92:95], v[150:153], v[204:207], v[92:95]
	v_mfma_f32_16x16x32_bf16 v[88:91], v[158:161], v[204:207], v[88:91]
	v_mfma_f32_16x16x32_bf16 v[76:79], v[150:153], v[212:215], v[76:79]
	v_mfma_f32_16x16x32_bf16 v[72:75], v[158:161], v[212:215], v[72:75]
	v_mfma_f32_16x16x32_bf16 v[124:127], v[154:157], v[192:195], v[124:127]
	v_mfma_f32_16x16x32_bf16 v[120:123], v[162:165], v[192:195], v[120:123]
	v_mfma_f32_16x16x32_bf16 v[108:111], v[154:157], v[200:203], v[108:111]
	v_mfma_f32_16x16x32_bf16 v[104:107], v[162:165], v[200:203], v[104:107]
	v_mfma_f32_16x16x32_bf16 v[92:95], v[154:157], v[208:211], v[92:95]
	v_mfma_f32_16x16x32_bf16 v[88:91], v[162:165], v[208:211], v[88:91]
	v_mfma_f32_16x16x32_bf16 v[76:79], v[154:157], v[216:219], v[76:79]
	v_mfma_f32_16x16x32_bf16 v[72:75], v[162:165], v[216:219], v[72:75]
	v_mfma_f32_16x16x32_bf16 v[116:119], v[166:169], v[182:185], v[116:119]
	v_mfma_f32_16x16x32_bf16 v[112:115], v[174:177], v[182:185], v[112:115]
	v_mfma_f32_16x16x32_bf16 v[100:103], v[166:169], v[196:199], v[100:103]
	v_mfma_f32_16x16x32_bf16 v[96:99], v[174:177], v[196:199], v[96:99]
	v_mfma_f32_16x16x32_bf16 v[84:87], v[166:169], v[204:207], v[84:87]
	v_mfma_f32_16x16x32_bf16 v[80:83], v[174:177], v[204:207], v[80:83]
	v_mfma_f32_16x16x32_bf16 v[68:71], v[166:169], v[212:215], v[68:71]
	v_mfma_f32_16x16x32_bf16 v[64:67], v[174:177], v[212:215], v[64:67]
	v_mfma_f32_16x16x32_bf16 v[116:119], v[170:173], v[192:195], v[116:119]
	v_mfma_f32_16x16x32_bf16 v[112:115], v[178:181], v[192:195], v[112:115]
	v_mfma_f32_16x16x32_bf16 v[100:103], v[170:173], v[200:203], v[100:103]
	v_mfma_f32_16x16x32_bf16 v[96:99], v[178:181], v[200:203], v[96:99]
	v_mfma_f32_16x16x32_bf16 v[84:87], v[170:173], v[208:211], v[84:87]
	v_mfma_f32_16x16x32_bf16 v[80:83], v[178:181], v[208:211], v[80:83]
	v_mfma_f32_16x16x32_bf16 v[68:71], v[170:173], v[216:219], v[68:71]
	v_mfma_f32_16x16x32_bf16 v[64:67], v[178:181], v[216:219], v[64:67]
	s_barrier
	s_setprio 0
	s_add_i32 s55, s46, s35
	v_lshl_add_u64 v[186:187], s[24:25], 0, v[132:133]
	s_mov_b32 m0, s55
	ds_read_b128 v[182:185], v149 offset:16384
	ds_read_b128 v[192:195], v149 offset:17408
	ds_read_b128 v[196:199], v149 offset:18432
	ds_read_b128 v[200:203], v149 offset:19456
	ds_read_b128 v[204:207], v149 offset:20480
	ds_read_b128 v[208:211], v149 offset:21504
	ds_read_b128 v[212:215], v149 offset:22528
	ds_read_b128 v[216:219], v149 offset:23552
	global_load_lds_dwordx4 v[186:187], off
	s_add_i32 m0, s55, 0x2000
	s_add_u32 s56, s24, 0x40000
	v_lshl_add_u64 v[220:221], s[24:25], 0, v[128:129]
	s_addc_u32 s57, s25, 0
	s_add_i32 s55, s47, s35
	global_load_lds_dwordx4 v[220:221], off
	v_lshl_add_u64 v[222:223], s[56:57], 0, v[132:133]
	s_mov_b32 m0, s55
	v_lshl_add_u64 v[224:225], s[30:31], 0, v[130:131]
	global_load_lds_dwordx4 v[222:223], off
	v_lshl_add_u64 v[222:223], s[56:57], 0, v[128:129]
	s_add_i32 m0, s55, 0x2000
	s_nop 0
	global_load_lds_dwordx4 v[222:223], off
	v_lshl_add_u64 v[222:223], s[30:31], 0, v[134:135]
	s_mov_b32 m0, s21
	s_nop 0
	global_load_lds_dwordx4 v[222:223], off
	s_mov_b32 m0, s38
	s_nop 0
	global_load_lds_dwordx4 v[224:225], off
	s_waitcnt vmcnt(8)
	s_waitcnt lgkmcnt(0)
	s_setprio 1
	s_barrier
; #define PG8_STAGE(bufoff, gbase, voff) do { _Pragma("unroll") for (int _i = 0; _i < 2; ++_i) \
;         __builtin_amdgcn_global_load_lds((const unsigned*)((const char*)(gbase) + (voff)[_i]), (PG8_LAS unsigned*)(lds + (bufoff) + ldsw + _i * 8192), 16, 0, 0); } while (0)
; #define PG8_LDA(dst, b, h) do { _Pragma("unroll") for (int m = 0; m < 4; ++m) _Pragma("unroll") for (int k = 0; k < 2; ++k) dst[m][k] = *(const PG8_LAS bf16x8*)(lds + PG8_SA(b, h) + aoff + m * 2048 + k * 1024); } while (0)
; #define PG8_LDB(dst, b, h) do { _Pragma("unroll") for (int n = 0; n < 2; ++n) _Pragma("unroll") for (int k = 0; k < 2; ++k) dst[n][k] = *(const PG8_LAS bf16x8*)(lds + PG8_SB(b, h) + boff + n * 2048 + k * 1024); } while (0)
; #define PG8_MMA(ai, bj, At, Bt) do { __builtin_amdgcn_s_setprio(1); _Pragma("unroll") for (int m = 0; m < 4; ++m) _Pragma("unroll") for (int n = 0; n < 2; ++n) _Pragma("unroll") for (int k = 0; k < 2; ++k) \
;         acc[ai][bj][m][n] = __builtin_amdgcn_mfma_f32_16x16x32_bf16(Bt[n][k], At[m][k], acc[ai][bj][m][n], 0, 0, 0); __builtin_amdgcn_s_setprio(0); } while (0)
; #define PG8_WAIT_V(n) asm volatile("s_waitcnt vmcnt(" #n ")" ::: "memory")
; #define PG8_WAIT_L(n) asm volatile("s_waitcnt lgkmcnt(" #n ")" ::: "memory")
; #define PG8_BAR __builtin_amdgcn_s_barrier()
; #define PG8_SCHED __builtin_amdgcn_sched_barrier(0)
; template <class Epi, class Sched, bool ALIGN_EPI = false, bool SP2 = false>
; __device__ __forceinline__ void gemm_phase(PG8_LAS unsigned char* lds, const Gemm g, const Sched& S, const Epi& E) {
;     ...
;             PG8_WAIT_V(8); PG8_WAIT_L(0); PG8_BAR; PG8_MMA(1, 0, At, B0); PG8_MMA(1, 1, At, B1); PG8_BAR; PG8_SCHED;
;             PG8_LDB(B0, 1, 0); PG8_LDB(B1, 1, 1); PG8_SCHED; PG8_LDA(At, 1, 0); PG8_STAGE(PG8_SA(0, 1), a2 + hstep, voffA);
;             PG8_WAIT_V(8); PG8_WAIT_L(0); PG8_BAR; PG8_MMA(0, 0, At, B0); PG8_MMA(0, 1, At, B1); PG8_BAR; PG8_SCHED;
	v_mfma_f32_16x16x32_bf16 v[60:63], v[150:153], v[182:185], v[60:63]
	v_mfma_f32_16x16x32_bf16 v[56:59], v[158:161], v[182:185], v[56:59]
	v_mfma_f32_16x16x32_bf16 v[44:47], v[150:153], v[196:199], v[44:47]
	v_mfma_f32_16x16x32_bf16 v[40:43], v[158:161], v[196:199], v[40:43]
	v_mfma_f32_16x16x32_bf16 v[28:31], v[150:153], v[204:207], v[28:31]
	v_mfma_f32_16x16x32_bf16 v[24:27], v[158:161], v[204:207], v[24:27]
	v_mfma_f32_16x16x32_bf16 v[12:15], v[150:153], v[212:215], v[12:15]
	v_mfma_f32_16x16x32_bf16 v[8:11], v[158:161], v[212:215], v[8:11]
	v_mfma_f32_16x16x32_bf16 v[60:63], v[154:157], v[192:195], v[60:63]
	v_mfma_f32_16x16x32_bf16 v[56:59], v[162:165], v[192:195], v[56:59]
	v_mfma_f32_16x16x32_bf16 v[44:47], v[154:157], v[200:203], v[44:47]
	v_mfma_f32_16x16x32_bf16 v[40:43], v[162:165], v[200:203], v[40:43]
	v_mfma_f32_16x16x32_bf16 v[28:31], v[154:157], v[208:211], v[28:31]
	v_mfma_f32_16x16x32_bf16 v[24:27], v[162:165], v[208:211], v[24:27]
	v_mfma_f32_16x16x32_bf16 v[12:15], v[154:157], v[216:219], v[12:15]
	v_mfma_f32_16x16x32_bf16 v[8:11], v[162:165], v[216:219], v[8:11]
	v_mfma_f32_16x16x32_bf16 v[52:55], v[166:169], v[182:185], v[52:55]
	v_mfma_f32_16x16x32_bf16 v[48:51], v[174:177], v[182:185], v[48:51]
	v_mfma_f32_16x16x32_bf16 v[36:39], v[166:169], v[196:199], v[36:39]
	v_mfma_f32_16x16x32_bf16 v[32:35], v[174:177], v[196:199], v[32:35]
	v_mfma_f32_16x16x32_bf16 v[20:23], v[166:169], v[204:207], v[20:23]
	v_mfma_f32_16x16x32_bf16 v[16:19], v[174:177], v[204:207], v[16:19]
	v_mfma_f32_16x16x32_bf16 v[4:7], v[166:169], v[212:215], v[4:7]
	v_mfma_f32_16x16x32_bf16 v[0:3], v[174:177], v[212:215], v[0:3]
	v_mfma_f32_16x16x32_bf16 v[52:55], v[170:173], v[192:195], v[52:55]
	v_mfma_f32_16x16x32_bf16 v[48:51], v[178:181], v[192:195], v[48:51]
	v_mfma_f32_16x16x32_bf16 v[36:39], v[170:173], v[200:203], v[36:39]
	v_mfma_f32_16x16x32_bf16 v[32:35], v[178:181], v[200:203], v[32:35]
	v_mfma_f32_16x16x32_bf16 v[20:23], v[170:173], v[208:211], v[20:23]
	v_mfma_f32_16x16x32_bf16 v[16:19], v[178:181], v[208:211], v[16:19]
	v_mfma_f32_16x16x32_bf16 v[4:7], v[170:173], v[216:219], v[4:7]
	v_mfma_f32_16x16x32_bf16 v[0:3], v[178:181], v[216:219], v[0:3]
	s_barrier
	s_setprio 0
	s_add_i32 s55, 0, 0x18000
	s_add_i32 s56, 0, 0x1c000
	v_add_u32_e32 v162, s55, v145
	v_add_u32_e32 v178, s56, v145
	ds_read_b128 v[150:153], v162
	ds_read_b128 v[154:157], v162 offset:1024
	ds_read_b128 v[158:161], v162 offset:2048
	ds_read_b128 v[162:165], v162 offset:3072
	ds_read_b128 v[166:169], v178
	ds_read_b128 v[170:173], v178 offset:1024
	ds_read_b128 v[174:177], v178 offset:2048
	ds_read_b128 v[178:181], v178 offset:3072
	s_add_u32 s30, s30, 0x40000
	s_addc_u32 s31, s31, 0
	s_mov_b32 m0, s39
	v_lshl_add_u64 v[226:227], s[30:31], 0, v[134:135]
	ds_read_b128 v[182:185], v149 offset:32768
	ds_read_b128 v[192:195], v149 offset:33792
	ds_read_b128 v[196:199], v149 offset:34816
	ds_read_b128 v[200:203], v149 offset:35840
	ds_read_b128 v[204:207], v149 offset:36864
	ds_read_b128 v[208:211], v149 offset:37888
	ds_read_b128 v[212:215], v149 offset:38912
	ds_read_b128 v[216:219], v149 offset:39936
	global_load_lds_dwordx4 v[226:227], off
	v_lshl_add_u64 v[226:227], s[30:31], 0, v[130:131]
	s_mov_b32 m0, s40
	s_nop 0
	global_load_lds_dwordx4 v[226:227], off
	s_waitcnt vmcnt(8)
	s_waitcnt lgkmcnt(0)
	s_setprio 1
	s_barrier
	v_mfma_f32_16x16x32_bf16 v[124:127], v[150:153], v[182:185], v[124:127]
	v_mfma_f32_16x16x32_bf16 v[120:123], v[158:161], v[182:185], v[120:123]
	v_mfma_f32_16x16x32_bf16 v[108:111], v[150:153], v[196:199], v[108:111]
	v_mfma_f32_16x16x32_bf16 v[104:107], v[158:161], v[196:199], v[104:107]
	v_mfma_f32_16x16x32_bf16 v[92:95], v[150:153], v[204:207], v[92:95]
	v_mfma_f32_16x16x32_bf16 v[88:91], v[158:161], v[204:207], v[88:91]
	v_mfma_f32_16x16x32_bf16 v[76:79], v[150:153], v[212:215], v[76:79]
	v_mfma_f32_16x16x32_bf16 v[72:75], v[158:161], v[212:215], v[72:75]
	v_mfma_f32_16x16x32_bf16 v[124:127], v[154:157], v[192:195], v[124:127]
	v_mfma_f32_16x16x32_bf16 v[120:123], v[162:165], v[192:195], v[120:123]
	v_mfma_f32_16x16x32_bf16 v[108:111], v[154:157], v[200:203], v[108:111]
	v_mfma_f32_16x16x32_bf16 v[104:107], v[162:165], v[200:203], v[104:107]
	v_mfma_f32_16x16x32_bf16 v[92:95], v[154:157], v[208:211], v[92:95]
	v_mfma_f32_16x16x32_bf16 v[88:91], v[162:165], v[208:211], v[88:91]
	v_mfma_f32_16x16x32_bf16 v[76:79], v[154:157], v[216:219], v[76:79]
	v_mfma_f32_16x16x32_bf16 v[72:75], v[162:165], v[216:219], v[72:75]
	v_mfma_f32_16x16x32_bf16 v[116:119], v[166:169], v[182:185], v[116:119]
	v_mfma_f32_16x16x32_bf16 v[112:115], v[174:177], v[182:185], v[112:115]
	v_mfma_f32_16x16x32_bf16 v[100:103], v[166:169], v[196:199], v[100:103]
	v_mfma_f32_16x16x32_bf16 v[96:99], v[174:177], v[196:199], v[96:99]
	v_mfma_f32_16x16x32_bf16 v[84:87], v[166:169], v[204:207], v[84:87]
	v_mfma_f32_16x16x32_bf16 v[80:83], v[174:177], v[204:207], v[80:83]
	v_mfma_f32_16x16x32_bf16 v[68:71], v[166:169], v[212:215], v[68:71]
	v_mfma_f32_16x16x32_bf16 v[64:67], v[174:177], v[212:215], v[64:67]
	v_mfma_f32_16x16x32_bf16 v[116:119], v[170:173], v[192:195], v[116:119]
	v_mfma_f32_16x16x32_bf16 v[112:115], v[178:181], v[192:195], v[112:115]
	v_mfma_f32_16x16x32_bf16 v[100:103], v[170:173], v[200:203], v[100:103]
	v_mfma_f32_16x16x32_bf16 v[96:99], v[178:181], v[200:203], v[96:99]
	v_mfma_f32_16x16x32_bf16 v[84:87], v[170:173], v[208:211], v[84:87]
	v_mfma_f32_16x16x32_bf16 v[80:83], v[178:181], v[208:211], v[80:83]
	v_mfma_f32_16x16x32_bf16 v[68:71], v[170:173], v[216:219], v[68:71]
	v_mfma_f32_16x16x32_bf16 v[64:67], v[178:181], v[216:219], v[64:67]
	s_barrier
; #define PG8_STAGE(bufoff, gbase, voff) do { _Pragma("unroll") for (int _i = 0; _i < 2; ++_i) \
;         __builtin_amdgcn_global_load_lds((const unsigned*)((const char*)(gbase) + (voff)[_i]), (PG8_LAS unsigned*)(lds + (bufoff) + ldsw + _i * 8192), 16, 0, 0); } while (0)
; #define PG8_LDA(dst, b, h) do { _Pragma("unroll") for (int m = 0; m < 4; ++m) _Pragma("unroll") for (int k = 0; k < 2; ++k) dst[m][k] = *(const PG8_LAS bf16x8*)(lds + PG8_SA(b, h) + aoff + m * 2048 + k * 1024); } while (0)
; #define PG8_MMA(ai, bj, At, Bt) do { __builtin_amdgcn_s_setprio(1); _Pragma("unroll") for (int m = 0; m < 4; ++m) _Pragma("unroll") for (int n = 0; n < 2; ++n) _Pragma("unroll") for (int k = 0; k < 2; ++k) \
;         acc[ai][bj][m][n] = __builtin_amdgcn_mfma_f32_16x16x32_bf16(Bt[n][k], At[m][k], acc[ai][bj][m][n], 0, 0, 0); __builtin_amdgcn_s_setprio(0); } while (0)
; #define PG8_WAIT_V(n) asm volatile("s_waitcnt vmcnt(" #n ")" ::: "memory")
; #define PG8_WAIT_L(n) asm volatile("s_waitcnt lgkmcnt(" #n ")" ::: "memory")
; #define PG8_BAR __builtin_amdgcn_s_barrier()
; #define PG8_SCHED __builtin_amdgcn_sched_barrier(0)
; template <class Epi, class Sched, bool ALIGN_EPI = false, bool SP2 = false>
; __device__ __forceinline__ void gemm_phase(PG8_LAS unsigned char* lds, const Gemm g, const Sched& S, const Epi& E) {
;     ...
;         for (int t = 0; t < nt; t += 2) {
;     ...
;             PG8_LDA(At, 1, 1); PG8_STAGE(PG8_SB(1, 0), b3, voffB); PG8_STAGE(PG8_SB(1, 1), b3 + hstep, voffB); PG8_STAGE(PG8_SA(1, 0), a3, voffA);
;             PG8_WAIT_V(8); PG8_WAIT_L(0); PG8_BAR; PG8_MMA(1, 0, At, B0); PG8_MMA(1, 1, At, B1); PG8_BAR; PG8_SCHED;
;     ...
;         if constexpr (ALIGN_EPI) { if (wr == 0) PG8_BAR; }
	s_setprio 0
	s_add_i32 s30, s55, s35
	v_lshl_add_u64 v[186:187], v[186:187], 0, s[4:5]
	s_mov_b32 m0, s30
	ds_read_b128 v[182:185], v149 offset:49152
	ds_read_b128 v[192:195], v149 offset:50176
	ds_read_b128 v[196:199], v149 offset:51200
	ds_read_b128 v[200:203], v149 offset:52224
	ds_read_b128 v[204:207], v149 offset:53248
	ds_read_b128 v[208:211], v149 offset:54272
	ds_read_b128 v[212:215], v149 offset:55296
	ds_read_b128 v[216:219], v149 offset:56320
	global_load_lds_dwordx4 v[186:187], off
	s_add_i32 m0, s30, 0x2000
	s_add_u32 s24, s24, 0x40080
	v_lshl_add_u64 v[186:187], v[220:221], 0, s[4:5]
	s_addc_u32 s25, s25, 0
	s_add_i32 s30, s56, s35
	global_load_lds_dwordx4 v[186:187], off
	v_lshl_add_u64 v[186:187], s[24:25], 0, v[132:133]
	s_mov_b32 m0, s30
	s_nop 0
	global_load_lds_dwordx4 v[186:187], off
	v_lshl_add_u64 v[186:187], s[24:25], 0, v[128:129]
	s_add_i32 m0, s30, 0x2000
	s_nop 0
	global_load_lds_dwordx4 v[186:187], off
	v_lshl_add_u64 v[186:187], v[222:223], 0, s[4:5]
	s_mov_b32 m0, s42
	s_nop 0
	global_load_lds_dwordx4 v[186:187], off
	v_lshl_add_u64 v[186:187], v[224:225], 0, s[4:5]
	s_mov_b32 m0, s43
	s_nop 0
	global_load_lds_dwordx4 v[186:187], off
	s_waitcnt vmcnt(8)
	s_waitcnt lgkmcnt(0)
	s_setprio 1
	s_barrier
	v_mfma_f32_16x16x32_bf16 v[60:63], v[150:153], v[182:185], v[60:63]
	v_mfma_f32_16x16x32_bf16 v[56:59], v[158:161], v[182:185], v[56:59]
	v_mfma_f32_16x16x32_bf16 v[44:47], v[150:153], v[196:199], v[44:47]
	v_mfma_f32_16x16x32_bf16 v[40:43], v[158:161], v[196:199], v[40:43]
	v_mfma_f32_16x16x32_bf16 v[28:31], v[150:153], v[204:207], v[28:31]
	v_mfma_f32_16x16x32_bf16 v[24:27], v[158:161], v[204:207], v[24:27]
	v_mfma_f32_16x16x32_bf16 v[12:15], v[150:153], v[212:215], v[12:15]
	v_mfma_f32_16x16x32_bf16 v[8:11], v[158:161], v[212:215], v[8:11]
	v_mfma_f32_16x16x32_bf16 v[60:63], v[154:157], v[192:195], v[60:63]
	v_mfma_f32_16x16x32_bf16 v[56:59], v[162:165], v[192:195], v[56:59]
	v_mfma_f32_16x16x32_bf16 v[44:47], v[154:157], v[200:203], v[44:47]
	v_mfma_f32_16x16x32_bf16 v[40:43], v[162:165], v[200:203], v[40:43]
	v_mfma_f32_16x16x32_bf16 v[28:31], v[154:157], v[208:211], v[28:31]
	v_mfma_f32_16x16x32_bf16 v[24:27], v[162:165], v[208:211], v[24:27]
	v_mfma_f32_16x16x32_bf16 v[12:15], v[154:157], v[216:219], v[12:15]
	v_mfma_f32_16x16x32_bf16 v[8:11], v[162:165], v[216:219], v[8:11]
	v_mfma_f32_16x16x32_bf16 v[52:55], v[166:169], v[182:185], v[52:55]
	v_mfma_f32_16x16x32_bf16 v[48:51], v[174:177], v[182:185], v[48:51]
	v_mfma_f32_16x16x32_bf16 v[36:39], v[166:169], v[196:199], v[36:39]
	v_mfma_f32_16x16x32_bf16 v[32:35], v[174:177], v[196:199], v[32:35]
	v_mfma_f32_16x16x32_bf16 v[20:23], v[166:169], v[204:207], v[20:23]
	v_mfma_f32_16x16x32_bf16 v[16:19], v[174:177], v[204:207], v[16:19]
	v_mfma_f32_16x16x32_bf16 v[4:7], v[166:169], v[212:215], v[4:7]
	v_mfma_f32_16x16x32_bf16 v[0:3], v[174:177], v[212:215], v[0:3]
	v_mfma_f32_16x16x32_bf16 v[52:55], v[170:173], v[192:195], v[52:55]
	v_mfma_f32_16x16x32_bf16 v[48:51], v[178:181], v[192:195], v[48:51]
	v_mfma_f32_16x16x32_bf16 v[36:39], v[170:173], v[200:203], v[36:39]
	v_mfma_f32_16x16x32_bf16 v[32:35], v[178:181], v[200:203], v[32:35]
	v_mfma_f32_16x16x32_bf16 v[20:23], v[170:173], v[208:211], v[20:23]
	v_mfma_f32_16x16x32_bf16 v[16:19], v[178:181], v[208:211], v[16:19]
	v_mfma_f32_16x16x32_bf16 v[4:7], v[170:173], v[216:219], v[4:7]
	v_mfma_f32_16x16x32_bf16 v[0:3], v[178:181], v[216:219], v[0:3]
	s_barrier
	s_setprio 0
	s_add_i32 s54, s54, 2
	s_add_u32 s22, s22, 0x100
	s_addc_u32 s23, s23, 0
	s_add_u32 s52, s52, 0x100
	s_addc_u32 s53, s53, 0
	s_cmp_gt_u32 s54, 13
	s_cbranch_scc0 .LBB0_192
	s_and_b64 vcc, exec, s[6:7]
	s_cbranch_vccz .LBB0_195
	s_barrier

; #define PG8_STAGE(bufoff, gbase, voff) do { _Pragma("unroll") for (int _i = 0; _i < 2; ++_i) \
;         __builtin_amdgcn_global_load_lds((const unsigned*)((const char*)(gbase) + (voff)[_i]), (PG8_LAS unsigned*)(lds + (bufoff) + ldsw + _i * 8192), 16, 0, 0); } while (0)
; #define PG8_LDA(dst, b, h) do { _Pragma("unroll") for (int m = 0; m < 4; ++m) _Pragma("unroll") for (int k = 0; k < 2; ++k) dst[m][k] = *(const PG8_LAS bf16x8*)(lds + PG8_SA(b, h) + aoff + m * 2048 + k * 1024); } while (0)
; #define PG8_LDB(dst, b, h) do { _Pragma("unroll") for (int n = 0; n < 2; ++n) _Pragma("unroll") for (int k = 0; k < 2; ++k) dst[n][k] = *(const PG8_LAS bf16x8*)(lds + PG8_SB(b, h) + boff + n * 2048 + k * 1024); } while (0)
; #define PG8_MMA(ai, bj, At, Bt) do { __builtin_amdgcn_s_setprio(1); _Pragma("unroll") for (int m = 0; m < 4; ++m) _Pragma("unroll") for (int n = 0; n < 2; ++n) _Pragma("unroll") for (int k = 0; k < 2; ++k) \
;         acc[ai][bj][m][n] = __builtin_amdgcn_mfma_f32_16x16x32_bf16(Bt[n][k], At[m][k], acc[ai][bj][m][n], 0, 0, 0); __builtin_amdgcn_s_setprio(0); } while (0)
; #define PG8_WAIT_V(n) asm volatile("s_waitcnt vmcnt(" #n ")" ::: "memory")
; template <class Epi, class Sched, bool ALIGN_EPI = false, bool SP2 = false>
; __device__ __forceinline__ void gemm_phase(PG8_LAS unsigned char* lds, const Gemm g, const Sched& S, const Epi& E) {
;     ...
;         const char* nA = has_next ? (const char*)g.A + (size_t)nxt.pm * tstep : cA; const char* nB = has_next ? (const char*)g.Bt + (size_t)nxt.pn * tstep : cB;
;         for (int t = 0; t < nt; t += 2) {
;             const bool last = (t == nt - 2);
;             const char* a1 = cA + (size_t)(t + 1) * kstep;
;             const char* a2 = last ? nA : cA + (size_t)(t + 2) * kstep; const char* b2 = last ? nB : cB + (size_t)(t + 2) * kstep;
;             const char* a3 = a2 + kstep; const char* b3 = b2 + kstep;
;             if (last && has_next) S.a_ready(nxt);
;             if constexpr (SP2) {
;             PG8_LDB(B0, 0, 0); PG8_LDB(B1, 0, 1); PG8_SCHED; PG8_LDA(At, 0, 0); PG8_STAGE(PG8_SA(1, 1), a1 + hstep, voffA);
;             PG8_WAIT_V(8); PG8_WAIT_L(0); PG8_BAR; PG8_MMA(0, 0, At, B0); PG8_MMA(0, 1, At, B1); PG8_BAR; PG8_SCHED;
;             PG8_LDA(At, 0, 1); PG8_STAGE(PG8_SB(0, 0), b2, voffB); PG8_STAGE(PG8_SB(0, 1), b2 + hstep, voffB); PG8_STAGE(PG8_SA(0, 0), a2, voffA);
.LBB0_273:
	s_add_u32 s58, s34, 0x100
	s_addc_u32 s59, s35, 0
	s_mov_b32 s60, -2
	s_waitcnt lgkmcnt(0)
	ds_read_b128 v[128:131], v161
	ds_read_b128 v[132:135], v161 offset:1024
	ds_read_b128 v[152:155], v161 offset:2048
	ds_read_b128 v[166:169], v161 offset:3072
	ds_read_b128 v[170:173], v162
	ds_read_b128 v[174:177], v162 offset:1024
	ds_read_b128 v[178:181], v162 offset:2048
	ds_read_b128 v[182:185], v162 offset:3072
	s_add_u32 s34, s8, 0x100
	s_addc_u32 s35, s9, 0
	s_cmp_eq_u32 s60, 40
	s_cselect_b32 s39, s1, s35
	s_cselect_b32 s38, s0, s34
	s_cselect_b32 s37, s31, s59
	s_cselect_b32 s36, s30, s58
	v_lshl_add_u64 v[156:157], s[8:9], 0, v[144:145]
	s_add_i32 m0, s42, 0xc000
	ds_read_b128 v[192:195], v163
	ds_read_b128 v[196:199], v163 offset:1024
	ds_read_b128 v[200:203], v163 offset:2048
	ds_read_b128 v[204:207], v163 offset:3072
	ds_read_b128 v[208:211], v163 offset:4096
	ds_read_b128 v[212:215], v163 offset:5120
	ds_read_b128 v[216:219], v163 offset:6144
	ds_read_b128 v[220:223], v163 offset:7168
	global_load_lds_dwordx4 v[156:157], off
	v_lshl_add_u64 v[156:157], s[8:9], 0, v[146:147]
	s_add_i32 m0, s42, 0xe000
	s_nop 0
	global_load_lds_dwordx4 v[156:157], off
	s_waitcnt vmcnt(8)
	s_waitcnt lgkmcnt(0)
	s_setprio 1
	s_barrier
	v_mfma_f32_16x16x32_bf16 v[124:127], v[128:131], v[192:195], 0
	v_mfma_f32_16x16x32_bf16 v[120:123], v[152:155], v[192:195], 0
	v_mfma_f32_16x16x32_bf16 v[108:111], v[128:131], v[200:203], 0
	v_mfma_f32_16x16x32_bf16 v[104:107], v[152:155], v[200:203], 0
	v_mfma_f32_16x16x32_bf16 v[92:95], v[128:131], v[208:211], 0
	v_mfma_f32_16x16x32_bf16 v[88:91], v[152:155], v[208:211], 0
	v_mfma_f32_16x16x32_bf16 v[76:79], v[128:131], v[216:219], 0
	v_mfma_f32_16x16x32_bf16 v[72:75], v[152:155], v[216:219], 0
	v_mfma_f32_16x16x32_bf16 v[124:127], v[132:135], v[196:199], v[124:127]
	v_mfma_f32_16x16x32_bf16 v[120:123], v[166:169], v[196:199], v[120:123]
	v_mfma_f32_16x16x32_bf16 v[108:111], v[132:135], v[204:207], v[108:111]
	v_mfma_f32_16x16x32_bf16 v[104:107], v[166:169], v[204:207], v[104:107]
	v_mfma_f32_16x16x32_bf16 v[92:95], v[132:135], v[212:215], v[92:95]
	v_mfma_f32_16x16x32_bf16 v[88:91], v[166:169], v[212:215], v[88:91]
	v_mfma_f32_16x16x32_bf16 v[76:79], v[132:135], v[220:223], v[76:79]
	v_mfma_f32_16x16x32_bf16 v[72:75], v[166:169], v[220:223], v[72:75]
	v_mfma_f32_16x16x32_bf16 v[116:119], v[170:173], v[192:195], 0
	v_mfma_f32_16x16x32_bf16 v[112:115], v[178:181], v[192:195], 0
	v_mfma_f32_16x16x32_bf16 v[100:103], v[170:173], v[200:203], 0
	v_mfma_f32_16x16x32_bf16 v[96:99], v[178:181], v[200:203], 0
	v_mfma_f32_16x16x32_bf16 v[84:87], v[170:173], v[208:211], 0
	v_mfma_f32_16x16x32_bf16 v[80:83], v[178:181], v[208:211], 0
	v_mfma_f32_16x16x32_bf16 v[68:71], v[170:173], v[216:219], 0
	v_mfma_f32_16x16x32_bf16 v[64:67], v[178:181], v[216:219], 0
	v_mfma_f32_16x16x32_bf16 v[116:119], v[174:177], v[196:199], v[116:119]
	v_mfma_f32_16x16x32_bf16 v[112:115], v[182:185], v[196:199], v[112:115]
	v_mfma_f32_16x16x32_bf16 v[100:103], v[174:177], v[204:207], v[100:103]
	v_mfma_f32_16x16x32_bf16 v[96:99], v[182:185], v[204:207], v[96:99]
	v_mfma_f32_16x16x32_bf16 v[84:87], v[174:177], v[212:215], v[84:87]
	v_mfma_f32_16x16x32_bf16 v[80:83], v[182:185], v[212:215], v[80:83]
	v_mfma_f32_16x16x32_bf16 v[68:71], v[174:177], v[220:223], v[68:71]
	v_mfma_f32_16x16x32_bf16 v[64:67], v[182:185], v[220:223], v[64:67]
	s_barrier
	s_setprio 0
	s_add_i32 s8, s52, s41
	v_lshl_add_u64 v[156:157], s[36:37], 0, v[138:139]
	s_mov_b32 m0, s8
	ds_read_b128 v[192:195], v163 offset:16384
	ds_read_b128 v[196:199], v163 offset:17408
	ds_read_b128 v[200:203], v163 offset:18432
	ds_read_b128 v[204:207], v163 offset:19456
	ds_read_b128 v[208:211], v163 offset:20480
	ds_read_b128 v[212:215], v163 offset:21504
	ds_read_b128 v[216:219], v163 offset:22528
	ds_read_b128 v[220:223], v163 offset:23552
	global_load_lds_dwordx4 v[156:157], off
	s_add_i32 m0, s8, 0x2000
	s_add_u32 s8, s36, 0xb0000
	v_lshl_add_u64 v[186:187], s[36:37], 0, v[142:143]
	s_addc_u32 s9, s37, 0
	s_add_i32 s61, s53, s41
	global_load_lds_dwordx4 v[186:187], off
	v_lshl_add_u64 v[224:225], s[8:9], 0, v[138:139]
	s_mov_b32 m0, s61
	v_lshl_add_u64 v[226:227], s[38:39], 0, v[140:141]
	global_load_lds_dwordx4 v[224:225], off
	v_lshl_add_u64 v[224:225], s[8:9], 0, v[142:143]
	s_add_i32 m0, s61, 0x2000
	s_nop 0
	global_load_lds_dwordx4 v[224:225], off
	v_lshl_add_u64 v[224:225], s[38:39], 0, v[136:137]
	s_mov_b32 m0, s42
	s_nop 0
	global_load_lds_dwordx4 v[224:225], off
	s_mov_b32 m0, s43
	s_nop 0
	global_load_lds_dwordx4 v[226:227], off
	s_waitcnt vmcnt(8)
	s_waitcnt lgkmcnt(0)
	s_setprio 1
	s_barrier
; #define PG8_STAGE(bufoff, gbase, voff) do { _Pragma("unroll") for (int _i = 0; _i < 2; ++_i) \
;         __builtin_amdgcn_global_load_lds((const unsigned*)((const char*)(gbase) + (voff)[_i]), (PG8_LAS unsigned*)(lds + (bufoff) + ldsw + _i * 8192), 16, 0, 0); } while (0)
; #define PG8_LDA(dst, b, h) do { _Pragma("unroll") for (int m = 0; m < 4; ++m) _Pragma("unroll") for (int k = 0; k < 2; ++k) dst[m][k] = *(const PG8_LAS bf16x8*)(lds + PG8_SA(b, h) + aoff + m * 2048 + k * 1024); } while (0)
; #define PG8_LDB(dst, b, h) do { _Pragma("unroll") for (int n = 0; n < 2; ++n) _Pragma("unroll") for (int k = 0; k < 2; ++k) dst[n][k] = *(const PG8_LAS bf16x8*)(lds + PG8_SB(b, h) + boff + n * 2048 + k * 1024); } while (0)
; #define PG8_MMA(ai, bj, At, Bt) do { __builtin_amdgcn_s_setprio(1); _Pragma("unroll") for (int m = 0; m < 4; ++m) _Pragma("unroll") for (int n = 0; n < 2; ++n) _Pragma("unroll") for (int k = 0; k < 2; ++k) \
;         acc[ai][bj][m][n] = __builtin_amdgcn_mfma_f32_16x16x32_bf16(Bt[n][k], At[m][k], acc[ai][bj][m][n], 0, 0, 0); __builtin_amdgcn_s_setprio(0); } while (0)
; #define PG8_WAIT_V(n) asm volatile("s_waitcnt vmcnt(" #n ")" ::: "memory")
; template <class Epi, class Sched, bool ALIGN_EPI = false, bool SP2 = false>
; __device__ __forceinline__ void gemm_phase(PG8_LAS unsigned char* lds, const Gemm g, const Sched& S, const Epi& E) {
;     ...
;             PG8_LDB(B0, 0, 0); PG8_LDB(B1, 0, 1); PG8_SCHED; PG8_LDA(At, 0, 0); PG8_STAGE(PG8_SA(1, 1), a1 + hstep, voffA);
;             PG8_WAIT_V(8); PG8_WAIT_L(0); PG8_BAR; PG8_MMA(0, 0, At, B0); PG8_MMA(0, 1, At, B1); PG8_BAR; PG8_SCHED;
;             PG8_LDA(At, 0, 1); PG8_STAGE(PG8_SB(0, 0), b2, voffB); PG8_STAGE(PG8_SB(0, 1), b2 + hstep, voffB); PG8_STAGE(PG8_SA(0, 0), a2, voffA);
;             PG8_WAIT_V(8); PG8_WAIT_L(0); PG8_BAR; PG8_MMA(1, 0, At, B0); PG8_MMA(1, 1, At, B1); PG8_BAR; PG8_SCHED;
;             PG8_LDB(B0, 1, 0); PG8_LDB(B1, 1, 1); PG8_SCHED; PG8_LDA(At, 1, 0); PG8_STAGE(PG8_SA(0, 1), a2 + hstep, voffA);
;             PG8_WAIT_V(8); PG8_WAIT_L(0); PG8_BAR; PG8_MMA(0, 0, At, B0); PG8_MMA(0, 1, At, B1); PG8_BAR; PG8_SCHED;
;             PG8_LDA(At, 1, 1); PG8_STAGE(PG8_SB(1, 0), b3, voffB); PG8_STAGE(PG8_SB(1, 1), b3 + hstep, voffB); PG8_STAGE(PG8_SA(1, 0), a3, voffA);
;             PG8_WAIT_V(8); PG8_WAIT_L(0); PG8_BAR; PG8_MMA(1, 0, At, B0); PG8_MMA(1, 1, At, B1); PG8_BAR; PG8_SCHED;
	v_mfma_f32_16x16x32_bf16 v[60:63], v[128:131], v[192:195], 0
	v_mfma_f32_16x16x32_bf16 v[56:59], v[152:155], v[192:195], 0
	v_mfma_f32_16x16x32_bf16 v[44:47], v[128:131], v[200:203], 0
	v_mfma_f32_16x16x32_bf16 v[40:43], v[152:155], v[200:203], 0
	v_mfma_f32_16x16x32_bf16 v[28:31], v[128:131], v[208:211], 0
	v_mfma_f32_16x16x32_bf16 v[24:27], v[152:155], v[208:211], 0
	v_mfma_f32_16x16x32_bf16 v[12:15], v[128:131], v[216:219], 0
	v_mfma_f32_16x16x32_bf16 v[8:11], v[152:155], v[216:219], 0
	v_mfma_f32_16x16x32_bf16 v[60:63], v[132:135], v[196:199], v[60:63]
	v_mfma_f32_16x16x32_bf16 v[56:59], v[166:169], v[196:199], v[56:59]
	v_mfma_f32_16x16x32_bf16 v[44:47], v[132:135], v[204:207], v[44:47]
	v_mfma_f32_16x16x32_bf16 v[40:43], v[166:169], v[204:207], v[40:43]
	v_mfma_f32_16x16x32_bf16 v[28:31], v[132:135], v[212:215], v[28:31]
	v_mfma_f32_16x16x32_bf16 v[24:27], v[166:169], v[212:215], v[24:27]
	v_mfma_f32_16x16x32_bf16 v[12:15], v[132:135], v[220:223], v[12:15]
	v_mfma_f32_16x16x32_bf16 v[8:11], v[166:169], v[220:223], v[8:11]
	v_mfma_f32_16x16x32_bf16 v[52:55], v[170:173], v[192:195], 0
	v_mfma_f32_16x16x32_bf16 v[48:51], v[178:181], v[192:195], 0
	v_mfma_f32_16x16x32_bf16 v[36:39], v[170:173], v[200:203], 0
	v_mfma_f32_16x16x32_bf16 v[32:35], v[178:181], v[200:203], 0
	v_mfma_f32_16x16x32_bf16 v[20:23], v[170:173], v[208:211], 0
	v_mfma_f32_16x16x32_bf16 v[16:19], v[178:181], v[208:211], 0
	v_mfma_f32_16x16x32_bf16 v[4:7], v[170:173], v[216:219], 0
	v_mfma_f32_16x16x32_bf16 v[0:3], v[178:181], v[216:219], 0
	v_mfma_f32_16x16x32_bf16 v[52:55], v[174:177], v[196:199], v[52:55]
	v_mfma_f32_16x16x32_bf16 v[48:51], v[182:185], v[196:199], v[48:51]
	v_mfma_f32_16x16x32_bf16 v[36:39], v[174:177], v[204:207], v[36:39]
	v_mfma_f32_16x16x32_bf16 v[32:35], v[182:185], v[204:207], v[32:35]
	v_mfma_f32_16x16x32_bf16 v[20:23], v[174:177], v[212:215], v[20:23]
	v_mfma_f32_16x16x32_bf16 v[16:19], v[182:185], v[212:215], v[16:19]
	v_mfma_f32_16x16x32_bf16 v[4:7], v[174:177], v[220:223], v[4:7]
	v_mfma_f32_16x16x32_bf16 v[0:3], v[182:185], v[220:223], v[0:3]
	s_barrier
	s_setprio 0
	s_add_i32 s61, 0, 0x18000
	v_add_u32_e32 v165, s61, v159
	s_add_i32 s62, 0, 0x1c000
	ds_read_b128 v[128:131], v165
	ds_read_b128 v[132:135], v165 offset:1024
	ds_read_b128 v[152:155], v165 offset:2048
	ds_read_b128 v[166:169], v165 offset:3072
	v_add_u32_e32 v165, s62, v159
	ds_read_b128 v[170:173], v165
	ds_read_b128 v[174:177], v165 offset:1024
	ds_read_b128 v[178:181], v165 offset:2048
	ds_read_b128 v[182:185], v165 offset:3072
	s_add_u32 s8, s38, 0xb0000
	s_addc_u32 s9, s39, 0
	s_mov_b32 m0, s44
	v_lshl_add_u64 v[228:229], s[8:9], 0, v[136:137]
	ds_read_b128 v[192:195], v163 offset:32768
	ds_read_b128 v[196:199], v163 offset:33792
	ds_read_b128 v[200:203], v163 offset:34816
	ds_read_b128 v[204:207], v163 offset:35840
	ds_read_b128 v[208:211], v163 offset:36864
	ds_read_b128 v[212:215], v163 offset:37888
	ds_read_b128 v[216:219], v163 offset:38912
	ds_read_b128 v[220:223], v163 offset:39936
	global_load_lds_dwordx4 v[228:229], off
	v_lshl_add_u64 v[228:229], s[8:9], 0, v[140:141]
	s_mov_b32 m0, s45
	s_nop 0
	global_load_lds_dwordx4 v[228:229], off
	s_waitcnt vmcnt(8)
	s_waitcnt lgkmcnt(0)
	s_setprio 1
	s_barrier
	v_mfma_f32_16x16x32_bf16 v[124:127], v[128:131], v[192:195], v[124:127]
	v_mfma_f32_16x16x32_bf16 v[120:123], v[152:155], v[192:195], v[120:123]
	v_mfma_f32_16x16x32_bf16 v[108:111], v[128:131], v[200:203], v[108:111]
	v_mfma_f32_16x16x32_bf16 v[104:107], v[152:155], v[200:203], v[104:107]
	v_mfma_f32_16x16x32_bf16 v[92:95], v[128:131], v[208:211], v[92:95]
	v_mfma_f32_16x16x32_bf16 v[88:91], v[152:155], v[208:211], v[88:91]
	v_mfma_f32_16x16x32_bf16 v[76:79], v[128:131], v[216:219], v[76:79]
	v_mfma_f32_16x16x32_bf16 v[72:75], v[152:155], v[216:219], v[72:75]
	v_mfma_f32_16x16x32_bf16 v[124:127], v[132:135], v[196:199], v[124:127]
	v_mfma_f32_16x16x32_bf16 v[120:123], v[166:169], v[196:199], v[120:123]
	v_mfma_f32_16x16x32_bf16 v[108:111], v[132:135], v[204:207], v[108:111]
	v_mfma_f32_16x16x32_bf16 v[104:107], v[166:169], v[204:207], v[104:107]
	v_mfma_f32_16x16x32_bf16 v[92:95], v[132:135], v[212:215], v[92:95]
	v_mfma_f32_16x16x32_bf16 v[88:91], v[166:169], v[212:215], v[88:91]
	v_mfma_f32_16x16x32_bf16 v[76:79], v[132:135], v[220:223], v[76:79]
	v_mfma_f32_16x16x32_bf16 v[72:75], v[166:169], v[220:223], v[72:75]
	v_mfma_f32_16x16x32_bf16 v[116:119], v[170:173], v[192:195], v[116:119]
	v_mfma_f32_16x16x32_bf16 v[112:115], v[178:181], v[192:195], v[112:115]
	v_mfma_f32_16x16x32_bf16 v[100:103], v[170:173], v[200:203], v[100:103]
	v_mfma_f32_16x16x32_bf16 v[96:99], v[178:181], v[200:203], v[96:99]
	v_mfma_f32_16x16x32_bf16 v[84:87], v[170:173], v[208:211], v[84:87]
	v_mfma_f32_16x16x32_bf16 v[80:83], v[178:181], v[208:211], v[80:83]
	v_mfma_f32_16x16x32_bf16 v[68:71], v[170:173], v[216:219], v[68:71]
	v_mfma_f32_16x16x32_bf16 v[64:67], v[178:181], v[216:219], v[64:67]
	v_mfma_f32_16x16x32_bf16 v[116:119], v[174:177], v[196:199], v[116:119]
	v_mfma_f32_16x16x32_bf16 v[112:115], v[182:185], v[196:199], v[112:115]
	v_mfma_f32_16x16x32_bf16 v[100:103], v[174:177], v[204:207], v[100:103]
	v_mfma_f32_16x16x32_bf16 v[96:99], v[182:185], v[204:207], v[96:99]
	v_mfma_f32_16x16x32_bf16 v[84:87], v[174:177], v[212:215], v[84:87]
	v_mfma_f32_16x16x32_bf16 v[80:83], v[182:185], v[212:215], v[80:83]
	v_mfma_f32_16x16x32_bf16 v[68:71], v[174:177], v[220:223], v[68:71]
	v_mfma_f32_16x16x32_bf16 v[64:67], v[182:185], v[220:223], v[64:67]
	s_barrier
; #define PG8_STAGE(bufoff, gbase, voff) do { _Pragma("unroll") for (int _i = 0; _i < 2; ++_i) \
;         __builtin_amdgcn_global_load_lds((const unsigned*)((const char*)(gbase) + (voff)[_i]), (PG8_LAS unsigned*)(lds + (bufoff) + ldsw + _i * 8192), 16, 0, 0); } while (0)
; #define PG8_LDA(dst, b, h) do { _Pragma("unroll") for (int m = 0; m < 4; ++m) _Pragma("unroll") for (int k = 0; k < 2; ++k) dst[m][k] = *(const PG8_LAS bf16x8*)(lds + PG8_SA(b, h) + aoff + m * 2048 + k * 1024); } while (0)
; #define PG8_LDB(dst, b, h) do { _Pragma("unroll") for (int n = 0; n < 2; ++n) _Pragma("unroll") for (int k = 0; k < 2; ++k) dst[n][k] = *(const PG8_LAS bf16x8*)(lds + PG8_SB(b, h) + boff + n * 2048 + k * 1024); } while (0)
; #define PG8_BAR __builtin_amdgcn_s_barrier()
; template <class Epi, class Sched, bool ALIGN_EPI = false, bool SP2 = false>
; __device__ __forceinline__ void gemm_phase(PG8_LAS unsigned char* lds, const Gemm g, const Sched& S, const Epi& E) {
;     ...
;             const bool last = (t == nt - 2);
;             const char* a1 = cA + (size_t)(t + 1) * kstep;
;             const char* a2 = last ? nA : cA + (size_t)(t + 2) * kstep; const char* b2 = last ? nB : cB + (size_t)(t + 2) * kstep;
;             const char* a3 = a2 + kstep; const char* b3 = b2 + kstep;
;             if (last && has_next) S.a_ready(nxt);
;             if constexpr (SP2) {
;             PG8_LDB(B0, 0, 0); PG8_LDB(B1, 0, 1); PG8_SCHED; PG8_LDA(At, 0, 0); PG8_STAGE(PG8_SA(1, 1), a1 + hstep, voffA);
;             PG8_WAIT_V(8); PG8_WAIT_L(0); PG8_BAR; PG8_MMA(0, 0, At, B0); PG8_MMA(0, 1, At, B1); PG8_BAR; PG8_SCHED;
;             PG8_LDA(At, 0, 1); PG8_STAGE(PG8_SB(0, 0), b2, voffB); PG8_STAGE(PG8_SB(0, 1), b2 + hstep, voffB); PG8_STAGE(PG8_SA(0, 0), a2, voffA);
;             PG8_WAIT_V(8); PG8_WAIT_L(0); PG8_BAR; PG8_MMA(1, 0, At, B0); PG8_MMA(1, 1, At, B1); PG8_BAR; PG8_SCHED;
;             PG8_LDB(B0, 1, 0); PG8_LDB(B1, 1, 1); PG8_SCHED; PG8_LDA(At, 1, 0); PG8_STAGE(PG8_SA(0, 1), a2 + hstep, voffA);
;             PG8_WAIT_V(8); PG8_WAIT_L(0); PG8_BAR; PG8_MMA(0, 0, At, B0); PG8_MMA(0, 1, At, B1); PG8_BAR; PG8_SCHED;
;             PG8_LDA(At, 1, 1); PG8_STAGE(PG8_SB(1, 0), b3, voffB); PG8_STAGE(PG8_SB(1, 1), b3 + hstep, voffB); PG8_STAGE(PG8_SA(1, 0), a3, voffA);
;             PG8_WAIT_V(8); PG8_WAIT_L(0); PG8_BAR; PG8_MMA(1, 0, At, B0); PG8_MMA(1, 1, At, B1); PG8_BAR; PG8_SCHED;
	s_setprio 0
	s_add_i32 s8, s61, s41
	v_lshl_add_u64 v[156:157], v[156:157], 0, s[14:15]
	s_mov_b32 m0, s8
	ds_read_b128 v[192:195], v163 offset:49152
	ds_read_b128 v[196:199], v163 offset:50176
	ds_read_b128 v[200:203], v163 offset:51200
	ds_read_b128 v[204:207], v163 offset:52224
	ds_read_b128 v[208:211], v163 offset:53248
	ds_read_b128 v[212:215], v163 offset:54272
	ds_read_b128 v[216:219], v163 offset:55296
	ds_read_b128 v[220:223], v163 offset:56320
	global_load_lds_dwordx4 v[156:157], off
	s_add_i32 m0, s8, 0x2000
	s_add_u32 s8, s36, 0xb0080
	v_lshl_add_u64 v[156:157], v[186:187], 0, s[14:15]
	s_addc_u32 s9, s37, 0
	s_add_i32 s36, s62, s41
	global_load_lds_dwordx4 v[156:157], off
	v_lshl_add_u64 v[156:157], s[8:9], 0, v[138:139]
	s_mov_b32 m0, s36
	s_nop 0
	global_load_lds_dwordx4 v[156:157], off
	v_lshl_add_u64 v[156:157], s[8:9], 0, v[142:143]
	s_add_i32 m0, s36, 0x2000
	s_nop 0
	global_load_lds_dwordx4 v[156:157], off
	v_lshl_add_u64 v[156:157], v[224:225], 0, s[14:15]
	s_mov_b32 m0, s47
	s_nop 0
	global_load_lds_dwordx4 v[156:157], off
	v_lshl_add_u64 v[156:157], v[226:227], 0, s[14:15]
	s_mov_b32 m0, s48
	s_nop 0
	global_load_lds_dwordx4 v[156:157], off
	s_waitcnt vmcnt(8)
	s_waitcnt lgkmcnt(0)
	s_setprio 1
	s_barrier
	v_mfma_f32_16x16x32_bf16 v[60:63], v[128:131], v[192:195], v[60:63]
	v_mfma_f32_16x16x32_bf16 v[56:59], v[152:155], v[192:195], v[56:59]
	v_mfma_f32_16x16x32_bf16 v[44:47], v[128:131], v[200:203], v[44:47]
	v_mfma_f32_16x16x32_bf16 v[40:43], v[152:155], v[200:203], v[40:43]
	v_mfma_f32_16x16x32_bf16 v[28:31], v[128:131], v[208:211], v[28:31]
	v_mfma_f32_16x16x32_bf16 v[24:27], v[152:155], v[208:211], v[24:27]
	v_mfma_f32_16x16x32_bf16 v[12:15], v[128:131], v[216:219], v[12:15]
	v_mfma_f32_16x16x32_bf16 v[8:11], v[152:155], v[216:219], v[8:11]
	v_mfma_f32_16x16x32_bf16 v[60:63], v[132:135], v[196:199], v[60:63]
	v_mfma_f32_16x16x32_bf16 v[56:59], v[166:169], v[196:199], v[56:59]
	v_mfma_f32_16x16x32_bf16 v[44:47], v[132:135], v[204:207], v[44:47]
	v_mfma_f32_16x16x32_bf16 v[40:43], v[166:169], v[204:207], v[40:43]
	v_mfma_f32_16x16x32_bf16 v[28:31], v[132:135], v[212:215], v[28:31]
	v_mfma_f32_16x16x32_bf16 v[24:27], v[166:169], v[212:215], v[24:27]
	v_mfma_f32_16x16x32_bf16 v[12:15], v[132:135], v[220:223], v[12:15]
	v_mfma_f32_16x16x32_bf16 v[8:11], v[166:169], v[220:223], v[8:11]
	v_mfma_f32_16x16x32_bf16 v[52:55], v[170:173], v[192:195], v[52:55]
	v_mfma_f32_16x16x32_bf16 v[48:51], v[178:181], v[192:195], v[48:51]
	v_mfma_f32_16x16x32_bf16 v[36:39], v[170:173], v[200:203], v[36:39]
	v_mfma_f32_16x16x32_bf16 v[32:35], v[178:181], v[200:203], v[32:35]
	v_mfma_f32_16x16x32_bf16 v[20:23], v[170:173], v[208:211], v[20:23]
	v_mfma_f32_16x16x32_bf16 v[16:19], v[178:181], v[208:211], v[16:19]
	v_mfma_f32_16x16x32_bf16 v[4:7], v[170:173], v[216:219], v[4:7]
	v_mfma_f32_16x16x32_bf16 v[0:3], v[178:181], v[216:219], v[0:3]
	v_mfma_f32_16x16x32_bf16 v[52:55], v[174:177], v[196:199], v[52:55]
	v_mfma_f32_16x16x32_bf16 v[48:51], v[182:185], v[196:199], v[48:51]
	v_mfma_f32_16x16x32_bf16 v[36:39], v[174:177], v[204:207], v[36:39]
	v_mfma_f32_16x16x32_bf16 v[32:35], v[182:185], v[204:207], v[32:35]
	v_mfma_f32_16x16x32_bf16 v[20:23], v[174:177], v[212:215], v[20:23]
	v_mfma_f32_16x16x32_bf16 v[16:19], v[182:185], v[212:215], v[16:19]
	v_mfma_f32_16x16x32_bf16 v[4:7], v[174:177], v[220:223], v[4:7]
	v_mfma_f32_16x16x32_bf16 v[0:3], v[182:185], v[220:223], v[0:3]
	s_barrier
	s_setprio 0
	s_add_i32 s60, s60, 2
	s_add_u32 s58, s58, 0x100
	s_addc_u32 s59, s59, 0
	s_mov_b64 s[8:9], s[34:35]
.LBB0_274:
	ds_read_b128 v[128:131], v161
	ds_read_b128 v[132:135], v161 offset:1024
	ds_read_b128 v[152:155], v161 offset:2048
	ds_read_b128 v[166:169], v161 offset:3072
	ds_read_b128 v[170:173], v162
	ds_read_b128 v[174:177], v162 offset:1024
	ds_read_b128 v[178:181], v162 offset:2048
	ds_read_b128 v[182:185], v162 offset:3072
	s_add_u32 s34, s8, 0x100
	s_addc_u32 s35, s9, 0
	s_cmp_eq_u32 s60, 40
	s_cselect_b32 s39, s1, s35
	s_cselect_b32 s38, s0, s34
	s_cselect_b32 s37, s31, s59
	s_cselect_b32 s36, s30, s58
	v_lshl_add_u64 v[156:157], s[8:9], 0, v[144:145]
	s_add_i32 m0, s42, 0xc000
	ds_read_b128 v[192:195], v163
	ds_read_b128 v[196:199], v163 offset:1024
	ds_read_b128 v[200:203], v163 offset:2048
	ds_read_b128 v[204:207], v163 offset:3072
	ds_read_b128 v[208:211], v163 offset:4096
	ds_read_b128 v[212:215], v163 offset:5120
	ds_read_b128 v[216:219], v163 offset:6144
	ds_read_b128 v[220:223], v163 offset:7168
	global_load_lds_dwordx4 v[156:157], off
	v_lshl_add_u64 v[156:157], s[8:9], 0, v[146:147]
	s_add_i32 m0, s42, 0xe000
	s_nop 0
	global_load_lds_dwordx4 v[156:157], off
	s_waitcnt vmcnt(8)
	s_waitcnt lgkmcnt(0)
	s_setprio 1
	s_barrier
; #define PG8_STAGE(bufoff, gbase, voff) do { _Pragma("unroll") for (int _i = 0; _i < 2; ++_i) \
;         __builtin_amdgcn_global_load_lds((const unsigned*)((const char*)(gbase) + (voff)[_i]), (PG8_LAS unsigned*)(lds + (bufoff) + ldsw + _i * 8192), 16, 0, 0); } while (0)
; #define PG8_LDA(dst, b, h) do { _Pragma("unroll") for (int m = 0; m < 4; ++m) _Pragma("unroll") for (int k = 0; k < 2; ++k) dst[m][k] = *(const PG8_LAS bf16x8*)(lds + PG8_SA(b, h) + aoff + m * 2048 + k * 1024); } while (0)
; #define PG8_MMA(ai, bj, At, Bt) do { __builtin_amdgcn_s_setprio(1); _Pragma("unroll") for (int m = 0; m < 4; ++m) _Pragma("unroll") for (int n = 0; n < 2; ++n) _Pragma("unroll") for (int k = 0; k < 2; ++k) \
;         acc[ai][bj][m][n] = __builtin_amdgcn_mfma_f32_16x16x32_bf16(Bt[n][k], At[m][k], acc[ai][bj][m][n], 0, 0, 0); __builtin_amdgcn_s_setprio(0); } while (0)
; #define PG8_WAIT_V(n) asm volatile("s_waitcnt vmcnt(" #n ")" ::: "memory")
; #define PG8_WAIT_L(n) asm volatile("s_waitcnt lgkmcnt(" #n ")" ::: "memory")
; #define PG8_BAR __builtin_amdgcn_s_barrier()
; #define PG8_SCHED __builtin_amdgcn_sched_barrier(0)
; template <class Epi, class Sched, bool ALIGN_EPI = false, bool SP2 = false>
; __device__ __forceinline__ void gemm_phase(PG8_LAS unsigned char* lds, const Gemm g, const Sched& S, const Epi& E) {
;     ...
;             PG8_WAIT_V(8); PG8_WAIT_L(0); PG8_BAR; PG8_MMA(0, 0, At, B0); PG8_MMA(0, 1, At, B1); PG8_BAR; PG8_SCHED;
;             PG8_LDA(At, 0, 1); PG8_STAGE(PG8_SB(0, 0), b2, voffB); PG8_STAGE(PG8_SB(0, 1), b2 + hstep, voffB); PG8_STAGE(PG8_SA(0, 0), a2, voffA);
;             PG8_WAIT_V(8); PG8_WAIT_L(0); PG8_BAR; PG8_MMA(1, 0, At, B0); PG8_MMA(1, 1, At, B1); PG8_BAR; PG8_SCHED;
	v_mfma_f32_16x16x32_bf16 v[124:127], v[128:131], v[192:195], v[124:127]
	v_mfma_f32_16x16x32_bf16 v[120:123], v[152:155], v[192:195], v[120:123]
	v_mfma_f32_16x16x32_bf16 v[108:111], v[128:131], v[200:203], v[108:111]
	v_mfma_f32_16x16x32_bf16 v[104:107], v[152:155], v[200:203], v[104:107]
	v_mfma_f32_16x16x32_bf16 v[92:95], v[128:131], v[208:211], v[92:95]
	v_mfma_f32_16x16x32_bf16 v[88:91], v[152:155], v[208:211], v[88:91]
	v_mfma_f32_16x16x32_bf16 v[76:79], v[128:131], v[216:219], v[76:79]
	v_mfma_f32_16x16x32_bf16 v[72:75], v[152:155], v[216:219], v[72:75]
	v_mfma_f32_16x16x32_bf16 v[124:127], v[132:135], v[196:199], v[124:127]
	v_mfma_f32_16x16x32_bf16 v[120:123], v[166:169], v[196:199], v[120:123]
	v_mfma_f32_16x16x32_bf16 v[108:111], v[132:135], v[204:207], v[108:111]
	v_mfma_f32_16x16x32_bf16 v[104:107], v[166:169], v[204:207], v[104:107]
	v_mfma_f32_16x16x32_bf16 v[92:95], v[132:135], v[212:215], v[92:95]
	v_mfma_f32_16x16x32_bf16 v[88:91], v[166:169], v[212:215], v[88:91]
	v_mfma_f32_16x16x32_bf16 v[76:79], v[132:135], v[220:223], v[76:79]
	v_mfma_f32_16x16x32_bf16 v[72:75], v[166:169], v[220:223], v[72:75]
	v_mfma_f32_16x16x32_bf16 v[116:119], v[170:173], v[192:195], v[116:119]
	v_mfma_f32_16x16x32_bf16 v[112:115], v[178:181], v[192:195], v[112:115]
	v_mfma_f32_16x16x32_bf16 v[100:103], v[170:173], v[200:203], v[100:103]
	v_mfma_f32_16x16x32_bf16 v[96:99], v[178:181], v[200:203], v[96:99]
	v_mfma_f32_16x16x32_bf16 v[84:87], v[170:173], v[208:211], v[84:87]
	v_mfma_f32_16x16x32_bf16 v[80:83], v[178:181], v[208:211], v[80:83]
	v_mfma_f32_16x16x32_bf16 v[68:71], v[170:173], v[216:219], v[68:71]
	v_mfma_f32_16x16x32_bf16 v[64:67], v[178:181], v[216:219], v[64:67]
	v_mfma_f32_16x16x32_bf16 v[116:119], v[174:177], v[196:199], v[116:119]
	v_mfma_f32_16x16x32_bf16 v[112:115], v[182:185], v[196:199], v[112:115]
	v_mfma_f32_16x16x32_bf16 v[100:103], v[174:177], v[204:207], v[100:103]
	v_mfma_f32_16x16x32_bf16 v[96:99], v[182:185], v[204:207], v[96:99]
	v_mfma_f32_16x16x32_bf16 v[84:87], v[174:177], v[212:215], v[84:87]
	v_mfma_f32_16x16x32_bf16 v[80:83], v[182:185], v[212:215], v[80:83]
	v_mfma_f32_16x16x32_bf16 v[68:71], v[174:177], v[220:223], v[68:71]
	v_mfma_f32_16x16x32_bf16 v[64:67], v[182:185], v[220:223], v[64:67]
	s_barrier
	s_setprio 0
	s_add_i32 s8, s52, s41
	v_lshl_add_u64 v[156:157], s[36:37], 0, v[138:139]
	s_mov_b32 m0, s8
	ds_read_b128 v[192:195], v163 offset:16384
	ds_read_b128 v[196:199], v163 offset:17408
	ds_read_b128 v[200:203], v163 offset:18432
	ds_read_b128 v[204:207], v163 offset:19456
	ds_read_b128 v[208:211], v163 offset:20480
	ds_read_b128 v[212:215], v163 offset:21504
	ds_read_b128 v[216:219], v163 offset:22528
	ds_read_b128 v[220:223], v163 offset:23552
	global_load_lds_dwordx4 v[156:157], off
	s_add_i32 m0, s8, 0x2000
	s_add_u32 s8, s36, 0xb0000
	v_lshl_add_u64 v[186:187], s[36:37], 0, v[142:143]
	s_addc_u32 s9, s37, 0
	s_add_i32 s61, s53, s41
	global_load_lds_dwordx4 v[186:187], off
	v_lshl_add_u64 v[224:225], s[8:9], 0, v[138:139]
	s_mov_b32 m0, s61
	v_lshl_add_u64 v[226:227], s[38:39], 0, v[140:141]
	global_load_lds_dwordx4 v[224:225], off
	v_lshl_add_u64 v[224:225], s[8:9], 0, v[142:143]
	s_add_i32 m0, s61, 0x2000
	s_nop 0
	global_load_lds_dwordx4 v[224:225], off
	v_lshl_add_u64 v[224:225], s[38:39], 0, v[136:137]
	s_mov_b32 m0, s42
	s_nop 0
	global_load_lds_dwordx4 v[224:225], off
	s_mov_b32 m0, s43
	s_nop 0
	global_load_lds_dwordx4 v[226:227], off
	s_waitcnt vmcnt(8)
	s_waitcnt lgkmcnt(0)
	s_setprio 1
	s_barrier
	v_mfma_f32_16x16x32_bf16 v[60:63], v[128:131], v[192:195], v[60:63]
	v_mfma_f32_16x16x32_bf16 v[56:59], v[152:155], v[192:195], v[56:59]
	v_mfma_f32_16x16x32_bf16 v[44:47], v[128:131], v[200:203], v[44:47]
	v_mfma_f32_16x16x32_bf16 v[40:43], v[152:155], v[200:203], v[40:43]
	v_mfma_f32_16x16x32_bf16 v[28:31], v[128:131], v[208:211], v[28:31]
	v_mfma_f32_16x16x32_bf16 v[24:27], v[152:155], v[208:211], v[24:27]
	v_mfma_f32_16x16x32_bf16 v[12:15], v[128:131], v[216:219], v[12:15]
	v_mfma_f32_16x16x32_bf16 v[8:11], v[152:155], v[216:219], v[8:11]
	v_mfma_f32_16x16x32_bf16 v[60:63], v[132:135], v[196:199], v[60:63]
	v_mfma_f32_16x16x32_bf16 v[56:59], v[166:169], v[196:199], v[56:59]
	v_mfma_f32_16x16x32_bf16 v[44:47], v[132:135], v[204:207], v[44:47]
	v_mfma_f32_16x16x32_bf16 v[40:43], v[166:169], v[204:207], v[40:43]
	v_mfma_f32_16x16x32_bf16 v[28:31], v[132:135], v[212:215], v[28:31]
	v_mfma_f32_16x16x32_bf16 v[24:27], v[166:169], v[212:215], v[24:27]
	v_mfma_f32_16x16x32_bf16 v[12:15], v[132:135], v[220:223], v[12:15]
	v_mfma_f32_16x16x32_bf16 v[8:11], v[166:169], v[220:223], v[8:11]
	v_mfma_f32_16x16x32_bf16 v[52:55], v[170:173], v[192:195], v[52:55]
	v_mfma_f32_16x16x32_bf16 v[48:51], v[178:181], v[192:195], v[48:51]
	v_mfma_f32_16x16x32_bf16 v[36:39], v[170:173], v[200:203], v[36:39]
	v_mfma_f32_16x16x32_bf16 v[32:35], v[178:181], v[200:203], v[32:35]
	v_mfma_f32_16x16x32_bf16 v[20:23], v[170:173], v[208:211], v[20:23]
	v_mfma_f32_16x16x32_bf16 v[16:19], v[178:181], v[208:211], v[16:19]
	v_mfma_f32_16x16x32_bf16 v[4:7], v[170:173], v[216:219], v[4:7]
	v_mfma_f32_16x16x32_bf16 v[0:3], v[178:181], v[216:219], v[0:3]
	v_mfma_f32_16x16x32_bf16 v[52:55], v[174:177], v[196:199], v[52:55]
	v_mfma_f32_16x16x32_bf16 v[48:51], v[182:185], v[196:199], v[48:51]
	v_mfma_f32_16x16x32_bf16 v[36:39], v[174:177], v[204:207], v[36:39]
	v_mfma_f32_16x16x32_bf16 v[32:35], v[182:185], v[204:207], v[32:35]
	v_mfma_f32_16x16x32_bf16 v[20:23], v[174:177], v[212:215], v[20:23]
	v_mfma_f32_16x16x32_bf16 v[16:19], v[182:185], v[212:215], v[16:19]
	v_mfma_f32_16x16x32_bf16 v[4:7], v[174:177], v[220:223], v[4:7]
	v_mfma_f32_16x16x32_bf16 v[0:3], v[182:185], v[220:223], v[0:3]
	s_barrier
; #define PG8_STAGE(bufoff, gbase, voff) do { _Pragma("unroll") for (int _i = 0; _i < 2; ++_i) \
;         __builtin_amdgcn_global_load_lds((const unsigned*)((const char*)(gbase) + (voff)[_i]), (PG8_LAS unsigned*)(lds + (bufoff) + ldsw + _i * 8192), 16, 0, 0); } while (0)
; #define PG8_LDA(dst, b, h) do { _Pragma("unroll") for (int m = 0; m < 4; ++m) _Pragma("unroll") for (int k = 0; k < 2; ++k) dst[m][k] = *(const PG8_LAS bf16x8*)(lds + PG8_SA(b, h) + aoff + m * 2048 + k * 1024); } while (0)
; #define PG8_LDB(dst, b, h) do { _Pragma("unroll") for (int n = 0; n < 2; ++n) _Pragma("unroll") for (int k = 0; k < 2; ++k) dst[n][k] = *(const PG8_LAS bf16x8*)(lds + PG8_SB(b, h) + boff + n * 2048 + k * 1024); } while (0)
; #define PG8_MMA(ai, bj, At, Bt) do { __builtin_amdgcn_s_setprio(1); _Pragma("unroll") for (int m = 0; m < 4; ++m) _Pragma("unroll") for (int n = 0; n < 2; ++n) _Pragma("unroll") for (int k = 0; k < 2; ++k) \
;         acc[ai][bj][m][n] = __builtin_amdgcn_mfma_f32_16x16x32_bf16(Bt[n][k], At[m][k], acc[ai][bj][m][n], 0, 0, 0); __builtin_amdgcn_s_setprio(0); } while (0)
; #define PG8_WAIT_V(n) asm volatile("s_waitcnt vmcnt(" #n ")" ::: "memory")
; #define PG8_WAIT_L(n) asm volatile("s_waitcnt lgkmcnt(" #n ")" ::: "memory")
; #define PG8_BAR __builtin_amdgcn_s_barrier()
; #define PG8_SCHED __builtin_amdgcn_sched_barrier(0)
; template <class Epi, class Sched, bool ALIGN_EPI = false, bool SP2 = false>
; __device__ __forceinline__ void gemm_phase(PG8_LAS unsigned char* lds, const Gemm g, const Sched& S, const Epi& E) {
;     ...
;             PG8_LDB(B0, 1, 0); PG8_LDB(B1, 1, 1); PG8_SCHED; PG8_LDA(At, 1, 0); PG8_STAGE(PG8_SA(0, 1), a2 + hstep, voffA);
;             PG8_WAIT_V(8); PG8_WAIT_L(0); PG8_BAR; PG8_MMA(0, 0, At, B0); PG8_MMA(0, 1, At, B1); PG8_BAR; PG8_SCHED;
	s_setprio 0
	s_add_i32 s61, 0, 0x18000
	v_add_u32_e32 v165, s61, v159
	s_add_i32 s62, 0, 0x1c000
	ds_read_b128 v[128:131], v165
	ds_read_b128 v[132:135], v165 offset:1024
	ds_read_b128 v[152:155], v165 offset:2048
	ds_read_b128 v[166:169], v165 offset:3072
	v_add_u32_e32 v165, s62, v159
	ds_read_b128 v[170:173], v165
	ds_read_b128 v[174:177], v165 offset:1024
	ds_read_b128 v[178:181], v165 offset:2048
	ds_read_b128 v[182:185], v165 offset:3072
	s_add_u32 s8, s38, 0xb0000
	s_addc_u32 s9, s39, 0
	s_mov_b32 m0, s44
	v_lshl_add_u64 v[228:229], s[8:9], 0, v[136:137]
	ds_read_b128 v[192:195], v163 offset:32768
	ds_read_b128 v[196:199], v163 offset:33792
	ds_read_b128 v[200:203], v163 offset:34816
	ds_read_b128 v[204:207], v163 offset:35840
	ds_read_b128 v[208:211], v163 offset:36864
	ds_read_b128 v[212:215], v163 offset:37888
	ds_read_b128 v[216:219], v163 offset:38912
	ds_read_b128 v[220:223], v163 offset:39936
	global_load_lds_dwordx4 v[228:229], off
	v_lshl_add_u64 v[228:229], s[8:9], 0, v[140:141]
	s_mov_b32 m0, s45
	s_nop 0
	global_load_lds_dwordx4 v[228:229], off
	s_waitcnt vmcnt(8)
	s_waitcnt lgkmcnt(0)
	s_setprio 1
	s_barrier
	v_mfma_f32_16x16x32_bf16 v[124:127], v[128:131], v[192:195], v[124:127]
	v_mfma_f32_16x16x32_bf16 v[120:123], v[152:155], v[192:195], v[120:123]
	v_mfma_f32_16x16x32_bf16 v[108:111], v[128:131], v[200:203], v[108:111]
	v_mfma_f32_16x16x32_bf16 v[104:107], v[152:155], v[200:203], v[104:107]
	v_mfma_f32_16x16x32_bf16 v[92:95], v[128:131], v[208:211], v[92:95]
	v_mfma_f32_16x16x32_bf16 v[88:91], v[152:155], v[208:211], v[88:91]
	v_mfma_f32_16x16x32_bf16 v[76:79], v[128:131], v[216:219], v[76:79]
	v_mfma_f32_16x16x32_bf16 v[72:75], v[152:155], v[216:219], v[72:75]
	v_mfma_f32_16x16x32_bf16 v[124:127], v[132:135], v[196:199], v[124:127]
	v_mfma_f32_16x16x32_bf16 v[120:123], v[166:169], v[196:199], v[120:123]
	v_mfma_f32_16x16x32_bf16 v[108:111], v[132:135], v[204:207], v[108:111]
	v_mfma_f32_16x16x32_bf16 v[104:107], v[166:169], v[204:207], v[104:107]
	v_mfma_f32_16x16x32_bf16 v[92:95], v[132:135], v[212:215], v[92:95]
	v_mfma_f32_16x16x32_bf16 v[88:91], v[166:169], v[212:215], v[88:91]
	v_mfma_f32_16x16x32_bf16 v[76:79], v[132:135], v[220:223], v[76:79]
	v_mfma_f32_16x16x32_bf16 v[72:75], v[166:169], v[220:223], v[72:75]
	v_mfma_f32_16x16x32_bf16 v[116:119], v[170:173], v[192:195], v[116:119]
	v_mfma_f32_16x16x32_bf16 v[112:115], v[178:181], v[192:195], v[112:115]
	v_mfma_f32_16x16x32_bf16 v[100:103], v[170:173], v[200:203], v[100:103]
	v_mfma_f32_16x16x32_bf16 v[96:99], v[178:181], v[200:203], v[96:99]
	v_mfma_f32_16x16x32_bf16 v[84:87], v[170:173], v[208:211], v[84:87]
	v_mfma_f32_16x16x32_bf16 v[80:83], v[178:181], v[208:211], v[80:83]
	v_mfma_f32_16x16x32_bf16 v[68:71], v[170:173], v[216:219], v[68:71]
	v_mfma_f32_16x16x32_bf16 v[64:67], v[178:181], v[216:219], v[64:67]
	v_mfma_f32_16x16x32_bf16 v[116:119], v[174:177], v[196:199], v[116:119]
	v_mfma_f32_16x16x32_bf16 v[112:115], v[182:185], v[196:199], v[112:115]
	v_mfma_f32_16x16x32_bf16 v[100:103], v[174:177], v[204:207], v[100:103]
	v_mfma_f32_16x16x32_bf16 v[96:99], v[182:185], v[204:207], v[96:99]
	v_mfma_f32_16x16x32_bf16 v[84:87], v[174:177], v[212:215], v[84:87]
	v_mfma_f32_16x16x32_bf16 v[80:83], v[182:185], v[212:215], v[80:83]
	v_mfma_f32_16x16x32_bf16 v[68:71], v[174:177], v[220:223], v[68:71]
	v_mfma_f32_16x16x32_bf16 v[64:67], v[182:185], v[220:223], v[64:67]
	s_barrier
; #define PG8_STAGE(bufoff, gbase, voff) do { _Pragma("unroll") for (int _i = 0; _i < 2; ++_i) \
;         __builtin_amdgcn_global_load_lds((const unsigned*)((const char*)(gbase) + (voff)[_i]), (PG8_LAS unsigned*)(lds + (bufoff) + ldsw + _i * 8192), 16, 0, 0); } while (0)
; #define PG8_LDA(dst, b, h) do { _Pragma("unroll") for (int m = 0; m < 4; ++m) _Pragma("unroll") for (int k = 0; k < 2; ++k) dst[m][k] = *(const PG8_LAS bf16x8*)(lds + PG8_SA(b, h) + aoff + m * 2048 + k * 1024); } while (0)
; #define PG8_MMA(ai, bj, At, Bt) do { __builtin_amdgcn_s_setprio(1); _Pragma("unroll") for (int m = 0; m < 4; ++m) _Pragma("unroll") for (int n = 0; n < 2; ++n) _Pragma("unroll") for (int k = 0; k < 2; ++k) \
;         acc[ai][bj][m][n] = __builtin_amdgcn_mfma_f32_16x16x32_bf16(Bt[n][k], At[m][k], acc[ai][bj][m][n], 0, 0, 0); __builtin_amdgcn_s_setprio(0); } while (0)
; #define PG8_WAIT_V(n) asm volatile("s_waitcnt vmcnt(" #n ")" ::: "memory")
; #define PG8_WAIT_L(n) asm volatile("s_waitcnt lgkmcnt(" #n ")" ::: "memory")
; #define PG8_BAR __builtin_amdgcn_s_barrier()
; #define PG8_SCHED __builtin_amdgcn_sched_barrier(0)
; template <class Epi, class Sched, bool ALIGN_EPI = false, bool SP2 = false>
; __device__ __forceinline__ void gemm_phase(PG8_LAS unsigned char* lds, const Gemm g, const Sched& S, const Epi& E) {
;     ...
;             PG8_LDA(At, 1, 1); PG8_STAGE(PG8_SB(1, 0), b3, voffB); PG8_STAGE(PG8_SB(1, 1), b3 + hstep, voffB); PG8_STAGE(PG8_SA(1, 0), a3, voffA);
;             PG8_WAIT_V(8); PG8_WAIT_L(0); PG8_BAR; PG8_MMA(1, 0, At, B0); PG8_MMA(1, 1, At, B1); PG8_BAR; PG8_SCHED;
;     ...
;         if constexpr (ALIGN_EPI) { if (wr == 0) PG8_BAR; }
	s_setprio 0
	s_add_i32 s8, s61, s41
	v_lshl_add_u64 v[156:157], v[156:157], 0, s[14:15]
	s_mov_b32 m0, s8
	ds_read_b128 v[192:195], v163 offset:49152
	ds_read_b128 v[196:199], v163 offset:50176
	ds_read_b128 v[200:203], v163 offset:51200
	ds_read_b128 v[204:207], v163 offset:52224
	ds_read_b128 v[208:211], v163 offset:53248
	ds_read_b128 v[212:215], v163 offset:54272
	ds_read_b128 v[216:219], v163 offset:55296
	ds_read_b128 v[220:223], v163 offset:56320
	global_load_lds_dwordx4 v[156:157], off
	s_add_i32 m0, s8, 0x2000
	s_add_u32 s8, s36, 0xb0080
	v_lshl_add_u64 v[156:157], v[186:187], 0, s[14:15]
	s_addc_u32 s9, s37, 0
	s_add_i32 s36, s62, s41
	global_load_lds_dwordx4 v[156:157], off
	v_lshl_add_u64 v[156:157], s[8:9], 0, v[138:139]
	s_mov_b32 m0, s36
	s_nop 0
	global_load_lds_dwordx4 v[156:157], off
	v_lshl_add_u64 v[156:157], s[8:9], 0, v[142:143]
	s_add_i32 m0, s36, 0x2000
	s_nop 0
	global_load_lds_dwordx4 v[156:157], off
	v_lshl_add_u64 v[156:157], v[224:225], 0, s[14:15]
	s_mov_b32 m0, s47
	s_nop 0
	global_load_lds_dwordx4 v[156:157], off
	v_lshl_add_u64 v[156:157], v[226:227], 0, s[14:15]
	s_mov_b32 m0, s48
	s_nop 0
	global_load_lds_dwordx4 v[156:157], off
	s_waitcnt vmcnt(8)
	s_waitcnt lgkmcnt(0)
	s_setprio 1
	s_barrier
	v_mfma_f32_16x16x32_bf16 v[60:63], v[128:131], v[192:195], v[60:63]
	v_mfma_f32_16x16x32_bf16 v[56:59], v[152:155], v[192:195], v[56:59]
	v_mfma_f32_16x16x32_bf16 v[44:47], v[128:131], v[200:203], v[44:47]
	v_mfma_f32_16x16x32_bf16 v[40:43], v[152:155], v[200:203], v[40:43]
	v_mfma_f32_16x16x32_bf16 v[28:31], v[128:131], v[208:211], v[28:31]
	v_mfma_f32_16x16x32_bf16 v[24:27], v[152:155], v[208:211], v[24:27]
	v_mfma_f32_16x16x32_bf16 v[12:15], v[128:131], v[216:219], v[12:15]
	v_mfma_f32_16x16x32_bf16 v[8:11], v[152:155], v[216:219], v[8:11]
	v_mfma_f32_16x16x32_bf16 v[60:63], v[132:135], v[196:199], v[60:63]
	v_mfma_f32_16x16x32_bf16 v[56:59], v[166:169], v[196:199], v[56:59]
	v_mfma_f32_16x16x32_bf16 v[44:47], v[132:135], v[204:207], v[44:47]
	v_mfma_f32_16x16x32_bf16 v[40:43], v[166:169], v[204:207], v[40:43]
	v_mfma_f32_16x16x32_bf16 v[28:31], v[132:135], v[212:215], v[28:31]
	v_mfma_f32_16x16x32_bf16 v[24:27], v[166:169], v[212:215], v[24:27]
	v_mfma_f32_16x16x32_bf16 v[12:15], v[132:135], v[220:223], v[12:15]
	v_mfma_f32_16x16x32_bf16 v[8:11], v[166:169], v[220:223], v[8:11]
	v_mfma_f32_16x16x32_bf16 v[52:55], v[170:173], v[192:195], v[52:55]
	v_mfma_f32_16x16x32_bf16 v[48:51], v[178:181], v[192:195], v[48:51]
	v_mfma_f32_16x16x32_bf16 v[36:39], v[170:173], v[200:203], v[36:39]
	v_mfma_f32_16x16x32_bf16 v[32:35], v[178:181], v[200:203], v[32:35]
	v_mfma_f32_16x16x32_bf16 v[20:23], v[170:173], v[208:211], v[20:23]
	v_mfma_f32_16x16x32_bf16 v[16:19], v[178:181], v[208:211], v[16:19]
	v_mfma_f32_16x16x32_bf16 v[4:7], v[170:173], v[216:219], v[4:7]
	v_mfma_f32_16x16x32_bf16 v[0:3], v[178:181], v[216:219], v[0:3]
	v_mfma_f32_16x16x32_bf16 v[52:55], v[174:177], v[196:199], v[52:55]
	v_mfma_f32_16x16x32_bf16 v[48:51], v[182:185], v[196:199], v[48:51]
	v_mfma_f32_16x16x32_bf16 v[36:39], v[174:177], v[204:207], v[36:39]
	v_mfma_f32_16x16x32_bf16 v[32:35], v[182:185], v[204:207], v[32:35]
	v_mfma_f32_16x16x32_bf16 v[20:23], v[174:177], v[212:215], v[20:23]
	v_mfma_f32_16x16x32_bf16 v[16:19], v[182:185], v[212:215], v[16:19]
	v_mfma_f32_16x16x32_bf16 v[4:7], v[174:177], v[220:223], v[4:7]
	v_mfma_f32_16x16x32_bf16 v[0:3], v[182:185], v[220:223], v[0:3]
	s_barrier
	s_setprio 0
	s_add_i32 s60, s60, 2
	s_add_u32 s58, s58, 0x100
	s_addc_u32 s59, s59, 0
	s_cmp_gt_u32 s60, 41
	s_mov_b64 s[8:9], s[34:35]
	s_cbranch_scc0 .LBB0_274
	s_and_b64 vcc, exec, s[16:17]
	s_cbranch_vccz .LBB0_277
	s_barrier

; #define PG8_STAGE(bufoff, gbase, voff) do { _Pragma("unroll") for (int _i = 0; _i < 2; ++_i) \
;         __builtin_amdgcn_global_load_lds((const unsigned*)((const char*)(gbase) + (voff)[_i]), (PG8_LAS unsigned*)(lds + (bufoff) + ldsw + _i * 8192), 16, 0, 0); } while (0)
; #define PG8_LDA(dst, b, h) do { _Pragma("unroll") for (int m = 0; m < 4; ++m) _Pragma("unroll") for (int k = 0; k < 2; ++k) dst[m][k] = *(const PG8_LAS bf16x8*)(lds + PG8_SA(b, h) + aoff + m * 2048 + k * 1024); } while (0)
; #define PG8_LDB(dst, b, h) do { _Pragma("unroll") for (int n = 0; n < 2; ++n) _Pragma("unroll") for (int k = 0; k < 2; ++k) dst[n][k] = *(const PG8_LAS bf16x8*)(lds + PG8_SB(b, h) + boff + n * 2048 + k * 1024); } while (0)
; #define PG8_WAIT_V(n) asm volatile("s_waitcnt vmcnt(" #n ")" ::: "memory")
; #define PG8_WAIT_L(n) asm volatile("s_waitcnt lgkmcnt(" #n ")" ::: "memory")
; #define PG8_BAR __builtin_amdgcn_s_barrier()
; #define PG8_SCHED __builtin_amdgcn_sched_barrier(0)
; template <class Epi, class Sched, bool ALIGN_EPI = false, bool SP2 = false>
; __device__ __forceinline__ void gemm_phase(PG8_LAS unsigned char* lds, const Gemm g, const Sched& S, const Epi& E) {
;     ...
;         const bool has_next = S.next(ui + 1, nxt);
;         const char* nA = has_next ? (const char*)g.A + (size_t)nxt.pm * tstep : cA; const char* nB = has_next ? (const char*)g.Bt + (size_t)nxt.pn * tstep : cB;
;         for (int t = 0; t < nt; t += 2) {
;             const bool last = (t == nt - 2);
;             const char* a1 = cA + (size_t)(t + 1) * kstep;
;             const char* a2 = last ? nA : cA + (size_t)(t + 2) * kstep; const char* b2 = last ? nB : cB + (size_t)(t + 2) * kstep;
;             const char* a3 = a2 + kstep; const char* b3 = b2 + kstep;
;             if (last && has_next) S.a_ready(nxt);
;             if constexpr (SP2) {
;             PG8_LDB(B0, 0, 0); PG8_LDB(B1, 0, 1); PG8_SCHED; PG8_LDA(At, 0, 0); PG8_STAGE(PG8_SA(1, 1), a1 + hstep, voffA);
;             PG8_WAIT_V(8); PG8_WAIT_L(0); PG8_BAR; PG8_MMA(0, 0, At, B0); PG8_MMA(0, 1, At, B1); PG8_BAR; PG8_SCHED;
;             PG8_LDA(At, 0, 1); PG8_STAGE(PG8_SB(0, 0), b2, voffB); PG8_STAGE(PG8_SB(0, 1), b2 + hstep, voffB); PG8_STAGE(PG8_SA(0, 0), a2, voffA);
;             PG8_WAIT_V(8); PG8_WAIT_L(0); PG8_BAR; PG8_MMA(1, 0, At, B0); PG8_MMA(1, 1, At, B1); PG8_BAR; PG8_SCHED;
.LBB0_373:
	s_ashr_i32 s31, s30, 31
	s_lshl_b64 s[34:35], s[30:31], 19
	v_readlane_b32 s36, v235, 31
	v_readlane_b32 s37, v235, 32
	s_add_u32 s34, s36, s34
	s_addc_u32 s35, s37, s35
	s_and_b64 s[36:37], s[6:7], exec
	s_cselect_b32 s1, s35, s3
	s_cselect_b32 s25, s34, s2
	s_ashr_i32 s29, s28, 31
	s_lshl_b64 s[36:37], s[28:29], 19
	s_add_u32 s36, s10, s36
	s_addc_u32 s37, s11, s37
	s_and_b64 s[40:41], s[6:7], exec
	s_cselect_b32 s29, s37, s39
	s_cselect_b32 s31, s36, s38
	s_add_u32 s2, s2, 0x40080
	s_addc_u32 s3, s3, 0
	s_add_u32 s58, s38, 0x100
	s_addc_u32 s59, s39, 0
	s_mov_b32 s60, -2
	ds_read_b128 v[128:131], v171
	ds_read_b128 v[132:135], v171 offset:1024
	ds_read_b128 v[136:139], v171 offset:2048
	ds_read_b128 v[140:143], v171 offset:3072
	ds_read_b128 v[164:167], v172
	ds_read_b128 v[178:181], v172 offset:1024
	ds_read_b128 v[182:185], v172 offset:2048
	ds_read_b128 v[192:195], v172 offset:3072
	s_add_u32 s38, s2, 0xfffc0080
	s_addc_u32 s39, s3, -1
	s_cmp_eq_u32 s60, 12
	s_cselect_b32 s41, s1, s39
	s_cselect_b32 s40, s25, s38
	s_cselect_b32 s39, s29, s59
	s_cselect_b32 s38, s31, s58
	v_lshl_add_u64 v[168:169], s[2:3], 0, v[156:157]
	s_add_i32 m0, s44, 0xc000
	ds_read_b128 v[196:199], v173
	ds_read_b128 v[200:203], v173 offset:1024
	ds_read_b128 v[204:207], v173 offset:2048
	ds_read_b128 v[208:211], v173 offset:3072
	ds_read_b128 v[212:215], v173 offset:4096
	ds_read_b128 v[216:219], v173 offset:5120
	ds_read_b128 v[220:223], v173 offset:6144
	ds_read_b128 v[224:227], v173 offset:7168
	global_load_lds_dwordx4 v[168:169], off
	v_lshl_add_u64 v[168:169], s[2:3], 0, v[158:159]
	s_add_i32 m0, s44, 0xe000
	s_nop 0
	global_load_lds_dwordx4 v[168:169], off
	s_waitcnt vmcnt(8)
	s_waitcnt lgkmcnt(0)
	s_setprio 1
	s_barrier
	v_mfma_f32_16x16x32_bf16 v[124:127], v[128:131], v[196:199], 0
	v_mfma_f32_16x16x32_bf16 v[120:123], v[136:139], v[196:199], 0
	v_mfma_f32_16x16x32_bf16 v[108:111], v[128:131], v[204:207], 0
	v_mfma_f32_16x16x32_bf16 v[104:107], v[136:139], v[204:207], 0
	v_mfma_f32_16x16x32_bf16 v[92:95], v[128:131], v[212:215], 0
	v_mfma_f32_16x16x32_bf16 v[88:91], v[136:139], v[212:215], 0
	v_mfma_f32_16x16x32_bf16 v[76:79], v[128:131], v[220:223], 0
	v_mfma_f32_16x16x32_bf16 v[72:75], v[136:139], v[220:223], 0
	v_mfma_f32_16x16x32_bf16 v[124:127], v[132:135], v[200:203], v[124:127]
	v_mfma_f32_16x16x32_bf16 v[120:123], v[140:143], v[200:203], v[120:123]
	v_mfma_f32_16x16x32_bf16 v[108:111], v[132:135], v[208:211], v[108:111]
	v_mfma_f32_16x16x32_bf16 v[104:107], v[140:143], v[208:211], v[104:107]
	v_mfma_f32_16x16x32_bf16 v[92:95], v[132:135], v[216:219], v[92:95]
	v_mfma_f32_16x16x32_bf16 v[88:91], v[140:143], v[216:219], v[88:91]
	v_mfma_f32_16x16x32_bf16 v[76:79], v[132:135], v[224:227], v[76:79]
	v_mfma_f32_16x16x32_bf16 v[72:75], v[140:143], v[224:227], v[72:75]
	v_mfma_f32_16x16x32_bf16 v[116:119], v[164:167], v[196:199], 0
	v_mfma_f32_16x16x32_bf16 v[112:115], v[182:185], v[196:199], 0
	v_mfma_f32_16x16x32_bf16 v[100:103], v[164:167], v[204:207], 0
	v_mfma_f32_16x16x32_bf16 v[96:99], v[182:185], v[204:207], 0
	v_mfma_f32_16x16x32_bf16 v[84:87], v[164:167], v[212:215], 0
	v_mfma_f32_16x16x32_bf16 v[80:83], v[182:185], v[212:215], 0
	v_mfma_f32_16x16x32_bf16 v[68:71], v[164:167], v[220:223], 0
	v_mfma_f32_16x16x32_bf16 v[64:67], v[182:185], v[220:223], 0
	v_mfma_f32_16x16x32_bf16 v[116:119], v[178:181], v[200:203], v[116:119]
	v_mfma_f32_16x16x32_bf16 v[112:115], v[192:195], v[200:203], v[112:115]
	v_mfma_f32_16x16x32_bf16 v[100:103], v[178:181], v[208:211], v[100:103]
	v_mfma_f32_16x16x32_bf16 v[96:99], v[192:195], v[208:211], v[96:99]
	v_mfma_f32_16x16x32_bf16 v[84:87], v[178:181], v[216:219], v[84:87]
	v_mfma_f32_16x16x32_bf16 v[80:83], v[192:195], v[216:219], v[80:83]
	v_mfma_f32_16x16x32_bf16 v[68:71], v[178:181], v[224:227], v[68:71]
	v_mfma_f32_16x16x32_bf16 v[64:67], v[192:195], v[224:227], v[64:67]
	s_barrier
	s_setprio 0
	s_add_i32 s61, s52, s33
	v_lshl_add_u64 v[168:169], s[38:39], 0, v[148:149]
	s_mov_b32 m0, s61
	ds_read_b128 v[196:199], v173 offset:16384
	ds_read_b128 v[200:203], v173 offset:17408
	ds_read_b128 v[204:207], v173 offset:18432
	ds_read_b128 v[208:211], v173 offset:19456
	ds_read_b128 v[212:215], v173 offset:20480
	ds_read_b128 v[216:219], v173 offset:21504
	ds_read_b128 v[220:223], v173 offset:22528
	ds_read_b128 v[224:227], v173 offset:23552
	global_load_lds_dwordx4 v[168:169], off
	s_add_i32 m0, s61, 0x2000
	s_add_u32 s62, s38, 0x40000
	v_lshl_add_u64 v[186:187], s[38:39], 0, v[144:145]
	s_addc_u32 s63, s39, 0
	s_add_i32 s61, s53, s33
	global_load_lds_dwordx4 v[186:187], off
	v_lshl_add_u64 v[228:229], s[62:63], 0, v[148:149]
	s_mov_b32 m0, s61
	v_lshl_add_u64 v[230:231], s[40:41], 0, v[146:147]
	global_load_lds_dwordx4 v[228:229], off
	v_lshl_add_u64 v[228:229], s[62:63], 0, v[144:145]
	s_add_i32 m0, s61, 0x2000
	s_nop 0
	global_load_lds_dwordx4 v[228:229], off
	v_lshl_add_u64 v[228:229], s[40:41], 0, v[150:151]
	s_mov_b32 m0, s44
	s_nop 0
	global_load_lds_dwordx4 v[228:229], off
	s_mov_b32 m0, s45
	s_nop 0
	global_load_lds_dwordx4 v[230:231], off
	s_waitcnt vmcnt(8)
	s_waitcnt lgkmcnt(0)
	s_setprio 1
	s_barrier
; #define PG8_STAGE(bufoff, gbase, voff) do { _Pragma("unroll") for (int _i = 0; _i < 2; ++_i) \
;         __builtin_amdgcn_global_load_lds((const unsigned*)((const char*)(gbase) + (voff)[_i]), (PG8_LAS unsigned*)(lds + (bufoff) + ldsw + _i * 8192), 16, 0, 0); } while (0)
; #define PG8_LDA(dst, b, h) do { _Pragma("unroll") for (int m = 0; m < 4; ++m) _Pragma("unroll") for (int k = 0; k < 2; ++k) dst[m][k] = *(const PG8_LAS bf16x8*)(lds + PG8_SA(b, h) + aoff + m * 2048 + k * 1024); } while (0)
; #define PG8_LDB(dst, b, h) do { _Pragma("unroll") for (int n = 0; n < 2; ++n) _Pragma("unroll") for (int k = 0; k < 2; ++k) dst[n][k] = *(const PG8_LAS bf16x8*)(lds + PG8_SB(b, h) + boff + n * 2048 + k * 1024); } while (0)
; #define PG8_MMA(ai, bj, At, Bt) do { __builtin_amdgcn_s_setprio(1); _Pragma("unroll") for (int m = 0; m < 4; ++m) _Pragma("unroll") for (int n = 0; n < 2; ++n) _Pragma("unroll") for (int k = 0; k < 2; ++k) \
;         acc[ai][bj][m][n] = __builtin_amdgcn_mfma_f32_16x16x32_bf16(Bt[n][k], At[m][k], acc[ai][bj][m][n], 0, 0, 0); __builtin_amdgcn_s_setprio(0); } while (0)
; #define PG8_WAIT_V(n) asm volatile("s_waitcnt vmcnt(" #n ")" ::: "memory")
; #define PG8_WAIT_L(n) asm volatile("s_waitcnt lgkmcnt(" #n ")" ::: "memory")
; #define PG8_BAR __builtin_amdgcn_s_barrier()
; #define PG8_SCHED __builtin_amdgcn_sched_barrier(0)
; template <class Epi, class Sched, bool ALIGN_EPI = false, bool SP2 = false>
; __device__ __forceinline__ void gemm_phase(PG8_LAS unsigned char* lds, const Gemm g, const Sched& S, const Epi& E) {
;     ...
;             PG8_WAIT_V(8); PG8_WAIT_L(0); PG8_BAR; PG8_MMA(1, 0, At, B0); PG8_MMA(1, 1, At, B1); PG8_BAR; PG8_SCHED;
;             PG8_LDB(B0, 1, 0); PG8_LDB(B1, 1, 1); PG8_SCHED; PG8_LDA(At, 1, 0); PG8_STAGE(PG8_SA(0, 1), a2 + hstep, voffA);
;             PG8_WAIT_V(8); PG8_WAIT_L(0); PG8_BAR; PG8_MMA(0, 0, At, B0); PG8_MMA(0, 1, At, B1); PG8_BAR; PG8_SCHED;
	v_mfma_f32_16x16x32_bf16 v[60:63], v[128:131], v[196:199], 0
	v_mfma_f32_16x16x32_bf16 v[56:59], v[136:139], v[196:199], 0
	v_mfma_f32_16x16x32_bf16 v[44:47], v[128:131], v[204:207], 0
	v_mfma_f32_16x16x32_bf16 v[40:43], v[136:139], v[204:207], 0
	v_mfma_f32_16x16x32_bf16 v[28:31], v[128:131], v[212:215], 0
	v_mfma_f32_16x16x32_bf16 v[24:27], v[136:139], v[212:215], 0
	v_mfma_f32_16x16x32_bf16 v[12:15], v[128:131], v[220:223], 0
	v_mfma_f32_16x16x32_bf16 v[8:11], v[136:139], v[220:223], 0
	v_mfma_f32_16x16x32_bf16 v[60:63], v[132:135], v[200:203], v[60:63]
	v_mfma_f32_16x16x32_bf16 v[56:59], v[140:143], v[200:203], v[56:59]
	v_mfma_f32_16x16x32_bf16 v[44:47], v[132:135], v[208:211], v[44:47]
	v_mfma_f32_16x16x32_bf16 v[40:43], v[140:143], v[208:211], v[40:43]
	v_mfma_f32_16x16x32_bf16 v[28:31], v[132:135], v[216:219], v[28:31]
	v_mfma_f32_16x16x32_bf16 v[24:27], v[140:143], v[216:219], v[24:27]
	v_mfma_f32_16x16x32_bf16 v[12:15], v[132:135], v[224:227], v[12:15]
	v_mfma_f32_16x16x32_bf16 v[8:11], v[140:143], v[224:227], v[8:11]
	v_mfma_f32_16x16x32_bf16 v[52:55], v[164:167], v[196:199], 0
	v_mfma_f32_16x16x32_bf16 v[48:51], v[182:185], v[196:199], 0
	v_mfma_f32_16x16x32_bf16 v[36:39], v[164:167], v[204:207], 0
	v_mfma_f32_16x16x32_bf16 v[32:35], v[182:185], v[204:207], 0
	v_mfma_f32_16x16x32_bf16 v[20:23], v[164:167], v[212:215], 0
	v_mfma_f32_16x16x32_bf16 v[16:19], v[182:185], v[212:215], 0
	v_mfma_f32_16x16x32_bf16 v[4:7], v[164:167], v[220:223], 0
	v_mfma_f32_16x16x32_bf16 v[0:3], v[182:185], v[220:223], 0
	v_mfma_f32_16x16x32_bf16 v[52:55], v[178:181], v[200:203], v[52:55]
	v_mfma_f32_16x16x32_bf16 v[48:51], v[192:195], v[200:203], v[48:51]
	v_mfma_f32_16x16x32_bf16 v[36:39], v[178:181], v[208:211], v[36:39]
	v_mfma_f32_16x16x32_bf16 v[32:35], v[192:195], v[208:211], v[32:35]
	v_mfma_f32_16x16x32_bf16 v[20:23], v[178:181], v[216:219], v[20:23]
	v_mfma_f32_16x16x32_bf16 v[16:19], v[192:195], v[216:219], v[16:19]
	v_mfma_f32_16x16x32_bf16 v[4:7], v[178:181], v[224:227], v[4:7]
	v_mfma_f32_16x16x32_bf16 v[0:3], v[192:195], v[224:227], v[0:3]
	s_barrier
	s_setprio 0
	s_add_i32 s61, 0, 0x18000
	s_add_i32 s62, 0, 0x1c000
	v_add_u32_e32 v140, s61, v170
	v_add_u32_e32 v152, s62, v170
	ds_read_b128 v[128:131], v140
	ds_read_b128 v[132:135], v140 offset:1024
	ds_read_b128 v[136:139], v140 offset:2048
	ds_read_b128 v[140:143], v140 offset:3072
	ds_read_b128 v[164:167], v152
	ds_read_b128 v[178:181], v152 offset:1024
	ds_read_b128 v[182:185], v152 offset:2048
	ds_read_b128 v[192:195], v152 offset:3072
	s_add_u32 s40, s40, 0x40000
	s_addc_u32 s41, s41, 0
	s_mov_b32 m0, s46
	v_lshl_add_u64 v[232:233], s[40:41], 0, v[150:151]
	ds_read_b128 v[196:199], v173 offset:32768
	ds_read_b128 v[200:203], v173 offset:33792
	ds_read_b128 v[204:207], v173 offset:34816
	ds_read_b128 v[208:211], v173 offset:35840
	ds_read_b128 v[212:215], v173 offset:36864
	ds_read_b128 v[216:219], v173 offset:37888
	ds_read_b128 v[220:223], v173 offset:38912
	ds_read_b128 v[224:227], v173 offset:39936
	global_load_lds_dwordx4 v[232:233], off
	v_lshl_add_u64 v[232:233], s[40:41], 0, v[146:147]
	s_mov_b32 m0, s47
	s_nop 0
	global_load_lds_dwordx4 v[232:233], off
	s_waitcnt vmcnt(8)
	s_waitcnt lgkmcnt(0)
	s_setprio 1
	s_barrier
	v_mfma_f32_16x16x32_bf16 v[124:127], v[128:131], v[196:199], v[124:127]
	v_mfma_f32_16x16x32_bf16 v[120:123], v[136:139], v[196:199], v[120:123]
	v_mfma_f32_16x16x32_bf16 v[108:111], v[128:131], v[204:207], v[108:111]
	v_mfma_f32_16x16x32_bf16 v[104:107], v[136:139], v[204:207], v[104:107]
	v_mfma_f32_16x16x32_bf16 v[92:95], v[128:131], v[212:215], v[92:95]
	v_mfma_f32_16x16x32_bf16 v[88:91], v[136:139], v[212:215], v[88:91]
	v_mfma_f32_16x16x32_bf16 v[76:79], v[128:131], v[220:223], v[76:79]
	v_mfma_f32_16x16x32_bf16 v[72:75], v[136:139], v[220:223], v[72:75]
	v_mfma_f32_16x16x32_bf16 v[124:127], v[132:135], v[200:203], v[124:127]
	v_mfma_f32_16x16x32_bf16 v[120:123], v[140:143], v[200:203], v[120:123]
	v_mfma_f32_16x16x32_bf16 v[108:111], v[132:135], v[208:211], v[108:111]
	v_mfma_f32_16x16x32_bf16 v[104:107], v[140:143], v[208:211], v[104:107]
	v_mfma_f32_16x16x32_bf16 v[92:95], v[132:135], v[216:219], v[92:95]
	v_mfma_f32_16x16x32_bf16 v[88:91], v[140:143], v[216:219], v[88:91]
	v_mfma_f32_16x16x32_bf16 v[76:79], v[132:135], v[224:227], v[76:79]
	v_mfma_f32_16x16x32_bf16 v[72:75], v[140:143], v[224:227], v[72:75]
	v_mfma_f32_16x16x32_bf16 v[116:119], v[164:167], v[196:199], v[116:119]
	v_mfma_f32_16x16x32_bf16 v[112:115], v[182:185], v[196:199], v[112:115]
	v_mfma_f32_16x16x32_bf16 v[100:103], v[164:167], v[204:207], v[100:103]
	v_mfma_f32_16x16x32_bf16 v[96:99], v[182:185], v[204:207], v[96:99]
	v_mfma_f32_16x16x32_bf16 v[84:87], v[164:167], v[212:215], v[84:87]
	v_mfma_f32_16x16x32_bf16 v[80:83], v[182:185], v[212:215], v[80:83]
	v_mfma_f32_16x16x32_bf16 v[68:71], v[164:167], v[220:223], v[68:71]
	v_mfma_f32_16x16x32_bf16 v[64:67], v[182:185], v[220:223], v[64:67]
	v_mfma_f32_16x16x32_bf16 v[116:119], v[178:181], v[200:203], v[116:119]
	v_mfma_f32_16x16x32_bf16 v[112:115], v[192:195], v[200:203], v[112:115]
	v_mfma_f32_16x16x32_bf16 v[100:103], v[178:181], v[208:211], v[100:103]
	v_mfma_f32_16x16x32_bf16 v[96:99], v[192:195], v[208:211], v[96:99]
	v_mfma_f32_16x16x32_bf16 v[84:87], v[178:181], v[216:219], v[84:87]
	v_mfma_f32_16x16x32_bf16 v[80:83], v[192:195], v[216:219], v[80:83]
	v_mfma_f32_16x16x32_bf16 v[68:71], v[178:181], v[224:227], v[68:71]
	v_mfma_f32_16x16x32_bf16 v[64:67], v[192:195], v[224:227], v[64:67]
	s_barrier
; #define PG8_STAGE(bufoff, gbase, voff) do { _Pragma("unroll") for (int _i = 0; _i < 2; ++_i) \
;         __builtin_amdgcn_global_load_lds((const unsigned*)((const char*)(gbase) + (voff)[_i]), (PG8_LAS unsigned*)(lds + (bufoff) + ldsw + _i * 8192), 16, 0, 0); } while (0)
; #define PG8_LDA(dst, b, h) do { _Pragma("unroll") for (int m = 0; m < 4; ++m) _Pragma("unroll") for (int k = 0; k < 2; ++k) dst[m][k] = *(const PG8_LAS bf16x8*)(lds + PG8_SA(b, h) + aoff + m * 2048 + k * 1024); } while (0)
; #define PG8_LDB(dst, b, h) do { _Pragma("unroll") for (int n = 0; n < 2; ++n) _Pragma("unroll") for (int k = 0; k < 2; ++k) dst[n][k] = *(const PG8_LAS bf16x8*)(lds + PG8_SB(b, h) + boff + n * 2048 + k * 1024); } while (0)
; #define PG8_BAR __builtin_amdgcn_s_barrier()
; template <class Epi, class Sched, bool ALIGN_EPI = false, bool SP2 = false>
; __device__ __forceinline__ void gemm_phase(PG8_LAS unsigned char* lds, const Gemm g, const Sched& S, const Epi& E) {
;     ...
;             const bool last = (t == nt - 2);
;             const char* a1 = cA + (size_t)(t + 1) * kstep;
;             const char* a2 = last ? nA : cA + (size_t)(t + 2) * kstep; const char* b2 = last ? nB : cB + (size_t)(t + 2) * kstep;
;             const char* a3 = a2 + kstep; const char* b3 = b2 + kstep;
;             if (last && has_next) S.a_ready(nxt);
;             if constexpr (SP2) {
;             PG8_LDB(B0, 0, 0); PG8_LDB(B1, 0, 1); PG8_SCHED; PG8_LDA(At, 0, 0); PG8_STAGE(PG8_SA(1, 1), a1 + hstep, voffA);
;             PG8_WAIT_V(8); PG8_WAIT_L(0); PG8_BAR; PG8_MMA(0, 0, At, B0); PG8_MMA(0, 1, At, B1); PG8_BAR; PG8_SCHED;
;             PG8_LDA(At, 0, 1); PG8_STAGE(PG8_SB(0, 0), b2, voffB); PG8_STAGE(PG8_SB(0, 1), b2 + hstep, voffB); PG8_STAGE(PG8_SA(0, 0), a2, voffA);
;             PG8_WAIT_V(8); PG8_WAIT_L(0); PG8_BAR; PG8_MMA(1, 0, At, B0); PG8_MMA(1, 1, At, B1); PG8_BAR; PG8_SCHED;
;             PG8_LDB(B0, 1, 0); PG8_LDB(B1, 1, 1); PG8_SCHED; PG8_LDA(At, 1, 0); PG8_STAGE(PG8_SA(0, 1), a2 + hstep, voffA);
;             PG8_WAIT_V(8); PG8_WAIT_L(0); PG8_BAR; PG8_MMA(0, 0, At, B0); PG8_MMA(0, 1, At, B1); PG8_BAR; PG8_SCHED;
;             PG8_LDA(At, 1, 1); PG8_STAGE(PG8_SB(1, 0), b3, voffB); PG8_STAGE(PG8_SB(1, 1), b3 + hstep, voffB); PG8_STAGE(PG8_SA(1, 0), a3, voffA);
;             PG8_WAIT_V(8); PG8_WAIT_L(0); PG8_BAR; PG8_MMA(1, 0, At, B0); PG8_MMA(1, 1, At, B1); PG8_BAR; PG8_SCHED;
	s_setprio 0
	s_add_i32 s40, s61, s33
	v_lshl_add_u64 v[168:169], v[168:169], 0, s[16:17]
	s_mov_b32 m0, s40
	ds_read_b128 v[196:199], v173 offset:49152
	ds_read_b128 v[200:203], v173 offset:50176
	ds_read_b128 v[204:207], v173 offset:51200
	ds_read_b128 v[208:211], v173 offset:52224
	ds_read_b128 v[212:215], v173 offset:53248
	ds_read_b128 v[216:219], v173 offset:54272
	ds_read_b128 v[220:223], v173 offset:55296
	ds_read_b128 v[224:227], v173 offset:56320
	global_load_lds_dwordx4 v[168:169], off
	s_add_i32 m0, s40, 0x2000
	s_add_u32 s38, s38, 0x40080
	v_lshl_add_u64 v[168:169], v[186:187], 0, s[16:17]
	s_addc_u32 s39, s39, 0
	s_add_i32 s40, s62, s33
	global_load_lds_dwordx4 v[168:169], off
	v_lshl_add_u64 v[168:169], s[38:39], 0, v[148:149]
	s_mov_b32 m0, s40
	s_nop 0
	global_load_lds_dwordx4 v[168:169], off
	v_lshl_add_u64 v[168:169], s[38:39], 0, v[144:145]
	s_add_i32 m0, s40, 0x2000
	s_nop 0
	global_load_lds_dwordx4 v[168:169], off
	v_lshl_add_u64 v[168:169], v[228:229], 0, s[16:17]
	s_mov_b32 m0, s48
	s_nop 0
	global_load_lds_dwordx4 v[168:169], off
	v_lshl_add_u64 v[168:169], v[230:231], 0, s[16:17]
	s_mov_b32 m0, s49
	s_nop 0
	global_load_lds_dwordx4 v[168:169], off
	s_waitcnt vmcnt(8)
	s_waitcnt lgkmcnt(0)
	s_setprio 1
	s_barrier
	v_mfma_f32_16x16x32_bf16 v[60:63], v[128:131], v[196:199], v[60:63]
	v_mfma_f32_16x16x32_bf16 v[56:59], v[136:139], v[196:199], v[56:59]
	v_mfma_f32_16x16x32_bf16 v[44:47], v[128:131], v[204:207], v[44:47]
	v_mfma_f32_16x16x32_bf16 v[40:43], v[136:139], v[204:207], v[40:43]
	v_mfma_f32_16x16x32_bf16 v[28:31], v[128:131], v[212:215], v[28:31]
	v_mfma_f32_16x16x32_bf16 v[24:27], v[136:139], v[212:215], v[24:27]
	v_mfma_f32_16x16x32_bf16 v[12:15], v[128:131], v[220:223], v[12:15]
	v_mfma_f32_16x16x32_bf16 v[8:11], v[136:139], v[220:223], v[8:11]
	v_mfma_f32_16x16x32_bf16 v[60:63], v[132:135], v[200:203], v[60:63]
	v_mfma_f32_16x16x32_bf16 v[56:59], v[140:143], v[200:203], v[56:59]
	v_mfma_f32_16x16x32_bf16 v[44:47], v[132:135], v[208:211], v[44:47]
	v_mfma_f32_16x16x32_bf16 v[40:43], v[140:143], v[208:211], v[40:43]
	v_mfma_f32_16x16x32_bf16 v[28:31], v[132:135], v[216:219], v[28:31]
	v_mfma_f32_16x16x32_bf16 v[24:27], v[140:143], v[216:219], v[24:27]
	v_mfma_f32_16x16x32_bf16 v[12:15], v[132:135], v[224:227], v[12:15]
	v_mfma_f32_16x16x32_bf16 v[8:11], v[140:143], v[224:227], v[8:11]
	v_mfma_f32_16x16x32_bf16 v[52:55], v[164:167], v[196:199], v[52:55]
	v_mfma_f32_16x16x32_bf16 v[48:51], v[182:185], v[196:199], v[48:51]
	v_mfma_f32_16x16x32_bf16 v[36:39], v[164:167], v[204:207], v[36:39]
	v_mfma_f32_16x16x32_bf16 v[32:35], v[182:185], v[204:207], v[32:35]
	v_mfma_f32_16x16x32_bf16 v[20:23], v[164:167], v[212:215], v[20:23]
	v_mfma_f32_16x16x32_bf16 v[16:19], v[182:185], v[212:215], v[16:19]
	v_mfma_f32_16x16x32_bf16 v[4:7], v[164:167], v[220:223], v[4:7]
	v_mfma_f32_16x16x32_bf16 v[0:3], v[182:185], v[220:223], v[0:3]
	v_mfma_f32_16x16x32_bf16 v[52:55], v[178:181], v[200:203], v[52:55]
	v_mfma_f32_16x16x32_bf16 v[48:51], v[192:195], v[200:203], v[48:51]
	v_mfma_f32_16x16x32_bf16 v[36:39], v[178:181], v[208:211], v[36:39]
	v_mfma_f32_16x16x32_bf16 v[32:35], v[192:195], v[208:211], v[32:35]
	v_mfma_f32_16x16x32_bf16 v[20:23], v[178:181], v[216:219], v[20:23]
	v_mfma_f32_16x16x32_bf16 v[16:19], v[192:195], v[216:219], v[16:19]
	v_mfma_f32_16x16x32_bf16 v[4:7], v[178:181], v[224:227], v[4:7]
	v_mfma_f32_16x16x32_bf16 v[0:3], v[192:195], v[224:227], v[0:3]
	s_barrier
	s_setprio 0
	s_add_i32 s60, s60, 2
	s_add_u32 s2, s2, 0x100
	s_addc_u32 s3, s3, 0
	s_add_u32 s58, s58, 0x100
	s_addc_u32 s59, s59, 0
.LBB0_374:
	ds_read_b128 v[128:131], v171
	ds_read_b128 v[132:135], v171 offset:1024
	ds_read_b128 v[136:139], v171 offset:2048
	ds_read_b128 v[140:143], v171 offset:3072
	ds_read_b128 v[164:167], v172
	ds_read_b128 v[178:181], v172 offset:1024
	ds_read_b128 v[182:185], v172 offset:2048
	ds_read_b128 v[192:195], v172 offset:3072
	s_add_u32 s38, s2, 0xfffc0080
	s_addc_u32 s39, s3, -1
	s_cmp_eq_u32 s60, 12
	s_cselect_b32 s41, s1, s39
	s_cselect_b32 s40, s25, s38
	s_cselect_b32 s39, s29, s59
	s_cselect_b32 s38, s31, s58
	v_lshl_add_u64 v[168:169], s[2:3], 0, v[156:157]
	s_add_i32 m0, s44, 0xc000
	ds_read_b128 v[196:199], v173
	ds_read_b128 v[200:203], v173 offset:1024
	ds_read_b128 v[204:207], v173 offset:2048
	ds_read_b128 v[208:211], v173 offset:3072
	ds_read_b128 v[212:215], v173 offset:4096
	ds_read_b128 v[216:219], v173 offset:5120
	ds_read_b128 v[220:223], v173 offset:6144
	ds_read_b128 v[224:227], v173 offset:7168
	global_load_lds_dwordx4 v[168:169], off
	v_lshl_add_u64 v[168:169], s[2:3], 0, v[158:159]
	s_add_i32 m0, s44, 0xe000
	s_nop 0
	global_load_lds_dwordx4 v[168:169], off
	s_waitcnt vmcnt(8)
	s_waitcnt lgkmcnt(0)
	s_setprio 1
	s_barrier
; #define PG8_STAGE(bufoff, gbase, voff) do { _Pragma("unroll") for (int _i = 0; _i < 2; ++_i) \
;         __builtin_amdgcn_global_load_lds((const unsigned*)((const char*)(gbase) + (voff)[_i]), (PG8_LAS unsigned*)(lds + (bufoff) + ldsw + _i * 8192), 16, 0, 0); } while (0)
; #define PG8_LDA(dst, b, h) do { _Pragma("unroll") for (int m = 0; m < 4; ++m) _Pragma("unroll") for (int k = 0; k < 2; ++k) dst[m][k] = *(const PG8_LAS bf16x8*)(lds + PG8_SA(b, h) + aoff + m * 2048 + k * 1024); } while (0)
; #define PG8_MMA(ai, bj, At, Bt) do { __builtin_amdgcn_s_setprio(1); _Pragma("unroll") for (int m = 0; m < 4; ++m) _Pragma("unroll") for (int n = 0; n < 2; ++n) _Pragma("unroll") for (int k = 0; k < 2; ++k) \
;         acc[ai][bj][m][n] = __builtin_amdgcn_mfma_f32_16x16x32_bf16(Bt[n][k], At[m][k], acc[ai][bj][m][n], 0, 0, 0); __builtin_amdgcn_s_setprio(0); } while (0)
; #define PG8_WAIT_V(n) asm volatile("s_waitcnt vmcnt(" #n ")" ::: "memory")
; #define PG8_WAIT_L(n) asm volatile("s_waitcnt lgkmcnt(" #n ")" ::: "memory")
; #define PG8_BAR __builtin_amdgcn_s_barrier()
; #define PG8_SCHED __builtin_amdgcn_sched_barrier(0)
; template <class Epi, class Sched, bool ALIGN_EPI = false, bool SP2 = false>
; __device__ __forceinline__ void gemm_phase(PG8_LAS unsigned char* lds, const Gemm g, const Sched& S, const Epi& E) {
;     ...
;             PG8_WAIT_V(8); PG8_WAIT_L(0); PG8_BAR; PG8_MMA(0, 0, At, B0); PG8_MMA(0, 1, At, B1); PG8_BAR; PG8_SCHED;
;             PG8_LDA(At, 0, 1); PG8_STAGE(PG8_SB(0, 0), b2, voffB); PG8_STAGE(PG8_SB(0, 1), b2 + hstep, voffB); PG8_STAGE(PG8_SA(0, 0), a2, voffA);
;             PG8_WAIT_V(8); PG8_WAIT_L(0); PG8_BAR; PG8_MMA(1, 0, At, B0); PG8_MMA(1, 1, At, B1); PG8_BAR; PG8_SCHED;
	v_mfma_f32_16x16x32_bf16 v[124:127], v[128:131], v[196:199], v[124:127]
	v_mfma_f32_16x16x32_bf16 v[120:123], v[136:139], v[196:199], v[120:123]
	v_mfma_f32_16x16x32_bf16 v[108:111], v[128:131], v[204:207], v[108:111]
	v_mfma_f32_16x16x32_bf16 v[104:107], v[136:139], v[204:207], v[104:107]
	v_mfma_f32_16x16x32_bf16 v[92:95], v[128:131], v[212:215], v[92:95]
	v_mfma_f32_16x16x32_bf16 v[88:91], v[136:139], v[212:215], v[88:91]
	v_mfma_f32_16x16x32_bf16 v[76:79], v[128:131], v[220:223], v[76:79]
	v_mfma_f32_16x16x32_bf16 v[72:75], v[136:139], v[220:223], v[72:75]
	v_mfma_f32_16x16x32_bf16 v[124:127], v[132:135], v[200:203], v[124:127]
	v_mfma_f32_16x16x32_bf16 v[120:123], v[140:143], v[200:203], v[120:123]
	v_mfma_f32_16x16x32_bf16 v[108:111], v[132:135], v[208:211], v[108:111]
	v_mfma_f32_16x16x32_bf16 v[104:107], v[140:143], v[208:211], v[104:107]
	v_mfma_f32_16x16x32_bf16 v[92:95], v[132:135], v[216:219], v[92:95]
	v_mfma_f32_16x16x32_bf16 v[88:91], v[140:143], v[216:219], v[88:91]
	v_mfma_f32_16x16x32_bf16 v[76:79], v[132:135], v[224:227], v[76:79]
	v_mfma_f32_16x16x32_bf16 v[72:75], v[140:143], v[224:227], v[72:75]
	v_mfma_f32_16x16x32_bf16 v[116:119], v[164:167], v[196:199], v[116:119]
	v_mfma_f32_16x16x32_bf16 v[112:115], v[182:185], v[196:199], v[112:115]
	v_mfma_f32_16x16x32_bf16 v[100:103], v[164:167], v[204:207], v[100:103]
	v_mfma_f32_16x16x32_bf16 v[96:99], v[182:185], v[204:207], v[96:99]
	v_mfma_f32_16x16x32_bf16 v[84:87], v[164:167], v[212:215], v[84:87]
	v_mfma_f32_16x16x32_bf16 v[80:83], v[182:185], v[212:215], v[80:83]
	v_mfma_f32_16x16x32_bf16 v[68:71], v[164:167], v[220:223], v[68:71]
	v_mfma_f32_16x16x32_bf16 v[64:67], v[182:185], v[220:223], v[64:67]
	v_mfma_f32_16x16x32_bf16 v[116:119], v[178:181], v[200:203], v[116:119]
	v_mfma_f32_16x16x32_bf16 v[112:115], v[192:195], v[200:203], v[112:115]
	v_mfma_f32_16x16x32_bf16 v[100:103], v[178:181], v[208:211], v[100:103]
	v_mfma_f32_16x16x32_bf16 v[96:99], v[192:195], v[208:211], v[96:99]
	v_mfma_f32_16x16x32_bf16 v[84:87], v[178:181], v[216:219], v[84:87]
	v_mfma_f32_16x16x32_bf16 v[80:83], v[192:195], v[216:219], v[80:83]
	v_mfma_f32_16x16x32_bf16 v[68:71], v[178:181], v[224:227], v[68:71]
	v_mfma_f32_16x16x32_bf16 v[64:67], v[192:195], v[224:227], v[64:67]
	s_barrier
	s_setprio 0
	s_add_i32 s61, s52, s33
	v_lshl_add_u64 v[168:169], s[38:39], 0, v[148:149]
	s_mov_b32 m0, s61
	ds_read_b128 v[196:199], v173 offset:16384
	ds_read_b128 v[200:203], v173 offset:17408
	ds_read_b128 v[204:207], v173 offset:18432
	ds_read_b128 v[208:211], v173 offset:19456
	ds_read_b128 v[212:215], v173 offset:20480
	ds_read_b128 v[216:219], v173 offset:21504
	ds_read_b128 v[220:223], v173 offset:22528
	ds_read_b128 v[224:227], v173 offset:23552
	global_load_lds_dwordx4 v[168:169], off
	s_add_i32 m0, s61, 0x2000
	s_add_u32 s62, s38, 0x40000
	v_lshl_add_u64 v[186:187], s[38:39], 0, v[144:145]
	s_addc_u32 s63, s39, 0
	s_add_i32 s61, s53, s33
	global_load_lds_dwordx4 v[186:187], off
	v_lshl_add_u64 v[228:229], s[62:63], 0, v[148:149]
	s_mov_b32 m0, s61
	v_lshl_add_u64 v[230:231], s[40:41], 0, v[146:147]
	global_load_lds_dwordx4 v[228:229], off
	v_lshl_add_u64 v[228:229], s[62:63], 0, v[144:145]
	s_add_i32 m0, s61, 0x2000
	s_nop 0
	global_load_lds_dwordx4 v[228:229], off
	v_lshl_add_u64 v[228:229], s[40:41], 0, v[150:151]
	s_mov_b32 m0, s44
	s_nop 0
	global_load_lds_dwordx4 v[228:229], off
	s_mov_b32 m0, s45
	s_nop 0
	global_load_lds_dwordx4 v[230:231], off
	s_waitcnt vmcnt(8)
	s_waitcnt lgkmcnt(0)
	s_setprio 1
	s_barrier
	v_mfma_f32_16x16x32_bf16 v[60:63], v[128:131], v[196:199], v[60:63]
	v_mfma_f32_16x16x32_bf16 v[56:59], v[136:139], v[196:199], v[56:59]
	v_mfma_f32_16x16x32_bf16 v[44:47], v[128:131], v[204:207], v[44:47]
	v_mfma_f32_16x16x32_bf16 v[40:43], v[136:139], v[204:207], v[40:43]
	v_mfma_f32_16x16x32_bf16 v[28:31], v[128:131], v[212:215], v[28:31]
	v_mfma_f32_16x16x32_bf16 v[24:27], v[136:139], v[212:215], v[24:27]
	v_mfma_f32_16x16x32_bf16 v[12:15], v[128:131], v[220:223], v[12:15]
	v_mfma_f32_16x16x32_bf16 v[8:11], v[136:139], v[220:223], v[8:11]
	v_mfma_f32_16x16x32_bf16 v[60:63], v[132:135], v[200:203], v[60:63]
	v_mfma_f32_16x16x32_bf16 v[56:59], v[140:143], v[200:203], v[56:59]
	v_mfma_f32_16x16x32_bf16 v[44:47], v[132:135], v[208:211], v[44:47]
	v_mfma_f32_16x16x32_bf16 v[40:43], v[140:143], v[208:211], v[40:43]
	v_mfma_f32_16x16x32_bf16 v[28:31], v[132:135], v[216:219], v[28:31]
	v_mfma_f32_16x16x32_bf16 v[24:27], v[140:143], v[216:219], v[24:27]
	v_mfma_f32_16x16x32_bf16 v[12:15], v[132:135], v[224:227], v[12:15]
	v_mfma_f32_16x16x32_bf16 v[8:11], v[140:143], v[224:227], v[8:11]
	v_mfma_f32_16x16x32_bf16 v[52:55], v[164:167], v[196:199], v[52:55]
	v_mfma_f32_16x16x32_bf16 v[48:51], v[182:185], v[196:199], v[48:51]
	v_mfma_f32_16x16x32_bf16 v[36:39], v[164:167], v[204:207], v[36:39]
	v_mfma_f32_16x16x32_bf16 v[32:35], v[182:185], v[204:207], v[32:35]
	v_mfma_f32_16x16x32_bf16 v[20:23], v[164:167], v[212:215], v[20:23]
	v_mfma_f32_16x16x32_bf16 v[16:19], v[182:185], v[212:215], v[16:19]
	v_mfma_f32_16x16x32_bf16 v[4:7], v[164:167], v[220:223], v[4:7]
	v_mfma_f32_16x16x32_bf16 v[0:3], v[182:185], v[220:223], v[0:3]
	v_mfma_f32_16x16x32_bf16 v[52:55], v[178:181], v[200:203], v[52:55]
	v_mfma_f32_16x16x32_bf16 v[48:51], v[192:195], v[200:203], v[48:51]
	v_mfma_f32_16x16x32_bf16 v[36:39], v[178:181], v[208:211], v[36:39]
	v_mfma_f32_16x16x32_bf16 v[32:35], v[192:195], v[208:211], v[32:35]
	v_mfma_f32_16x16x32_bf16 v[20:23], v[178:181], v[216:219], v[20:23]
	v_mfma_f32_16x16x32_bf16 v[16:19], v[192:195], v[216:219], v[16:19]
	v_mfma_f32_16x16x32_bf16 v[4:7], v[178:181], v[224:227], v[4:7]
	v_mfma_f32_16x16x32_bf16 v[0:3], v[192:195], v[224:227], v[0:3]
	s_barrier
; #define PG8_STAGE(bufoff, gbase, voff) do { _Pragma("unroll") for (int _i = 0; _i < 2; ++_i) \
;         __builtin_amdgcn_global_load_lds((const unsigned*)((const char*)(gbase) + (voff)[_i]), (PG8_LAS unsigned*)(lds + (bufoff) + ldsw + _i * 8192), 16, 0, 0); } while (0)
; #define PG8_LDA(dst, b, h) do { _Pragma("unroll") for (int m = 0; m < 4; ++m) _Pragma("unroll") for (int k = 0; k < 2; ++k) dst[m][k] = *(const PG8_LAS bf16x8*)(lds + PG8_SA(b, h) + aoff + m * 2048 + k * 1024); } while (0)
; #define PG8_LDB(dst, b, h) do { _Pragma("unroll") for (int n = 0; n < 2; ++n) _Pragma("unroll") for (int k = 0; k < 2; ++k) dst[n][k] = *(const PG8_LAS bf16x8*)(lds + PG8_SB(b, h) + boff + n * 2048 + k * 1024); } while (0)
; #define PG8_MMA(ai, bj, At, Bt) do { __builtin_amdgcn_s_setprio(1); _Pragma("unroll") for (int m = 0; m < 4; ++m) _Pragma("unroll") for (int n = 0; n < 2; ++n) _Pragma("unroll") for (int k = 0; k < 2; ++k) \
;         acc[ai][bj][m][n] = __builtin_amdgcn_mfma_f32_16x16x32_bf16(Bt[n][k], At[m][k], acc[ai][bj][m][n], 0, 0, 0); __builtin_amdgcn_s_setprio(0); } while (0)
; #define PG8_WAIT_V(n) asm volatile("s_waitcnt vmcnt(" #n ")" ::: "memory")
; #define PG8_WAIT_L(n) asm volatile("s_waitcnt lgkmcnt(" #n ")" ::: "memory")
; #define PG8_BAR __builtin_amdgcn_s_barrier()
; #define PG8_SCHED __builtin_amdgcn_sched_barrier(0)
; template <class Epi, class Sched, bool ALIGN_EPI = false, bool SP2 = false>
; __device__ __forceinline__ void gemm_phase(PG8_LAS unsigned char* lds, const Gemm g, const Sched& S, const Epi& E) {
;     ...
;             PG8_LDB(B0, 1, 0); PG8_LDB(B1, 1, 1); PG8_SCHED; PG8_LDA(At, 1, 0); PG8_STAGE(PG8_SA(0, 1), a2 + hstep, voffA);
;             PG8_WAIT_V(8); PG8_WAIT_L(0); PG8_BAR; PG8_MMA(0, 0, At, B0); PG8_MMA(0, 1, At, B1); PG8_BAR; PG8_SCHED;
	s_setprio 0
	s_add_i32 s61, 0, 0x18000
	s_add_i32 s62, 0, 0x1c000
	v_add_u32_e32 v140, s61, v170
	v_add_u32_e32 v152, s62, v170
	ds_read_b128 v[128:131], v140
	ds_read_b128 v[132:135], v140 offset:1024
	ds_read_b128 v[136:139], v140 offset:2048
	ds_read_b128 v[140:143], v140 offset:3072
	ds_read_b128 v[164:167], v152
	ds_read_b128 v[178:181], v152 offset:1024
	ds_read_b128 v[182:185], v152 offset:2048
	ds_read_b128 v[192:195], v152 offset:3072
	s_add_u32 s40, s40, 0x40000
	s_addc_u32 s41, s41, 0
	s_mov_b32 m0, s46
	v_lshl_add_u64 v[232:233], s[40:41], 0, v[150:151]
	ds_read_b128 v[196:199], v173 offset:32768
	ds_read_b128 v[200:203], v173 offset:33792
	ds_read_b128 v[204:207], v173 offset:34816
	ds_read_b128 v[208:211], v173 offset:35840
	ds_read_b128 v[212:215], v173 offset:36864
	ds_read_b128 v[216:219], v173 offset:37888
	ds_read_b128 v[220:223], v173 offset:38912
	ds_read_b128 v[224:227], v173 offset:39936
	global_load_lds_dwordx4 v[232:233], off
	v_lshl_add_u64 v[232:233], s[40:41], 0, v[146:147]
	s_mov_b32 m0, s47
	s_nop 0
	global_load_lds_dwordx4 v[232:233], off
	s_waitcnt vmcnt(8)
	s_waitcnt lgkmcnt(0)
	s_setprio 1
	s_barrier
	v_mfma_f32_16x16x32_bf16 v[124:127], v[128:131], v[196:199], v[124:127]
	v_mfma_f32_16x16x32_bf16 v[120:123], v[136:139], v[196:199], v[120:123]
	v_mfma_f32_16x16x32_bf16 v[108:111], v[128:131], v[204:207], v[108:111]
	v_mfma_f32_16x16x32_bf16 v[104:107], v[136:139], v[204:207], v[104:107]
	v_mfma_f32_16x16x32_bf16 v[92:95], v[128:131], v[212:215], v[92:95]
	v_mfma_f32_16x16x32_bf16 v[88:91], v[136:139], v[212:215], v[88:91]
	v_mfma_f32_16x16x32_bf16 v[76:79], v[128:131], v[220:223], v[76:79]
	v_mfma_f32_16x16x32_bf16 v[72:75], v[136:139], v[220:223], v[72:75]
	v_mfma_f32_16x16x32_bf16 v[124:127], v[132:135], v[200:203], v[124:127]
	v_mfma_f32_16x16x32_bf16 v[120:123], v[140:143], v[200:203], v[120:123]
	v_mfma_f32_16x16x32_bf16 v[108:111], v[132:135], v[208:211], v[108:111]
	v_mfma_f32_16x16x32_bf16 v[104:107], v[140:143], v[208:211], v[104:107]
	v_mfma_f32_16x16x32_bf16 v[92:95], v[132:135], v[216:219], v[92:95]
	v_mfma_f32_16x16x32_bf16 v[88:91], v[140:143], v[216:219], v[88:91]
	v_mfma_f32_16x16x32_bf16 v[76:79], v[132:135], v[224:227], v[76:79]
	v_mfma_f32_16x16x32_bf16 v[72:75], v[140:143], v[224:227], v[72:75]
	v_mfma_f32_16x16x32_bf16 v[116:119], v[164:167], v[196:199], v[116:119]
	v_mfma_f32_16x16x32_bf16 v[112:115], v[182:185], v[196:199], v[112:115]
	v_mfma_f32_16x16x32_bf16 v[100:103], v[164:167], v[204:207], v[100:103]
	v_mfma_f32_16x16x32_bf16 v[96:99], v[182:185], v[204:207], v[96:99]
	v_mfma_f32_16x16x32_bf16 v[84:87], v[164:167], v[212:215], v[84:87]
	v_mfma_f32_16x16x32_bf16 v[80:83], v[182:185], v[212:215], v[80:83]
	v_mfma_f32_16x16x32_bf16 v[68:71], v[164:167], v[220:223], v[68:71]
	v_mfma_f32_16x16x32_bf16 v[64:67], v[182:185], v[220:223], v[64:67]
	v_mfma_f32_16x16x32_bf16 v[116:119], v[178:181], v[200:203], v[116:119]
	v_mfma_f32_16x16x32_bf16 v[112:115], v[192:195], v[200:203], v[112:115]
	v_mfma_f32_16x16x32_bf16 v[100:103], v[178:181], v[208:211], v[100:103]
	v_mfma_f32_16x16x32_bf16 v[96:99], v[192:195], v[208:211], v[96:99]
	v_mfma_f32_16x16x32_bf16 v[84:87], v[178:181], v[216:219], v[84:87]
	v_mfma_f32_16x16x32_bf16 v[80:83], v[192:195], v[216:219], v[80:83]
	v_mfma_f32_16x16x32_bf16 v[68:71], v[178:181], v[224:227], v[68:71]
	v_mfma_f32_16x16x32_bf16 v[64:67], v[192:195], v[224:227], v[64:67]
	s_barrier
; #define PG8_STAGE(bufoff, gbase, voff) do { _Pragma("unroll") for (int _i = 0; _i < 2; ++_i) \
;         __builtin_amdgcn_global_load_lds((const unsigned*)((const char*)(gbase) + (voff)[_i]), (PG8_LAS unsigned*)(lds + (bufoff) + ldsw + _i * 8192), 16, 0, 0); } while (0)
; #define PG8_LDA(dst, b, h) do { _Pragma("unroll") for (int m = 0; m < 4; ++m) _Pragma("unroll") for (int k = 0; k < 2; ++k) dst[m][k] = *(const PG8_LAS bf16x8*)(lds + PG8_SA(b, h) + aoff + m * 2048 + k * 1024); } while (0)
; #define PG8_MMA(ai, bj, At, Bt) do { __builtin_amdgcn_s_setprio(1); _Pragma("unroll") for (int m = 0; m < 4; ++m) _Pragma("unroll") for (int n = 0; n < 2; ++n) _Pragma("unroll") for (int k = 0; k < 2; ++k) \
;         acc[ai][bj][m][n] = __builtin_amdgcn_mfma_f32_16x16x32_bf16(Bt[n][k], At[m][k], acc[ai][bj][m][n], 0, 0, 0); __builtin_amdgcn_s_setprio(0); } while (0)
; #define PG8_WAIT_V(n) asm volatile("s_waitcnt vmcnt(" #n ")" ::: "memory")
; #define PG8_WAIT_L(n) asm volatile("s_waitcnt lgkmcnt(" #n ")" ::: "memory")
; #define PG8_BAR __builtin_amdgcn_s_barrier()
; #define PG8_SCHED __builtin_amdgcn_sched_barrier(0)
; template <class Epi, class Sched, bool ALIGN_EPI = false, bool SP2 = false>
; __device__ __forceinline__ void gemm_phase(PG8_LAS unsigned char* lds, const Gemm g, const Sched& S, const Epi& E) {
;     ...
;             PG8_LDA(At, 1, 1); PG8_STAGE(PG8_SB(1, 0), b3, voffB); PG8_STAGE(PG8_SB(1, 1), b3 + hstep, voffB); PG8_STAGE(PG8_SA(1, 0), a3, voffA);
;             PG8_WAIT_V(8); PG8_WAIT_L(0); PG8_BAR; PG8_MMA(1, 0, At, B0); PG8_MMA(1, 1, At, B1); PG8_BAR; PG8_SCHED;
;     __device__ __forceinline__ void operator()(const f32x4 (&acc)[2][2][4][2], const pg8::Unit& u, int wr, int wc, int fr, int fq) const {
;         const int row0 = u.pm * 256 + wr * 64 + fr;
;         if (u.pn < 4) {
	s_setprio 0
	s_add_i32 s40, s61, s33
	v_lshl_add_u64 v[168:169], v[168:169], 0, s[16:17]
	s_mov_b32 m0, s40
	ds_read_b128 v[196:199], v173 offset:49152
	ds_read_b128 v[200:203], v173 offset:50176
	ds_read_b128 v[204:207], v173 offset:51200
	ds_read_b128 v[208:211], v173 offset:52224
	ds_read_b128 v[212:215], v173 offset:53248
	ds_read_b128 v[216:219], v173 offset:54272
	ds_read_b128 v[220:223], v173 offset:55296
	ds_read_b128 v[224:227], v173 offset:56320
	global_load_lds_dwordx4 v[168:169], off
	s_add_i32 m0, s40, 0x2000
	s_add_u32 s38, s38, 0x40080
	v_lshl_add_u64 v[168:169], v[186:187], 0, s[16:17]
	s_addc_u32 s39, s39, 0
	s_add_i32 s40, s62, s33
	global_load_lds_dwordx4 v[168:169], off
	v_lshl_add_u64 v[168:169], s[38:39], 0, v[148:149]
	s_mov_b32 m0, s40
	s_nop 0
	global_load_lds_dwordx4 v[168:169], off
	v_lshl_add_u64 v[168:169], s[38:39], 0, v[144:145]
	s_add_i32 m0, s40, 0x2000
	s_nop 0
	global_load_lds_dwordx4 v[168:169], off
	v_lshl_add_u64 v[168:169], v[228:229], 0, s[16:17]
	s_mov_b32 m0, s48
	s_nop 0
	global_load_lds_dwordx4 v[168:169], off
	v_lshl_add_u64 v[168:169], v[230:231], 0, s[16:17]
	s_mov_b32 m0, s49
	s_nop 0
	global_load_lds_dwordx4 v[168:169], off
	s_waitcnt vmcnt(8)
	s_waitcnt lgkmcnt(0)
	s_setprio 1
	s_barrier
	v_mfma_f32_16x16x32_bf16 v[60:63], v[128:131], v[196:199], v[60:63]
	v_mfma_f32_16x16x32_bf16 v[56:59], v[136:139], v[196:199], v[56:59]
	v_mfma_f32_16x16x32_bf16 v[44:47], v[128:131], v[204:207], v[44:47]
	v_mfma_f32_16x16x32_bf16 v[40:43], v[136:139], v[204:207], v[40:43]
	v_mfma_f32_16x16x32_bf16 v[28:31], v[128:131], v[212:215], v[28:31]
	v_mfma_f32_16x16x32_bf16 v[24:27], v[136:139], v[212:215], v[24:27]
	v_mfma_f32_16x16x32_bf16 v[12:15], v[128:131], v[220:223], v[12:15]
	v_mfma_f32_16x16x32_bf16 v[8:11], v[136:139], v[220:223], v[8:11]
	v_mfma_f32_16x16x32_bf16 v[60:63], v[132:135], v[200:203], v[60:63]
	v_mfma_f32_16x16x32_bf16 v[56:59], v[140:143], v[200:203], v[56:59]
	v_mfma_f32_16x16x32_bf16 v[44:47], v[132:135], v[208:211], v[44:47]
	v_mfma_f32_16x16x32_bf16 v[40:43], v[140:143], v[208:211], v[40:43]
	v_mfma_f32_16x16x32_bf16 v[28:31], v[132:135], v[216:219], v[28:31]
	v_mfma_f32_16x16x32_bf16 v[24:27], v[140:143], v[216:219], v[24:27]
	v_mfma_f32_16x16x32_bf16 v[12:15], v[132:135], v[224:227], v[12:15]
	v_mfma_f32_16x16x32_bf16 v[8:11], v[140:143], v[224:227], v[8:11]
	v_mfma_f32_16x16x32_bf16 v[52:55], v[164:167], v[196:199], v[52:55]
	v_mfma_f32_16x16x32_bf16 v[48:51], v[182:185], v[196:199], v[48:51]
	v_mfma_f32_16x16x32_bf16 v[36:39], v[164:167], v[204:207], v[36:39]
	v_mfma_f32_16x16x32_bf16 v[32:35], v[182:185], v[204:207], v[32:35]
	v_mfma_f32_16x16x32_bf16 v[20:23], v[164:167], v[212:215], v[20:23]
	v_mfma_f32_16x16x32_bf16 v[16:19], v[182:185], v[212:215], v[16:19]
	v_mfma_f32_16x16x32_bf16 v[4:7], v[164:167], v[220:223], v[4:7]
	v_mfma_f32_16x16x32_bf16 v[0:3], v[182:185], v[220:223], v[0:3]
	v_mfma_f32_16x16x32_bf16 v[52:55], v[178:181], v[200:203], v[52:55]
	v_mfma_f32_16x16x32_bf16 v[48:51], v[192:195], v[200:203], v[48:51]
	v_mfma_f32_16x16x32_bf16 v[36:39], v[178:181], v[208:211], v[36:39]
	v_mfma_f32_16x16x32_bf16 v[32:35], v[192:195], v[208:211], v[32:35]
	v_mfma_f32_16x16x32_bf16 v[20:23], v[178:181], v[216:219], v[20:23]
	v_mfma_f32_16x16x32_bf16 v[16:19], v[192:195], v[216:219], v[16:19]
	v_mfma_f32_16x16x32_bf16 v[4:7], v[178:181], v[224:227], v[4:7]
	v_mfma_f32_16x16x32_bf16 v[0:3], v[192:195], v[224:227], v[0:3]
	s_barrier
	s_setprio 0
	s_add_i32 s60, s60, 2
	s_add_u32 s2, s2, 0x100
	s_addc_u32 s3, s3, 0
	s_add_u32 s58, s58, 0x100
	s_addc_u32 s59, s59, 0
	s_cmp_gt_u32 s60, 13
	s_cbranch_scc0 .LBB0_374
	s_and_b64 vcc, exec, s[18:19]
	s_cbranch_vccnz .LBB0_379
	v_lshl_add_u32 v164, s0, 8, v155
	s_cmp_gt_i32 s57, 3
	s_mov_b64 s[0:1], -1
	s_cbranch_scc1 .LBB0_380

; #define PG8_STAGE(bufoff, gbase, voff) do { _Pragma("unroll") for (int _i = 0; _i < 2; ++_i) \
;         __builtin_amdgcn_global_load_lds((const unsigned*)((const char*)(gbase) + (voff)[_i]), (PG8_LAS unsigned*)(lds + (bufoff) + ldsw + _i * 8192), 16, 0, 0); } while (0)
; #define PG8_LDA(dst, b, h) do { _Pragma("unroll") for (int m = 0; m < 4; ++m) _Pragma("unroll") for (int k = 0; k < 2; ++k) dst[m][k] = *(const PG8_LAS bf16x8*)(lds + PG8_SA(b, h) + aoff + m * 2048 + k * 1024); } while (0)
; #define PG8_LDB(dst, b, h) do { _Pragma("unroll") for (int n = 0; n < 2; ++n) _Pragma("unroll") for (int k = 0; k < 2; ++k) dst[n][k] = *(const PG8_LAS bf16x8*)(lds + PG8_SB(b, h) + boff + n * 2048 + k * 1024); } while (0)
; #define PG8_WAIT_V(n) asm volatile("s_waitcnt vmcnt(" #n ")" ::: "memory")
; #define PG8_WAIT_L(n) asm volatile("s_waitcnt lgkmcnt(" #n ")" ::: "memory")
; #define PG8_BAR __builtin_amdgcn_s_barrier()
; #define PG8_SCHED __builtin_amdgcn_sched_barrier(0)
; template <class Epi, class Sched, bool ALIGN_EPI = false, bool SP2 = false>
; __device__ __forceinline__ void gemm_phase(PG8_LAS unsigned char* lds, const Gemm g, const Sched& S, const Epi& E) {
;     ...
;         const bool has_next = S.next(ui + 1, nxt);
;         const char* nA = has_next ? (const char*)g.A + (size_t)nxt.pm * tstep : cA; const char* nB = has_next ? (const char*)g.Bt + (size_t)nxt.pn * tstep : cB;
;         for (int t = 0; t < nt; t += 2) {
;             const bool last = (t == nt - 2);
;             const char* a1 = cA + (size_t)(t + 1) * kstep;
;             const char* a2 = last ? nA : cA + (size_t)(t + 2) * kstep; const char* b2 = last ? nB : cB + (size_t)(t + 2) * kstep;
;             const char* a3 = a2 + kstep; const char* b3 = b2 + kstep;
;             if (last && has_next) S.a_ready(nxt);
;             if constexpr (SP2) {
;             PG8_LDB(B0, 0, 0); PG8_LDB(B1, 0, 1); PG8_SCHED; PG8_LDA(At, 0, 0); PG8_STAGE(PG8_SA(1, 1), a1 + hstep, voffA);
;             PG8_WAIT_V(8); PG8_WAIT_L(0); PG8_BAR; PG8_MMA(0, 0, At, B0); PG8_MMA(0, 1, At, B1); PG8_BAR; PG8_SCHED;
;             PG8_LDA(At, 0, 1); PG8_STAGE(PG8_SB(0, 0), b2, voffB); PG8_STAGE(PG8_SB(0, 1), b2 + hstep, voffB); PG8_STAGE(PG8_SA(0, 0), a2, voffA);
;             PG8_WAIT_V(8); PG8_WAIT_L(0); PG8_BAR; PG8_MMA(1, 0, At, B0); PG8_MMA(1, 1, At, B1); PG8_BAR; PG8_SCHED;
.LBB0_697:
	s_ashr_i32 s17, s16, 31
	s_lshl_b64 s[18:19], s[16:17], 19
	v_readlane_b32 s48, v235, 2
	v_readlane_b32 s49, v235, 3
	s_add_u32 s18, s48, s18
	s_addc_u32 s19, s49, s19
	s_and_b64 s[20:21], s[6:7], exec
	s_cselect_b32 s17, s19, s27
	s_cselect_b32 s23, s18, s26
	s_ashr_i32 s15, s14, 31
	s_lshl_b64 s[20:21], s[14:15], 19
	s_add_u32 s20, s33, s20
	s_addc_u32 s21, s34, s21
	s_and_b64 s[30:31], s[6:7], exec
	s_cselect_b32 s15, s21, s29
	s_cselect_b32 s47, s20, s28
	s_add_u32 s26, s26, 0x40080
	s_addc_u32 s27, s27, 0
	v_readlane_b32 s50, v235, 4
	s_add_u32 s48, s28, 0x100
	s_addc_u32 s49, s29, 0
	s_mov_b32 s50, -2
	s_waitcnt lgkmcnt(0)
	v_readlane_b32 s51, v235, 5
	ds_read_b128 v[144:147], v151
	ds_read_b128 v[156:159], v151 offset:1024
	ds_read_b128 v[160:163], v151 offset:2048
	ds_read_b128 v[164:167], v151 offset:3072
	ds_read_b128 v[168:171], v152
	ds_read_b128 v[172:175], v152 offset:1024
	ds_read_b128 v[176:179], v152 offset:2048
	ds_read_b128 v[180:183], v152 offset:3072
	s_add_u32 s28, s26, 0xfffc0080
	s_addc_u32 s29, s27, -1
	s_cmp_eq_u32 s50, 12
	s_cselect_b32 s31, s17, s29
	s_cselect_b32 s30, s23, s28
	s_cselect_b32 s29, s15, s49
	s_cselect_b32 s28, s47, s48
	v_lshl_add_u64 v[218:219], s[26:27], 0, v[136:137]
	s_add_i32 m0, s25, 0xc000
	ds_read_b128 v[184:187], v153
	ds_read_b128 v[190:193], v153 offset:1024
	ds_read_b128 v[194:197], v153 offset:2048
	ds_read_b128 v[198:201], v153 offset:3072
	ds_read_b128 v[202:205], v153 offset:4096
	ds_read_b128 v[206:209], v153 offset:5120
	ds_read_b128 v[210:213], v153 offset:6144
	ds_read_b128 v[214:217], v153 offset:7168
	global_load_lds_dwordx4 v[218:219], off
	v_lshl_add_u64 v[218:219], s[26:27], 0, v[138:139]
	s_add_i32 m0, s25, 0xe000
	s_nop 0
	global_load_lds_dwordx4 v[218:219], off
	s_waitcnt vmcnt(8)
	s_waitcnt lgkmcnt(0)
	s_setprio 1
	s_barrier
	v_mfma_f32_16x16x32_bf16 v[124:127], v[144:147], v[184:187], 0
	v_mfma_f32_16x16x32_bf16 v[120:123], v[160:163], v[184:187], 0
	v_mfma_f32_16x16x32_bf16 v[108:111], v[144:147], v[194:197], 0
	v_mfma_f32_16x16x32_bf16 v[104:107], v[160:163], v[194:197], 0
	v_mfma_f32_16x16x32_bf16 v[92:95], v[144:147], v[202:205], 0
	v_mfma_f32_16x16x32_bf16 v[88:91], v[160:163], v[202:205], 0
	v_mfma_f32_16x16x32_bf16 v[76:79], v[144:147], v[210:213], 0
	v_mfma_f32_16x16x32_bf16 v[72:75], v[160:163], v[210:213], 0
	v_mfma_f32_16x16x32_bf16 v[124:127], v[156:159], v[190:193], v[124:127]
	v_mfma_f32_16x16x32_bf16 v[120:123], v[164:167], v[190:193], v[120:123]
	v_mfma_f32_16x16x32_bf16 v[108:111], v[156:159], v[198:201], v[108:111]
	v_mfma_f32_16x16x32_bf16 v[104:107], v[164:167], v[198:201], v[104:107]
	v_mfma_f32_16x16x32_bf16 v[92:95], v[156:159], v[206:209], v[92:95]
	v_mfma_f32_16x16x32_bf16 v[88:91], v[164:167], v[206:209], v[88:91]
	v_mfma_f32_16x16x32_bf16 v[76:79], v[156:159], v[214:217], v[76:79]
	v_mfma_f32_16x16x32_bf16 v[72:75], v[164:167], v[214:217], v[72:75]
	v_mfma_f32_16x16x32_bf16 v[116:119], v[168:171], v[184:187], 0
	v_mfma_f32_16x16x32_bf16 v[112:115], v[176:179], v[184:187], 0
	v_mfma_f32_16x16x32_bf16 v[100:103], v[168:171], v[194:197], 0
	v_mfma_f32_16x16x32_bf16 v[96:99], v[176:179], v[194:197], 0
	v_mfma_f32_16x16x32_bf16 v[84:87], v[168:171], v[202:205], 0
	v_mfma_f32_16x16x32_bf16 v[80:83], v[176:179], v[202:205], 0
	v_mfma_f32_16x16x32_bf16 v[68:71], v[168:171], v[210:213], 0
	v_mfma_f32_16x16x32_bf16 v[64:67], v[176:179], v[210:213], 0
	v_mfma_f32_16x16x32_bf16 v[116:119], v[172:175], v[190:193], v[116:119]
	v_mfma_f32_16x16x32_bf16 v[112:115], v[180:183], v[190:193], v[112:115]
	v_mfma_f32_16x16x32_bf16 v[100:103], v[172:175], v[198:201], v[100:103]
	v_mfma_f32_16x16x32_bf16 v[96:99], v[180:183], v[198:201], v[96:99]
	v_mfma_f32_16x16x32_bf16 v[84:87], v[172:175], v[206:209], v[84:87]
	v_mfma_f32_16x16x32_bf16 v[80:83], v[180:183], v[206:209], v[80:83]
	v_mfma_f32_16x16x32_bf16 v[68:71], v[172:175], v[214:217], v[68:71]
	v_mfma_f32_16x16x32_bf16 v[64:67], v[180:183], v[214:217], v[64:67]
	s_barrier
	s_setprio 0
	s_add_i32 s51, s45, s35
	v_lshl_add_u64 v[218:219], s[28:29], 0, v[130:131]
	s_mov_b32 m0, s51
	ds_read_b128 v[184:187], v153 offset:16384
	ds_read_b128 v[190:193], v153 offset:17408
	ds_read_b128 v[194:197], v153 offset:18432
	ds_read_b128 v[198:201], v153 offset:19456
	ds_read_b128 v[202:205], v153 offset:20480
	ds_read_b128 v[206:209], v153 offset:21504
	ds_read_b128 v[210:213], v153 offset:22528
	ds_read_b128 v[214:217], v153 offset:23552
	global_load_lds_dwordx4 v[218:219], off
	s_add_i32 m0, s51, 0x2000
	s_add_u32 s52, s28, 0x40000
	v_lshl_add_u64 v[220:221], s[28:29], 0, v[134:135]
	s_addc_u32 s53, s29, 0
	s_add_i32 s51, s46, s35
	global_load_lds_dwordx4 v[220:221], off
	v_lshl_add_u64 v[222:223], s[52:53], 0, v[130:131]
	s_mov_b32 m0, s51
	v_lshl_add_u64 v[224:225], s[30:31], 0, v[132:133]
	global_load_lds_dwordx4 v[222:223], off
	v_lshl_add_u64 v[222:223], s[52:53], 0, v[134:135]
	s_add_i32 m0, s51, 0x2000
	s_nop 0
	global_load_lds_dwordx4 v[222:223], off
	v_lshl_add_u64 v[222:223], s[30:31], 0, v[128:129]
	s_mov_b32 m0, s25
	s_nop 0
	global_load_lds_dwordx4 v[222:223], off
	s_mov_b32 m0, s36
	s_nop 0
	global_load_lds_dwordx4 v[224:225], off
	s_waitcnt vmcnt(8)
	s_waitcnt lgkmcnt(0)
	s_setprio 1
	s_barrier
; #define PG8_STAGE(bufoff, gbase, voff) do { _Pragma("unroll") for (int _i = 0; _i < 2; ++_i) \
;         __builtin_amdgcn_global_load_lds((const unsigned*)((const char*)(gbase) + (voff)[_i]), (PG8_LAS unsigned*)(lds + (bufoff) + ldsw + _i * 8192), 16, 0, 0); } while (0)
; #define PG8_LDA(dst, b, h) do { _Pragma("unroll") for (int m = 0; m < 4; ++m) _Pragma("unroll") for (int k = 0; k < 2; ++k) dst[m][k] = *(const PG8_LAS bf16x8*)(lds + PG8_SA(b, h) + aoff + m * 2048 + k * 1024); } while (0)
; #define PG8_LDB(dst, b, h) do { _Pragma("unroll") for (int n = 0; n < 2; ++n) _Pragma("unroll") for (int k = 0; k < 2; ++k) dst[n][k] = *(const PG8_LAS bf16x8*)(lds + PG8_SB(b, h) + boff + n * 2048 + k * 1024); } while (0)
; #define PG8_MMA(ai, bj, At, Bt) do { __builtin_amdgcn_s_setprio(1); _Pragma("unroll") for (int m = 0; m < 4; ++m) _Pragma("unroll") for (int n = 0; n < 2; ++n) _Pragma("unroll") for (int k = 0; k < 2; ++k) \
;         acc[ai][bj][m][n] = __builtin_amdgcn_mfma_f32_16x16x32_bf16(Bt[n][k], At[m][k], acc[ai][bj][m][n], 0, 0, 0); __builtin_amdgcn_s_setprio(0); } while (0)
; #define PG8_WAIT_V(n) asm volatile("s_waitcnt vmcnt(" #n ")" ::: "memory")
; #define PG8_WAIT_L(n) asm volatile("s_waitcnt lgkmcnt(" #n ")" ::: "memory")
; #define PG8_BAR __builtin_amdgcn_s_barrier()
; #define PG8_SCHED __builtin_amdgcn_sched_barrier(0)
; template <class Epi, class Sched, bool ALIGN_EPI = false, bool SP2 = false>
; __device__ __forceinline__ void gemm_phase(PG8_LAS unsigned char* lds, const Gemm g, const Sched& S, const Epi& E) {
;     ...
;             PG8_WAIT_V(8); PG8_WAIT_L(0); PG8_BAR; PG8_MMA(1, 0, At, B0); PG8_MMA(1, 1, At, B1); PG8_BAR; PG8_SCHED;
;             PG8_LDB(B0, 1, 0); PG8_LDB(B1, 1, 1); PG8_SCHED; PG8_LDA(At, 1, 0); PG8_STAGE(PG8_SA(0, 1), a2 + hstep, voffA);
;             PG8_WAIT_V(8); PG8_WAIT_L(0); PG8_BAR; PG8_MMA(0, 0, At, B0); PG8_MMA(0, 1, At, B1); PG8_BAR; PG8_SCHED;
	v_mfma_f32_16x16x32_bf16 v[60:63], v[144:147], v[184:187], 0
	v_mfma_f32_16x16x32_bf16 v[56:59], v[160:163], v[184:187], 0
	v_mfma_f32_16x16x32_bf16 v[44:47], v[144:147], v[194:197], 0
	v_mfma_f32_16x16x32_bf16 v[40:43], v[160:163], v[194:197], 0
	v_mfma_f32_16x16x32_bf16 v[28:31], v[144:147], v[202:205], 0
	v_mfma_f32_16x16x32_bf16 v[24:27], v[160:163], v[202:205], 0
	v_mfma_f32_16x16x32_bf16 v[12:15], v[144:147], v[210:213], 0
	v_mfma_f32_16x16x32_bf16 v[8:11], v[160:163], v[210:213], 0
	v_mfma_f32_16x16x32_bf16 v[60:63], v[156:159], v[190:193], v[60:63]
	v_mfma_f32_16x16x32_bf16 v[56:59], v[164:167], v[190:193], v[56:59]
	v_mfma_f32_16x16x32_bf16 v[44:47], v[156:159], v[198:201], v[44:47]
	v_mfma_f32_16x16x32_bf16 v[40:43], v[164:167], v[198:201], v[40:43]
	v_mfma_f32_16x16x32_bf16 v[28:31], v[156:159], v[206:209], v[28:31]
	v_mfma_f32_16x16x32_bf16 v[24:27], v[164:167], v[206:209], v[24:27]
	v_mfma_f32_16x16x32_bf16 v[12:15], v[156:159], v[214:217], v[12:15]
	v_mfma_f32_16x16x32_bf16 v[8:11], v[164:167], v[214:217], v[8:11]
	v_mfma_f32_16x16x32_bf16 v[52:55], v[168:171], v[184:187], 0
	v_mfma_f32_16x16x32_bf16 v[48:51], v[176:179], v[184:187], 0
	v_mfma_f32_16x16x32_bf16 v[36:39], v[168:171], v[194:197], 0
	v_mfma_f32_16x16x32_bf16 v[32:35], v[176:179], v[194:197], 0
	v_mfma_f32_16x16x32_bf16 v[20:23], v[168:171], v[202:205], 0
	v_mfma_f32_16x16x32_bf16 v[16:19], v[176:179], v[202:205], 0
	v_mfma_f32_16x16x32_bf16 v[4:7], v[168:171], v[210:213], 0
	v_mfma_f32_16x16x32_bf16 v[0:3], v[176:179], v[210:213], 0
	v_mfma_f32_16x16x32_bf16 v[52:55], v[172:175], v[190:193], v[52:55]
	v_mfma_f32_16x16x32_bf16 v[48:51], v[180:183], v[190:193], v[48:51]
	v_mfma_f32_16x16x32_bf16 v[36:39], v[172:175], v[198:201], v[36:39]
	v_mfma_f32_16x16x32_bf16 v[32:35], v[180:183], v[198:201], v[32:35]
	v_mfma_f32_16x16x32_bf16 v[20:23], v[172:175], v[206:209], v[20:23]
	v_mfma_f32_16x16x32_bf16 v[16:19], v[180:183], v[206:209], v[16:19]
	v_mfma_f32_16x16x32_bf16 v[4:7], v[172:175], v[214:217], v[4:7]
	v_mfma_f32_16x16x32_bf16 v[0:3], v[180:183], v[214:217], v[0:3]
	s_barrier
	s_setprio 0
	s_add_i32 s51, 0, 0x18000
	v_add_u32_e32 v155, s51, v149
	s_add_i32 s52, 0, 0x1c000
	ds_read_b128 v[144:147], v155
	ds_read_b128 v[156:159], v155 offset:1024
	ds_read_b128 v[160:163], v155 offset:2048
	ds_read_b128 v[164:167], v155 offset:3072
	v_add_u32_e32 v155, s52, v149
	ds_read_b128 v[168:171], v155
	ds_read_b128 v[172:175], v155 offset:1024
	ds_read_b128 v[176:179], v155 offset:2048
	ds_read_b128 v[180:183], v155 offset:3072
	s_add_u32 s30, s30, 0x40000
	s_addc_u32 s31, s31, 0
	s_mov_b32 m0, s37
	v_lshl_add_u64 v[226:227], s[30:31], 0, v[128:129]
	ds_read_b128 v[184:187], v153 offset:32768
	ds_read_b128 v[190:193], v153 offset:33792
	ds_read_b128 v[194:197], v153 offset:34816
	ds_read_b128 v[198:201], v153 offset:35840
	ds_read_b128 v[202:205], v153 offset:36864
	ds_read_b128 v[206:209], v153 offset:37888
	ds_read_b128 v[210:213], v153 offset:38912
	ds_read_b128 v[214:217], v153 offset:39936
	global_load_lds_dwordx4 v[226:227], off
	v_lshl_add_u64 v[226:227], s[30:31], 0, v[132:133]
	s_mov_b32 m0, s38
	s_nop 0
	global_load_lds_dwordx4 v[226:227], off
	s_waitcnt vmcnt(8)
	s_waitcnt lgkmcnt(0)
	s_setprio 1
	s_barrier
	v_mfma_f32_16x16x32_bf16 v[124:127], v[144:147], v[184:187], v[124:127]
	v_mfma_f32_16x16x32_bf16 v[120:123], v[160:163], v[184:187], v[120:123]
	v_mfma_f32_16x16x32_bf16 v[108:111], v[144:147], v[194:197], v[108:111]
	v_mfma_f32_16x16x32_bf16 v[104:107], v[160:163], v[194:197], v[104:107]
	v_mfma_f32_16x16x32_bf16 v[92:95], v[144:147], v[202:205], v[92:95]
	v_mfma_f32_16x16x32_bf16 v[88:91], v[160:163], v[202:205], v[88:91]
	v_mfma_f32_16x16x32_bf16 v[76:79], v[144:147], v[210:213], v[76:79]
	v_mfma_f32_16x16x32_bf16 v[72:75], v[160:163], v[210:213], v[72:75]
	v_mfma_f32_16x16x32_bf16 v[124:127], v[156:159], v[190:193], v[124:127]
	v_mfma_f32_16x16x32_bf16 v[120:123], v[164:167], v[190:193], v[120:123]
	v_mfma_f32_16x16x32_bf16 v[108:111], v[156:159], v[198:201], v[108:111]
	v_mfma_f32_16x16x32_bf16 v[104:107], v[164:167], v[198:201], v[104:107]
	v_mfma_f32_16x16x32_bf16 v[92:95], v[156:159], v[206:209], v[92:95]
	v_mfma_f32_16x16x32_bf16 v[88:91], v[164:167], v[206:209], v[88:91]
	v_mfma_f32_16x16x32_bf16 v[76:79], v[156:159], v[214:217], v[76:79]
	v_mfma_f32_16x16x32_bf16 v[72:75], v[164:167], v[214:217], v[72:75]
	v_mfma_f32_16x16x32_bf16 v[116:119], v[168:171], v[184:187], v[116:119]
	v_mfma_f32_16x16x32_bf16 v[112:115], v[176:179], v[184:187], v[112:115]
	v_mfma_f32_16x16x32_bf16 v[100:103], v[168:171], v[194:197], v[100:103]
	v_mfma_f32_16x16x32_bf16 v[96:99], v[176:179], v[194:197], v[96:99]
	v_mfma_f32_16x16x32_bf16 v[84:87], v[168:171], v[202:205], v[84:87]
	v_mfma_f32_16x16x32_bf16 v[80:83], v[176:179], v[202:205], v[80:83]
	v_mfma_f32_16x16x32_bf16 v[68:71], v[168:171], v[210:213], v[68:71]
	v_mfma_f32_16x16x32_bf16 v[64:67], v[176:179], v[210:213], v[64:67]
	v_mfma_f32_16x16x32_bf16 v[116:119], v[172:175], v[190:193], v[116:119]
	v_mfma_f32_16x16x32_bf16 v[112:115], v[180:183], v[190:193], v[112:115]
	v_mfma_f32_16x16x32_bf16 v[100:103], v[172:175], v[198:201], v[100:103]
	v_mfma_f32_16x16x32_bf16 v[96:99], v[180:183], v[198:201], v[96:99]
	v_mfma_f32_16x16x32_bf16 v[84:87], v[172:175], v[206:209], v[84:87]
	v_mfma_f32_16x16x32_bf16 v[80:83], v[180:183], v[206:209], v[80:83]
	v_mfma_f32_16x16x32_bf16 v[68:71], v[172:175], v[214:217], v[68:71]
	v_mfma_f32_16x16x32_bf16 v[64:67], v[180:183], v[214:217], v[64:67]
	s_barrier
; #define PG8_STAGE(bufoff, gbase, voff) do { _Pragma("unroll") for (int _i = 0; _i < 2; ++_i) \
;         __builtin_amdgcn_global_load_lds((const unsigned*)((const char*)(gbase) + (voff)[_i]), (PG8_LAS unsigned*)(lds + (bufoff) + ldsw + _i * 8192), 16, 0, 0); } while (0)
; #define PG8_LDA(dst, b, h) do { _Pragma("unroll") for (int m = 0; m < 4; ++m) _Pragma("unroll") for (int k = 0; k < 2; ++k) dst[m][k] = *(const PG8_LAS bf16x8*)(lds + PG8_SA(b, h) + aoff + m * 2048 + k * 1024); } while (0)
; #define PG8_LDB(dst, b, h) do { _Pragma("unroll") for (int n = 0; n < 2; ++n) _Pragma("unroll") for (int k = 0; k < 2; ++k) dst[n][k] = *(const PG8_LAS bf16x8*)(lds + PG8_SB(b, h) + boff + n * 2048 + k * 1024); } while (0)
; #define PG8_BAR __builtin_amdgcn_s_barrier()
; template <class Epi, class Sched, bool ALIGN_EPI = false, bool SP2 = false>
; __device__ __forceinline__ void gemm_phase(PG8_LAS unsigned char* lds, const Gemm g, const Sched& S, const Epi& E) {
;     ...
;             const bool last = (t == nt - 2);
;             const char* a1 = cA + (size_t)(t + 1) * kstep;
;             const char* a2 = last ? nA : cA + (size_t)(t + 2) * kstep; const char* b2 = last ? nB : cB + (size_t)(t + 2) * kstep;
;             const char* a3 = a2 + kstep; const char* b3 = b2 + kstep;
;             if (last && has_next) S.a_ready(nxt);
;             if constexpr (SP2) {
;             PG8_LDB(B0, 0, 0); PG8_LDB(B1, 0, 1); PG8_SCHED; PG8_LDA(At, 0, 0); PG8_STAGE(PG8_SA(1, 1), a1 + hstep, voffA);
;             PG8_WAIT_V(8); PG8_WAIT_L(0); PG8_BAR; PG8_MMA(0, 0, At, B0); PG8_MMA(0, 1, At, B1); PG8_BAR; PG8_SCHED;
;             PG8_LDA(At, 0, 1); PG8_STAGE(PG8_SB(0, 0), b2, voffB); PG8_STAGE(PG8_SB(0, 1), b2 + hstep, voffB); PG8_STAGE(PG8_SA(0, 0), a2, voffA);
;             PG8_WAIT_V(8); PG8_WAIT_L(0); PG8_BAR; PG8_MMA(1, 0, At, B0); PG8_MMA(1, 1, At, B1); PG8_BAR; PG8_SCHED;
;             PG8_LDB(B0, 1, 0); PG8_LDB(B1, 1, 1); PG8_SCHED; PG8_LDA(At, 1, 0); PG8_STAGE(PG8_SA(0, 1), a2 + hstep, voffA);
;             PG8_WAIT_V(8); PG8_WAIT_L(0); PG8_BAR; PG8_MMA(0, 0, At, B0); PG8_MMA(0, 1, At, B1); PG8_BAR; PG8_SCHED;
;             PG8_LDA(At, 1, 1); PG8_STAGE(PG8_SB(1, 0), b3, voffB); PG8_STAGE(PG8_SB(1, 1), b3 + hstep, voffB); PG8_STAGE(PG8_SA(1, 0), a3, voffA);
;             PG8_WAIT_V(8); PG8_WAIT_L(0); PG8_BAR; PG8_MMA(1, 0, At, B0); PG8_MMA(1, 1, At, B1); PG8_BAR; PG8_SCHED;
	s_setprio 0
	s_add_i32 s30, s51, s35
	v_lshl_add_u64 v[218:219], v[218:219], 0, s[2:3]
	s_mov_b32 m0, s30
	ds_read_b128 v[184:187], v153 offset:49152
	ds_read_b128 v[190:193], v153 offset:50176
	ds_read_b128 v[194:197], v153 offset:51200
	ds_read_b128 v[198:201], v153 offset:52224
	ds_read_b128 v[202:205], v153 offset:53248
	ds_read_b128 v[206:209], v153 offset:54272
	ds_read_b128 v[210:213], v153 offset:55296
	ds_read_b128 v[214:217], v153 offset:56320
	global_load_lds_dwordx4 v[218:219], off
	s_add_i32 m0, s30, 0x2000
	s_add_u32 s28, s28, 0x40080
	v_lshl_add_u64 v[218:219], v[220:221], 0, s[2:3]
	s_addc_u32 s29, s29, 0
	s_add_i32 s30, s52, s35
	global_load_lds_dwordx4 v[218:219], off
	v_lshl_add_u64 v[218:219], s[28:29], 0, v[130:131]
	s_mov_b32 m0, s30
	s_nop 0
	global_load_lds_dwordx4 v[218:219], off
	v_lshl_add_u64 v[218:219], s[28:29], 0, v[134:135]
	s_add_i32 m0, s30, 0x2000
	s_nop 0
	global_load_lds_dwordx4 v[218:219], off
	v_lshl_add_u64 v[218:219], v[222:223], 0, s[2:3]
	s_mov_b32 m0, s40
	s_nop 0
	global_load_lds_dwordx4 v[218:219], off
	v_lshl_add_u64 v[218:219], v[224:225], 0, s[2:3]
	s_mov_b32 m0, s41
	s_nop 0
	global_load_lds_dwordx4 v[218:219], off
	s_waitcnt vmcnt(8)
	s_waitcnt lgkmcnt(0)
	s_setprio 1
	s_barrier
	v_mfma_f32_16x16x32_bf16 v[60:63], v[144:147], v[184:187], v[60:63]
	v_mfma_f32_16x16x32_bf16 v[56:59], v[160:163], v[184:187], v[56:59]
	v_mfma_f32_16x16x32_bf16 v[44:47], v[144:147], v[194:197], v[44:47]
	v_mfma_f32_16x16x32_bf16 v[40:43], v[160:163], v[194:197], v[40:43]
	v_mfma_f32_16x16x32_bf16 v[28:31], v[144:147], v[202:205], v[28:31]
	v_mfma_f32_16x16x32_bf16 v[24:27], v[160:163], v[202:205], v[24:27]
	v_mfma_f32_16x16x32_bf16 v[12:15], v[144:147], v[210:213], v[12:15]
	v_mfma_f32_16x16x32_bf16 v[8:11], v[160:163], v[210:213], v[8:11]
	v_mfma_f32_16x16x32_bf16 v[60:63], v[156:159], v[190:193], v[60:63]
	v_mfma_f32_16x16x32_bf16 v[56:59], v[164:167], v[190:193], v[56:59]
	v_mfma_f32_16x16x32_bf16 v[44:47], v[156:159], v[198:201], v[44:47]
	v_mfma_f32_16x16x32_bf16 v[40:43], v[164:167], v[198:201], v[40:43]
	v_mfma_f32_16x16x32_bf16 v[28:31], v[156:159], v[206:209], v[28:31]
	v_mfma_f32_16x16x32_bf16 v[24:27], v[164:167], v[206:209], v[24:27]
	v_mfma_f32_16x16x32_bf16 v[12:15], v[156:159], v[214:217], v[12:15]
	v_mfma_f32_16x16x32_bf16 v[8:11], v[164:167], v[214:217], v[8:11]
	v_mfma_f32_16x16x32_bf16 v[52:55], v[168:171], v[184:187], v[52:55]
	v_mfma_f32_16x16x32_bf16 v[48:51], v[176:179], v[184:187], v[48:51]
	v_mfma_f32_16x16x32_bf16 v[36:39], v[168:171], v[194:197], v[36:39]
	v_mfma_f32_16x16x32_bf16 v[32:35], v[176:179], v[194:197], v[32:35]
	v_mfma_f32_16x16x32_bf16 v[20:23], v[168:171], v[202:205], v[20:23]
	v_mfma_f32_16x16x32_bf16 v[16:19], v[176:179], v[202:205], v[16:19]
	v_mfma_f32_16x16x32_bf16 v[4:7], v[168:171], v[210:213], v[4:7]
	v_mfma_f32_16x16x32_bf16 v[0:3], v[176:179], v[210:213], v[0:3]
	v_mfma_f32_16x16x32_bf16 v[52:55], v[172:175], v[190:193], v[52:55]
	v_mfma_f32_16x16x32_bf16 v[48:51], v[180:183], v[190:193], v[48:51]
	v_mfma_f32_16x16x32_bf16 v[36:39], v[172:175], v[198:201], v[36:39]
	v_mfma_f32_16x16x32_bf16 v[32:35], v[180:183], v[198:201], v[32:35]
	v_mfma_f32_16x16x32_bf16 v[20:23], v[172:175], v[206:209], v[20:23]
	v_mfma_f32_16x16x32_bf16 v[16:19], v[180:183], v[206:209], v[16:19]
	v_mfma_f32_16x16x32_bf16 v[4:7], v[172:175], v[214:217], v[4:7]
	v_mfma_f32_16x16x32_bf16 v[0:3], v[180:183], v[214:217], v[0:3]
	s_barrier
	s_setprio 0
	s_add_i32 s50, s50, 2
	s_add_u32 s26, s26, 0x100
	s_addc_u32 s27, s27, 0
	s_add_u32 s48, s48, 0x100
	s_addc_u32 s49, s49, 0
.LBB0_698:
	ds_read_b128 v[144:147], v151
	ds_read_b128 v[156:159], v151 offset:1024
	ds_read_b128 v[160:163], v151 offset:2048
	ds_read_b128 v[164:167], v151 offset:3072
	ds_read_b128 v[168:171], v152
	ds_read_b128 v[172:175], v152 offset:1024
	ds_read_b128 v[176:179], v152 offset:2048
	ds_read_b128 v[180:183], v152 offset:3072
	s_add_u32 s28, s26, 0xfffc0080
	s_addc_u32 s29, s27, -1
	s_cmp_eq_u32 s50, 12
	s_cselect_b32 s31, s17, s29
	s_cselect_b32 s30, s23, s28
	s_cselect_b32 s29, s15, s49
	s_cselect_b32 s28, s47, s48
	v_lshl_add_u64 v[218:219], s[26:27], 0, v[136:137]
	s_add_i32 m0, s25, 0xc000
	ds_read_b128 v[184:187], v153
	ds_read_b128 v[190:193], v153 offset:1024
	ds_read_b128 v[194:197], v153 offset:2048
	ds_read_b128 v[198:201], v153 offset:3072
	ds_read_b128 v[202:205], v153 offset:4096
	ds_read_b128 v[206:209], v153 offset:5120
	ds_read_b128 v[210:213], v153 offset:6144
	ds_read_b128 v[214:217], v153 offset:7168
	global_load_lds_dwordx4 v[218:219], off
	v_lshl_add_u64 v[218:219], s[26:27], 0, v[138:139]
	s_add_i32 m0, s25, 0xe000
	s_nop 0
	global_load_lds_dwordx4 v[218:219], off
	s_waitcnt vmcnt(8)
	s_waitcnt lgkmcnt(0)
	s_setprio 1
	s_barrier
; #define PG8_STAGE(bufoff, gbase, voff) do { _Pragma("unroll") for (int _i = 0; _i < 2; ++_i) \
;         __builtin_amdgcn_global_load_lds((const unsigned*)((const char*)(gbase) + (voff)[_i]), (PG8_LAS unsigned*)(lds + (bufoff) + ldsw + _i * 8192), 16, 0, 0); } while (0)
; #define PG8_LDA(dst, b, h) do { _Pragma("unroll") for (int m = 0; m < 4; ++m) _Pragma("unroll") for (int k = 0; k < 2; ++k) dst[m][k] = *(const PG8_LAS bf16x8*)(lds + PG8_SA(b, h) + aoff + m * 2048 + k * 1024); } while (0)
; #define PG8_MMA(ai, bj, At, Bt) do { __builtin_amdgcn_s_setprio(1); _Pragma("unroll") for (int m = 0; m < 4; ++m) _Pragma("unroll") for (int n = 0; n < 2; ++n) _Pragma("unroll") for (int k = 0; k < 2; ++k) \
;         acc[ai][bj][m][n] = __builtin_amdgcn_mfma_f32_16x16x32_bf16(Bt[n][k], At[m][k], acc[ai][bj][m][n], 0, 0, 0); __builtin_amdgcn_s_setprio(0); } while (0)
; #define PG8_WAIT_V(n) asm volatile("s_waitcnt vmcnt(" #n ")" ::: "memory")
; #define PG8_WAIT_L(n) asm volatile("s_waitcnt lgkmcnt(" #n ")" ::: "memory")
; #define PG8_BAR __builtin_amdgcn_s_barrier()
; #define PG8_SCHED __builtin_amdgcn_sched_barrier(0)
; template <class Epi, class Sched, bool ALIGN_EPI = false, bool SP2 = false>
; __device__ __forceinline__ void gemm_phase(PG8_LAS unsigned char* lds, const Gemm g, const Sched& S, const Epi& E) {
;     ...
;             PG8_WAIT_V(8); PG8_WAIT_L(0); PG8_BAR; PG8_MMA(0, 0, At, B0); PG8_MMA(0, 1, At, B1); PG8_BAR; PG8_SCHED;
;             PG8_LDA(At, 0, 1); PG8_STAGE(PG8_SB(0, 0), b2, voffB); PG8_STAGE(PG8_SB(0, 1), b2 + hstep, voffB); PG8_STAGE(PG8_SA(0, 0), a2, voffA);
;             PG8_WAIT_V(8); PG8_WAIT_L(0); PG8_BAR; PG8_MMA(1, 0, At, B0); PG8_MMA(1, 1, At, B1); PG8_BAR; PG8_SCHED;
	v_mfma_f32_16x16x32_bf16 v[124:127], v[144:147], v[184:187], v[124:127]
	v_mfma_f32_16x16x32_bf16 v[120:123], v[160:163], v[184:187], v[120:123]
	v_mfma_f32_16x16x32_bf16 v[108:111], v[144:147], v[194:197], v[108:111]
	v_mfma_f32_16x16x32_bf16 v[104:107], v[160:163], v[194:197], v[104:107]
	v_mfma_f32_16x16x32_bf16 v[92:95], v[144:147], v[202:205], v[92:95]
	v_mfma_f32_16x16x32_bf16 v[88:91], v[160:163], v[202:205], v[88:91]
	v_mfma_f32_16x16x32_bf16 v[76:79], v[144:147], v[210:213], v[76:79]
	v_mfma_f32_16x16x32_bf16 v[72:75], v[160:163], v[210:213], v[72:75]
	v_mfma_f32_16x16x32_bf16 v[124:127], v[156:159], v[190:193], v[124:127]
	v_mfma_f32_16x16x32_bf16 v[120:123], v[164:167], v[190:193], v[120:123]
	v_mfma_f32_16x16x32_bf16 v[108:111], v[156:159], v[198:201], v[108:111]
	v_mfma_f32_16x16x32_bf16 v[104:107], v[164:167], v[198:201], v[104:107]
	v_mfma_f32_16x16x32_bf16 v[92:95], v[156:159], v[206:209], v[92:95]
	v_mfma_f32_16x16x32_bf16 v[88:91], v[164:167], v[206:209], v[88:91]
	v_mfma_f32_16x16x32_bf16 v[76:79], v[156:159], v[214:217], v[76:79]
	v_mfma_f32_16x16x32_bf16 v[72:75], v[164:167], v[214:217], v[72:75]
	v_mfma_f32_16x16x32_bf16 v[116:119], v[168:171], v[184:187], v[116:119]
	v_mfma_f32_16x16x32_bf16 v[112:115], v[176:179], v[184:187], v[112:115]
	v_mfma_f32_16x16x32_bf16 v[100:103], v[168:171], v[194:197], v[100:103]
	v_mfma_f32_16x16x32_bf16 v[96:99], v[176:179], v[194:197], v[96:99]
	v_mfma_f32_16x16x32_bf16 v[84:87], v[168:171], v[202:205], v[84:87]
	v_mfma_f32_16x16x32_bf16 v[80:83], v[176:179], v[202:205], v[80:83]
	v_mfma_f32_16x16x32_bf16 v[68:71], v[168:171], v[210:213], v[68:71]
	v_mfma_f32_16x16x32_bf16 v[64:67], v[176:179], v[210:213], v[64:67]
	v_mfma_f32_16x16x32_bf16 v[116:119], v[172:175], v[190:193], v[116:119]
	v_mfma_f32_16x16x32_bf16 v[112:115], v[180:183], v[190:193], v[112:115]
	v_mfma_f32_16x16x32_bf16 v[100:103], v[172:175], v[198:201], v[100:103]
	v_mfma_f32_16x16x32_bf16 v[96:99], v[180:183], v[198:201], v[96:99]
	v_mfma_f32_16x16x32_bf16 v[84:87], v[172:175], v[206:209], v[84:87]
	v_mfma_f32_16x16x32_bf16 v[80:83], v[180:183], v[206:209], v[80:83]
	v_mfma_f32_16x16x32_bf16 v[68:71], v[172:175], v[214:217], v[68:71]
	v_mfma_f32_16x16x32_bf16 v[64:67], v[180:183], v[214:217], v[64:67]
	s_barrier
	s_setprio 0
	s_add_i32 s51, s45, s35
	v_lshl_add_u64 v[218:219], s[28:29], 0, v[130:131]
	s_mov_b32 m0, s51
	ds_read_b128 v[184:187], v153 offset:16384
	ds_read_b128 v[190:193], v153 offset:17408
	ds_read_b128 v[194:197], v153 offset:18432
	ds_read_b128 v[198:201], v153 offset:19456
	ds_read_b128 v[202:205], v153 offset:20480
	ds_read_b128 v[206:209], v153 offset:21504
	ds_read_b128 v[210:213], v153 offset:22528
	ds_read_b128 v[214:217], v153 offset:23552
	global_load_lds_dwordx4 v[218:219], off
	s_add_i32 m0, s51, 0x2000
	s_add_u32 s52, s28, 0x40000
	v_lshl_add_u64 v[220:221], s[28:29], 0, v[134:135]
	s_addc_u32 s53, s29, 0
	s_add_i32 s51, s46, s35
	global_load_lds_dwordx4 v[220:221], off
	v_lshl_add_u64 v[222:223], s[52:53], 0, v[130:131]
	s_mov_b32 m0, s51
	v_lshl_add_u64 v[224:225], s[30:31], 0, v[132:133]
	global_load_lds_dwordx4 v[222:223], off
	v_lshl_add_u64 v[222:223], s[52:53], 0, v[134:135]
	s_add_i32 m0, s51, 0x2000
	s_nop 0
	global_load_lds_dwordx4 v[222:223], off
	v_lshl_add_u64 v[222:223], s[30:31], 0, v[128:129]
	s_mov_b32 m0, s25
	s_nop 0
	global_load_lds_dwordx4 v[222:223], off
	s_mov_b32 m0, s36
	s_nop 0
	global_load_lds_dwordx4 v[224:225], off
	s_waitcnt vmcnt(8)
	s_waitcnt lgkmcnt(0)
	s_setprio 1
	s_barrier
	v_mfma_f32_16x16x32_bf16 v[60:63], v[144:147], v[184:187], v[60:63]
	v_mfma_f32_16x16x32_bf16 v[56:59], v[160:163], v[184:187], v[56:59]
	v_mfma_f32_16x16x32_bf16 v[44:47], v[144:147], v[194:197], v[44:47]
	v_mfma_f32_16x16x32_bf16 v[40:43], v[160:163], v[194:197], v[40:43]
	v_mfma_f32_16x16x32_bf16 v[28:31], v[144:147], v[202:205], v[28:31]
	v_mfma_f32_16x16x32_bf16 v[24:27], v[160:163], v[202:205], v[24:27]
	v_mfma_f32_16x16x32_bf16 v[12:15], v[144:147], v[210:213], v[12:15]
	v_mfma_f32_16x16x32_bf16 v[8:11], v[160:163], v[210:213], v[8:11]
	v_mfma_f32_16x16x32_bf16 v[60:63], v[156:159], v[190:193], v[60:63]
	v_mfma_f32_16x16x32_bf16 v[56:59], v[164:167], v[190:193], v[56:59]
	v_mfma_f32_16x16x32_bf16 v[44:47], v[156:159], v[198:201], v[44:47]
	v_mfma_f32_16x16x32_bf16 v[40:43], v[164:167], v[198:201], v[40:43]
	v_mfma_f32_16x16x32_bf16 v[28:31], v[156:159], v[206:209], v[28:31]
	v_mfma_f32_16x16x32_bf16 v[24:27], v[164:167], v[206:209], v[24:27]
	v_mfma_f32_16x16x32_bf16 v[12:15], v[156:159], v[214:217], v[12:15]
	v_mfma_f32_16x16x32_bf16 v[8:11], v[164:167], v[214:217], v[8:11]
	v_mfma_f32_16x16x32_bf16 v[52:55], v[168:171], v[184:187], v[52:55]
	v_mfma_f32_16x16x32_bf16 v[48:51], v[176:179], v[184:187], v[48:51]
	v_mfma_f32_16x16x32_bf16 v[36:39], v[168:171], v[194:197], v[36:39]
	v_mfma_f32_16x16x32_bf16 v[32:35], v[176:179], v[194:197], v[32:35]
	v_mfma_f32_16x16x32_bf16 v[20:23], v[168:171], v[202:205], v[20:23]
	v_mfma_f32_16x16x32_bf16 v[16:19], v[176:179], v[202:205], v[16:19]
	v_mfma_f32_16x16x32_bf16 v[4:7], v[168:171], v[210:213], v[4:7]
	v_mfma_f32_16x16x32_bf16 v[0:3], v[176:179], v[210:213], v[0:3]
	v_mfma_f32_16x16x32_bf16 v[52:55], v[172:175], v[190:193], v[52:55]
	v_mfma_f32_16x16x32_bf16 v[48:51], v[180:183], v[190:193], v[48:51]
	v_mfma_f32_16x16x32_bf16 v[36:39], v[172:175], v[198:201], v[36:39]
	v_mfma_f32_16x16x32_bf16 v[32:35], v[180:183], v[198:201], v[32:35]
	v_mfma_f32_16x16x32_bf16 v[20:23], v[172:175], v[206:209], v[20:23]
	v_mfma_f32_16x16x32_bf16 v[16:19], v[180:183], v[206:209], v[16:19]
	v_mfma_f32_16x16x32_bf16 v[4:7], v[172:175], v[214:217], v[4:7]
	v_mfma_f32_16x16x32_bf16 v[0:3], v[180:183], v[214:217], v[0:3]
	s_barrier
; #define PG8_STAGE(bufoff, gbase, voff) do { _Pragma("unroll") for (int _i = 0; _i < 2; ++_i) \
;         __builtin_amdgcn_global_load_lds((const unsigned*)((const char*)(gbase) + (voff)[_i]), (PG8_LAS unsigned*)(lds + (bufoff) + ldsw + _i * 8192), 16, 0, 0); } while (0)
; #define PG8_LDA(dst, b, h) do { _Pragma("unroll") for (int m = 0; m < 4; ++m) _Pragma("unroll") for (int k = 0; k < 2; ++k) dst[m][k] = *(const PG8_LAS bf16x8*)(lds + PG8_SA(b, h) + aoff + m * 2048 + k * 1024); } while (0)
; #define PG8_LDB(dst, b, h) do { _Pragma("unroll") for (int n = 0; n < 2; ++n) _Pragma("unroll") for (int k = 0; k < 2; ++k) dst[n][k] = *(const PG8_LAS bf16x8*)(lds + PG8_SB(b, h) + boff + n * 2048 + k * 1024); } while (0)
; #define PG8_MMA(ai, bj, At, Bt) do { __builtin_amdgcn_s_setprio(1); _Pragma("unroll") for (int m = 0; m < 4; ++m) _Pragma("unroll") for (int n = 0; n < 2; ++n) _Pragma("unroll") for (int k = 0; k < 2; ++k) \
;         acc[ai][bj][m][n] = __builtin_amdgcn_mfma_f32_16x16x32_bf16(Bt[n][k], At[m][k], acc[ai][bj][m][n], 0, 0, 0); __builtin_amdgcn_s_setprio(0); } while (0)
; #define PG8_WAIT_V(n) asm volatile("s_waitcnt vmcnt(" #n ")" ::: "memory")
; #define PG8_WAIT_L(n) asm volatile("s_waitcnt lgkmcnt(" #n ")" ::: "memory")
; #define PG8_BAR __builtin_amdgcn_s_barrier()
; #define PG8_SCHED __builtin_amdgcn_sched_barrier(0)
; template <class Epi, class Sched, bool ALIGN_EPI = false, bool SP2 = false>
; __device__ __forceinline__ void gemm_phase(PG8_LAS unsigned char* lds, const Gemm g, const Sched& S, const Epi& E) {
;     ...
;             PG8_LDB(B0, 1, 0); PG8_LDB(B1, 1, 1); PG8_SCHED; PG8_LDA(At, 1, 0); PG8_STAGE(PG8_SA(0, 1), a2 + hstep, voffA);
;             PG8_WAIT_V(8); PG8_WAIT_L(0); PG8_BAR; PG8_MMA(0, 0, At, B0); PG8_MMA(0, 1, At, B1); PG8_BAR; PG8_SCHED;
	s_setprio 0
	s_add_i32 s51, 0, 0x18000
	v_add_u32_e32 v155, s51, v149
	s_add_i32 s52, 0, 0x1c000
	ds_read_b128 v[144:147], v155
	ds_read_b128 v[156:159], v155 offset:1024
	ds_read_b128 v[160:163], v155 offset:2048
	ds_read_b128 v[164:167], v155 offset:3072
	v_add_u32_e32 v155, s52, v149
	ds_read_b128 v[168:171], v155
	ds_read_b128 v[172:175], v155 offset:1024
	ds_read_b128 v[176:179], v155 offset:2048
	ds_read_b128 v[180:183], v155 offset:3072
	s_add_u32 s30, s30, 0x40000
	s_addc_u32 s31, s31, 0
	s_mov_b32 m0, s37
	v_lshl_add_u64 v[226:227], s[30:31], 0, v[128:129]
	ds_read_b128 v[184:187], v153 offset:32768
	ds_read_b128 v[190:193], v153 offset:33792
	ds_read_b128 v[194:197], v153 offset:34816
	ds_read_b128 v[198:201], v153 offset:35840
	ds_read_b128 v[202:205], v153 offset:36864
	ds_read_b128 v[206:209], v153 offset:37888
	ds_read_b128 v[210:213], v153 offset:38912
	ds_read_b128 v[214:217], v153 offset:39936
	global_load_lds_dwordx4 v[226:227], off
	v_lshl_add_u64 v[226:227], s[30:31], 0, v[132:133]
	s_mov_b32 m0, s38
	s_nop 0
	global_load_lds_dwordx4 v[226:227], off
	s_waitcnt vmcnt(8)
	s_waitcnt lgkmcnt(0)
	s_setprio 1
	s_barrier
	v_mfma_f32_16x16x32_bf16 v[124:127], v[144:147], v[184:187], v[124:127]
	v_mfma_f32_16x16x32_bf16 v[120:123], v[160:163], v[184:187], v[120:123]
	v_mfma_f32_16x16x32_bf16 v[108:111], v[144:147], v[194:197], v[108:111]
	v_mfma_f32_16x16x32_bf16 v[104:107], v[160:163], v[194:197], v[104:107]
	v_mfma_f32_16x16x32_bf16 v[92:95], v[144:147], v[202:205], v[92:95]
	v_mfma_f32_16x16x32_bf16 v[88:91], v[160:163], v[202:205], v[88:91]
	v_mfma_f32_16x16x32_bf16 v[76:79], v[144:147], v[210:213], v[76:79]
	v_mfma_f32_16x16x32_bf16 v[72:75], v[160:163], v[210:213], v[72:75]
	v_mfma_f32_16x16x32_bf16 v[124:127], v[156:159], v[190:193], v[124:127]
	v_mfma_f32_16x16x32_bf16 v[120:123], v[164:167], v[190:193], v[120:123]
	v_mfma_f32_16x16x32_bf16 v[108:111], v[156:159], v[198:201], v[108:111]
	v_mfma_f32_16x16x32_bf16 v[104:107], v[164:167], v[198:201], v[104:107]
	v_mfma_f32_16x16x32_bf16 v[92:95], v[156:159], v[206:209], v[92:95]
	v_mfma_f32_16x16x32_bf16 v[88:91], v[164:167], v[206:209], v[88:91]
	v_mfma_f32_16x16x32_bf16 v[76:79], v[156:159], v[214:217], v[76:79]
	v_mfma_f32_16x16x32_bf16 v[72:75], v[164:167], v[214:217], v[72:75]
	v_mfma_f32_16x16x32_bf16 v[116:119], v[168:171], v[184:187], v[116:119]
	v_mfma_f32_16x16x32_bf16 v[112:115], v[176:179], v[184:187], v[112:115]
	v_mfma_f32_16x16x32_bf16 v[100:103], v[168:171], v[194:197], v[100:103]
	v_mfma_f32_16x16x32_bf16 v[96:99], v[176:179], v[194:197], v[96:99]
	v_mfma_f32_16x16x32_bf16 v[84:87], v[168:171], v[202:205], v[84:87]
	v_mfma_f32_16x16x32_bf16 v[80:83], v[176:179], v[202:205], v[80:83]
	v_mfma_f32_16x16x32_bf16 v[68:71], v[168:171], v[210:213], v[68:71]
	v_mfma_f32_16x16x32_bf16 v[64:67], v[176:179], v[210:213], v[64:67]
	v_mfma_f32_16x16x32_bf16 v[116:119], v[172:175], v[190:193], v[116:119]
	v_mfma_f32_16x16x32_bf16 v[112:115], v[180:183], v[190:193], v[112:115]
	v_mfma_f32_16x16x32_bf16 v[100:103], v[172:175], v[198:201], v[100:103]
	v_mfma_f32_16x16x32_bf16 v[96:99], v[180:183], v[198:201], v[96:99]
	v_mfma_f32_16x16x32_bf16 v[84:87], v[172:175], v[206:209], v[84:87]
	v_mfma_f32_16x16x32_bf16 v[80:83], v[180:183], v[206:209], v[80:83]
	v_mfma_f32_16x16x32_bf16 v[68:71], v[172:175], v[214:217], v[68:71]
	v_mfma_f32_16x16x32_bf16 v[64:67], v[180:183], v[214:217], v[64:67]
	s_barrier
; #define PG8_STAGE(bufoff, gbase, voff) do { _Pragma("unroll") for (int _i = 0; _i < 2; ++_i) \
;         __builtin_amdgcn_global_load_lds((const unsigned*)((const char*)(gbase) + (voff)[_i]), (PG8_LAS unsigned*)(lds + (bufoff) + ldsw + _i * 8192), 16, 0, 0); } while (0)
; #define PG8_LDA(dst, b, h) do { _Pragma("unroll") for (int m = 0; m < 4; ++m) _Pragma("unroll") for (int k = 0; k < 2; ++k) dst[m][k] = *(const PG8_LAS bf16x8*)(lds + PG8_SA(b, h) + aoff + m * 2048 + k * 1024); } while (0)
; #define PG8_MMA(ai, bj, At, Bt) do { __builtin_amdgcn_s_setprio(1); _Pragma("unroll") for (int m = 0; m < 4; ++m) _Pragma("unroll") for (int n = 0; n < 2; ++n) _Pragma("unroll") for (int k = 0; k < 2; ++k) \
;         acc[ai][bj][m][n] = __builtin_amdgcn_mfma_f32_16x16x32_bf16(Bt[n][k], At[m][k], acc[ai][bj][m][n], 0, 0, 0); __builtin_amdgcn_s_setprio(0); } while (0)
; #define PG8_WAIT_V(n) asm volatile("s_waitcnt vmcnt(" #n ")" ::: "memory")
; #define PG8_WAIT_L(n) asm volatile("s_waitcnt lgkmcnt(" #n ")" ::: "memory")
; #define PG8_BAR __builtin_amdgcn_s_barrier()
; #define PG8_SCHED __builtin_amdgcn_sched_barrier(0)
; template <class Epi, class Sched, bool ALIGN_EPI = false, bool SP2 = false>
; __device__ __forceinline__ void gemm_phase(PG8_LAS unsigned char* lds, const Gemm g, const Sched& S, const Epi& E) {
;     ...
;             PG8_LDA(At, 1, 1); PG8_STAGE(PG8_SB(1, 0), b3, voffB); PG8_STAGE(PG8_SB(1, 1), b3 + hstep, voffB); PG8_STAGE(PG8_SA(1, 0), a3, voffA);
;             PG8_WAIT_V(8); PG8_WAIT_L(0); PG8_BAR; PG8_MMA(1, 0, At, B0); PG8_MMA(1, 1, At, B1); PG8_BAR; PG8_SCHED;
;     ...
;         if constexpr (ALIGN_EPI) { if (wr == 0) PG8_BAR; }
	s_setprio 0
	s_add_i32 s30, s51, s35
	v_lshl_add_u64 v[218:219], v[218:219], 0, s[2:3]
	s_mov_b32 m0, s30
	ds_read_b128 v[184:187], v153 offset:49152
	ds_read_b128 v[190:193], v153 offset:50176
	ds_read_b128 v[194:197], v153 offset:51200
	ds_read_b128 v[198:201], v153 offset:52224
	ds_read_b128 v[202:205], v153 offset:53248
	ds_read_b128 v[206:209], v153 offset:54272
	ds_read_b128 v[210:213], v153 offset:55296
	ds_read_b128 v[214:217], v153 offset:56320
	global_load_lds_dwordx4 v[218:219], off
	s_add_i32 m0, s30, 0x2000
	s_add_u32 s28, s28, 0x40080
	v_lshl_add_u64 v[218:219], v[220:221], 0, s[2:3]
	s_addc_u32 s29, s29, 0
	s_add_i32 s30, s52, s35
	global_load_lds_dwordx4 v[218:219], off
	v_lshl_add_u64 v[218:219], s[28:29], 0, v[130:131]
	s_mov_b32 m0, s30
	s_nop 0
	global_load_lds_dwordx4 v[218:219], off
	v_lshl_add_u64 v[218:219], s[28:29], 0, v[134:135]
	s_add_i32 m0, s30, 0x2000
	s_nop 0
	global_load_lds_dwordx4 v[218:219], off
	v_lshl_add_u64 v[218:219], v[222:223], 0, s[2:3]
	s_mov_b32 m0, s40
	s_nop 0
	global_load_lds_dwordx4 v[218:219], off
	v_lshl_add_u64 v[218:219], v[224:225], 0, s[2:3]
	s_mov_b32 m0, s41
	s_nop 0
	global_load_lds_dwordx4 v[218:219], off
	s_waitcnt vmcnt(8)
	s_waitcnt lgkmcnt(0)
	s_setprio 1
	s_barrier
	v_mfma_f32_16x16x32_bf16 v[60:63], v[144:147], v[184:187], v[60:63]
	v_mfma_f32_16x16x32_bf16 v[56:59], v[160:163], v[184:187], v[56:59]
	v_mfma_f32_16x16x32_bf16 v[44:47], v[144:147], v[194:197], v[44:47]
	v_mfma_f32_16x16x32_bf16 v[40:43], v[160:163], v[194:197], v[40:43]
	v_mfma_f32_16x16x32_bf16 v[28:31], v[144:147], v[202:205], v[28:31]
	v_mfma_f32_16x16x32_bf16 v[24:27], v[160:163], v[202:205], v[24:27]
	v_mfma_f32_16x16x32_bf16 v[12:15], v[144:147], v[210:213], v[12:15]
	v_mfma_f32_16x16x32_bf16 v[8:11], v[160:163], v[210:213], v[8:11]
	v_mfma_f32_16x16x32_bf16 v[60:63], v[156:159], v[190:193], v[60:63]
	v_mfma_f32_16x16x32_bf16 v[56:59], v[164:167], v[190:193], v[56:59]
	v_mfma_f32_16x16x32_bf16 v[44:47], v[156:159], v[198:201], v[44:47]
	v_mfma_f32_16x16x32_bf16 v[40:43], v[164:167], v[198:201], v[40:43]
	v_mfma_f32_16x16x32_bf16 v[28:31], v[156:159], v[206:209], v[28:31]
	v_mfma_f32_16x16x32_bf16 v[24:27], v[164:167], v[206:209], v[24:27]
	v_mfma_f32_16x16x32_bf16 v[12:15], v[156:159], v[214:217], v[12:15]
	v_mfma_f32_16x16x32_bf16 v[8:11], v[164:167], v[214:217], v[8:11]
	v_mfma_f32_16x16x32_bf16 v[52:55], v[168:171], v[184:187], v[52:55]
	v_mfma_f32_16x16x32_bf16 v[48:51], v[176:179], v[184:187], v[48:51]
	v_mfma_f32_16x16x32_bf16 v[36:39], v[168:171], v[194:197], v[36:39]
	v_mfma_f32_16x16x32_bf16 v[32:35], v[176:179], v[194:197], v[32:35]
	v_mfma_f32_16x16x32_bf16 v[20:23], v[168:171], v[202:205], v[20:23]
	v_mfma_f32_16x16x32_bf16 v[16:19], v[176:179], v[202:205], v[16:19]
	v_mfma_f32_16x16x32_bf16 v[4:7], v[168:171], v[210:213], v[4:7]
	v_mfma_f32_16x16x32_bf16 v[0:3], v[176:179], v[210:213], v[0:3]
	v_mfma_f32_16x16x32_bf16 v[52:55], v[172:175], v[190:193], v[52:55]
	v_mfma_f32_16x16x32_bf16 v[48:51], v[180:183], v[190:193], v[48:51]
	v_mfma_f32_16x16x32_bf16 v[36:39], v[172:175], v[198:201], v[36:39]
	v_mfma_f32_16x16x32_bf16 v[32:35], v[180:183], v[198:201], v[32:35]
	v_mfma_f32_16x16x32_bf16 v[20:23], v[172:175], v[206:209], v[20:23]
	v_mfma_f32_16x16x32_bf16 v[16:19], v[180:183], v[206:209], v[16:19]
	v_mfma_f32_16x16x32_bf16 v[4:7], v[172:175], v[214:217], v[4:7]
	v_mfma_f32_16x16x32_bf16 v[0:3], v[180:183], v[214:217], v[0:3]
	s_barrier
	s_setprio 0
	s_add_i32 s50, s50, 2
	s_add_u32 s26, s26, 0x100
	s_addc_u32 s27, s27, 0
	s_add_u32 s48, s48, 0x100
	s_addc_u32 s49, s49, 0
	s_cmp_gt_u32 s50, 13
	s_cbranch_scc0 .LBB0_698
	s_and_b64 vcc, exec, s[12:13]
	s_cbranch_vccz .LBB0_701
	s_barrier

; #define PG8_STAGE(bufoff, gbase, voff) do { _Pragma("unroll") for (int _i = 0; _i < 2; ++_i) \
;         __builtin_amdgcn_global_load_lds((const unsigned*)((const char*)(gbase) + (voff)[_i]), (PG8_LAS unsigned*)(lds + (bufoff) + ldsw + _i * 8192), 16, 0, 0); } while (0)
; #define PG8_LDA(dst, b, h) do { _Pragma("unroll") for (int m = 0; m < 4; ++m) _Pragma("unroll") for (int k = 0; k < 2; ++k) dst[m][k] = *(const PG8_LAS bf16x8*)(lds + PG8_SA(b, h) + aoff + m * 2048 + k * 1024); } while (0)
; #define PG8_LDB(dst, b, h) do { _Pragma("unroll") for (int n = 0; n < 2; ++n) _Pragma("unroll") for (int k = 0; k < 2; ++k) dst[n][k] = *(const PG8_LAS bf16x8*)(lds + PG8_SB(b, h) + boff + n * 2048 + k * 1024); } while (0)
; #define PG8_WAIT_V(n) asm volatile("s_waitcnt vmcnt(" #n ")" ::: "memory")
; #define PG8_WAIT_L(n) asm volatile("s_waitcnt lgkmcnt(" #n ")" ::: "memory")
; #define PG8_BAR __builtin_amdgcn_s_barrier()
; #define PG8_SCHED __builtin_amdgcn_sched_barrier(0)
; template <class Epi, class Sched, bool ALIGN_EPI = false, bool SP2 = false>
; __device__ __forceinline__ void gemm_phase(PG8_LAS unsigned char* lds, const Gemm g, const Sched& S, const Epi& E) {
;     ...
;         const bool has_next = S.next(ui + 1, nxt);
;         const char* nA = has_next ? (const char*)g.A + (size_t)nxt.pm * tstep : cA; const char* nB = has_next ? (const char*)g.Bt + (size_t)nxt.pn * tstep : cB;
;         for (int t = 0; t < nt; t += 2) {
;             const bool last = (t == nt - 2);
;             const char* a1 = cA + (size_t)(t + 1) * kstep;
;             const char* a2 = last ? nA : cA + (size_t)(t + 2) * kstep; const char* b2 = last ? nB : cB + (size_t)(t + 2) * kstep;
;             const char* a3 = a2 + kstep; const char* b3 = b2 + kstep;
;             if (last && has_next) S.a_ready(nxt);
;             if constexpr (SP2) {
;             PG8_LDB(B0, 0, 0); PG8_LDB(B1, 0, 1); PG8_SCHED; PG8_LDA(At, 0, 0); PG8_STAGE(PG8_SA(1, 1), a1 + hstep, voffA);
;             PG8_WAIT_V(8); PG8_WAIT_L(0); PG8_BAR; PG8_MMA(0, 0, At, B0); PG8_MMA(0, 1, At, B1); PG8_BAR; PG8_SCHED;
;             PG8_LDA(At, 0, 1); PG8_STAGE(PG8_SB(0, 0), b2, voffB); PG8_STAGE(PG8_SB(0, 1), b2 + hstep, voffB); PG8_STAGE(PG8_SA(0, 0), a2, voffA);
;             PG8_WAIT_V(8); PG8_WAIT_L(0); PG8_BAR; PG8_MMA(1, 0, At, B0); PG8_MMA(1, 1, At, B1); PG8_BAR; PG8_SCHED;
.LBB0_781:
	s_ashr_i32 s17, s16, 31
	s_lshl_b64 s[18:19], s[16:17], 19
	s_add_u32 s18, s8, s18
	s_addc_u32 s19, s9, s19
	s_and_b64 s[20:21], s[4:5], exec
	s_cselect_b32 s17, s19, s23
	s_cselect_b32 s47, s18, s22
	s_ashr_i32 s15, s14, 31
	s_lshl_b64 s[20:21], s[14:15], 19
	s_add_u32 s20, s28, s20
	s_addc_u32 s21, s29, s21
	s_and_b64 s[26:27], s[4:5], exec
	s_cselect_b32 s15, s21, s25
	s_cselect_b32 s48, s20, s24
	s_add_u32 s22, s22, 0x40080
	s_addc_u32 s23, s23, 0
	s_add_u32 s49, s24, 0x100
	s_addc_u32 s50, s25, 0
	s_mov_b32 s51, -2
	ds_read_b128 v[144:147], v151
	ds_read_b128 v[156:159], v151 offset:1024
	ds_read_b128 v[160:163], v151 offset:2048
	ds_read_b128 v[164:167], v151 offset:3072
	ds_read_b128 v[168:171], v152
	ds_read_b128 v[172:175], v152 offset:1024
	ds_read_b128 v[176:179], v152 offset:2048
	ds_read_b128 v[180:183], v152 offset:3072
	s_add_u32 s24, s22, 0xfffc0080
	s_addc_u32 s25, s23, -1
	s_cmp_eq_u32 s51, 12
	s_cselect_b32 s27, s17, s25
	s_cselect_b32 s26, s47, s24
	s_cselect_b32 s25, s15, s50
	s_cselect_b32 s24, s48, s49
	v_lshl_add_u64 v[218:219], s[22:23], 0, v[136:137]
	s_add_i32 m0, s34, 0xc000
	ds_read_b128 v[184:187], v153
	ds_read_b128 v[190:193], v153 offset:1024
	ds_read_b128 v[194:197], v153 offset:2048
	ds_read_b128 v[198:201], v153 offset:3072
	ds_read_b128 v[202:205], v153 offset:4096
	ds_read_b128 v[206:209], v153 offset:5120
	ds_read_b128 v[210:213], v153 offset:6144
	ds_read_b128 v[214:217], v153 offset:7168
	global_load_lds_dwordx4 v[218:219], off
	v_lshl_add_u64 v[218:219], s[22:23], 0, v[138:139]
	s_add_i32 m0, s34, 0xe000
	s_nop 0
	global_load_lds_dwordx4 v[218:219], off
	s_waitcnt vmcnt(16)
	s_waitcnt lgkmcnt(0)
	s_setprio 1
	s_barrier
	v_mfma_f32_16x16x32_bf16 v[116:119], v[144:147], v[184:187], 0
	v_mfma_f32_16x16x32_bf16 v[112:115], v[160:163], v[184:187], 0
	v_mfma_f32_16x16x32_bf16 v[100:103], v[144:147], v[194:197], 0
	v_mfma_f32_16x16x32_bf16 v[96:99], v[160:163], v[194:197], 0
	v_mfma_f32_16x16x32_bf16 v[84:87], v[144:147], v[202:205], 0
	v_mfma_f32_16x16x32_bf16 v[80:83], v[160:163], v[202:205], 0
	v_mfma_f32_16x16x32_bf16 v[72:75], v[144:147], v[210:213], 0
	v_mfma_f32_16x16x32_bf16 v[64:67], v[160:163], v[210:213], 0
	v_mfma_f32_16x16x32_bf16 v[116:119], v[156:159], v[190:193], v[116:119]
	v_mfma_f32_16x16x32_bf16 v[112:115], v[164:167], v[190:193], v[112:115]
	v_mfma_f32_16x16x32_bf16 v[100:103], v[156:159], v[198:201], v[100:103]
	v_mfma_f32_16x16x32_bf16 v[96:99], v[164:167], v[198:201], v[96:99]
	v_mfma_f32_16x16x32_bf16 v[84:87], v[156:159], v[206:209], v[84:87]
	v_mfma_f32_16x16x32_bf16 v[80:83], v[164:167], v[206:209], v[80:83]
	v_mfma_f32_16x16x32_bf16 v[72:75], v[156:159], v[214:217], v[72:75]
	v_mfma_f32_16x16x32_bf16 v[64:67], v[164:167], v[214:217], v[64:67]
	v_mfma_f32_16x16x32_bf16 v[124:127], v[168:171], v[184:187], 0
	v_mfma_f32_16x16x32_bf16 v[120:123], v[176:179], v[184:187], 0
	v_mfma_f32_16x16x32_bf16 v[108:111], v[168:171], v[194:197], 0
	v_mfma_f32_16x16x32_bf16 v[104:107], v[176:179], v[194:197], 0
	v_mfma_f32_16x16x32_bf16 v[92:95], v[168:171], v[202:205], 0
	v_mfma_f32_16x16x32_bf16 v[88:91], v[176:179], v[202:205], 0
	v_mfma_f32_16x16x32_bf16 v[76:79], v[168:171], v[210:213], 0
	v_mfma_f32_16x16x32_bf16 v[68:71], v[176:179], v[210:213], 0
	v_mfma_f32_16x16x32_bf16 v[124:127], v[172:175], v[190:193], v[124:127]
	v_mfma_f32_16x16x32_bf16 v[120:123], v[180:183], v[190:193], v[120:123]
	v_mfma_f32_16x16x32_bf16 v[108:111], v[172:175], v[198:201], v[108:111]
	v_mfma_f32_16x16x32_bf16 v[104:107], v[180:183], v[198:201], v[104:107]
	v_mfma_f32_16x16x32_bf16 v[92:95], v[172:175], v[206:209], v[92:95]
	v_mfma_f32_16x16x32_bf16 v[88:91], v[180:183], v[206:209], v[88:91]
	v_mfma_f32_16x16x32_bf16 v[76:79], v[172:175], v[214:217], v[76:79]
	v_mfma_f32_16x16x32_bf16 v[68:71], v[180:183], v[214:217], v[68:71]
	s_barrier
	s_setprio 0
	s_add_i32 s52, s43, s30
	v_lshl_add_u64 v[218:219], s[24:25], 0, v[132:133]
	s_mov_b32 m0, s52
	ds_read_b128 v[184:187], v153 offset:16384
	ds_read_b128 v[190:193], v153 offset:17408
	ds_read_b128 v[194:197], v153 offset:18432
	ds_read_b128 v[198:201], v153 offset:19456
	ds_read_b128 v[202:205], v153 offset:20480
	ds_read_b128 v[206:209], v153 offset:21504
	ds_read_b128 v[210:213], v153 offset:22528
	ds_read_b128 v[214:217], v153 offset:23552
	global_load_lds_dwordx4 v[218:219], off
	s_add_i32 m0, s52, 0x2000
	s_add_u32 s52, s24, 0x40000
	v_lshl_add_u64 v[220:221], s[24:25], 0, v[128:129]
	s_addc_u32 s53, s25, 0
	s_add_i32 s54, s44, s30
	global_load_lds_dwordx4 v[220:221], off
	v_lshl_add_u64 v[222:223], s[52:53], 0, v[132:133]
	s_mov_b32 m0, s54
	v_lshl_add_u64 v[224:225], s[26:27], 0, v[130:131]
	global_load_lds_dwordx4 v[222:223], off
	v_lshl_add_u64 v[222:223], s[52:53], 0, v[128:129]
	s_add_i32 m0, s54, 0x2000
	s_nop 0
	global_load_lds_dwordx4 v[222:223], off
	v_lshl_add_u64 v[222:223], s[26:27], 0, v[134:135]
	s_mov_b32 m0, s34
	s_nop 0
	global_load_lds_dwordx4 v[222:223], off
	s_mov_b32 m0, s35
	s_nop 0
	global_load_lds_dwordx4 v[224:225], off
	s_waitcnt vmcnt(16)
	s_waitcnt lgkmcnt(0)
	s_setprio 1
	s_barrier
; #define PG8_STAGE(bufoff, gbase, voff) do { _Pragma("unroll") for (int _i = 0; _i < 2; ++_i) \
;         __builtin_amdgcn_global_load_lds((const unsigned*)((const char*)(gbase) + (voff)[_i]), (PG8_LAS unsigned*)(lds + (bufoff) + ldsw + _i * 8192), 16, 0, 0); } while (0)
; #define PG8_LDA(dst, b, h) do { _Pragma("unroll") for (int m = 0; m < 4; ++m) _Pragma("unroll") for (int k = 0; k < 2; ++k) dst[m][k] = *(const PG8_LAS bf16x8*)(lds + PG8_SA(b, h) + aoff + m * 2048 + k * 1024); } while (0)
; #define PG8_LDB(dst, b, h) do { _Pragma("unroll") for (int n = 0; n < 2; ++n) _Pragma("unroll") for (int k = 0; k < 2; ++k) dst[n][k] = *(const PG8_LAS bf16x8*)(lds + PG8_SB(b, h) + boff + n * 2048 + k * 1024); } while (0)
; #define PG8_MMA(ai, bj, At, Bt) do { __builtin_amdgcn_s_setprio(1); _Pragma("unroll") for (int m = 0; m < 4; ++m) _Pragma("unroll") for (int n = 0; n < 2; ++n) _Pragma("unroll") for (int k = 0; k < 2; ++k) \
;         acc[ai][bj][m][n] = __builtin_amdgcn_mfma_f32_16x16x32_bf16(Bt[n][k], At[m][k], acc[ai][bj][m][n], 0, 0, 0); __builtin_amdgcn_s_setprio(0); } while (0)
; #define PG8_WAIT_V(n) asm volatile("s_waitcnt vmcnt(" #n ")" ::: "memory")
; #define PG8_WAIT_L(n) asm volatile("s_waitcnt lgkmcnt(" #n ")" ::: "memory")
; #define PG8_BAR __builtin_amdgcn_s_barrier()
; #define PG8_SCHED __builtin_amdgcn_sched_barrier(0)
; template <class Epi, class Sched, bool ALIGN_EPI = false, bool SP2 = false>
; __device__ __forceinline__ void gemm_phase(PG8_LAS unsigned char* lds, const Gemm g, const Sched& S, const Epi& E) {
;     ...
;             PG8_WAIT_V(8); PG8_WAIT_L(0); PG8_BAR; PG8_MMA(1, 0, At, B0); PG8_MMA(1, 1, At, B1); PG8_BAR; PG8_SCHED;
;             PG8_LDB(B0, 1, 0); PG8_LDB(B1, 1, 1); PG8_SCHED; PG8_LDA(At, 1, 0); PG8_STAGE(PG8_SA(0, 1), a2 + hstep, voffA);
;             PG8_WAIT_V(8); PG8_WAIT_L(0); PG8_BAR; PG8_MMA(0, 0, At, B0); PG8_MMA(0, 1, At, B1); PG8_BAR; PG8_SCHED;
	v_mfma_f32_16x16x32_bf16 v[56:59], v[144:147], v[184:187], 0
	v_mfma_f32_16x16x32_bf16 v[48:51], v[160:163], v[184:187], 0
	v_mfma_f32_16x16x32_bf16 v[40:43], v[144:147], v[194:197], 0
	v_mfma_f32_16x16x32_bf16 v[32:35], v[160:163], v[194:197], 0
	v_mfma_f32_16x16x32_bf16 v[24:27], v[144:147], v[202:205], 0
	v_mfma_f32_16x16x32_bf16 v[16:19], v[160:163], v[202:205], 0
	v_mfma_f32_16x16x32_bf16 v[8:11], v[144:147], v[210:213], 0
	v_mfma_f32_16x16x32_bf16 v[0:3], v[160:163], v[210:213], 0
	v_mfma_f32_16x16x32_bf16 v[56:59], v[156:159], v[190:193], v[56:59]
	v_mfma_f32_16x16x32_bf16 v[48:51], v[164:167], v[190:193], v[48:51]
	v_mfma_f32_16x16x32_bf16 v[40:43], v[156:159], v[198:201], v[40:43]
	v_mfma_f32_16x16x32_bf16 v[32:35], v[164:167], v[198:201], v[32:35]
	v_mfma_f32_16x16x32_bf16 v[24:27], v[156:159], v[206:209], v[24:27]
	v_mfma_f32_16x16x32_bf16 v[16:19], v[164:167], v[206:209], v[16:19]
	v_mfma_f32_16x16x32_bf16 v[8:11], v[156:159], v[214:217], v[8:11]
	v_mfma_f32_16x16x32_bf16 v[0:3], v[164:167], v[214:217], v[0:3]
	v_mfma_f32_16x16x32_bf16 v[60:63], v[168:171], v[184:187], 0
	v_mfma_f32_16x16x32_bf16 v[52:55], v[176:179], v[184:187], 0
	v_mfma_f32_16x16x32_bf16 v[44:47], v[168:171], v[194:197], 0
	v_mfma_f32_16x16x32_bf16 v[36:39], v[176:179], v[194:197], 0
	v_mfma_f32_16x16x32_bf16 v[28:31], v[168:171], v[202:205], 0
	v_mfma_f32_16x16x32_bf16 v[20:23], v[176:179], v[202:205], 0
	v_mfma_f32_16x16x32_bf16 v[12:15], v[168:171], v[210:213], 0
	v_mfma_f32_16x16x32_bf16 v[4:7], v[176:179], v[210:213], 0
	v_mfma_f32_16x16x32_bf16 v[60:63], v[172:175], v[190:193], v[60:63]
	v_mfma_f32_16x16x32_bf16 v[52:55], v[180:183], v[190:193], v[52:55]
	v_mfma_f32_16x16x32_bf16 v[44:47], v[172:175], v[198:201], v[44:47]
	v_mfma_f32_16x16x32_bf16 v[36:39], v[180:183], v[198:201], v[36:39]
	v_mfma_f32_16x16x32_bf16 v[28:31], v[172:175], v[206:209], v[28:31]
	v_mfma_f32_16x16x32_bf16 v[20:23], v[180:183], v[206:209], v[20:23]
	v_mfma_f32_16x16x32_bf16 v[12:15], v[172:175], v[214:217], v[12:15]
	v_mfma_f32_16x16x32_bf16 v[4:7], v[180:183], v[214:217], v[4:7]
	s_barrier
	s_setprio 0
	s_add_i32 s52, 0, 0x18000
	v_add_u32_e32 v155, s52, v149
	s_add_i32 s53, 0, 0x1c000
	ds_read_b128 v[144:147], v155
	ds_read_b128 v[156:159], v155 offset:1024
	ds_read_b128 v[160:163], v155 offset:2048
	ds_read_b128 v[164:167], v155 offset:3072
	v_add_u32_e32 v155, s53, v149
	ds_read_b128 v[168:171], v155
	ds_read_b128 v[172:175], v155 offset:1024
	ds_read_b128 v[176:179], v155 offset:2048
	ds_read_b128 v[180:183], v155 offset:3072
	s_add_u32 s26, s26, 0x40000
	s_addc_u32 s27, s27, 0
	s_mov_b32 m0, s36
	v_lshl_add_u64 v[226:227], s[26:27], 0, v[134:135]
	ds_read_b128 v[184:187], v153 offset:32768
	ds_read_b128 v[190:193], v153 offset:33792
	ds_read_b128 v[194:197], v153 offset:34816
	ds_read_b128 v[198:201], v153 offset:35840
	ds_read_b128 v[202:205], v153 offset:36864
	ds_read_b128 v[206:209], v153 offset:37888
	ds_read_b128 v[210:213], v153 offset:38912
	ds_read_b128 v[214:217], v153 offset:39936
	global_load_lds_dwordx4 v[226:227], off
	v_lshl_add_u64 v[226:227], s[26:27], 0, v[130:131]
	s_mov_b32 m0, s37
	s_nop 0
	global_load_lds_dwordx4 v[226:227], off
	s_waitcnt vmcnt(8)
	s_waitcnt lgkmcnt(0)
	s_setprio 1
	s_barrier
	v_mfma_f32_16x16x32_bf16 v[116:119], v[144:147], v[184:187], v[116:119]
	v_mfma_f32_16x16x32_bf16 v[112:115], v[160:163], v[184:187], v[112:115]
	v_mfma_f32_16x16x32_bf16 v[100:103], v[144:147], v[194:197], v[100:103]
	v_mfma_f32_16x16x32_bf16 v[96:99], v[160:163], v[194:197], v[96:99]
	v_mfma_f32_16x16x32_bf16 v[84:87], v[144:147], v[202:205], v[84:87]
	v_mfma_f32_16x16x32_bf16 v[80:83], v[160:163], v[202:205], v[80:83]
	v_mfma_f32_16x16x32_bf16 v[72:75], v[144:147], v[210:213], v[72:75]
	v_mfma_f32_16x16x32_bf16 v[64:67], v[160:163], v[210:213], v[64:67]
	v_mfma_f32_16x16x32_bf16 v[116:119], v[156:159], v[190:193], v[116:119]
	v_mfma_f32_16x16x32_bf16 v[112:115], v[164:167], v[190:193], v[112:115]
	v_mfma_f32_16x16x32_bf16 v[100:103], v[156:159], v[198:201], v[100:103]
	v_mfma_f32_16x16x32_bf16 v[96:99], v[164:167], v[198:201], v[96:99]
	v_mfma_f32_16x16x32_bf16 v[84:87], v[156:159], v[206:209], v[84:87]
	v_mfma_f32_16x16x32_bf16 v[80:83], v[164:167], v[206:209], v[80:83]
	v_mfma_f32_16x16x32_bf16 v[72:75], v[156:159], v[214:217], v[72:75]
	v_mfma_f32_16x16x32_bf16 v[64:67], v[164:167], v[214:217], v[64:67]
	v_mfma_f32_16x16x32_bf16 v[124:127], v[168:171], v[184:187], v[124:127]
	v_mfma_f32_16x16x32_bf16 v[120:123], v[176:179], v[184:187], v[120:123]
	v_mfma_f32_16x16x32_bf16 v[108:111], v[168:171], v[194:197], v[108:111]
	v_mfma_f32_16x16x32_bf16 v[104:107], v[176:179], v[194:197], v[104:107]
	v_mfma_f32_16x16x32_bf16 v[92:95], v[168:171], v[202:205], v[92:95]
	v_mfma_f32_16x16x32_bf16 v[88:91], v[176:179], v[202:205], v[88:91]
	v_mfma_f32_16x16x32_bf16 v[76:79], v[168:171], v[210:213], v[76:79]
	v_mfma_f32_16x16x32_bf16 v[68:71], v[176:179], v[210:213], v[68:71]
	v_mfma_f32_16x16x32_bf16 v[124:127], v[172:175], v[190:193], v[124:127]
	v_mfma_f32_16x16x32_bf16 v[120:123], v[180:183], v[190:193], v[120:123]
	v_mfma_f32_16x16x32_bf16 v[108:111], v[172:175], v[198:201], v[108:111]
	v_mfma_f32_16x16x32_bf16 v[104:107], v[180:183], v[198:201], v[104:107]
	v_mfma_f32_16x16x32_bf16 v[92:95], v[172:175], v[206:209], v[92:95]
	v_mfma_f32_16x16x32_bf16 v[88:91], v[180:183], v[206:209], v[88:91]
	v_mfma_f32_16x16x32_bf16 v[76:79], v[172:175], v[214:217], v[76:79]
	v_mfma_f32_16x16x32_bf16 v[68:71], v[180:183], v[214:217], v[68:71]
	s_barrier
; #define PG8_STAGE(bufoff, gbase, voff) do { _Pragma("unroll") for (int _i = 0; _i < 2; ++_i) \
;         __builtin_amdgcn_global_load_lds((const unsigned*)((const char*)(gbase) + (voff)[_i]), (PG8_LAS unsigned*)(lds + (bufoff) + ldsw + _i * 8192), 16, 0, 0); } while (0)
; #define PG8_LDA(dst, b, h) do { _Pragma("unroll") for (int m = 0; m < 4; ++m) _Pragma("unroll") for (int k = 0; k < 2; ++k) dst[m][k] = *(const PG8_LAS bf16x8*)(lds + PG8_SA(b, h) + aoff + m * 2048 + k * 1024); } while (0)
; #define PG8_LDB(dst, b, h) do { _Pragma("unroll") for (int n = 0; n < 2; ++n) _Pragma("unroll") for (int k = 0; k < 2; ++k) dst[n][k] = *(const PG8_LAS bf16x8*)(lds + PG8_SB(b, h) + boff + n * 2048 + k * 1024); } while (0)
; #define PG8_BAR __builtin_amdgcn_s_barrier()
; template <class Epi, class Sched, bool ALIGN_EPI = false, bool SP2 = false>
; __device__ __forceinline__ void gemm_phase(PG8_LAS unsigned char* lds, const Gemm g, const Sched& S, const Epi& E) {
;     ...
;             const bool last = (t == nt - 2);
;             const char* a1 = cA + (size_t)(t + 1) * kstep;
;             const char* a2 = last ? nA : cA + (size_t)(t + 2) * kstep; const char* b2 = last ? nB : cB + (size_t)(t + 2) * kstep;
;             const char* a3 = a2 + kstep; const char* b3 = b2 + kstep;
;             if (last && has_next) S.a_ready(nxt);
;             if constexpr (SP2) {
;             PG8_LDB(B0, 0, 0); PG8_LDB(B1, 0, 1); PG8_SCHED; PG8_LDA(At, 0, 0); PG8_STAGE(PG8_SA(1, 1), a1 + hstep, voffA);
;             PG8_WAIT_V(8); PG8_WAIT_L(0); PG8_BAR; PG8_MMA(0, 0, At, B0); PG8_MMA(0, 1, At, B1); PG8_BAR; PG8_SCHED;
;             PG8_LDA(At, 0, 1); PG8_STAGE(PG8_SB(0, 0), b2, voffB); PG8_STAGE(PG8_SB(0, 1), b2 + hstep, voffB); PG8_STAGE(PG8_SA(0, 0), a2, voffA);
;             PG8_WAIT_V(8); PG8_WAIT_L(0); PG8_BAR; PG8_MMA(1, 0, At, B0); PG8_MMA(1, 1, At, B1); PG8_BAR; PG8_SCHED;
;             PG8_LDB(B0, 1, 0); PG8_LDB(B1, 1, 1); PG8_SCHED; PG8_LDA(At, 1, 0); PG8_STAGE(PG8_SA(0, 1), a2 + hstep, voffA);
;             PG8_WAIT_V(8); PG8_WAIT_L(0); PG8_BAR; PG8_MMA(0, 0, At, B0); PG8_MMA(0, 1, At, B1); PG8_BAR; PG8_SCHED;
;             PG8_LDA(At, 1, 1); PG8_STAGE(PG8_SB(1, 0), b3, voffB); PG8_STAGE(PG8_SB(1, 1), b3 + hstep, voffB); PG8_STAGE(PG8_SA(1, 0), a3, voffA);
;             PG8_WAIT_V(8); PG8_WAIT_L(0); PG8_BAR; PG8_MMA(1, 0, At, B0); PG8_MMA(1, 1, At, B1); PG8_BAR; PG8_SCHED;
	s_setprio 0
	s_add_i32 s26, s52, s30
	v_lshl_add_u64 v[218:219], v[218:219], 0, s[6:7]
	s_mov_b32 m0, s26
	ds_read_b128 v[184:187], v153 offset:49152
	ds_read_b128 v[190:193], v153 offset:50176
	ds_read_b128 v[194:197], v153 offset:51200
	ds_read_b128 v[198:201], v153 offset:52224
	ds_read_b128 v[202:205], v153 offset:53248
	ds_read_b128 v[206:209], v153 offset:54272
	ds_read_b128 v[210:213], v153 offset:55296
	ds_read_b128 v[214:217], v153 offset:56320
	global_load_lds_dwordx4 v[218:219], off
	s_add_i32 m0, s26, 0x2000
	s_add_u32 s24, s24, 0x40080
	v_lshl_add_u64 v[218:219], v[220:221], 0, s[6:7]
	s_addc_u32 s25, s25, 0
	s_add_i32 s26, s53, s30
	global_load_lds_dwordx4 v[218:219], off
	v_lshl_add_u64 v[218:219], s[24:25], 0, v[132:133]
	s_mov_b32 m0, s26
	s_nop 0
	global_load_lds_dwordx4 v[218:219], off
	v_lshl_add_u64 v[218:219], s[24:25], 0, v[128:129]
	s_add_i32 m0, s26, 0x2000
	s_nop 0
	global_load_lds_dwordx4 v[218:219], off
	v_lshl_add_u64 v[218:219], v[222:223], 0, s[6:7]
	s_mov_b32 m0, s39
	s_nop 0
	global_load_lds_dwordx4 v[218:219], off
	v_lshl_add_u64 v[218:219], v[224:225], 0, s[6:7]
	s_mov_b32 m0, s40
	s_nop 0
	global_load_lds_dwordx4 v[218:219], off
	s_waitcnt vmcnt(8)
	s_waitcnt lgkmcnt(0)
	s_setprio 1
	s_barrier
	v_mfma_f32_16x16x32_bf16 v[56:59], v[144:147], v[184:187], v[56:59]
	v_mfma_f32_16x16x32_bf16 v[48:51], v[160:163], v[184:187], v[48:51]
	v_mfma_f32_16x16x32_bf16 v[40:43], v[144:147], v[194:197], v[40:43]
	v_mfma_f32_16x16x32_bf16 v[32:35], v[160:163], v[194:197], v[32:35]
	v_mfma_f32_16x16x32_bf16 v[24:27], v[144:147], v[202:205], v[24:27]
	v_mfma_f32_16x16x32_bf16 v[16:19], v[160:163], v[202:205], v[16:19]
	v_mfma_f32_16x16x32_bf16 v[8:11], v[144:147], v[210:213], v[8:11]
	v_mfma_f32_16x16x32_bf16 v[0:3], v[160:163], v[210:213], v[0:3]
	v_mfma_f32_16x16x32_bf16 v[56:59], v[156:159], v[190:193], v[56:59]
	v_mfma_f32_16x16x32_bf16 v[48:51], v[164:167], v[190:193], v[48:51]
	v_mfma_f32_16x16x32_bf16 v[40:43], v[156:159], v[198:201], v[40:43]
	v_mfma_f32_16x16x32_bf16 v[32:35], v[164:167], v[198:201], v[32:35]
	v_mfma_f32_16x16x32_bf16 v[24:27], v[156:159], v[206:209], v[24:27]
	v_mfma_f32_16x16x32_bf16 v[16:19], v[164:167], v[206:209], v[16:19]
	v_mfma_f32_16x16x32_bf16 v[8:11], v[156:159], v[214:217], v[8:11]
	v_mfma_f32_16x16x32_bf16 v[0:3], v[164:167], v[214:217], v[0:3]
	v_mfma_f32_16x16x32_bf16 v[60:63], v[168:171], v[184:187], v[60:63]
	v_mfma_f32_16x16x32_bf16 v[52:55], v[176:179], v[184:187], v[52:55]
	v_mfma_f32_16x16x32_bf16 v[44:47], v[168:171], v[194:197], v[44:47]
	v_mfma_f32_16x16x32_bf16 v[36:39], v[176:179], v[194:197], v[36:39]
	v_mfma_f32_16x16x32_bf16 v[28:31], v[168:171], v[202:205], v[28:31]
	v_mfma_f32_16x16x32_bf16 v[20:23], v[176:179], v[202:205], v[20:23]
	v_mfma_f32_16x16x32_bf16 v[12:15], v[168:171], v[210:213], v[12:15]
	v_mfma_f32_16x16x32_bf16 v[4:7], v[176:179], v[210:213], v[4:7]
	v_mfma_f32_16x16x32_bf16 v[60:63], v[172:175], v[190:193], v[60:63]
	v_mfma_f32_16x16x32_bf16 v[52:55], v[180:183], v[190:193], v[52:55]
	v_mfma_f32_16x16x32_bf16 v[44:47], v[172:175], v[198:201], v[44:47]
	v_mfma_f32_16x16x32_bf16 v[36:39], v[180:183], v[198:201], v[36:39]
	v_mfma_f32_16x16x32_bf16 v[28:31], v[172:175], v[206:209], v[28:31]
	v_mfma_f32_16x16x32_bf16 v[20:23], v[180:183], v[206:209], v[20:23]
	v_mfma_f32_16x16x32_bf16 v[12:15], v[172:175], v[214:217], v[12:15]
	v_mfma_f32_16x16x32_bf16 v[4:7], v[180:183], v[214:217], v[4:7]
	s_barrier
	s_setprio 0
	s_add_i32 s51, s51, 2
	s_add_u32 s22, s22, 0x100
	s_addc_u32 s23, s23, 0
	s_add_u32 s49, s49, 0x100
	s_addc_u32 s50, s50, 0
.LBB0_782:
	ds_read_b128 v[144:147], v151
	ds_read_b128 v[156:159], v151 offset:1024
	ds_read_b128 v[160:163], v151 offset:2048
	ds_read_b128 v[164:167], v151 offset:3072
	ds_read_b128 v[168:171], v152
	ds_read_b128 v[172:175], v152 offset:1024
	ds_read_b128 v[176:179], v152 offset:2048
	ds_read_b128 v[180:183], v152 offset:3072
	s_add_u32 s24, s22, 0xfffc0080
	s_addc_u32 s25, s23, -1
	s_cmp_eq_u32 s51, 12
	s_cselect_b32 s27, s17, s25
	s_cselect_b32 s26, s47, s24
	s_cselect_b32 s25, s15, s50
	s_cselect_b32 s24, s48, s49
	v_lshl_add_u64 v[218:219], s[22:23], 0, v[136:137]
	s_add_i32 m0, s34, 0xc000
	ds_read_b128 v[184:187], v153
	ds_read_b128 v[190:193], v153 offset:1024
	ds_read_b128 v[194:197], v153 offset:2048
	ds_read_b128 v[198:201], v153 offset:3072
	ds_read_b128 v[202:205], v153 offset:4096
	ds_read_b128 v[206:209], v153 offset:5120
	ds_read_b128 v[210:213], v153 offset:6144
	ds_read_b128 v[214:217], v153 offset:7168
	global_load_lds_dwordx4 v[218:219], off
	v_lshl_add_u64 v[218:219], s[22:23], 0, v[138:139]
	s_add_i32 m0, s34, 0xe000
	s_nop 0
	global_load_lds_dwordx4 v[218:219], off
	s_waitcnt vmcnt(8)
	s_waitcnt lgkmcnt(0)
	s_setprio 1
	s_barrier
; #define PG8_STAGE(bufoff, gbase, voff) do { _Pragma("unroll") for (int _i = 0; _i < 2; ++_i) \
;         __builtin_amdgcn_global_load_lds((const unsigned*)((const char*)(gbase) + (voff)[_i]), (PG8_LAS unsigned*)(lds + (bufoff) + ldsw + _i * 8192), 16, 0, 0); } while (0)
; #define PG8_LDA(dst, b, h) do { _Pragma("unroll") for (int m = 0; m < 4; ++m) _Pragma("unroll") for (int k = 0; k < 2; ++k) dst[m][k] = *(const PG8_LAS bf16x8*)(lds + PG8_SA(b, h) + aoff + m * 2048 + k * 1024); } while (0)
; #define PG8_MMA(ai, bj, At, Bt) do { __builtin_amdgcn_s_setprio(1); _Pragma("unroll") for (int m = 0; m < 4; ++m) _Pragma("unroll") for (int n = 0; n < 2; ++n) _Pragma("unroll") for (int k = 0; k < 2; ++k) \
;         acc[ai][bj][m][n] = __builtin_amdgcn_mfma_f32_16x16x32_bf16(Bt[n][k], At[m][k], acc[ai][bj][m][n], 0, 0, 0); __builtin_amdgcn_s_setprio(0); } while (0)
; #define PG8_WAIT_V(n) asm volatile("s_waitcnt vmcnt(" #n ")" ::: "memory")
; #define PG8_WAIT_L(n) asm volatile("s_waitcnt lgkmcnt(" #n ")" ::: "memory")
; #define PG8_BAR __builtin_amdgcn_s_barrier()
; #define PG8_SCHED __builtin_amdgcn_sched_barrier(0)
; template <class Epi, class Sched, bool ALIGN_EPI = false, bool SP2 = false>
; __device__ __forceinline__ void gemm_phase(PG8_LAS unsigned char* lds, const Gemm g, const Sched& S, const Epi& E) {
;     ...
;             PG8_WAIT_V(8); PG8_WAIT_L(0); PG8_BAR; PG8_MMA(0, 0, At, B0); PG8_MMA(0, 1, At, B1); PG8_BAR; PG8_SCHED;
;             PG8_LDA(At, 0, 1); PG8_STAGE(PG8_SB(0, 0), b2, voffB); PG8_STAGE(PG8_SB(0, 1), b2 + hstep, voffB); PG8_STAGE(PG8_SA(0, 0), a2, voffA);
;             PG8_WAIT_V(8); PG8_WAIT_L(0); PG8_BAR; PG8_MMA(1, 0, At, B0); PG8_MMA(1, 1, At, B1); PG8_BAR; PG8_SCHED;
	v_mfma_f32_16x16x32_bf16 v[116:119], v[144:147], v[184:187], v[116:119]
	v_mfma_f32_16x16x32_bf16 v[112:115], v[160:163], v[184:187], v[112:115]
	v_mfma_f32_16x16x32_bf16 v[100:103], v[144:147], v[194:197], v[100:103]
	v_mfma_f32_16x16x32_bf16 v[96:99], v[160:163], v[194:197], v[96:99]
	v_mfma_f32_16x16x32_bf16 v[84:87], v[144:147], v[202:205], v[84:87]
	v_mfma_f32_16x16x32_bf16 v[80:83], v[160:163], v[202:205], v[80:83]
	v_mfma_f32_16x16x32_bf16 v[72:75], v[144:147], v[210:213], v[72:75]
	v_mfma_f32_16x16x32_bf16 v[64:67], v[160:163], v[210:213], v[64:67]
	v_mfma_f32_16x16x32_bf16 v[116:119], v[156:159], v[190:193], v[116:119]
	v_mfma_f32_16x16x32_bf16 v[112:115], v[164:167], v[190:193], v[112:115]
	v_mfma_f32_16x16x32_bf16 v[100:103], v[156:159], v[198:201], v[100:103]
	v_mfma_f32_16x16x32_bf16 v[96:99], v[164:167], v[198:201], v[96:99]
	v_mfma_f32_16x16x32_bf16 v[84:87], v[156:159], v[206:209], v[84:87]
	v_mfma_f32_16x16x32_bf16 v[80:83], v[164:167], v[206:209], v[80:83]
	v_mfma_f32_16x16x32_bf16 v[72:75], v[156:159], v[214:217], v[72:75]
	v_mfma_f32_16x16x32_bf16 v[64:67], v[164:167], v[214:217], v[64:67]
	v_mfma_f32_16x16x32_bf16 v[124:127], v[168:171], v[184:187], v[124:127]
	v_mfma_f32_16x16x32_bf16 v[120:123], v[176:179], v[184:187], v[120:123]
	v_mfma_f32_16x16x32_bf16 v[108:111], v[168:171], v[194:197], v[108:111]
	v_mfma_f32_16x16x32_bf16 v[104:107], v[176:179], v[194:197], v[104:107]
	v_mfma_f32_16x16x32_bf16 v[92:95], v[168:171], v[202:205], v[92:95]
	v_mfma_f32_16x16x32_bf16 v[88:91], v[176:179], v[202:205], v[88:91]
	v_mfma_f32_16x16x32_bf16 v[76:79], v[168:171], v[210:213], v[76:79]
	v_mfma_f32_16x16x32_bf16 v[68:71], v[176:179], v[210:213], v[68:71]
	v_mfma_f32_16x16x32_bf16 v[124:127], v[172:175], v[190:193], v[124:127]
	v_mfma_f32_16x16x32_bf16 v[120:123], v[180:183], v[190:193], v[120:123]
	v_mfma_f32_16x16x32_bf16 v[108:111], v[172:175], v[198:201], v[108:111]
	v_mfma_f32_16x16x32_bf16 v[104:107], v[180:183], v[198:201], v[104:107]
	v_mfma_f32_16x16x32_bf16 v[92:95], v[172:175], v[206:209], v[92:95]
	v_mfma_f32_16x16x32_bf16 v[88:91], v[180:183], v[206:209], v[88:91]
	v_mfma_f32_16x16x32_bf16 v[76:79], v[172:175], v[214:217], v[76:79]
	v_mfma_f32_16x16x32_bf16 v[68:71], v[180:183], v[214:217], v[68:71]
	s_barrier
	s_setprio 0
	s_add_i32 s52, s43, s30
	v_lshl_add_u64 v[218:219], s[24:25], 0, v[132:133]
	s_mov_b32 m0, s52
	ds_read_b128 v[184:187], v153 offset:16384
	ds_read_b128 v[190:193], v153 offset:17408
	ds_read_b128 v[194:197], v153 offset:18432
	ds_read_b128 v[198:201], v153 offset:19456
	ds_read_b128 v[202:205], v153 offset:20480
	ds_read_b128 v[206:209], v153 offset:21504
	ds_read_b128 v[210:213], v153 offset:22528
	ds_read_b128 v[214:217], v153 offset:23552
	global_load_lds_dwordx4 v[218:219], off
	s_add_i32 m0, s52, 0x2000
	s_add_u32 s52, s24, 0x40000
	v_lshl_add_u64 v[220:221], s[24:25], 0, v[128:129]
	s_addc_u32 s53, s25, 0
	s_add_i32 s54, s44, s30
	global_load_lds_dwordx4 v[220:221], off
	v_lshl_add_u64 v[222:223], s[52:53], 0, v[132:133]
	s_mov_b32 m0, s54
	v_lshl_add_u64 v[224:225], s[26:27], 0, v[130:131]
	global_load_lds_dwordx4 v[222:223], off
	v_lshl_add_u64 v[222:223], s[52:53], 0, v[128:129]
	s_add_i32 m0, s54, 0x2000
	s_nop 0
	global_load_lds_dwordx4 v[222:223], off
	v_lshl_add_u64 v[222:223], s[26:27], 0, v[134:135]
	s_mov_b32 m0, s34
	s_nop 0
	global_load_lds_dwordx4 v[222:223], off
	s_mov_b32 m0, s35
	s_nop 0
	global_load_lds_dwordx4 v[224:225], off
	s_waitcnt vmcnt(8)
	s_waitcnt lgkmcnt(0)
	s_setprio 1
	s_barrier
	v_mfma_f32_16x16x32_bf16 v[56:59], v[144:147], v[184:187], v[56:59]
	v_mfma_f32_16x16x32_bf16 v[48:51], v[160:163], v[184:187], v[48:51]
	v_mfma_f32_16x16x32_bf16 v[40:43], v[144:147], v[194:197], v[40:43]
	v_mfma_f32_16x16x32_bf16 v[32:35], v[160:163], v[194:197], v[32:35]
	v_mfma_f32_16x16x32_bf16 v[24:27], v[144:147], v[202:205], v[24:27]
	v_mfma_f32_16x16x32_bf16 v[16:19], v[160:163], v[202:205], v[16:19]
	v_mfma_f32_16x16x32_bf16 v[8:11], v[144:147], v[210:213], v[8:11]
	v_mfma_f32_16x16x32_bf16 v[0:3], v[160:163], v[210:213], v[0:3]
	v_mfma_f32_16x16x32_bf16 v[56:59], v[156:159], v[190:193], v[56:59]
	v_mfma_f32_16x16x32_bf16 v[48:51], v[164:167], v[190:193], v[48:51]
	v_mfma_f32_16x16x32_bf16 v[40:43], v[156:159], v[198:201], v[40:43]
	v_mfma_f32_16x16x32_bf16 v[32:35], v[164:167], v[198:201], v[32:35]
	v_mfma_f32_16x16x32_bf16 v[24:27], v[156:159], v[206:209], v[24:27]
	v_mfma_f32_16x16x32_bf16 v[16:19], v[164:167], v[206:209], v[16:19]
	v_mfma_f32_16x16x32_bf16 v[8:11], v[156:159], v[214:217], v[8:11]
	v_mfma_f32_16x16x32_bf16 v[0:3], v[164:167], v[214:217], v[0:3]
	v_mfma_f32_16x16x32_bf16 v[60:63], v[168:171], v[184:187], v[60:63]
	v_mfma_f32_16x16x32_bf16 v[52:55], v[176:179], v[184:187], v[52:55]
	v_mfma_f32_16x16x32_bf16 v[44:47], v[168:171], v[194:197], v[44:47]
	v_mfma_f32_16x16x32_bf16 v[36:39], v[176:179], v[194:197], v[36:39]
	v_mfma_f32_16x16x32_bf16 v[28:31], v[168:171], v[202:205], v[28:31]
	v_mfma_f32_16x16x32_bf16 v[20:23], v[176:179], v[202:205], v[20:23]
	v_mfma_f32_16x16x32_bf16 v[12:15], v[168:171], v[210:213], v[12:15]
	v_mfma_f32_16x16x32_bf16 v[4:7], v[176:179], v[210:213], v[4:7]
	v_mfma_f32_16x16x32_bf16 v[60:63], v[172:175], v[190:193], v[60:63]
	v_mfma_f32_16x16x32_bf16 v[52:55], v[180:183], v[190:193], v[52:55]
	v_mfma_f32_16x16x32_bf16 v[44:47], v[172:175], v[198:201], v[44:47]
	v_mfma_f32_16x16x32_bf16 v[36:39], v[180:183], v[198:201], v[36:39]
	v_mfma_f32_16x16x32_bf16 v[28:31], v[172:175], v[206:209], v[28:31]
	v_mfma_f32_16x16x32_bf16 v[20:23], v[180:183], v[206:209], v[20:23]
	v_mfma_f32_16x16x32_bf16 v[12:15], v[172:175], v[214:217], v[12:15]
	v_mfma_f32_16x16x32_bf16 v[4:7], v[180:183], v[214:217], v[4:7]
	s_barrier
; #define PG8_STAGE(bufoff, gbase, voff) do { _Pragma("unroll") for (int _i = 0; _i < 2; ++_i) \
;         __builtin_amdgcn_global_load_lds((const unsigned*)((const char*)(gbase) + (voff)[_i]), (PG8_LAS unsigned*)(lds + (bufoff) + ldsw + _i * 8192), 16, 0, 0); } while (0)
; #define PG8_LDA(dst, b, h) do { _Pragma("unroll") for (int m = 0; m < 4; ++m) _Pragma("unroll") for (int k = 0; k < 2; ++k) dst[m][k] = *(const PG8_LAS bf16x8*)(lds + PG8_SA(b, h) + aoff + m * 2048 + k * 1024); } while (0)
; #define PG8_LDB(dst, b, h) do { _Pragma("unroll") for (int n = 0; n < 2; ++n) _Pragma("unroll") for (int k = 0; k < 2; ++k) dst[n][k] = *(const PG8_LAS bf16x8*)(lds + PG8_SB(b, h) + boff + n * 2048 + k * 1024); } while (0)
; #define PG8_MMA(ai, bj, At, Bt) do { __builtin_amdgcn_s_setprio(1); _Pragma("unroll") for (int m = 0; m < 4; ++m) _Pragma("unroll") for (int n = 0; n < 2; ++n) _Pragma("unroll") for (int k = 0; k < 2; ++k) \
;         acc[ai][bj][m][n] = __builtin_amdgcn_mfma_f32_16x16x32_bf16(Bt[n][k], At[m][k], acc[ai][bj][m][n], 0, 0, 0); __builtin_amdgcn_s_setprio(0); } while (0)
; #define PG8_WAIT_V(n) asm volatile("s_waitcnt vmcnt(" #n ")" ::: "memory")
; #define PG8_WAIT_L(n) asm volatile("s_waitcnt lgkmcnt(" #n ")" ::: "memory")
; #define PG8_BAR __builtin_amdgcn_s_barrier()
; #define PG8_SCHED __builtin_amdgcn_sched_barrier(0)
; template <class Epi, class Sched, bool ALIGN_EPI = false, bool SP2 = false>
; __device__ __forceinline__ void gemm_phase(PG8_LAS unsigned char* lds, const Gemm g, const Sched& S, const Epi& E) {
;     ...
;             PG8_LDB(B0, 1, 0); PG8_LDB(B1, 1, 1); PG8_SCHED; PG8_LDA(At, 1, 0); PG8_STAGE(PG8_SA(0, 1), a2 + hstep, voffA);
;             PG8_WAIT_V(8); PG8_WAIT_L(0); PG8_BAR; PG8_MMA(0, 0, At, B0); PG8_MMA(0, 1, At, B1); PG8_BAR; PG8_SCHED;
	s_setprio 0
	s_add_i32 s52, 0, 0x18000
	v_add_u32_e32 v155, s52, v149
	s_add_i32 s53, 0, 0x1c000
	ds_read_b128 v[144:147], v155
	ds_read_b128 v[156:159], v155 offset:1024
	ds_read_b128 v[160:163], v155 offset:2048
	ds_read_b128 v[164:167], v155 offset:3072
	v_add_u32_e32 v155, s53, v149
	ds_read_b128 v[168:171], v155
	ds_read_b128 v[172:175], v155 offset:1024
	ds_read_b128 v[176:179], v155 offset:2048
	ds_read_b128 v[180:183], v155 offset:3072
	s_add_u32 s26, s26, 0x40000
	s_addc_u32 s27, s27, 0
	s_mov_b32 m0, s36
	v_lshl_add_u64 v[226:227], s[26:27], 0, v[134:135]
	ds_read_b128 v[184:187], v153 offset:32768
	ds_read_b128 v[190:193], v153 offset:33792
	ds_read_b128 v[194:197], v153 offset:34816
	ds_read_b128 v[198:201], v153 offset:35840
	ds_read_b128 v[202:205], v153 offset:36864
	ds_read_b128 v[206:209], v153 offset:37888
	ds_read_b128 v[210:213], v153 offset:38912
	ds_read_b128 v[214:217], v153 offset:39936
	global_load_lds_dwordx4 v[226:227], off
	v_lshl_add_u64 v[226:227], s[26:27], 0, v[130:131]
	s_mov_b32 m0, s37
	s_nop 0
	global_load_lds_dwordx4 v[226:227], off
	s_waitcnt vmcnt(8)
	s_waitcnt lgkmcnt(0)
	s_setprio 1
	s_barrier
	v_mfma_f32_16x16x32_bf16 v[116:119], v[144:147], v[184:187], v[116:119]
	v_mfma_f32_16x16x32_bf16 v[112:115], v[160:163], v[184:187], v[112:115]
	v_mfma_f32_16x16x32_bf16 v[100:103], v[144:147], v[194:197], v[100:103]
	v_mfma_f32_16x16x32_bf16 v[96:99], v[160:163], v[194:197], v[96:99]
	v_mfma_f32_16x16x32_bf16 v[84:87], v[144:147], v[202:205], v[84:87]
	v_mfma_f32_16x16x32_bf16 v[80:83], v[160:163], v[202:205], v[80:83]
	v_mfma_f32_16x16x32_bf16 v[72:75], v[144:147], v[210:213], v[72:75]
	v_mfma_f32_16x16x32_bf16 v[64:67], v[160:163], v[210:213], v[64:67]
	v_mfma_f32_16x16x32_bf16 v[116:119], v[156:159], v[190:193], v[116:119]
	v_mfma_f32_16x16x32_bf16 v[112:115], v[164:167], v[190:193], v[112:115]
	v_mfma_f32_16x16x32_bf16 v[100:103], v[156:159], v[198:201], v[100:103]
	v_mfma_f32_16x16x32_bf16 v[96:99], v[164:167], v[198:201], v[96:99]
	v_mfma_f32_16x16x32_bf16 v[84:87], v[156:159], v[206:209], v[84:87]
	v_mfma_f32_16x16x32_bf16 v[80:83], v[164:167], v[206:209], v[80:83]
	v_mfma_f32_16x16x32_bf16 v[72:75], v[156:159], v[214:217], v[72:75]
	v_mfma_f32_16x16x32_bf16 v[64:67], v[164:167], v[214:217], v[64:67]
	v_mfma_f32_16x16x32_bf16 v[124:127], v[168:171], v[184:187], v[124:127]
	v_mfma_f32_16x16x32_bf16 v[120:123], v[176:179], v[184:187], v[120:123]
	v_mfma_f32_16x16x32_bf16 v[108:111], v[168:171], v[194:197], v[108:111]
	v_mfma_f32_16x16x32_bf16 v[104:107], v[176:179], v[194:197], v[104:107]
	v_mfma_f32_16x16x32_bf16 v[92:95], v[168:171], v[202:205], v[92:95]
	v_mfma_f32_16x16x32_bf16 v[88:91], v[176:179], v[202:205], v[88:91]
	v_mfma_f32_16x16x32_bf16 v[76:79], v[168:171], v[210:213], v[76:79]
	v_mfma_f32_16x16x32_bf16 v[68:71], v[176:179], v[210:213], v[68:71]
	v_mfma_f32_16x16x32_bf16 v[124:127], v[172:175], v[190:193], v[124:127]
	v_mfma_f32_16x16x32_bf16 v[120:123], v[180:183], v[190:193], v[120:123]
	v_mfma_f32_16x16x32_bf16 v[108:111], v[172:175], v[198:201], v[108:111]
	v_mfma_f32_16x16x32_bf16 v[104:107], v[180:183], v[198:201], v[104:107]
	v_mfma_f32_16x16x32_bf16 v[92:95], v[172:175], v[206:209], v[92:95]
	v_mfma_f32_16x16x32_bf16 v[88:91], v[180:183], v[206:209], v[88:91]
	v_mfma_f32_16x16x32_bf16 v[76:79], v[172:175], v[214:217], v[76:79]
	v_mfma_f32_16x16x32_bf16 v[68:71], v[180:183], v[214:217], v[68:71]
	s_barrier
; #define PG8_STAGE(bufoff, gbase, voff) do { _Pragma("unroll") for (int _i = 0; _i < 2; ++_i) \
;         __builtin_amdgcn_global_load_lds((const unsigned*)((const char*)(gbase) + (voff)[_i]), (PG8_LAS unsigned*)(lds + (bufoff) + ldsw + _i * 8192), 16, 0, 0); } while (0)
; #define PG8_LDA(dst, b, h) do { _Pragma("unroll") for (int m = 0; m < 4; ++m) _Pragma("unroll") for (int k = 0; k < 2; ++k) dst[m][k] = *(const PG8_LAS bf16x8*)(lds + PG8_SA(b, h) + aoff + m * 2048 + k * 1024); } while (0)
; #define PG8_MMA(ai, bj, At, Bt) do { __builtin_amdgcn_s_setprio(1); _Pragma("unroll") for (int m = 0; m < 4; ++m) _Pragma("unroll") for (int n = 0; n < 2; ++n) _Pragma("unroll") for (int k = 0; k < 2; ++k) \
;         acc[ai][bj][m][n] = __builtin_amdgcn_mfma_f32_16x16x32_bf16(Bt[n][k], At[m][k], acc[ai][bj][m][n], 0, 0, 0); __builtin_amdgcn_s_setprio(0); } while (0)
; #define PG8_WAIT_V(n) asm volatile("s_waitcnt vmcnt(" #n ")" ::: "memory")
; #define PG8_WAIT_L(n) asm volatile("s_waitcnt lgkmcnt(" #n ")" ::: "memory")
; #define PG8_BAR __builtin_amdgcn_s_barrier()
; #define PG8_SCHED __builtin_amdgcn_sched_barrier(0)
; template <class Epi, class Sched, bool ALIGN_EPI = false, bool SP2 = false>
; __device__ __forceinline__ void gemm_phase(PG8_LAS unsigned char* lds, const Gemm g, const Sched& S, const Epi& E) {
;     ...
;             PG8_LDA(At, 1, 1); PG8_STAGE(PG8_SB(1, 0), b3, voffB); PG8_STAGE(PG8_SB(1, 1), b3 + hstep, voffB); PG8_STAGE(PG8_SA(1, 0), a3, voffA);
;             PG8_WAIT_V(8); PG8_WAIT_L(0); PG8_BAR; PG8_MMA(1, 0, At, B0); PG8_MMA(1, 1, At, B1); PG8_BAR; PG8_SCHED;
;     ...
;         if constexpr (ALIGN_EPI) { if (wr == 0) PG8_BAR; }
	s_setprio 0
	s_add_i32 s26, s52, s30
	v_lshl_add_u64 v[218:219], v[218:219], 0, s[6:7]
	s_mov_b32 m0, s26
	ds_read_b128 v[184:187], v153 offset:49152
	ds_read_b128 v[190:193], v153 offset:50176
	ds_read_b128 v[194:197], v153 offset:51200
	ds_read_b128 v[198:201], v153 offset:52224
	ds_read_b128 v[202:205], v153 offset:53248
	ds_read_b128 v[206:209], v153 offset:54272
	ds_read_b128 v[210:213], v153 offset:55296
	ds_read_b128 v[214:217], v153 offset:56320
	global_load_lds_dwordx4 v[218:219], off
	s_add_i32 m0, s26, 0x2000
	s_add_u32 s24, s24, 0x40080
	v_lshl_add_u64 v[218:219], v[220:221], 0, s[6:7]
	s_addc_u32 s25, s25, 0
	s_add_i32 s26, s53, s30
	global_load_lds_dwordx4 v[218:219], off
	v_lshl_add_u64 v[218:219], s[24:25], 0, v[132:133]
	s_mov_b32 m0, s26
	s_nop 0
	global_load_lds_dwordx4 v[218:219], off
	v_lshl_add_u64 v[218:219], s[24:25], 0, v[128:129]
	s_add_i32 m0, s26, 0x2000
	s_nop 0
	global_load_lds_dwordx4 v[218:219], off
	v_lshl_add_u64 v[218:219], v[222:223], 0, s[6:7]
	s_mov_b32 m0, s39
	s_nop 0
	global_load_lds_dwordx4 v[218:219], off
	v_lshl_add_u64 v[218:219], v[224:225], 0, s[6:7]
	s_mov_b32 m0, s40
	s_nop 0
	global_load_lds_dwordx4 v[218:219], off
	s_waitcnt vmcnt(8)
	s_waitcnt lgkmcnt(0)
	s_setprio 1
	s_barrier
	v_mfma_f32_16x16x32_bf16 v[56:59], v[144:147], v[184:187], v[56:59]
	v_mfma_f32_16x16x32_bf16 v[48:51], v[160:163], v[184:187], v[48:51]
	v_mfma_f32_16x16x32_bf16 v[40:43], v[144:147], v[194:197], v[40:43]
	v_mfma_f32_16x16x32_bf16 v[32:35], v[160:163], v[194:197], v[32:35]
	v_mfma_f32_16x16x32_bf16 v[24:27], v[144:147], v[202:205], v[24:27]
	v_mfma_f32_16x16x32_bf16 v[16:19], v[160:163], v[202:205], v[16:19]
	v_mfma_f32_16x16x32_bf16 v[8:11], v[144:147], v[210:213], v[8:11]
	v_mfma_f32_16x16x32_bf16 v[0:3], v[160:163], v[210:213], v[0:3]
	v_mfma_f32_16x16x32_bf16 v[56:59], v[156:159], v[190:193], v[56:59]
	v_mfma_f32_16x16x32_bf16 v[48:51], v[164:167], v[190:193], v[48:51]
	v_mfma_f32_16x16x32_bf16 v[40:43], v[156:159], v[198:201], v[40:43]
	v_mfma_f32_16x16x32_bf16 v[32:35], v[164:167], v[198:201], v[32:35]
	v_mfma_f32_16x16x32_bf16 v[24:27], v[156:159], v[206:209], v[24:27]
	v_mfma_f32_16x16x32_bf16 v[16:19], v[164:167], v[206:209], v[16:19]
	v_mfma_f32_16x16x32_bf16 v[8:11], v[156:159], v[214:217], v[8:11]
	v_mfma_f32_16x16x32_bf16 v[0:3], v[164:167], v[214:217], v[0:3]
	v_mfma_f32_16x16x32_bf16 v[60:63], v[168:171], v[184:187], v[60:63]
	v_mfma_f32_16x16x32_bf16 v[52:55], v[176:179], v[184:187], v[52:55]
	v_mfma_f32_16x16x32_bf16 v[44:47], v[168:171], v[194:197], v[44:47]
	v_mfma_f32_16x16x32_bf16 v[36:39], v[176:179], v[194:197], v[36:39]
	v_mfma_f32_16x16x32_bf16 v[28:31], v[168:171], v[202:205], v[28:31]
	v_mfma_f32_16x16x32_bf16 v[20:23], v[176:179], v[202:205], v[20:23]
	v_mfma_f32_16x16x32_bf16 v[12:15], v[168:171], v[210:213], v[12:15]
	v_mfma_f32_16x16x32_bf16 v[4:7], v[176:179], v[210:213], v[4:7]
	v_mfma_f32_16x16x32_bf16 v[60:63], v[172:175], v[190:193], v[60:63]
	v_mfma_f32_16x16x32_bf16 v[52:55], v[180:183], v[190:193], v[52:55]
	v_mfma_f32_16x16x32_bf16 v[44:47], v[172:175], v[198:201], v[44:47]
	v_mfma_f32_16x16x32_bf16 v[36:39], v[180:183], v[198:201], v[36:39]
	v_mfma_f32_16x16x32_bf16 v[28:31], v[172:175], v[206:209], v[28:31]
	v_mfma_f32_16x16x32_bf16 v[20:23], v[180:183], v[206:209], v[20:23]
	v_mfma_f32_16x16x32_bf16 v[12:15], v[172:175], v[214:217], v[12:15]
	v_mfma_f32_16x16x32_bf16 v[4:7], v[180:183], v[214:217], v[4:7]
	s_barrier
	s_setprio 0
	s_add_i32 s51, s51, 2
	s_add_u32 s22, s22, 0x100
	s_addc_u32 s23, s23, 0
	s_add_u32 s49, s49, 0x100
	s_addc_u32 s50, s50, 0
	s_cmp_gt_u32 s51, 13
	s_cbranch_scc0 .LBB0_782
	s_and_b64 vcc, exec, s[12:13]
	s_cbranch_vccz .LBB0_785
	s_barrier

; #define PG8_STAGE(bufoff, gbase, voff) do { _Pragma("unroll") for (int _i = 0; _i < 2; ++_i) \
;         __builtin_amdgcn_global_load_lds((const unsigned*)((const char*)(gbase) + (voff)[_i]), (PG8_LAS unsigned*)(lds + (bufoff) + ldsw + _i * 8192), 16, 0, 0); } while (0)
; #define PG8_LDA(dst, b, h) do { _Pragma("unroll") for (int m = 0; m < 4; ++m) _Pragma("unroll") for (int k = 0; k < 2; ++k) dst[m][k] = *(const PG8_LAS bf16x8*)(lds + PG8_SA(b, h) + aoff + m * 2048 + k * 1024); } while (0)
; #define PG8_LDB(dst, b, h) do { _Pragma("unroll") for (int n = 0; n < 2; ++n) _Pragma("unroll") for (int k = 0; k < 2; ++k) dst[n][k] = *(const PG8_LAS bf16x8*)(lds + PG8_SB(b, h) + boff + n * 2048 + k * 1024); } while (0)
; #define PG8_MMA(ai, bj, At, Bt) do { __builtin_amdgcn_s_setprio(1); _Pragma("unroll") for (int m = 0; m < 4; ++m) _Pragma("unroll") for (int n = 0; n < 2; ++n) _Pragma("unroll") for (int k = 0; k < 2; ++k) \
;         acc[ai][bj][m][n] = __builtin_amdgcn_mfma_f32_16x16x32_bf16(Bt[n][k], At[m][k], acc[ai][bj][m][n], 0, 0, 0); __builtin_amdgcn_s_setprio(0); } while (0)
; #define PG8_WAIT_V(n) asm volatile("s_waitcnt vmcnt(" #n ")" ::: "memory")
; #define PG8_WAIT_L(n) asm volatile("s_waitcnt lgkmcnt(" #n ")" ::: "memory")
; template <class Epi, class Sched, bool ALIGN_EPI = false, bool SP2 = false>
; __device__ __forceinline__ void gemm_phase(PG8_LAS unsigned char* lds, const Gemm g, const Sched& S, const Epi& E) {
;     ...
;             const bool last = (t == nt - 2);
;             const char* a1 = cA + (size_t)(t + 1) * kstep;
;             const char* a2 = last ? nA : cA + (size_t)(t + 2) * kstep; const char* b2 = last ? nB : cB + (size_t)(t + 2) * kstep;
;             const char* a3 = a2 + kstep; const char* b3 = b2 + kstep;
;             if (last && has_next) S.a_ready(nxt);
;             if constexpr (SP2) {
;             PG8_LDB(B0, 0, 0); PG8_LDB(B1, 0, 1); PG8_SCHED; PG8_LDA(At, 0, 0); PG8_STAGE(PG8_SA(1, 1), a1 + hstep, voffA);
;             PG8_WAIT_V(8); PG8_WAIT_L(0); PG8_BAR; PG8_MMA(0, 0, At, B0); PG8_MMA(0, 1, At, B1); PG8_BAR; PG8_SCHED;
;             PG8_LDA(At, 0, 1); PG8_STAGE(PG8_SB(0, 0), b2, voffB); PG8_STAGE(PG8_SB(0, 1), b2 + hstep, voffB); PG8_STAGE(PG8_SA(0, 0), a2, voffA);
;             PG8_WAIT_V(8); PG8_WAIT_L(0); PG8_BAR; PG8_MMA(1, 0, At, B0); PG8_MMA(1, 1, At, B1); PG8_BAR; PG8_SCHED;
.LBB0_861:
	s_add_u32 s49, s24, 0x100
	s_addc_u32 s50, s25, 0
	s_mov_b32 s51, -2
	ds_read_b128 v[144:147], v153
	ds_read_b128 v[156:159], v153 offset:1024
	ds_read_b128 v[160:163], v153 offset:2048
	ds_read_b128 v[164:167], v153 offset:3072
	ds_read_b128 v[168:171], v154
	ds_read_b128 v[172:175], v154 offset:1024
	ds_read_b128 v[176:179], v154 offset:2048
	ds_read_b128 v[180:183], v154 offset:3072
	s_add_u32 s24, s22, 0x100
	s_addc_u32 s25, s23, 0
	s_cmp_eq_u32 s51, 40
	s_cselect_b32 s29, s5, s25
	s_cselect_b32 s28, s4, s24
	s_cselect_b32 s27, s21, s50
	s_cselect_b32 s26, s20, s49
	v_lshl_add_u64 v[148:149], s[22:23], 0, v[136:137]
	s_add_i32 m0, s35, 0xc000
	ds_read_b128 v[184:187], v155
	ds_read_b128 v[188:191], v155 offset:1024
	ds_read_b128 v[192:195], v155 offset:2048
	ds_read_b128 v[196:199], v155 offset:3072
	ds_read_b128 v[200:203], v155 offset:4096
	ds_read_b128 v[204:207], v155 offset:5120
	ds_read_b128 v[208:211], v155 offset:6144
	ds_read_b128 v[212:215], v155 offset:7168
	global_load_lds_dwordx4 v[148:149], off
	v_lshl_add_u64 v[148:149], s[22:23], 0, v[138:139]
	s_add_i32 m0, s35, 0xe000
	s_nop 0
	global_load_lds_dwordx4 v[148:149], off
	s_waitcnt vmcnt(8)
	s_waitcnt lgkmcnt(0)
	s_setprio 1
	s_barrier
	v_mfma_f32_16x16x32_bf16 v[124:127], v[144:147], v[184:187], 0
	v_mfma_f32_16x16x32_bf16 v[120:123], v[160:163], v[184:187], 0
	v_mfma_f32_16x16x32_bf16 v[108:111], v[144:147], v[192:195], 0
	v_mfma_f32_16x16x32_bf16 v[104:107], v[160:163], v[192:195], 0
	v_mfma_f32_16x16x32_bf16 v[92:95], v[144:147], v[200:203], 0
	v_mfma_f32_16x16x32_bf16 v[88:91], v[160:163], v[200:203], 0
	v_mfma_f32_16x16x32_bf16 v[76:79], v[144:147], v[208:211], 0
	v_mfma_f32_16x16x32_bf16 v[72:75], v[160:163], v[208:211], 0
	v_mfma_f32_16x16x32_bf16 v[124:127], v[156:159], v[188:191], v[124:127]
	v_mfma_f32_16x16x32_bf16 v[120:123], v[164:167], v[188:191], v[120:123]
	v_mfma_f32_16x16x32_bf16 v[108:111], v[156:159], v[196:199], v[108:111]
	v_mfma_f32_16x16x32_bf16 v[104:107], v[164:167], v[196:199], v[104:107]
	v_mfma_f32_16x16x32_bf16 v[92:95], v[156:159], v[204:207], v[92:95]
	v_mfma_f32_16x16x32_bf16 v[88:91], v[164:167], v[204:207], v[88:91]
	v_mfma_f32_16x16x32_bf16 v[76:79], v[156:159], v[212:215], v[76:79]
	v_mfma_f32_16x16x32_bf16 v[72:75], v[164:167], v[212:215], v[72:75]
	v_mfma_f32_16x16x32_bf16 v[116:119], v[168:171], v[184:187], 0
	v_mfma_f32_16x16x32_bf16 v[112:115], v[176:179], v[184:187], 0
	v_mfma_f32_16x16x32_bf16 v[100:103], v[168:171], v[192:195], 0
	v_mfma_f32_16x16x32_bf16 v[96:99], v[176:179], v[192:195], 0
	v_mfma_f32_16x16x32_bf16 v[84:87], v[168:171], v[200:203], 0
	v_mfma_f32_16x16x32_bf16 v[80:83], v[176:179], v[200:203], 0
	v_mfma_f32_16x16x32_bf16 v[68:71], v[168:171], v[208:211], 0
	v_mfma_f32_16x16x32_bf16 v[64:67], v[176:179], v[208:211], 0
	v_mfma_f32_16x16x32_bf16 v[116:119], v[172:175], v[188:191], v[116:119]
	v_mfma_f32_16x16x32_bf16 v[112:115], v[180:183], v[188:191], v[112:115]
	v_mfma_f32_16x16x32_bf16 v[100:103], v[172:175], v[196:199], v[100:103]
	v_mfma_f32_16x16x32_bf16 v[96:99], v[180:183], v[196:199], v[96:99]
	v_mfma_f32_16x16x32_bf16 v[84:87], v[172:175], v[204:207], v[84:87]
	v_mfma_f32_16x16x32_bf16 v[80:83], v[180:183], v[204:207], v[80:83]
	v_mfma_f32_16x16x32_bf16 v[68:71], v[172:175], v[212:215], v[68:71]
	v_mfma_f32_16x16x32_bf16 v[64:67], v[180:183], v[212:215], v[64:67]
	s_barrier
	s_setprio 0
	s_add_i32 s22, s43, s34
	v_lshl_add_u64 v[148:149], s[26:27], 0, v[130:131]
	s_mov_b32 m0, s22
	ds_read_b128 v[184:187], v155 offset:16384
	ds_read_b128 v[188:191], v155 offset:17408
	ds_read_b128 v[192:195], v155 offset:18432
	ds_read_b128 v[196:199], v155 offset:19456
	ds_read_b128 v[200:203], v155 offset:20480
	ds_read_b128 v[204:207], v155 offset:21504
	ds_read_b128 v[208:211], v155 offset:22528
	ds_read_b128 v[212:215], v155 offset:23552
	global_load_lds_dwordx4 v[148:149], off
	s_add_i32 m0, s22, 0x2000
	s_add_u32 s22, s26, 0xb0000
	v_lshl_add_u64 v[216:217], s[26:27], 0, v[134:135]
	s_addc_u32 s23, s27, 0
	s_add_i32 s52, s44, s34
	global_load_lds_dwordx4 v[216:217], off
	v_lshl_add_u64 v[218:219], s[22:23], 0, v[130:131]
	s_mov_b32 m0, s52
	v_lshl_add_u64 v[220:221], s[28:29], 0, v[132:133]
	global_load_lds_dwordx4 v[218:219], off
	v_lshl_add_u64 v[218:219], s[22:23], 0, v[134:135]
	s_add_i32 m0, s52, 0x2000
	s_nop 0
	global_load_lds_dwordx4 v[218:219], off
	v_lshl_add_u64 v[218:219], s[28:29], 0, v[128:129]
	s_mov_b32 m0, s35
	s_nop 0
	global_load_lds_dwordx4 v[218:219], off
	s_mov_b32 m0, s36
	s_nop 0
	global_load_lds_dwordx4 v[220:221], off
	s_waitcnt vmcnt(8)
	s_waitcnt lgkmcnt(0)
	s_setprio 1
	s_barrier
; #define PG8_STAGE(bufoff, gbase, voff) do { _Pragma("unroll") for (int _i = 0; _i < 2; ++_i) \
;         __builtin_amdgcn_global_load_lds((const unsigned*)((const char*)(gbase) + (voff)[_i]), (PG8_LAS unsigned*)(lds + (bufoff) + ldsw + _i * 8192), 16, 0, 0); } while (0)
; #define PG8_LDA(dst, b, h) do { _Pragma("unroll") for (int m = 0; m < 4; ++m) _Pragma("unroll") for (int k = 0; k < 2; ++k) dst[m][k] = *(const PG8_LAS bf16x8*)(lds + PG8_SA(b, h) + aoff + m * 2048 + k * 1024); } while (0)
; #define PG8_LDB(dst, b, h) do { _Pragma("unroll") for (int n = 0; n < 2; ++n) _Pragma("unroll") for (int k = 0; k < 2; ++k) dst[n][k] = *(const PG8_LAS bf16x8*)(lds + PG8_SB(b, h) + boff + n * 2048 + k * 1024); } while (0)
; #define PG8_MMA(ai, bj, At, Bt) do { __builtin_amdgcn_s_setprio(1); _Pragma("unroll") for (int m = 0; m < 4; ++m) _Pragma("unroll") for (int n = 0; n < 2; ++n) _Pragma("unroll") for (int k = 0; k < 2; ++k) \
;         acc[ai][bj][m][n] = __builtin_amdgcn_mfma_f32_16x16x32_bf16(Bt[n][k], At[m][k], acc[ai][bj][m][n], 0, 0, 0); __builtin_amdgcn_s_setprio(0); } while (0)
; #define PG8_WAIT_V(n) asm volatile("s_waitcnt vmcnt(" #n ")" ::: "memory")
; #define PG8_WAIT_L(n) asm volatile("s_waitcnt lgkmcnt(" #n ")" ::: "memory")
; #define PG8_BAR __builtin_amdgcn_s_barrier()
; #define PG8_SCHED __builtin_amdgcn_sched_barrier(0)
; template <class Epi, class Sched, bool ALIGN_EPI = false, bool SP2 = false>
; __device__ __forceinline__ void gemm_phase(PG8_LAS unsigned char* lds, const Gemm g, const Sched& S, const Epi& E) {
;     ...
;             PG8_WAIT_V(8); PG8_WAIT_L(0); PG8_BAR; PG8_MMA(1, 0, At, B0); PG8_MMA(1, 1, At, B1); PG8_BAR; PG8_SCHED;
;             PG8_LDB(B0, 1, 0); PG8_LDB(B1, 1, 1); PG8_SCHED; PG8_LDA(At, 1, 0); PG8_STAGE(PG8_SA(0, 1), a2 + hstep, voffA);
;             PG8_WAIT_V(8); PG8_WAIT_L(0); PG8_BAR; PG8_MMA(0, 0, At, B0); PG8_MMA(0, 1, At, B1); PG8_BAR; PG8_SCHED;
	v_mfma_f32_16x16x32_bf16 v[60:63], v[144:147], v[184:187], 0
	v_mfma_f32_16x16x32_bf16 v[56:59], v[160:163], v[184:187], 0
	v_mfma_f32_16x16x32_bf16 v[44:47], v[144:147], v[192:195], 0
	v_mfma_f32_16x16x32_bf16 v[40:43], v[160:163], v[192:195], 0
	v_mfma_f32_16x16x32_bf16 v[28:31], v[144:147], v[200:203], 0
	v_mfma_f32_16x16x32_bf16 v[24:27], v[160:163], v[200:203], 0
	v_mfma_f32_16x16x32_bf16 v[12:15], v[144:147], v[208:211], 0
	v_mfma_f32_16x16x32_bf16 v[8:11], v[160:163], v[208:211], 0
	v_mfma_f32_16x16x32_bf16 v[60:63], v[156:159], v[188:191], v[60:63]
	v_mfma_f32_16x16x32_bf16 v[56:59], v[164:167], v[188:191], v[56:59]
	v_mfma_f32_16x16x32_bf16 v[44:47], v[156:159], v[196:199], v[44:47]
	v_mfma_f32_16x16x32_bf16 v[40:43], v[164:167], v[196:199], v[40:43]
	v_mfma_f32_16x16x32_bf16 v[28:31], v[156:159], v[204:207], v[28:31]
	v_mfma_f32_16x16x32_bf16 v[24:27], v[164:167], v[204:207], v[24:27]
	v_mfma_f32_16x16x32_bf16 v[12:15], v[156:159], v[212:215], v[12:15]
	v_mfma_f32_16x16x32_bf16 v[8:11], v[164:167], v[212:215], v[8:11]
	v_mfma_f32_16x16x32_bf16 v[52:55], v[168:171], v[184:187], 0
	v_mfma_f32_16x16x32_bf16 v[48:51], v[176:179], v[184:187], 0
	v_mfma_f32_16x16x32_bf16 v[36:39], v[168:171], v[192:195], 0
	v_mfma_f32_16x16x32_bf16 v[32:35], v[176:179], v[192:195], 0
	v_mfma_f32_16x16x32_bf16 v[20:23], v[168:171], v[200:203], 0
	v_mfma_f32_16x16x32_bf16 v[16:19], v[176:179], v[200:203], 0
	v_mfma_f32_16x16x32_bf16 v[4:7], v[168:171], v[208:211], 0
	v_mfma_f32_16x16x32_bf16 v[0:3], v[176:179], v[208:211], 0
	v_mfma_f32_16x16x32_bf16 v[52:55], v[172:175], v[188:191], v[52:55]
	v_mfma_f32_16x16x32_bf16 v[48:51], v[180:183], v[188:191], v[48:51]
	v_mfma_f32_16x16x32_bf16 v[36:39], v[172:175], v[196:199], v[36:39]
	v_mfma_f32_16x16x32_bf16 v[32:35], v[180:183], v[196:199], v[32:35]
	v_mfma_f32_16x16x32_bf16 v[20:23], v[172:175], v[204:207], v[20:23]
	v_mfma_f32_16x16x32_bf16 v[16:19], v[180:183], v[204:207], v[16:19]
	v_mfma_f32_16x16x32_bf16 v[4:7], v[172:175], v[212:215], v[4:7]
	v_mfma_f32_16x16x32_bf16 v[0:3], v[180:183], v[212:215], v[0:3]
	s_barrier
	s_setprio 0
	s_add_i32 s52, 0, 0x18000
	s_add_i32 s53, 0, 0x1c000
	v_add_u32_e32 v164, s52, v151
	v_add_u32_e32 v180, s53, v151
	ds_read_b128 v[144:147], v164
	ds_read_b128 v[156:159], v164 offset:1024
	ds_read_b128 v[160:163], v164 offset:2048
	ds_read_b128 v[164:167], v164 offset:3072
	ds_read_b128 v[168:171], v180
	ds_read_b128 v[172:175], v180 offset:1024
	ds_read_b128 v[176:179], v180 offset:2048
	ds_read_b128 v[180:183], v180 offset:3072
	s_add_u32 s22, s28, 0xb0000
	s_addc_u32 s23, s29, 0
	s_mov_b32 m0, s37
	v_lshl_add_u64 v[222:223], s[22:23], 0, v[128:129]
	ds_read_b128 v[184:187], v155 offset:32768
	ds_read_b128 v[188:191], v155 offset:33792
	ds_read_b128 v[192:195], v155 offset:34816
	ds_read_b128 v[196:199], v155 offset:35840
	ds_read_b128 v[200:203], v155 offset:36864
	ds_read_b128 v[204:207], v155 offset:37888
	ds_read_b128 v[208:211], v155 offset:38912
	ds_read_b128 v[212:215], v155 offset:39936
	global_load_lds_dwordx4 v[222:223], off
	v_lshl_add_u64 v[222:223], s[22:23], 0, v[132:133]
	s_mov_b32 m0, s38
	s_nop 0
	global_load_lds_dwordx4 v[222:223], off
	s_waitcnt vmcnt(8)
	s_waitcnt lgkmcnt(0)
	s_setprio 1
	s_barrier
	v_mfma_f32_16x16x32_bf16 v[124:127], v[144:147], v[184:187], v[124:127]
	v_mfma_f32_16x16x32_bf16 v[120:123], v[160:163], v[184:187], v[120:123]
	v_mfma_f32_16x16x32_bf16 v[108:111], v[144:147], v[192:195], v[108:111]
	v_mfma_f32_16x16x32_bf16 v[104:107], v[160:163], v[192:195], v[104:107]
	v_mfma_f32_16x16x32_bf16 v[92:95], v[144:147], v[200:203], v[92:95]
	v_mfma_f32_16x16x32_bf16 v[88:91], v[160:163], v[200:203], v[88:91]
	v_mfma_f32_16x16x32_bf16 v[76:79], v[144:147], v[208:211], v[76:79]
	v_mfma_f32_16x16x32_bf16 v[72:75], v[160:163], v[208:211], v[72:75]
	v_mfma_f32_16x16x32_bf16 v[124:127], v[156:159], v[188:191], v[124:127]
	v_mfma_f32_16x16x32_bf16 v[120:123], v[164:167], v[188:191], v[120:123]
	v_mfma_f32_16x16x32_bf16 v[108:111], v[156:159], v[196:199], v[108:111]
	v_mfma_f32_16x16x32_bf16 v[104:107], v[164:167], v[196:199], v[104:107]
	v_mfma_f32_16x16x32_bf16 v[92:95], v[156:159], v[204:207], v[92:95]
	v_mfma_f32_16x16x32_bf16 v[88:91], v[164:167], v[204:207], v[88:91]
	v_mfma_f32_16x16x32_bf16 v[76:79], v[156:159], v[212:215], v[76:79]
	v_mfma_f32_16x16x32_bf16 v[72:75], v[164:167], v[212:215], v[72:75]
	v_mfma_f32_16x16x32_bf16 v[116:119], v[168:171], v[184:187], v[116:119]
	v_mfma_f32_16x16x32_bf16 v[112:115], v[176:179], v[184:187], v[112:115]
	v_mfma_f32_16x16x32_bf16 v[100:103], v[168:171], v[192:195], v[100:103]
	v_mfma_f32_16x16x32_bf16 v[96:99], v[176:179], v[192:195], v[96:99]
	v_mfma_f32_16x16x32_bf16 v[84:87], v[168:171], v[200:203], v[84:87]
	v_mfma_f32_16x16x32_bf16 v[80:83], v[176:179], v[200:203], v[80:83]
	v_mfma_f32_16x16x32_bf16 v[68:71], v[168:171], v[208:211], v[68:71]
	v_mfma_f32_16x16x32_bf16 v[64:67], v[176:179], v[208:211], v[64:67]
	v_mfma_f32_16x16x32_bf16 v[116:119], v[172:175], v[188:191], v[116:119]
	v_mfma_f32_16x16x32_bf16 v[112:115], v[180:183], v[188:191], v[112:115]
	v_mfma_f32_16x16x32_bf16 v[100:103], v[172:175], v[196:199], v[100:103]
	v_mfma_f32_16x16x32_bf16 v[96:99], v[180:183], v[196:199], v[96:99]
	v_mfma_f32_16x16x32_bf16 v[84:87], v[172:175], v[204:207], v[84:87]
	v_mfma_f32_16x16x32_bf16 v[80:83], v[180:183], v[204:207], v[80:83]
	v_mfma_f32_16x16x32_bf16 v[68:71], v[172:175], v[212:215], v[68:71]
	v_mfma_f32_16x16x32_bf16 v[64:67], v[180:183], v[212:215], v[64:67]
	s_barrier
; #define PG8_STAGE(bufoff, gbase, voff) do { _Pragma("unroll") for (int _i = 0; _i < 2; ++_i) \
;         __builtin_amdgcn_global_load_lds((const unsigned*)((const char*)(gbase) + (voff)[_i]), (PG8_LAS unsigned*)(lds + (bufoff) + ldsw + _i * 8192), 16, 0, 0); } while (0)
; #define PG8_LDA(dst, b, h) do { _Pragma("unroll") for (int m = 0; m < 4; ++m) _Pragma("unroll") for (int k = 0; k < 2; ++k) dst[m][k] = *(const PG8_LAS bf16x8*)(lds + PG8_SA(b, h) + aoff + m * 2048 + k * 1024); } while (0)
; #define PG8_LDB(dst, b, h) do { _Pragma("unroll") for (int n = 0; n < 2; ++n) _Pragma("unroll") for (int k = 0; k < 2; ++k) dst[n][k] = *(const PG8_LAS bf16x8*)(lds + PG8_SB(b, h) + boff + n * 2048 + k * 1024); } while (0)
; #define PG8_BAR __builtin_amdgcn_s_barrier()
; template <class Epi, class Sched, bool ALIGN_EPI = false, bool SP2 = false>
; __device__ __forceinline__ void gemm_phase(PG8_LAS unsigned char* lds, const Gemm g, const Sched& S, const Epi& E) {
;     ...
;             const bool last = (t == nt - 2);
;             const char* a1 = cA + (size_t)(t + 1) * kstep;
;             const char* a2 = last ? nA : cA + (size_t)(t + 2) * kstep; const char* b2 = last ? nB : cB + (size_t)(t + 2) * kstep;
;             const char* a3 = a2 + kstep; const char* b3 = b2 + kstep;
;             if (last && has_next) S.a_ready(nxt);
;             if constexpr (SP2) {
;             PG8_LDB(B0, 0, 0); PG8_LDB(B1, 0, 1); PG8_SCHED; PG8_LDA(At, 0, 0); PG8_STAGE(PG8_SA(1, 1), a1 + hstep, voffA);
;             PG8_WAIT_V(8); PG8_WAIT_L(0); PG8_BAR; PG8_MMA(0, 0, At, B0); PG8_MMA(0, 1, At, B1); PG8_BAR; PG8_SCHED;
;             PG8_LDA(At, 0, 1); PG8_STAGE(PG8_SB(0, 0), b2, voffB); PG8_STAGE(PG8_SB(0, 1), b2 + hstep, voffB); PG8_STAGE(PG8_SA(0, 0), a2, voffA);
;             PG8_WAIT_V(8); PG8_WAIT_L(0); PG8_BAR; PG8_MMA(1, 0, At, B0); PG8_MMA(1, 1, At, B1); PG8_BAR; PG8_SCHED;
;             PG8_LDB(B0, 1, 0); PG8_LDB(B1, 1, 1); PG8_SCHED; PG8_LDA(At, 1, 0); PG8_STAGE(PG8_SA(0, 1), a2 + hstep, voffA);
;             PG8_WAIT_V(8); PG8_WAIT_L(0); PG8_BAR; PG8_MMA(0, 0, At, B0); PG8_MMA(0, 1, At, B1); PG8_BAR; PG8_SCHED;
;             PG8_LDA(At, 1, 1); PG8_STAGE(PG8_SB(1, 0), b3, voffB); PG8_STAGE(PG8_SB(1, 1), b3 + hstep, voffB); PG8_STAGE(PG8_SA(1, 0), a3, voffA);
;             PG8_WAIT_V(8); PG8_WAIT_L(0); PG8_BAR; PG8_MMA(1, 0, At, B0); PG8_MMA(1, 1, At, B1); PG8_BAR; PG8_SCHED;
	s_setprio 0
	s_add_i32 s22, s52, s34
	v_lshl_add_u64 v[148:149], v[148:149], 0, s[6:7]
	s_mov_b32 m0, s22
	ds_read_b128 v[184:187], v155 offset:49152
	ds_read_b128 v[188:191], v155 offset:50176
	ds_read_b128 v[192:195], v155 offset:51200
	ds_read_b128 v[196:199], v155 offset:52224
	ds_read_b128 v[200:203], v155 offset:53248
	ds_read_b128 v[204:207], v155 offset:54272
	ds_read_b128 v[208:211], v155 offset:55296
	ds_read_b128 v[212:215], v155 offset:56320
	global_load_lds_dwordx4 v[148:149], off
	s_add_i32 m0, s22, 0x2000
	s_add_u32 s22, s26, 0xb0080
	v_lshl_add_u64 v[148:149], v[216:217], 0, s[6:7]
	s_addc_u32 s23, s27, 0
	s_add_i32 s26, s53, s34
	global_load_lds_dwordx4 v[148:149], off
	v_lshl_add_u64 v[148:149], s[22:23], 0, v[130:131]
	s_mov_b32 m0, s26
	s_nop 0
	global_load_lds_dwordx4 v[148:149], off
	v_lshl_add_u64 v[148:149], s[22:23], 0, v[134:135]
	s_add_i32 m0, s26, 0x2000
	s_nop 0
	global_load_lds_dwordx4 v[148:149], off
	v_lshl_add_u64 v[148:149], v[218:219], 0, s[6:7]
	s_mov_b32 m0, s40
	s_nop 0
	global_load_lds_dwordx4 v[148:149], off
	v_lshl_add_u64 v[148:149], v[220:221], 0, s[6:7]
	s_mov_b32 m0, s41
	s_nop 0
	global_load_lds_dwordx4 v[148:149], off
	s_waitcnt vmcnt(8)
	s_waitcnt lgkmcnt(0)
	s_setprio 1
	s_barrier
	v_mfma_f32_16x16x32_bf16 v[60:63], v[144:147], v[184:187], v[60:63]
	v_mfma_f32_16x16x32_bf16 v[56:59], v[160:163], v[184:187], v[56:59]
	v_mfma_f32_16x16x32_bf16 v[44:47], v[144:147], v[192:195], v[44:47]
	v_mfma_f32_16x16x32_bf16 v[40:43], v[160:163], v[192:195], v[40:43]
	v_mfma_f32_16x16x32_bf16 v[28:31], v[144:147], v[200:203], v[28:31]
	v_mfma_f32_16x16x32_bf16 v[24:27], v[160:163], v[200:203], v[24:27]
	v_mfma_f32_16x16x32_bf16 v[12:15], v[144:147], v[208:211], v[12:15]
	v_mfma_f32_16x16x32_bf16 v[8:11], v[160:163], v[208:211], v[8:11]
	v_mfma_f32_16x16x32_bf16 v[60:63], v[156:159], v[188:191], v[60:63]
	v_mfma_f32_16x16x32_bf16 v[56:59], v[164:167], v[188:191], v[56:59]
	v_mfma_f32_16x16x32_bf16 v[44:47], v[156:159], v[196:199], v[44:47]
	v_mfma_f32_16x16x32_bf16 v[40:43], v[164:167], v[196:199], v[40:43]
	v_mfma_f32_16x16x32_bf16 v[28:31], v[156:159], v[204:207], v[28:31]
	v_mfma_f32_16x16x32_bf16 v[24:27], v[164:167], v[204:207], v[24:27]
	v_mfma_f32_16x16x32_bf16 v[12:15], v[156:159], v[212:215], v[12:15]
	v_mfma_f32_16x16x32_bf16 v[8:11], v[164:167], v[212:215], v[8:11]
	v_mfma_f32_16x16x32_bf16 v[52:55], v[168:171], v[184:187], v[52:55]
	v_mfma_f32_16x16x32_bf16 v[48:51], v[176:179], v[184:187], v[48:51]
	v_mfma_f32_16x16x32_bf16 v[36:39], v[168:171], v[192:195], v[36:39]
	v_mfma_f32_16x16x32_bf16 v[32:35], v[176:179], v[192:195], v[32:35]
	v_mfma_f32_16x16x32_bf16 v[20:23], v[168:171], v[200:203], v[20:23]
	v_mfma_f32_16x16x32_bf16 v[16:19], v[176:179], v[200:203], v[16:19]
	v_mfma_f32_16x16x32_bf16 v[4:7], v[168:171], v[208:211], v[4:7]
	v_mfma_f32_16x16x32_bf16 v[0:3], v[176:179], v[208:211], v[0:3]
	v_mfma_f32_16x16x32_bf16 v[52:55], v[172:175], v[188:191], v[52:55]
	v_mfma_f32_16x16x32_bf16 v[48:51], v[180:183], v[188:191], v[48:51]
	v_mfma_f32_16x16x32_bf16 v[36:39], v[172:175], v[196:199], v[36:39]
	v_mfma_f32_16x16x32_bf16 v[32:35], v[180:183], v[196:199], v[32:35]
	v_mfma_f32_16x16x32_bf16 v[20:23], v[172:175], v[204:207], v[20:23]
	v_mfma_f32_16x16x32_bf16 v[16:19], v[180:183], v[204:207], v[16:19]
	v_mfma_f32_16x16x32_bf16 v[4:7], v[172:175], v[212:215], v[4:7]
	v_mfma_f32_16x16x32_bf16 v[0:3], v[180:183], v[212:215], v[0:3]
	s_barrier
	s_setprio 0
	s_add_i32 s51, s51, 2
	s_add_u32 s49, s49, 0x100
	s_addc_u32 s50, s50, 0
	s_mov_b64 s[22:23], s[24:25]
.LBB0_862:
	ds_read_b128 v[144:147], v153
	ds_read_b128 v[156:159], v153 offset:1024
	ds_read_b128 v[160:163], v153 offset:2048
	ds_read_b128 v[164:167], v153 offset:3072
	ds_read_b128 v[168:171], v154
	ds_read_b128 v[172:175], v154 offset:1024
	ds_read_b128 v[176:179], v154 offset:2048
	ds_read_b128 v[180:183], v154 offset:3072
	s_add_u32 s24, s22, 0x100
	s_addc_u32 s25, s23, 0
	s_cmp_eq_u32 s51, 40
	s_cselect_b32 s29, s5, s25
	s_cselect_b32 s28, s4, s24
	s_cselect_b32 s27, s21, s50
	s_cselect_b32 s26, s20, s49
	v_lshl_add_u64 v[148:149], s[22:23], 0, v[136:137]
	s_add_i32 m0, s35, 0xc000
	ds_read_b128 v[184:187], v155
	ds_read_b128 v[188:191], v155 offset:1024
	ds_read_b128 v[192:195], v155 offset:2048
	ds_read_b128 v[196:199], v155 offset:3072
	ds_read_b128 v[200:203], v155 offset:4096
	ds_read_b128 v[204:207], v155 offset:5120
	ds_read_b128 v[208:211], v155 offset:6144
	ds_read_b128 v[212:215], v155 offset:7168
	global_load_lds_dwordx4 v[148:149], off
	v_lshl_add_u64 v[148:149], s[22:23], 0, v[138:139]
	s_add_i32 m0, s35, 0xe000
	s_nop 0
	global_load_lds_dwordx4 v[148:149], off
	s_waitcnt vmcnt(8)
	s_waitcnt lgkmcnt(0)
	s_setprio 1
	s_barrier
; #define PG8_STAGE(bufoff, gbase, voff) do { _Pragma("unroll") for (int _i = 0; _i < 2; ++_i) \
;         __builtin_amdgcn_global_load_lds((const unsigned*)((const char*)(gbase) + (voff)[_i]), (PG8_LAS unsigned*)(lds + (bufoff) + ldsw + _i * 8192), 16, 0, 0); } while (0)
; #define PG8_LDA(dst, b, h) do { _Pragma("unroll") for (int m = 0; m < 4; ++m) _Pragma("unroll") for (int k = 0; k < 2; ++k) dst[m][k] = *(const PG8_LAS bf16x8*)(lds + PG8_SA(b, h) + aoff + m * 2048 + k * 1024); } while (0)
; #define PG8_MMA(ai, bj, At, Bt) do { __builtin_amdgcn_s_setprio(1); _Pragma("unroll") for (int m = 0; m < 4; ++m) _Pragma("unroll") for (int n = 0; n < 2; ++n) _Pragma("unroll") for (int k = 0; k < 2; ++k) \
;         acc[ai][bj][m][n] = __builtin_amdgcn_mfma_f32_16x16x32_bf16(Bt[n][k], At[m][k], acc[ai][bj][m][n], 0, 0, 0); __builtin_amdgcn_s_setprio(0); } while (0)
; #define PG8_WAIT_V(n) asm volatile("s_waitcnt vmcnt(" #n ")" ::: "memory")
; #define PG8_WAIT_L(n) asm volatile("s_waitcnt lgkmcnt(" #n ")" ::: "memory")
; #define PG8_BAR __builtin_amdgcn_s_barrier()
; #define PG8_SCHED __builtin_amdgcn_sched_barrier(0)
; template <class Epi, class Sched, bool ALIGN_EPI = false, bool SP2 = false>
; __device__ __forceinline__ void gemm_phase(PG8_LAS unsigned char* lds, const Gemm g, const Sched& S, const Epi& E) {
;     ...
;             PG8_WAIT_V(8); PG8_WAIT_L(0); PG8_BAR; PG8_MMA(0, 0, At, B0); PG8_MMA(0, 1, At, B1); PG8_BAR; PG8_SCHED;
;             PG8_LDA(At, 0, 1); PG8_STAGE(PG8_SB(0, 0), b2, voffB); PG8_STAGE(PG8_SB(0, 1), b2 + hstep, voffB); PG8_STAGE(PG8_SA(0, 0), a2, voffA);
;             PG8_WAIT_V(8); PG8_WAIT_L(0); PG8_BAR; PG8_MMA(1, 0, At, B0); PG8_MMA(1, 1, At, B1); PG8_BAR; PG8_SCHED;
	v_mfma_f32_16x16x32_bf16 v[124:127], v[144:147], v[184:187], v[124:127]
	v_mfma_f32_16x16x32_bf16 v[120:123], v[160:163], v[184:187], v[120:123]
	v_mfma_f32_16x16x32_bf16 v[108:111], v[144:147], v[192:195], v[108:111]
	v_mfma_f32_16x16x32_bf16 v[104:107], v[160:163], v[192:195], v[104:107]
	v_mfma_f32_16x16x32_bf16 v[92:95], v[144:147], v[200:203], v[92:95]
	v_mfma_f32_16x16x32_bf16 v[88:91], v[160:163], v[200:203], v[88:91]
	v_mfma_f32_16x16x32_bf16 v[76:79], v[144:147], v[208:211], v[76:79]
	v_mfma_f32_16x16x32_bf16 v[72:75], v[160:163], v[208:211], v[72:75]
	v_mfma_f32_16x16x32_bf16 v[124:127], v[156:159], v[188:191], v[124:127]
	v_mfma_f32_16x16x32_bf16 v[120:123], v[164:167], v[188:191], v[120:123]
	v_mfma_f32_16x16x32_bf16 v[108:111], v[156:159], v[196:199], v[108:111]
	v_mfma_f32_16x16x32_bf16 v[104:107], v[164:167], v[196:199], v[104:107]
	v_mfma_f32_16x16x32_bf16 v[92:95], v[156:159], v[204:207], v[92:95]
	v_mfma_f32_16x16x32_bf16 v[88:91], v[164:167], v[204:207], v[88:91]
	v_mfma_f32_16x16x32_bf16 v[76:79], v[156:159], v[212:215], v[76:79]
	v_mfma_f32_16x16x32_bf16 v[72:75], v[164:167], v[212:215], v[72:75]
	v_mfma_f32_16x16x32_bf16 v[116:119], v[168:171], v[184:187], v[116:119]
	v_mfma_f32_16x16x32_bf16 v[112:115], v[176:179], v[184:187], v[112:115]
	v_mfma_f32_16x16x32_bf16 v[100:103], v[168:171], v[192:195], v[100:103]
	v_mfma_f32_16x16x32_bf16 v[96:99], v[176:179], v[192:195], v[96:99]
	v_mfma_f32_16x16x32_bf16 v[84:87], v[168:171], v[200:203], v[84:87]
	v_mfma_f32_16x16x32_bf16 v[80:83], v[176:179], v[200:203], v[80:83]
	v_mfma_f32_16x16x32_bf16 v[68:71], v[168:171], v[208:211], v[68:71]
	v_mfma_f32_16x16x32_bf16 v[64:67], v[176:179], v[208:211], v[64:67]
	v_mfma_f32_16x16x32_bf16 v[116:119], v[172:175], v[188:191], v[116:119]
	v_mfma_f32_16x16x32_bf16 v[112:115], v[180:183], v[188:191], v[112:115]
	v_mfma_f32_16x16x32_bf16 v[100:103], v[172:175], v[196:199], v[100:103]
	v_mfma_f32_16x16x32_bf16 v[96:99], v[180:183], v[196:199], v[96:99]
	v_mfma_f32_16x16x32_bf16 v[84:87], v[172:175], v[204:207], v[84:87]
	v_mfma_f32_16x16x32_bf16 v[80:83], v[180:183], v[204:207], v[80:83]
	v_mfma_f32_16x16x32_bf16 v[68:71], v[172:175], v[212:215], v[68:71]
	v_mfma_f32_16x16x32_bf16 v[64:67], v[180:183], v[212:215], v[64:67]
	s_barrier
	s_setprio 0
	s_add_i32 s22, s43, s34
	v_lshl_add_u64 v[148:149], s[26:27], 0, v[130:131]
	s_mov_b32 m0, s22
	ds_read_b128 v[184:187], v155 offset:16384
	ds_read_b128 v[188:191], v155 offset:17408
	ds_read_b128 v[192:195], v155 offset:18432
	ds_read_b128 v[196:199], v155 offset:19456
	ds_read_b128 v[200:203], v155 offset:20480
	ds_read_b128 v[204:207], v155 offset:21504
	ds_read_b128 v[208:211], v155 offset:22528
	ds_read_b128 v[212:215], v155 offset:23552
	global_load_lds_dwordx4 v[148:149], off
	s_add_i32 m0, s22, 0x2000
	s_add_u32 s22, s26, 0xb0000
	v_lshl_add_u64 v[216:217], s[26:27], 0, v[134:135]
	s_addc_u32 s23, s27, 0
	s_add_i32 s52, s44, s34
	global_load_lds_dwordx4 v[216:217], off
	v_lshl_add_u64 v[218:219], s[22:23], 0, v[130:131]
	s_mov_b32 m0, s52
	v_lshl_add_u64 v[220:221], s[28:29], 0, v[132:133]
	global_load_lds_dwordx4 v[218:219], off
	v_lshl_add_u64 v[218:219], s[22:23], 0, v[134:135]
	s_add_i32 m0, s52, 0x2000
	s_nop 0
	global_load_lds_dwordx4 v[218:219], off
	v_lshl_add_u64 v[218:219], s[28:29], 0, v[128:129]
	s_mov_b32 m0, s35
	s_nop 0
	global_load_lds_dwordx4 v[218:219], off
	s_mov_b32 m0, s36
	s_nop 0
	global_load_lds_dwordx4 v[220:221], off
	s_waitcnt vmcnt(8)
	s_waitcnt lgkmcnt(0)
	s_setprio 1
	s_barrier
	v_mfma_f32_16x16x32_bf16 v[60:63], v[144:147], v[184:187], v[60:63]
	v_mfma_f32_16x16x32_bf16 v[56:59], v[160:163], v[184:187], v[56:59]
	v_mfma_f32_16x16x32_bf16 v[44:47], v[144:147], v[192:195], v[44:47]
	v_mfma_f32_16x16x32_bf16 v[40:43], v[160:163], v[192:195], v[40:43]
	v_mfma_f32_16x16x32_bf16 v[28:31], v[144:147], v[200:203], v[28:31]
	v_mfma_f32_16x16x32_bf16 v[24:27], v[160:163], v[200:203], v[24:27]
	v_mfma_f32_16x16x32_bf16 v[12:15], v[144:147], v[208:211], v[12:15]
	v_mfma_f32_16x16x32_bf16 v[8:11], v[160:163], v[208:211], v[8:11]
	v_mfma_f32_16x16x32_bf16 v[60:63], v[156:159], v[188:191], v[60:63]
	v_mfma_f32_16x16x32_bf16 v[56:59], v[164:167], v[188:191], v[56:59]
	v_mfma_f32_16x16x32_bf16 v[44:47], v[156:159], v[196:199], v[44:47]
	v_mfma_f32_16x16x32_bf16 v[40:43], v[164:167], v[196:199], v[40:43]
	v_mfma_f32_16x16x32_bf16 v[28:31], v[156:159], v[204:207], v[28:31]
	v_mfma_f32_16x16x32_bf16 v[24:27], v[164:167], v[204:207], v[24:27]
	v_mfma_f32_16x16x32_bf16 v[12:15], v[156:159], v[212:215], v[12:15]
	v_mfma_f32_16x16x32_bf16 v[8:11], v[164:167], v[212:215], v[8:11]
	v_mfma_f32_16x16x32_bf16 v[52:55], v[168:171], v[184:187], v[52:55]
	v_mfma_f32_16x16x32_bf16 v[48:51], v[176:179], v[184:187], v[48:51]
	v_mfma_f32_16x16x32_bf16 v[36:39], v[168:171], v[192:195], v[36:39]
	v_mfma_f32_16x16x32_bf16 v[32:35], v[176:179], v[192:195], v[32:35]
	v_mfma_f32_16x16x32_bf16 v[20:23], v[168:171], v[200:203], v[20:23]
	v_mfma_f32_16x16x32_bf16 v[16:19], v[176:179], v[200:203], v[16:19]
	v_mfma_f32_16x16x32_bf16 v[4:7], v[168:171], v[208:211], v[4:7]
	v_mfma_f32_16x16x32_bf16 v[0:3], v[176:179], v[208:211], v[0:3]
	v_mfma_f32_16x16x32_bf16 v[52:55], v[172:175], v[188:191], v[52:55]
	v_mfma_f32_16x16x32_bf16 v[48:51], v[180:183], v[188:191], v[48:51]
	v_mfma_f32_16x16x32_bf16 v[36:39], v[172:175], v[196:199], v[36:39]
	v_mfma_f32_16x16x32_bf16 v[32:35], v[180:183], v[196:199], v[32:35]
	v_mfma_f32_16x16x32_bf16 v[20:23], v[172:175], v[204:207], v[20:23]
	v_mfma_f32_16x16x32_bf16 v[16:19], v[180:183], v[204:207], v[16:19]
	v_mfma_f32_16x16x32_bf16 v[4:7], v[172:175], v[212:215], v[4:7]
	v_mfma_f32_16x16x32_bf16 v[0:3], v[180:183], v[212:215], v[0:3]
	s_barrier
; #define PG8_STAGE(bufoff, gbase, voff) do { _Pragma("unroll") for (int _i = 0; _i < 2; ++_i) \
;         __builtin_amdgcn_global_load_lds((const unsigned*)((const char*)(gbase) + (voff)[_i]), (PG8_LAS unsigned*)(lds + (bufoff) + ldsw + _i * 8192), 16, 0, 0); } while (0)
; #define PG8_LDA(dst, b, h) do { _Pragma("unroll") for (int m = 0; m < 4; ++m) _Pragma("unroll") for (int k = 0; k < 2; ++k) dst[m][k] = *(const PG8_LAS bf16x8*)(lds + PG8_SA(b, h) + aoff + m * 2048 + k * 1024); } while (0)
; #define PG8_LDB(dst, b, h) do { _Pragma("unroll") for (int n = 0; n < 2; ++n) _Pragma("unroll") for (int k = 0; k < 2; ++k) dst[n][k] = *(const PG8_LAS bf16x8*)(lds + PG8_SB(b, h) + boff + n * 2048 + k * 1024); } while (0)
; #define PG8_MMA(ai, bj, At, Bt) do { __builtin_amdgcn_s_setprio(1); _Pragma("unroll") for (int m = 0; m < 4; ++m) _Pragma("unroll") for (int n = 0; n < 2; ++n) _Pragma("unroll") for (int k = 0; k < 2; ++k) \
;         acc[ai][bj][m][n] = __builtin_amdgcn_mfma_f32_16x16x32_bf16(Bt[n][k], At[m][k], acc[ai][bj][m][n], 0, 0, 0); __builtin_amdgcn_s_setprio(0); } while (0)
; #define PG8_WAIT_V(n) asm volatile("s_waitcnt vmcnt(" #n ")" ::: "memory")
; #define PG8_WAIT_L(n) asm volatile("s_waitcnt lgkmcnt(" #n ")" ::: "memory")
; #define PG8_BAR __builtin_amdgcn_s_barrier()
; #define PG8_SCHED __builtin_amdgcn_sched_barrier(0)
; template <class Epi, class Sched, bool ALIGN_EPI = false, bool SP2 = false>
; __device__ __forceinline__ void gemm_phase(PG8_LAS unsigned char* lds, const Gemm g, const Sched& S, const Epi& E) {
;     ...
;             PG8_LDB(B0, 1, 0); PG8_LDB(B1, 1, 1); PG8_SCHED; PG8_LDA(At, 1, 0); PG8_STAGE(PG8_SA(0, 1), a2 + hstep, voffA);
;             PG8_WAIT_V(8); PG8_WAIT_L(0); PG8_BAR; PG8_MMA(0, 0, At, B0); PG8_MMA(0, 1, At, B1); PG8_BAR; PG8_SCHED;
	s_setprio 0
	s_add_i32 s52, 0, 0x18000
	s_add_i32 s53, 0, 0x1c000
	v_add_u32_e32 v164, s52, v151
	v_add_u32_e32 v180, s53, v151
	ds_read_b128 v[144:147], v164
	ds_read_b128 v[156:159], v164 offset:1024
	ds_read_b128 v[160:163], v164 offset:2048
	ds_read_b128 v[164:167], v164 offset:3072
	ds_read_b128 v[168:171], v180
	ds_read_b128 v[172:175], v180 offset:1024
	ds_read_b128 v[176:179], v180 offset:2048
	ds_read_b128 v[180:183], v180 offset:3072
	s_add_u32 s22, s28, 0xb0000
	s_addc_u32 s23, s29, 0
	s_mov_b32 m0, s37
	v_lshl_add_u64 v[222:223], s[22:23], 0, v[128:129]
	ds_read_b128 v[184:187], v155 offset:32768
	ds_read_b128 v[188:191], v155 offset:33792
	ds_read_b128 v[192:195], v155 offset:34816
	ds_read_b128 v[196:199], v155 offset:35840
	ds_read_b128 v[200:203], v155 offset:36864
	ds_read_b128 v[204:207], v155 offset:37888
	ds_read_b128 v[208:211], v155 offset:38912
	ds_read_b128 v[212:215], v155 offset:39936
	global_load_lds_dwordx4 v[222:223], off
	v_lshl_add_u64 v[222:223], s[22:23], 0, v[132:133]
	s_mov_b32 m0, s38
	s_nop 0
	global_load_lds_dwordx4 v[222:223], off
	s_waitcnt vmcnt(8)
	s_waitcnt lgkmcnt(0)
	s_setprio 1
	s_barrier
	v_mfma_f32_16x16x32_bf16 v[124:127], v[144:147], v[184:187], v[124:127]
	v_mfma_f32_16x16x32_bf16 v[120:123], v[160:163], v[184:187], v[120:123]
	v_mfma_f32_16x16x32_bf16 v[108:111], v[144:147], v[192:195], v[108:111]
	v_mfma_f32_16x16x32_bf16 v[104:107], v[160:163], v[192:195], v[104:107]
	v_mfma_f32_16x16x32_bf16 v[92:95], v[144:147], v[200:203], v[92:95]
	v_mfma_f32_16x16x32_bf16 v[88:91], v[160:163], v[200:203], v[88:91]
	v_mfma_f32_16x16x32_bf16 v[76:79], v[144:147], v[208:211], v[76:79]
	v_mfma_f32_16x16x32_bf16 v[72:75], v[160:163], v[208:211], v[72:75]
	v_mfma_f32_16x16x32_bf16 v[124:127], v[156:159], v[188:191], v[124:127]
	v_mfma_f32_16x16x32_bf16 v[120:123], v[164:167], v[188:191], v[120:123]
	v_mfma_f32_16x16x32_bf16 v[108:111], v[156:159], v[196:199], v[108:111]
	v_mfma_f32_16x16x32_bf16 v[104:107], v[164:167], v[196:199], v[104:107]
	v_mfma_f32_16x16x32_bf16 v[92:95], v[156:159], v[204:207], v[92:95]
	v_mfma_f32_16x16x32_bf16 v[88:91], v[164:167], v[204:207], v[88:91]
	v_mfma_f32_16x16x32_bf16 v[76:79], v[156:159], v[212:215], v[76:79]
	v_mfma_f32_16x16x32_bf16 v[72:75], v[164:167], v[212:215], v[72:75]
	v_mfma_f32_16x16x32_bf16 v[116:119], v[168:171], v[184:187], v[116:119]
	v_mfma_f32_16x16x32_bf16 v[112:115], v[176:179], v[184:187], v[112:115]
	v_mfma_f32_16x16x32_bf16 v[100:103], v[168:171], v[192:195], v[100:103]
	v_mfma_f32_16x16x32_bf16 v[96:99], v[176:179], v[192:195], v[96:99]
	v_mfma_f32_16x16x32_bf16 v[84:87], v[168:171], v[200:203], v[84:87]
	v_mfma_f32_16x16x32_bf16 v[80:83], v[176:179], v[200:203], v[80:83]
	v_mfma_f32_16x16x32_bf16 v[68:71], v[168:171], v[208:211], v[68:71]
	v_mfma_f32_16x16x32_bf16 v[64:67], v[176:179], v[208:211], v[64:67]
	v_mfma_f32_16x16x32_bf16 v[116:119], v[172:175], v[188:191], v[116:119]
	v_mfma_f32_16x16x32_bf16 v[112:115], v[180:183], v[188:191], v[112:115]
	v_mfma_f32_16x16x32_bf16 v[100:103], v[172:175], v[196:199], v[100:103]
	v_mfma_f32_16x16x32_bf16 v[96:99], v[180:183], v[196:199], v[96:99]
	v_mfma_f32_16x16x32_bf16 v[84:87], v[172:175], v[204:207], v[84:87]
	v_mfma_f32_16x16x32_bf16 v[80:83], v[180:183], v[204:207], v[80:83]
	v_mfma_f32_16x16x32_bf16 v[68:71], v[172:175], v[212:215], v[68:71]
	v_mfma_f32_16x16x32_bf16 v[64:67], v[180:183], v[212:215], v[64:67]
	s_barrier
; #define PG8_STAGE(bufoff, gbase, voff) do { _Pragma("unroll") for (int _i = 0; _i < 2; ++_i) \
;         __builtin_amdgcn_global_load_lds((const unsigned*)((const char*)(gbase) + (voff)[_i]), (PG8_LAS unsigned*)(lds + (bufoff) + ldsw + _i * 8192), 16, 0, 0); } while (0)
; #define PG8_LDA(dst, b, h) do { _Pragma("unroll") for (int m = 0; m < 4; ++m) _Pragma("unroll") for (int k = 0; k < 2; ++k) dst[m][k] = *(const PG8_LAS bf16x8*)(lds + PG8_SA(b, h) + aoff + m * 2048 + k * 1024); } while (0)
; #define PG8_MMA(ai, bj, At, Bt) do { __builtin_amdgcn_s_setprio(1); _Pragma("unroll") for (int m = 0; m < 4; ++m) _Pragma("unroll") for (int n = 0; n < 2; ++n) _Pragma("unroll") for (int k = 0; k < 2; ++k) \
;         acc[ai][bj][m][n] = __builtin_amdgcn_mfma_f32_16x16x32_bf16(Bt[n][k], At[m][k], acc[ai][bj][m][n], 0, 0, 0); __builtin_amdgcn_s_setprio(0); } while (0)
; #define PG8_WAIT_V(n) asm volatile("s_waitcnt vmcnt(" #n ")" ::: "memory")
; #define PG8_WAIT_L(n) asm volatile("s_waitcnt lgkmcnt(" #n ")" ::: "memory")
; #define PG8_BAR __builtin_amdgcn_s_barrier()
; #define PG8_SCHED __builtin_amdgcn_sched_barrier(0)
; template <class Epi, class Sched, bool ALIGN_EPI = false, bool SP2 = false>
; __device__ __forceinline__ void gemm_phase(PG8_LAS unsigned char* lds, const Gemm g, const Sched& S, const Epi& E) {
;     ...
;         for (int t = 0; t < nt; t += 2) {
;     ...
;             PG8_LDA(At, 1, 1); PG8_STAGE(PG8_SB(1, 0), b3, voffB); PG8_STAGE(PG8_SB(1, 1), b3 + hstep, voffB); PG8_STAGE(PG8_SA(1, 0), a3, voffA);
;             PG8_WAIT_V(8); PG8_WAIT_L(0); PG8_BAR; PG8_MMA(1, 0, At, B0); PG8_MMA(1, 1, At, B1); PG8_BAR; PG8_SCHED;
	s_setprio 0
	s_add_i32 s22, s52, s34
	v_lshl_add_u64 v[148:149], v[148:149], 0, s[6:7]
	s_mov_b32 m0, s22
	ds_read_b128 v[184:187], v155 offset:49152
	ds_read_b128 v[188:191], v155 offset:50176
	ds_read_b128 v[192:195], v155 offset:51200
	ds_read_b128 v[196:199], v155 offset:52224
	ds_read_b128 v[200:203], v155 offset:53248
	ds_read_b128 v[204:207], v155 offset:54272
	ds_read_b128 v[208:211], v155 offset:55296
	ds_read_b128 v[212:215], v155 offset:56320
	global_load_lds_dwordx4 v[148:149], off
	s_add_i32 m0, s22, 0x2000
	s_add_u32 s22, s26, 0xb0080
	v_lshl_add_u64 v[148:149], v[216:217], 0, s[6:7]
	s_addc_u32 s23, s27, 0
	s_add_i32 s26, s53, s34
	global_load_lds_dwordx4 v[148:149], off
	v_lshl_add_u64 v[148:149], s[22:23], 0, v[130:131]
	s_mov_b32 m0, s26
	s_nop 0
	global_load_lds_dwordx4 v[148:149], off
	v_lshl_add_u64 v[148:149], s[22:23], 0, v[134:135]
	s_add_i32 m0, s26, 0x2000
	s_nop 0
	global_load_lds_dwordx4 v[148:149], off
	v_lshl_add_u64 v[148:149], v[218:219], 0, s[6:7]
	s_mov_b32 m0, s40
	s_nop 0
	global_load_lds_dwordx4 v[148:149], off
	v_lshl_add_u64 v[148:149], v[220:221], 0, s[6:7]
	s_mov_b32 m0, s41
	s_nop 0
	global_load_lds_dwordx4 v[148:149], off
	s_waitcnt vmcnt(8)
	s_waitcnt lgkmcnt(0)
	s_setprio 1
	s_barrier
	v_mfma_f32_16x16x32_bf16 v[60:63], v[144:147], v[184:187], v[60:63]
	v_mfma_f32_16x16x32_bf16 v[56:59], v[160:163], v[184:187], v[56:59]
	v_mfma_f32_16x16x32_bf16 v[44:47], v[144:147], v[192:195], v[44:47]
	v_mfma_f32_16x16x32_bf16 v[40:43], v[160:163], v[192:195], v[40:43]
	v_mfma_f32_16x16x32_bf16 v[28:31], v[144:147], v[200:203], v[28:31]
	v_mfma_f32_16x16x32_bf16 v[24:27], v[160:163], v[200:203], v[24:27]
	v_mfma_f32_16x16x32_bf16 v[12:15], v[144:147], v[208:211], v[12:15]
	v_mfma_f32_16x16x32_bf16 v[8:11], v[160:163], v[208:211], v[8:11]
	v_mfma_f32_16x16x32_bf16 v[60:63], v[156:159], v[188:191], v[60:63]
	v_mfma_f32_16x16x32_bf16 v[56:59], v[164:167], v[188:191], v[56:59]
	v_mfma_f32_16x16x32_bf16 v[44:47], v[156:159], v[196:199], v[44:47]
	v_mfma_f32_16x16x32_bf16 v[40:43], v[164:167], v[196:199], v[40:43]
	v_mfma_f32_16x16x32_bf16 v[28:31], v[156:159], v[204:207], v[28:31]
	v_mfma_f32_16x16x32_bf16 v[24:27], v[164:167], v[204:207], v[24:27]
	v_mfma_f32_16x16x32_bf16 v[12:15], v[156:159], v[212:215], v[12:15]
	v_mfma_f32_16x16x32_bf16 v[8:11], v[164:167], v[212:215], v[8:11]
	v_mfma_f32_16x16x32_bf16 v[52:55], v[168:171], v[184:187], v[52:55]
	v_mfma_f32_16x16x32_bf16 v[48:51], v[176:179], v[184:187], v[48:51]
	v_mfma_f32_16x16x32_bf16 v[36:39], v[168:171], v[192:195], v[36:39]
	v_mfma_f32_16x16x32_bf16 v[32:35], v[176:179], v[192:195], v[32:35]
	v_mfma_f32_16x16x32_bf16 v[20:23], v[168:171], v[200:203], v[20:23]
	v_mfma_f32_16x16x32_bf16 v[16:19], v[176:179], v[200:203], v[16:19]
	v_mfma_f32_16x16x32_bf16 v[4:7], v[168:171], v[208:211], v[4:7]
	v_mfma_f32_16x16x32_bf16 v[0:3], v[176:179], v[208:211], v[0:3]
	v_mfma_f32_16x16x32_bf16 v[52:55], v[172:175], v[188:191], v[52:55]
	v_mfma_f32_16x16x32_bf16 v[48:51], v[180:183], v[188:191], v[48:51]
	v_mfma_f32_16x16x32_bf16 v[36:39], v[172:175], v[196:199], v[36:39]
	v_mfma_f32_16x16x32_bf16 v[32:35], v[180:183], v[196:199], v[32:35]
	v_mfma_f32_16x16x32_bf16 v[20:23], v[172:175], v[204:207], v[20:23]
	v_mfma_f32_16x16x32_bf16 v[16:19], v[180:183], v[204:207], v[16:19]
	v_mfma_f32_16x16x32_bf16 v[4:7], v[172:175], v[212:215], v[4:7]
	v_mfma_f32_16x16x32_bf16 v[0:3], v[180:183], v[212:215], v[0:3]
	s_barrier
	s_setprio 0
	s_add_i32 s51, s51, 2
	s_add_u32 s49, s49, 0x100
	s_addc_u32 s50, s50, 0
	s_cmp_gt_u32 s51, 41
	s_mov_b64 s[22:23], s[24:25]
	s_cbranch_scc0 .LBB0_862
	s_and_b64 vcc, exec, s[10:11]
	s_cbranch_vccz .LBB0_865
	s_barrier
